# bit-trick bf16 packs replaced by v_cvt_pk_bf16_f32 across whole kernel (176 more pairs)
# speedup vs baseline: 1.0282x; 1.0022x over previous
.LBB0_428:
	s_waitcnt vmcnt(7)
	v_add_f32_e32 v0, v33, v32
	v_add_f32_e32 v0, v34, v0
	v_add_f32_e32 v1, v37, v36
	v_add_f32_e32 v0, v35, v0
	v_add_f32_e32 v1, v38, v1
	v_add_f32_e32 v0, 0, v0
	v_add_f32_e32 v1, v39, v1
	v_add_f32_e32 v0, v1, v0
	v_add_f32_e32 v1, v41, v40
	v_add_f32_e32 v1, v42, v1
	v_add_f32_e32 v1, v43, v1
	v_add_f32_e32 v0, v1, v0
	v_add_f32_e32 v1, v45, v44
	v_add_f32_e32 v1, v46, v1
	v_add_f32_e32 v1, v47, v1
	s_waitcnt vmcnt(6)
	v_add_f32_e32 v4, v1, v0
	v_mov_b32_e32 v0, v57
	v_mov_b32_e32 v1, v49
	v_mov_b32_e32 v2, v56
	v_mov_b32_e32 v3, v48
	v_pk_add_f32 v[0:1], v[0:1], v[2:3]
	v_mov_b32_e32 v2, v58
	v_mov_b32_e32 v3, v50
	v_pk_add_f32 v[0:1], v[2:3], v[0:1]
	v_mov_b32_e32 v2, v59
	v_mov_b32_e32 v3, v51
	v_pk_add_f32 v[0:1], v[2:3], v[0:1]
	v_mov_b32_e32 v2, v60
	v_add_f32_e32 v1, v1, v4
	v_add_f32_e32 v4, v0, v1
	v_mov_b32_e32 v0, v61
	v_mov_b32_e32 v1, v53
	v_mov_b32_e32 v3, v52
	v_pk_add_f32 v[0:1], v[0:1], v[2:3]
	v_mov_b32_e32 v2, v62
	v_mov_b32_e32 v3, v54
	v_pk_add_f32 v[0:1], v[2:3], v[0:1]
	v_mov_b32_e32 v2, v63
	v_mov_b32_e32 v3, v55
	v_pk_add_f32 v[0:1], v[2:3], v[0:1]
	v_cmp_lt_i32_e32 vcc, v97, v95
	v_add_f32_e32 v1, v1, v4
	v_add_f32_e32 v0, v0, v1
	v_cndmask_b32_e32 v1, v110, v97, vcc
	v_lshlrev_b32_e32 v97, 2, v1
	v_cmp_lt_i32_e32 vcc, v99, v95
	s_movk_i32 s15, 0xfff
	s_mov_b64 s[16:17], 0x2000
	s_waitcnt lgkmcnt(0)
	v_mov_b32_e32 v1, v0
	s_nop 1
	v_permlane32_swap_b32_e32 v1, v0
	v_add_f32_e32 v0, v0, v1
	v_cndmask_b32_e32 v1, v110, v99, vcc
	v_lshlrev_b32_e32 v99, 2, v1
	v_cmp_lt_i32_e32 vcc, v101, v95
	s_waitcnt lgkmcnt(0)
	v_mov_b32_e32 v1, v0
	s_nop 1
	v_permlane16_swap_b32_e32 v1, v0
	v_add_f32_e32 v0, v0, v1
	v_cndmask_b32_e32 v1, v110, v101, vcc
	v_lshlrev_b32_e32 v101, 2, v1
	v_cmp_lt_i32_e32 vcc, v103, v95
	s_waitcnt lgkmcnt(0)
	s_nop 1
	v_add_f32_dpp v0, v0, v0 row_mirror row_mask:0xf bank_mask:0xf
	v_cndmask_b32_e32 v1, v110, v103, vcc
	v_lshlrev_b32_e32 v103, 2, v1
	v_cmp_lt_i32_e32 vcc, v105, v95
	s_waitcnt lgkmcnt(0)
	s_nop 1
	v_add_f32_dpp v0, v0, v0 row_half_mirror row_mask:0xf bank_mask:0xf
	v_cndmask_b32_e32 v1, v110, v105, vcc
	v_lshlrev_b32_e32 v105, 2, v1
	v_cmp_lt_i32_e32 vcc, v107, v95
	s_waitcnt lgkmcnt(0)
	s_nop 1
	v_add_f32_dpp v0, v0, v0 quad_perm:[2,3,0,1] row_mask:0xf bank_mask:0xf
	v_cndmask_b32_e32 v1, v110, v107, vcc
	v_lshlrev_b32_e32 v95, 2, v1
	v_cmp_lt_i32_e32 vcc, s15, v88
	v_mov_b32_e32 v107, v161
	s_movk_i32 s15, 0x1fff
	s_waitcnt lgkmcnt(0)
	s_nop 1
	v_add_f32_dpp v0, v0, v0 quad_perm:[1,0,3,2] row_mask:0xf bank_mask:0xf
	v_mul_f32_e32 v6, 0x3a000000, v0
	v_ashrrev_i32_e32 v0, 10, v65
	v_add_u32_e32 v0, 1, v0
	v_cndmask_b32_e32 v0, 0, v0, vcc
	v_add_u32_e32 v0, s11, v0
	v_mul_i32_i24_e32 v0, 0x1800, v0
	v_ashrrev_i32_e32 v1, 31, v0
	v_lshl_add_u64 v[0:1], v[0:1], 2, s[48:49]
	v_lshl_add_u64 v[2:3], v[0:1], 0, s[16:17]
	s_waitcnt vmcnt(3)
	v_lshl_add_u64 v[18:19], v[0:1], 0, v[160:161]
	v_lshl_add_u64 v[4:5], v[2:3], 0, v[160:161]
	global_load_dwordx4 v[10:13], v[18:19], off
	global_load_dwordx4 v[14:17], v[4:5], off
	s_waitcnt vmcnt(4)
	v_pk_add_f32 v[20:21], v[32:33], v[6:7] op_sel_hi:[1,0] neg_lo:[0,1] neg_hi:[0,1]
	s_waitcnt vmcnt(3)
	v_pk_add_f32 v[26:27], v[36:37], v[6:7] op_sel_hi:[1,0] neg_lo:[0,1] neg_hi:[0,1]
	v_pk_mul_f32 v[8:9], v[20:21], v[20:21]
	v_pk_add_f32 v[22:23], v[34:35], v[6:7] op_sel_hi:[1,0] neg_lo:[0,1] neg_hi:[0,1]
	s_waitcnt vmcnt(2)
	v_pk_mul_f32 v[28:29], v[26:27], v[26:27]
	v_pk_add_f32 v[30:31], v[38:39], v[6:7] op_sel_hi:[1,0] neg_lo:[0,1] neg_hi:[0,1]
	v_pk_add_f32 v[34:35], v[40:41], v[6:7] op_sel_hi:[1,0] neg_lo:[0,1] neg_hi:[0,1]
	v_pk_add_f32 v[48:49], v[48:49], v[6:7] op_sel_hi:[1,0] neg_lo:[0,1] neg_hi:[0,1]
	v_pk_add_f32 v[56:57], v[56:57], v[6:7] op_sel_hi:[1,0] neg_lo:[0,1] neg_hi:[0,1]
	v_pk_mul_f32 v[24:25], v[22:23], v[22:23]
	v_pk_mul_f32 v[32:33], v[30:31], v[30:31]
	v_pk_mul_f32 v[36:37], v[34:35], v[34:35]
	v_pk_add_f32 v[38:39], v[42:43], v[6:7] op_sel_hi:[1,0] neg_lo:[0,1] neg_hi:[0,1]
	v_mov_b32_e32 v112, v57
	v_mov_b32_e32 v113, v49
	v_add_f32_e32 v28, v28, v29
	v_add_f32_e32 v8, v8, v9
	v_pk_mul_f32 v[40:41], v[38:39], v[38:39]
	v_pk_add_f32 v[50:51], v[50:51], v[6:7] op_sel_hi:[1,0] neg_lo:[0,1] neg_hi:[0,1]
	v_pk_add_f32 v[58:59], v[58:59], v[6:7] op_sel_hi:[1,0] neg_lo:[0,1] neg_hi:[0,1]
	v_mov_b32_e32 v4, v56
	v_mov_b32_e32 v5, v48
	v_pk_mul_f32 v[112:113], v[112:113], v[112:113]
	v_add_f32_e32 v28, v32, v28
	v_add_f32_e32 v8, v24, v8
	v_add_f32_e32 v9, v36, v37
	v_pk_add_f32 v[42:43], v[44:45], v[6:7] op_sel_hi:[1,0] neg_lo:[0,1] neg_hi:[0,1]
	v_pk_fma_f32 v[4:5], v[4:5], v[4:5], v[112:113]
	v_mov_b32_e32 v112, v58
	v_mov_b32_e32 v113, v50
	v_add_f32_e32 v28, v33, v28
	v_add_f32_e32 v8, v25, v8
	v_add_f32_e32 v9, v40, v9
	v_pk_mul_f32 v[44:45], v[42:43], v[42:43]
	v_pk_add_f32 v[46:47], v[46:47], v[6:7] op_sel_hi:[1,0] neg_lo:[0,1] neg_hi:[0,1]
	v_mov_b32_e32 v114, v59
	v_mov_b32_e32 v115, v51
	v_pk_fma_f32 v[4:5], v[112:113], v[112:113], v[4:5]
	v_add_f32_e32 v8, v8, v28
	v_add_f32_e32 v9, v41, v9
	v_pk_mul_f32 v[110:111], v[46:47], v[46:47]
	v_pk_fma_f32 v[112:113], v[114:115], v[114:115], v[4:5]
	v_pk_add_f32 v[52:53], v[52:53], v[6:7] op_sel_hi:[1,0] neg_lo:[0,1] neg_hi:[0,1]
	v_pk_add_f32 v[4:5], v[60:61], v[6:7] op_sel_hi:[1,0] neg_lo:[0,1] neg_hi:[0,1]
	v_add_f32_e32 v8, v9, v8
	v_add_f32_e32 v9, v44, v45
	v_pk_add_f32 v[54:55], v[54:55], v[6:7] op_sel_hi:[1,0] neg_lo:[0,1] neg_hi:[0,1]
	v_pk_add_f32 v[6:7], v[62:63], v[6:7] op_sel_hi:[1,0] neg_lo:[0,1] neg_hi:[0,1]
	v_mov_b32_e32 v62, v5
	v_mov_b32_e32 v63, v53
	v_add_f32_e32 v9, v110, v9
	v_mov_b32_e32 v60, v4
	v_mov_b32_e32 v61, v52
	v_pk_mul_f32 v[62:63], v[62:63], v[62:63]
	v_add_f32_e32 v9, v111, v9
	v_pk_fma_f32 v[60:61], v[60:61], v[60:61], v[62:63]
	v_mov_b32_e32 v62, v6
	v_mov_b32_e32 v63, v54
	v_add_f32_e32 v8, v9, v8
	v_mov_b32_e32 v114, v7
	v_mov_b32_e32 v115, v55
	v_pk_fma_f32 v[60:61], v[62:63], v[62:63], v[60:61]
	v_add_f32_e32 v8, v113, v8
	v_pk_fma_f32 v[60:61], v[114:115], v[114:115], v[60:61]
	v_add_f32_e32 v8, v112, v8
	v_add_f32_e32 v8, v61, v8
	v_add_f32_e32 v8, v60, v8
	v_mov_b32_e32 v97, v161
	v_readlane_b32 s16, v251, 22
	v_readlane_b32 s17, v251, 23
	s_waitcnt lgkmcnt(0)
	v_mov_b32_e32 v9, v8
	s_nop 1
	v_permlane32_swap_b32_e32 v9, v8
	v_add_f32_e32 v8, v8, v9
	v_mov_b32_e32 v99, v161
	v_lshl_add_u64 v[90:91], v[90:91], 0, s[16:17]
	v_readlane_b32 s16, v251, 26
	v_readlane_b32 s17, v251, 27
	s_waitcnt lgkmcnt(0)
	v_mov_b32_e32 v9, v8
	s_nop 1
	v_permlane16_swap_b32_e32 v9, v8
	v_add_f32_e32 v8, v8, v9
	s_waitcnt vmcnt(0)
	v_pk_add_f32 v[14:15], v[14:15], 1.0 op_sel_hi:[1,0]
	v_pk_add_f32 v[16:17], v[16:17], 1.0 op_sel_hi:[1,0]
	v_mov_b32_e32 v101, v161
	v_lshl_add_u64 v[88:89], v[88:89], 0, s[16:17]
	s_waitcnt lgkmcnt(0)
	s_nop 1
	v_add_f32_dpp v8, v8, v8 row_mirror row_mask:0xf bank_mask:0xf
	v_mov_b32_e32 v103, v161
	v_readlane_b32 s16, v251, 28
	v_readlane_b32 s17, v251, 29
	s_waitcnt lgkmcnt(0)
	s_nop 1
	v_add_f32_dpp v8, v8, v8 row_half_mirror row_mask:0xf bank_mask:0xf
	v_mov_b32_e32 v105, v161
	v_lshl_add_u64 v[92:93], v[92:93], 0, s[16:17]
	s_waitcnt lgkmcnt(0)
	s_nop 1
	v_add_f32_dpp v24, v8, v8 quad_perm:[2,3,0,1] row_mask:0xf bank_mask:0xf
	v_lshlrev_b64 v[8:9], 12, v[108:109]
	v_lshl_add_u64 v[8:9], v[86:87], 0, v[8:9]
	v_mov_b32_e32 v95, v161
	s_waitcnt lgkmcnt(0)
	s_nop 1
	v_add_f32_dpp v24, v24, v24 quad_perm:[1,0,3,2] row_mask:0xf bank_mask:0xf
	v_fmamk_f32 v24, v24, 0x3a000000, v190
	v_mul_f32_e32 v25, 0x4b800000, v24
	v_cmp_gt_f32_e32 vcc, s79, v24
	s_nop 1
	v_cndmask_b32_e32 v24, v24, v25, vcc
	v_rsq_f32_e32 v28, v24
	v_lshl_add_u64 v[24:25], v[2:3], 0, v[94:95]
	v_mul_f32_e32 v29, 0x45800000, v28
	v_cndmask_b32_e32 v28, v28, v29, vcc
	v_pk_mul_f32 v[20:21], v[20:21], v[28:29] op_sel_hi:[1,0]
	v_pk_mul_f32 v[4:5], v[4:5], v[28:29] op_sel_hi:[1,0]
	v_pk_fma_f32 v[10:11], v[14:15], v[20:21], v[10:11]
	v_pk_mul_f32 v[14:15], v[22:23], v[28:29] op_sel_hi:[1,0]
	v_pk_mul_f32 v[22:23], v[26:27], v[28:29] op_sel_hi:[1,0]
	v_pk_fma_f32 v[12:13], v[16:17], v[14:15], v[12:13]
	v_bfe_u32 v16, v11, 16, 1
	v_bfe_u32 v17, v10, 16, 1
	v_add3_u32 v10, v10, v17, s94
	v_add3_u32 v16, v11, v16, s94
	v_cvt_pk_bf16_f32 v12, v12, v13
	v_mov_b32_e32 v11, v12
	v_perm_b32 v10, v16, v10, s95
	global_store_dwordx2 v[8:9], v[10:11], off
	global_load_dwordx4 v[10:13], v[24:25], off
	s_nop 0
	global_load_dwordx4 v[14:17], v[18:19], off offset:1024
	v_lshl_add_u64 v[20:21], v[2:3], 0, v[96:97]
	v_pk_mul_f32 v[24:25], v[38:39], v[28:29] op_sel_hi:[1,0]
	v_pk_mul_f32 v[6:7], v[6:7], v[28:29] op_sel_hi:[1,0]
	v_cmp_lt_i32_e32 vcc, s15, v88
	s_or_b64 s[38:39], vcc, s[38:39]
	s_waitcnt vmcnt(1)
	v_pk_add_f32 v[10:11], v[10:11], 1.0 op_sel_hi:[1,0]
	s_waitcnt vmcnt(0)
	v_pk_fma_f32 v[10:11], v[10:11], v[22:23], v[14:15]
	v_pk_mul_f32 v[14:15], v[30:31], v[28:29] op_sel_hi:[1,0]
	v_pk_add_f32 v[12:13], v[12:13], 1.0 op_sel_hi:[1,0]
	v_pk_mul_f32 v[22:23], v[34:35], v[28:29] op_sel_hi:[1,0]
	v_pk_fma_f32 v[12:13], v[12:13], v[14:15], v[16:17]
	v_cvt_pk_bf16_f32 v12, v12, v13
	v_cvt_pk_bf16_f32 v10, v10, v11
	v_mov_b32_e32 v11, v12
	global_store_dwordx2 v[8:9], v[10:11], off offset:512
	global_load_dwordx4 v[10:13], v[20:21], off
	s_nop 0
	global_load_dwordx4 v[14:17], v[18:19], off offset:2048
	v_lshl_add_u64 v[20:21], v[2:3], 0, v[98:99]
	s_waitcnt vmcnt(1)
	v_pk_add_f32 v[10:11], v[10:11], 1.0 op_sel_hi:[1,0]
	v_pk_add_f32 v[12:13], v[12:13], 1.0 op_sel_hi:[1,0]
	s_waitcnt vmcnt(0)
	v_pk_fma_f32 v[10:11], v[10:11], v[22:23], v[14:15]
	v_pk_fma_f32 v[12:13], v[12:13], v[24:25], v[16:17]
	v_cvt_pk_bf16_f32 v12, v12, v13
	v_cvt_pk_bf16_f32 v10, v10, v11
	v_mov_b32_e32 v11, v12
	global_store_dwordx2 v[8:9], v[10:11], off offset:1024
	global_load_dwordx4 v[10:13], v[20:21], off
	s_nop 0
	global_load_dwordx4 v[14:17], v[18:19], off offset:3072
	v_pk_mul_f32 v[20:21], v[42:43], v[28:29] op_sel_hi:[1,0]
	v_pk_mul_f32 v[22:23], v[46:47], v[28:29] op_sel_hi:[1,0]
	v_lshl_add_u64 v[18:19], v[2:3], 0, v[100:101]
	s_waitcnt vmcnt(1)
	v_pk_add_f32 v[10:11], v[10:11], 1.0 op_sel_hi:[1,0]
	v_pk_add_f32 v[12:13], v[12:13], 1.0 op_sel_hi:[1,0]
	s_waitcnt vmcnt(0)
	v_pk_fma_f32 v[10:11], v[20:21], v[10:11], v[14:15]
	v_pk_fma_f32 v[12:13], v[22:23], v[12:13], v[16:17]
	v_cvt_pk_bf16_f32 v12, v12, v13
	v_cvt_pk_bf16_f32 v10, v10, v11
	v_mov_b32_e32 v11, v12
	global_store_dwordx2 v[8:9], v[10:11], off offset:1536
	global_load_dwordx4 v[10:13], v[18:19], off
	v_lshl_add_u64 v[14:15], v[0:1], 0, v[100:101]
	global_load_dwordx4 v[14:17], v[14:15], off
	v_pk_mul_f32 v[20:21], v[48:49], v[28:29] op_sel_hi:[1,0]
	v_pk_mul_f32 v[22:23], v[50:51], v[28:29] op_sel_hi:[1,0]
	v_lshl_add_u64 v[18:19], v[2:3], 0, v[102:103]
	s_waitcnt vmcnt(1)
	v_pk_add_f32 v[10:11], v[10:11], 1.0 op_sel_hi:[1,0]
	v_pk_add_f32 v[12:13], v[12:13], 1.0 op_sel_hi:[1,0]
	s_waitcnt vmcnt(0)
	v_pk_fma_f32 v[10:11], v[20:21], v[10:11], v[14:15]
	v_pk_fma_f32 v[12:13], v[22:23], v[12:13], v[16:17]
	v_cvt_pk_bf16_f32 v12, v12, v13
	v_cvt_pk_bf16_f32 v10, v10, v11
	v_mov_b32_e32 v11, v12
	global_store_dwordx2 v[8:9], v[10:11], off offset:2048
	global_load_dwordx4 v[10:13], v[18:19], off
	v_lshl_add_u64 v[14:15], v[0:1], 0, v[102:103]
	global_load_dwordx4 v[14:17], v[14:15], off
	v_pk_mul_f32 v[20:21], v[56:57], v[28:29] op_sel_hi:[1,0]
	v_pk_mul_f32 v[22:23], v[58:59], v[28:29] op_sel_hi:[1,0]
	v_lshl_add_u64 v[18:19], v[2:3], 0, v[104:105]
	v_lshl_add_u64 v[2:3], v[2:3], 0, v[106:107]
	s_waitcnt vmcnt(1)
	v_pk_add_f32 v[10:11], v[10:11], 1.0 op_sel_hi:[1,0]
	v_pk_add_f32 v[12:13], v[12:13], 1.0 op_sel_hi:[1,0]
	s_waitcnt vmcnt(0)
	v_pk_fma_f32 v[10:11], v[20:21], v[10:11], v[14:15]
	v_pk_fma_f32 v[12:13], v[22:23], v[12:13], v[16:17]
	v_cvt_pk_bf16_f32 v12, v12, v13
	v_cvt_pk_bf16_f32 v10, v10, v11
	v_mov_b32_e32 v11, v12
	global_store_dwordx2 v[8:9], v[10:11], off offset:2560
	global_load_dwordx4 v[10:13], v[18:19], off
	v_lshl_add_u64 v[14:15], v[0:1], 0, v[104:105]
	global_load_dwordx4 v[14:17], v[14:15], off
	v_pk_mul_f32 v[18:19], v[52:53], v[28:29] op_sel_hi:[1,0]
	v_pk_mul_f32 v[20:21], v[54:55], v[28:29] op_sel_hi:[1,0]
	v_lshl_add_u64 v[0:1], v[0:1], 0, v[106:107]
	s_waitcnt vmcnt(1)
	v_pk_add_f32 v[10:11], v[10:11], 1.0 op_sel_hi:[1,0]
	v_pk_add_f32 v[12:13], v[12:13], 1.0 op_sel_hi:[1,0]
	s_waitcnt vmcnt(0)
	v_pk_fma_f32 v[10:11], v[18:19], v[10:11], v[14:15]
	v_pk_fma_f32 v[12:13], v[20:21], v[12:13], v[16:17]
	v_cvt_pk_bf16_f32 v12, v12, v13
	v_cvt_pk_bf16_f32 v10, v10, v11
	v_mov_b32_e32 v11, v12
	global_store_dwordx2 v[8:9], v[10:11], off offset:3072
	global_load_dwordx4 v[10:13], v[2:3], off
	s_waitcnt vmcnt(0)
	v_pk_add_f32 v[10:11], v[10:11], 1.0 op_sel_hi:[1,0]
	global_load_dwordx4 v[0:3], v[0:1], off
	v_pk_add_f32 v[12:13], v[12:13], 1.0 op_sel_hi:[1,0]
	s_waitcnt vmcnt(0)
	v_pk_fma_f32 v[0:1], v[4:5], v[10:11], v[0:1]
	v_pk_fma_f32 v[2:3], v[6:7], v[12:13], v[2:3]
	v_cvt_pk_bf16_f32 v2, v2, v3
	v_cvt_pk_bf16_f32 v0, v0, v1
	v_mov_b32_e32 v1, v2
	global_store_dwordx2 v[8:9], v[0:1], off offset:3584
	s_andn2_b64 exec, exec, s[38:39]
	s_cbranch_execz .LBB0_437

.LBB0_641:
	s_or_b64 exec, exec, s[36:37]
	v_mov_b32_e32 v0, s1
	s_waitcnt lgkmcnt(0)
	s_barrier
	ds_read_b32 v0, v0
	s_mov_b64 s[36:37], -1
	s_waitcnt lgkmcnt(0)
	v_cmp_le_i32_e32 vcc, s15, v0
	v_readfirstlane_b32 s18, v0
	s_cbranch_vccnz .LBB0_636
	s_cmp_gt_i32 s18, 63
	s_cbranch_scc0 .LBB0_840
	s_lshl_b32 s42, s18, 1
	v_readlane_b32 s19, v251, 54
	s_add_i32 s19, s19, s42
	s_cmpk_gt_i32 s19, 0xff
	s_cbranch_scc0 .LBB0_775
	s_cmpk_gt_u32 s19, 0x1ff
	s_cbranch_scc0 .LBB0_751
	s_cmpk_gt_u32 s19, 0x3ff
	s_cbranch_scc0 .LBB0_704
	s_cmpk_gt_u32 s19, 0x4ff
	s_cbranch_scc0 .LBB0_696
	s_cmpk_gt_u32 s19, 0x5ff
	s_cbranch_scc0 .LBB0_673
	s_cmpk_gt_u32 s19, 0x6ff
	s_cbranch_scc0 .LBB0_654
	s_cmpk_gt_u32 s19, 0xa3f
	s_cbranch_scc0 .LBB0_651
	s_lshl_b32 s20, s19, 3
	s_and_b32 s20, s20, 0x7fffffc0
	s_add_i32 s70, s20, 0xffffae00
	s_lshl_b32 s20, s19, 8
	v_mov_b32_e32 v2, v189
	s_and_b32 s20, s20, 0x700
	s_lshl_b32 s21, s20, 2
	v_ashrrev_i32_e32 v3, 6, v2
	v_readlane_b32 s22, v252, 45
	v_add_u32_e32 v0, s70, v3
	s_add_u32 s22, s22, s21
	v_readlane_b32 s21, v252, 46
	v_lshlrev_b32_e32 v1, 4, v2
	s_addc_u32 s23, s21, 0
	v_and_b32_e32 v160, 0x3f0, v1
	v_ashrrev_i32_e32 v1, 31, v0
	v_lshl_add_u64 v[4:5], s[22:23], 0, v[160:161]
	v_lshlrev_b64 v[0:1], 13, v[0:1]
	v_lshl_add_u64 v[0:1], v[4:5], 0, v[0:1]
	global_load_dwordx4 v[4:7], v[0:1], off
	s_movk_i32 s36, 0x404
	v_mul_lo_u32 v3, v3, s36
	v_add3_u32 v3, s17, v160, v3
	s_mov_b32 s21, 0x8000
	v_add_u32_e32 v8, 0x1010, v3
	s_lshl_b64 s[22:23], s[70:71], 1
	s_waitcnt vmcnt(0)
	ds_write2_b32 v3, v4, v5 offset1:1
	ds_write2_b32 v3, v6, v7 offset0:2 offset1:3
	v_add_co_u32_e32 v4, vcc, s21, v0
	s_mov_b32 s21, 0x10000
	s_nop 0
	v_addc_co_u32_e32 v5, vcc, 0, v1, vcc
	global_load_dwordx4 v[4:7], v[4:5], off
	s_waitcnt vmcnt(0)
	ds_write2_b32 v8, v4, v5 offset1:1
	v_add_u32_e32 v4, 0x1018, v3
	ds_write2_b32 v4, v6, v7 offset1:1
	v_add_co_u32_e32 v4, vcc, s21, v0
	v_add_u32_e32 v8, 0x2020, v3
	s_nop 0
	v_addc_co_u32_e32 v5, vcc, 0, v1, vcc
	global_load_dwordx4 v[4:7], v[4:5], off
	s_mov_b32 s21, 0x18000
	s_waitcnt vmcnt(0)
	ds_write2_b32 v8, v4, v5 offset1:1
	v_add_u32_e32 v4, 0x2028, v3
	ds_write2_b32 v4, v6, v7 offset1:1
	v_add_co_u32_e32 v4, vcc, s21, v0
	v_add_u32_e32 v8, 0x3030, v3
	s_nop 0
	v_addc_co_u32_e32 v5, vcc, 0, v1, vcc
	global_load_dwordx4 v[4:7], v[4:5], off
	s_mov_b32 s21, 0x20000
	s_waitcnt vmcnt(0)
	ds_write2_b32 v8, v4, v5 offset1:1
	v_add_u32_e32 v4, 0x3038, v3
	ds_write2_b32 v4, v6, v7 offset1:1
	v_add_co_u32_e32 v4, vcc, s21, v0
	v_add_u32_e32 v8, 0x4040, v3
	s_nop 0
	v_addc_co_u32_e32 v5, vcc, 0, v1, vcc
	global_load_dwordx4 v[4:7], v[4:5], off
	s_mov_b32 s21, 0x28000
	s_waitcnt vmcnt(0)
	ds_write2_b32 v8, v4, v5 offset1:1
	v_add_u32_e32 v4, 0x4048, v3
	ds_write2_b32 v4, v6, v7 offset1:1
	v_add_co_u32_e32 v4, vcc, s21, v0
	v_add_u32_e32 v8, 0x5050, v3
	s_nop 0
	v_addc_co_u32_e32 v5, vcc, 0, v1, vcc
	global_load_dwordx4 v[4:7], v[4:5], off
	s_mov_b32 s21, 0x30000
	s_waitcnt vmcnt(0)
	ds_write2_b32 v8, v4, v5 offset1:1
	v_add_u32_e32 v4, 0x5058, v3
	ds_write2_b32 v4, v6, v7 offset1:1
	v_add_co_u32_e32 v4, vcc, s21, v0
	v_add_u32_e32 v8, 0x6060, v3
	s_nop 0
	v_addc_co_u32_e32 v5, vcc, 0, v1, vcc
	global_load_dwordx4 v[4:7], v[4:5], off
	s_mov_b32 s21, 0x38000
	s_waitcnt vmcnt(0)
	ds_write2_b32 v8, v4, v5 offset1:1
	v_add_u32_e32 v4, 0x6068, v3
	ds_write2_b32 v4, v6, v7 offset1:1
	v_add_co_u32_e32 v4, vcc, s21, v0
	v_add_u32_e32 v8, 0x7070, v3
	s_nop 0
	v_addc_co_u32_e32 v5, vcc, 0, v1, vcc
	global_load_dwordx4 v[4:7], v[4:5], off
	s_mov_b32 s21, 0x40000
	s_waitcnt vmcnt(0)
	ds_write2_b32 v8, v4, v5 offset1:1
	v_add_u32_e32 v4, 0x7078, v3
	ds_write2_b32 v4, v6, v7 offset1:1
	v_add_co_u32_e32 v4, vcc, s21, v0
	v_add_u32_e32 v8, 0x8080, v3
	s_nop 0
	v_addc_co_u32_e32 v5, vcc, 0, v1, vcc
	global_load_dwordx4 v[4:7], v[4:5], off
	s_mov_b32 s21, 0x48000
	s_waitcnt vmcnt(0)
	ds_write2_b32 v8, v4, v5 offset1:1
	v_add_u32_e32 v4, 0x8088, v3
	ds_write2_b32 v4, v6, v7 offset1:1
	v_add_co_u32_e32 v4, vcc, s21, v0
	v_add_u32_e32 v8, 0x9090, v3
	s_nop 0
	v_addc_co_u32_e32 v5, vcc, 0, v1, vcc
	global_load_dwordx4 v[4:7], v[4:5], off
	s_mov_b32 s21, 0x50000
	s_waitcnt vmcnt(0)
	ds_write2_b32 v8, v4, v5 offset1:1
	v_add_u32_e32 v4, 0x9098, v3
	ds_write2_b32 v4, v6, v7 offset1:1
	v_add_co_u32_e32 v4, vcc, s21, v0
	v_add_u32_e32 v8, 0xa0a0, v3
	s_nop 0
	v_addc_co_u32_e32 v5, vcc, 0, v1, vcc
	global_load_dwordx4 v[4:7], v[4:5], off
	s_mov_b32 s21, 0x58000
	s_waitcnt vmcnt(0)
	ds_write2_b32 v8, v4, v5 offset1:1
	v_add_u32_e32 v4, 0xa0a8, v3
	ds_write2_b32 v4, v6, v7 offset1:1
	v_add_co_u32_e32 v4, vcc, s21, v0
	v_add_u32_e32 v8, 0xb0b0, v3
	s_nop 0
	v_addc_co_u32_e32 v5, vcc, 0, v1, vcc
	global_load_dwordx4 v[4:7], v[4:5], off
	s_mov_b32 s21, 0x60000
	s_waitcnt vmcnt(0)
	ds_write2_b32 v8, v4, v5 offset1:1
	v_add_u32_e32 v4, 0xb0b8, v3
	ds_write2_b32 v4, v6, v7 offset1:1
	v_add_co_u32_e32 v4, vcc, s21, v0
	v_add_u32_e32 v8, 0xc0c0, v3
	s_nop 0
	v_addc_co_u32_e32 v5, vcc, 0, v1, vcc
	global_load_dwordx4 v[4:7], v[4:5], off
	s_mov_b32 s21, 0x68000
	s_waitcnt vmcnt(0)
	ds_write2_b32 v8, v4, v5 offset1:1
	v_add_u32_e32 v4, 0xc0c8, v3
	ds_write2_b32 v4, v6, v7 offset1:1
	v_add_co_u32_e32 v4, vcc, s21, v0
	v_add_u32_e32 v8, 0xd0d0, v3
	s_nop 0
	v_addc_co_u32_e32 v5, vcc, 0, v1, vcc
	global_load_dwordx4 v[4:7], v[4:5], off
	s_mov_b32 s21, 0x70000
	s_waitcnt vmcnt(0)
	ds_write2_b32 v8, v4, v5 offset1:1
	v_add_u32_e32 v4, 0xd0d8, v3
	ds_write2_b32 v4, v6, v7 offset1:1
	v_add_co_u32_e32 v4, vcc, s21, v0
	s_mov_b32 s21, 0x78000
	s_nop 0
	v_addc_co_u32_e32 v5, vcc, 0, v1, vcc
	global_load_dwordx4 v[4:7], v[4:5], off
	v_add_u32_e32 v8, 0xe0e0, v3
	v_add_co_u32_e32 v0, vcc, s21, v0
	v_readlane_b32 s21, v252, 47
	s_nop 0
	v_addc_co_u32_e32 v1, vcc, 0, v1, vcc
	s_add_u32 s22, s21, s22
	v_readlane_b32 s21, v252, 48
	s_addc_u32 s23, s21, s23
	s_waitcnt vmcnt(0)
	ds_write2_b32 v8, v4, v5 offset1:1
	v_add_u32_e32 v4, 0xe0e8, v3
	ds_write2_b32 v4, v6, v7 offset1:1
	global_load_dwordx4 v[4:7], v[0:1], off
	v_add_u32_e32 v0, 0xf0f8, v3
	v_add_u32_e32 v8, 0xf0f0, v3
	s_waitcnt vmcnt(0)
	ds_write2_b32 v0, v6, v7 offset1:1
	v_lshlrev_b32_e32 v0, 3, v2
	ds_write2_b32 v8, v4, v5 offset1:1
	v_and_b32_e32 v3, 56, v0
	v_mov_b32_e32 v4, s17
	v_lshlrev_b32_e32 v160, 1, v3
	v_ashrrev_i32_e32 v8, 3, v2
	v_mad_u32_u24 v3, v3, s36, v4
	v_lshl_add_u32 v4, v8, 2, v3
	s_waitcnt lgkmcnt(0)
	s_barrier
	ds_read_b32 v5, v4
	ds_read_b32 v6, v4 offset:1028
	ds_read_b32 v7, v4 offset:2056
	ds_read_b32 v9, v4 offset:3084
	ds_read_b32 v10, v4 offset:4112
	ds_read_b32 v11, v4 offset:5140
	ds_read_b32 v12, v4 offset:6168
	ds_read_b32 v4, v4 offset:7196
	s_waitcnt lgkmcnt(4)
	v_bfe_u32 v20, v5, 16, 1
	v_add3_u32 v20, v5, v20, s94
	v_cvt_pk_bf16_f32 v9, v7, v9
	v_add_u32_e32 v8, s20, v8
	s_waitcnt lgkmcnt(0)
	v_bfe_u32 v19, v6, 16, 1
	v_mov_b32_e32 v5, v9
	v_ashrrev_i32_e32 v9, 31, v8
	v_lshl_add_u64 v[0:1], s[22:23], 0, v[160:161]
	v_add3_u32 v19, v6, v19, s94
	v_cvt_pk_bf16_f32 v10, v10, v11
	v_cvt_pk_bf16_f32 v4, v12, v4
	v_lshlrev_b64 v[8:9], 12, v[8:9]
	v_mov_b32_e32 v7, v4
	v_mov_b32_e32 v6, v10
	v_perm_b32 v4, v19, v20, s95
	v_lshl_add_u64 v[8:9], v[0:1], 0, v[8:9]
	global_store_dwordx4 v[8:9], v[4:7], off
	s_mov_b64 s[36:37], 0
	s_nop 0
	v_add_u32_e32 v4, 0x100, v2
	v_ashrrev_i32_e32 v8, 3, v4
	v_lshl_add_u32 v4, v8, 2, v3
	ds_read_b32 v5, v4
	ds_read_b32 v6, v4 offset:1028
	ds_read_b32 v7, v4 offset:2056
	ds_read_b32 v9, v4 offset:3084
	ds_read_b32 v10, v4 offset:4112
	ds_read_b32 v11, v4 offset:5140
	ds_read_b32 v12, v4 offset:6168
	ds_read_b32 v4, v4 offset:7196
	s_waitcnt lgkmcnt(4)
	v_bfe_u32 v20, v5, 16, 1
	v_add3_u32 v20, v5, v20, s94
	v_cvt_pk_bf16_f32 v9, v7, v9
	v_add_u32_e32 v8, s20, v8
	s_waitcnt lgkmcnt(0)
	v_bfe_u32 v19, v6, 16, 1
	v_mov_b32_e32 v5, v9
	v_ashrrev_i32_e32 v9, 31, v8
	v_add3_u32 v19, v6, v19, s94
	v_cvt_pk_bf16_f32 v10, v10, v11
	v_cvt_pk_bf16_f32 v4, v12, v4
	v_lshlrev_b64 v[8:9], 12, v[8:9]
	v_mov_b32_e32 v7, v4
	v_mov_b32_e32 v6, v10
	v_perm_b32 v4, v19, v20, s95
	v_lshl_add_u64 v[8:9], v[0:1], 0, v[8:9]
	global_store_dwordx4 v[8:9], v[4:7], off
	s_nop 1
	v_add_u32_e32 v4, 0x200, v2
	v_ashrrev_i32_e32 v8, 3, v4
	v_lshl_add_u32 v4, v8, 2, v3
	ds_read_b32 v5, v4
	ds_read_b32 v6, v4 offset:1028
	ds_read_b32 v7, v4 offset:2056
	ds_read_b32 v9, v4 offset:3084
	ds_read_b32 v10, v4 offset:4112
	ds_read_b32 v11, v4 offset:5140
	ds_read_b32 v12, v4 offset:6168
	ds_read_b32 v4, v4 offset:7196
	s_waitcnt lgkmcnt(4)
	v_bfe_u32 v20, v5, 16, 1
	v_add3_u32 v20, v5, v20, s94
	v_cvt_pk_bf16_f32 v9, v7, v9
	v_add_u32_e32 v8, s20, v8
	s_waitcnt lgkmcnt(0)
	v_bfe_u32 v19, v6, 16, 1
	v_mov_b32_e32 v5, v9
	v_ashrrev_i32_e32 v9, 31, v8
	v_add3_u32 v19, v6, v19, s94
	v_cvt_pk_bf16_f32 v10, v10, v11
	v_cvt_pk_bf16_f32 v4, v12, v4
	v_lshlrev_b64 v[8:9], 12, v[8:9]
	v_mov_b32_e32 v7, v4
	v_mov_b32_e32 v6, v10
	v_perm_b32 v4, v19, v20, s95
	v_lshl_add_u64 v[8:9], v[0:1], 0, v[8:9]
	global_store_dwordx4 v[8:9], v[4:7], off
	s_nop 1
	v_add_u32_e32 v4, 0x300, v2
	v_ashrrev_i32_e32 v8, 3, v4
	v_lshl_add_u32 v4, v8, 2, v3
	ds_read_b32 v5, v4
	ds_read_b32 v6, v4 offset:1028
	ds_read_b32 v7, v4 offset:2056
	ds_read_b32 v9, v4 offset:3084
	ds_read_b32 v10, v4 offset:4112
	ds_read_b32 v11, v4 offset:5140
	ds_read_b32 v12, v4 offset:6168
	ds_read_b32 v4, v4 offset:7196
	s_waitcnt lgkmcnt(4)
	v_bfe_u32 v20, v5, 16, 1
	v_add3_u32 v20, v5, v20, s94
	v_cvt_pk_bf16_f32 v9, v7, v9
	v_add_u32_e32 v8, s20, v8
	s_waitcnt lgkmcnt(0)
	v_bfe_u32 v19, v6, 16, 1
	v_mov_b32_e32 v5, v9
	v_ashrrev_i32_e32 v9, 31, v8
	v_add3_u32 v19, v6, v19, s94
	v_cvt_pk_bf16_f32 v10, v10, v11
	v_cvt_pk_bf16_f32 v4, v12, v4
	v_lshlrev_b64 v[8:9], 12, v[8:9]
	v_mov_b32_e32 v7, v4
	v_mov_b32_e32 v6, v10
	v_perm_b32 v4, v19, v20, s95
	v_lshl_add_u64 v[8:9], v[0:1], 0, v[8:9]
	global_store_dwordx4 v[8:9], v[4:7], off
	s_nop 1
	v_add_u32_e32 v4, 0x400, v2
	v_ashrrev_i32_e32 v8, 3, v4
	v_lshl_add_u32 v4, v8, 2, v3
	ds_read_b32 v5, v4
	ds_read_b32 v6, v4 offset:1028
	ds_read_b32 v7, v4 offset:2056
	ds_read_b32 v9, v4 offset:3084
	ds_read_b32 v10, v4 offset:4112
	ds_read_b32 v11, v4 offset:5140
	ds_read_b32 v12, v4 offset:6168
	ds_read_b32 v4, v4 offset:7196
	s_waitcnt lgkmcnt(4)
	v_bfe_u32 v20, v5, 16, 1
	v_add3_u32 v20, v5, v20, s94
	v_cvt_pk_bf16_f32 v9, v7, v9
	v_add_u32_e32 v8, s20, v8
	s_waitcnt lgkmcnt(0)
	v_bfe_u32 v19, v6, 16, 1
	v_mov_b32_e32 v5, v9
	v_ashrrev_i32_e32 v9, 31, v8
	v_add3_u32 v19, v6, v19, s94
	v_cvt_pk_bf16_f32 v10, v10, v11
	v_cvt_pk_bf16_f32 v4, v12, v4
	v_lshlrev_b64 v[8:9], 12, v[8:9]
	v_mov_b32_e32 v7, v4
	v_mov_b32_e32 v6, v10
	v_perm_b32 v4, v19, v20, s95
	v_lshl_add_u64 v[8:9], v[0:1], 0, v[8:9]
	global_store_dwordx4 v[8:9], v[4:7], off
	s_nop 1
	v_add_u32_e32 v4, 0x500, v2
	v_ashrrev_i32_e32 v8, 3, v4
	v_lshl_add_u32 v4, v8, 2, v3
	ds_read_b32 v5, v4
	ds_read_b32 v6, v4 offset:1028
	ds_read_b32 v7, v4 offset:2056
	ds_read_b32 v9, v4 offset:3084
	ds_read_b32 v10, v4 offset:4112
	ds_read_b32 v11, v4 offset:5140
	ds_read_b32 v12, v4 offset:6168
	ds_read_b32 v4, v4 offset:7196
	s_waitcnt lgkmcnt(4)
	v_bfe_u32 v20, v5, 16, 1
	v_add3_u32 v20, v5, v20, s94
	v_cvt_pk_bf16_f32 v9, v7, v9
	v_add_u32_e32 v8, s20, v8
	s_waitcnt lgkmcnt(0)
	v_bfe_u32 v19, v6, 16, 1
	v_mov_b32_e32 v5, v9
	v_ashrrev_i32_e32 v9, 31, v8
	v_add3_u32 v19, v6, v19, s94
	v_cvt_pk_bf16_f32 v10, v10, v11
	v_cvt_pk_bf16_f32 v4, v12, v4
	v_lshlrev_b64 v[8:9], 12, v[8:9]
	v_mov_b32_e32 v7, v4
	v_mov_b32_e32 v6, v10
	v_perm_b32 v4, v19, v20, s95
	v_lshl_add_u64 v[8:9], v[0:1], 0, v[8:9]
	global_store_dwordx4 v[8:9], v[4:7], off
	s_nop 1
	v_add_u32_e32 v4, 0x600, v2
	v_ashrrev_i32_e32 v8, 3, v4
	v_lshl_add_u32 v4, v8, 2, v3
	ds_read_b32 v5, v4
	ds_read_b32 v6, v4 offset:1028
	ds_read_b32 v7, v4 offset:2056
	ds_read_b32 v9, v4 offset:3084
	ds_read_b32 v10, v4 offset:4112
	ds_read_b32 v11, v4 offset:5140
	ds_read_b32 v12, v4 offset:6168
	ds_read_b32 v4, v4 offset:7196
	s_waitcnt lgkmcnt(4)
	v_bfe_u32 v20, v5, 16, 1
	v_add3_u32 v20, v5, v20, s94
	v_cvt_pk_bf16_f32 v9, v7, v9
	v_add_u32_e32 v8, s20, v8
	s_waitcnt lgkmcnt(0)
	v_bfe_u32 v19, v6, 16, 1
	v_mov_b32_e32 v5, v9
	v_ashrrev_i32_e32 v9, 31, v8
	v_add3_u32 v19, v6, v19, s94
	v_cvt_pk_bf16_f32 v10, v10, v11
	v_cvt_pk_bf16_f32 v4, v12, v4
	v_lshlrev_b64 v[8:9], 12, v[8:9]
	v_mov_b32_e32 v7, v4
	v_mov_b32_e32 v6, v10
	v_perm_b32 v4, v19, v20, s95
	v_lshl_add_u64 v[8:9], v[0:1], 0, v[8:9]
	v_add_u32_e32 v2, 0x700, v2
	global_store_dwordx4 v[8:9], v[4:7], off
	s_nop 1
	v_ashrrev_i32_e32 v6, 3, v2
	v_lshl_add_u32 v2, v6, 2, v3
	ds_read_b32 v3, v2
	ds_read_b32 v4, v2 offset:1028
	ds_read_b32 v5, v2 offset:2056
	ds_read_b32 v7, v2 offset:3084
	ds_read_b32 v8, v2 offset:4112
	ds_read_b32 v9, v2 offset:5140
	ds_read_b32 v10, v2 offset:6168
	ds_read_b32 v2, v2 offset:7196
	s_waitcnt lgkmcnt(4)
	v_bfe_u32 v18, v3, 16, 1
	v_add3_u32 v18, v3, v18, s94
	v_cvt_pk_bf16_f32 v7, v5, v7
	v_add_u32_e32 v6, s20, v6
	s_waitcnt lgkmcnt(0)
	v_bfe_u32 v17, v4, 16, 1
	v_mov_b32_e32 v3, v7
	v_ashrrev_i32_e32 v7, 31, v6
	v_add3_u32 v17, v4, v17, s94
	v_cvt_pk_bf16_f32 v8, v8, v9
	v_cvt_pk_bf16_f32 v2, v10, v2
	v_lshlrev_b64 v[6:7], 12, v[6:7]
	v_mov_b32_e32 v5, v2
	v_mov_b32_e32 v4, v8
	v_perm_b32 v2, v17, v18, s95
	v_lshl_add_u64 v[0:1], v[0:1], 0, v[6:7]
	global_store_dwordx4 v[0:1], v[2:5], off
	s_barrier
.LBB0_651:
	s_andn2_b64 vcc, exec, s[36:37]
	s_cbranch_vccnz .LBB0_653
	s_add_i32 s20, s19, 0xf900
	s_and_b32 s21, s20, 0xffff
	s_mulk_i32 s21, 0x4ec5
	s_lshr_b32 s21, s21, 19
	s_mul_i32 s22, s21, 26
	s_sub_i32 s20, s20, s22
	s_lshl_b32 s20, s20, 8
	s_and_b32 s20, s20, 0xff00
	v_mov_b32_e32 v22, v189
	s_lshl_b32 s22, s20, 2
	v_readlane_b32 s23, v252, 49
	s_add_u32 s22, s23, s22
	v_ashrrev_i32_e32 v23, 6, v22
	v_readlane_b32 s23, v252, 50
	v_lshlrev_b32_e32 v0, 4, v22
	v_lshl_add_u32 v26, s21, 6, v23
	s_addc_u32 s23, s23, 0
	v_and_b32_e32 v160, 0x3f0, v0
	v_lshl_add_u64 v[0:1], s[22:23], 0, v[160:161]
	s_movk_i32 s36, 0x6800
	v_add_u32_e32 v2, 4, v26
	v_mad_i64_i32 v[28:29], s[22:23], v2, s36, v[0:1]
	v_add_u32_e32 v2, 8, v26
	v_mad_i64_i32 v[30:31], s[22:23], v2, s36, v[0:1]
	v_add_u32_e32 v2, 12, v26
	v_mad_i64_i32 v[32:33], s[22:23], v2, s36, v[0:1]
	v_add_u32_e32 v2, 16, v26
	v_mad_i64_i32 v[34:35], s[22:23], v2, s36, v[0:1]
	v_add_u32_e32 v2, 20, v26
	v_mad_i64_i32 v[20:21], s[22:23], v2, s36, v[0:1]
	v_add_u32_e32 v2, 24, v26
	v_mad_i64_i32 v[18:19], s[22:23], v2, s36, v[0:1]
	v_add_u32_e32 v2, 28, v26
	v_mad_i64_i32 v[16:17], s[22:23], v2, s36, v[0:1]
	v_add_u32_e32 v2, 32, v26
	v_mad_i64_i32 v[14:15], s[22:23], v2, s36, v[0:1]
	v_add_u32_e32 v2, 36, v26
	v_mad_i64_i32 v[12:13], s[22:23], v2, s36, v[0:1]
	v_add_u32_e32 v2, 40, v26
	v_mad_i64_i32 v[10:11], s[22:23], v2, s36, v[0:1]
	v_add_u32_e32 v2, 44, v26
	v_mad_i64_i32 v[8:9], s[22:23], v2, s36, v[0:1]
	v_add_u32_e32 v2, 48, v26
	v_mad_i64_i32 v[6:7], s[22:23], v2, s36, v[0:1]
	v_add_u32_e32 v2, 52, v26
	v_mad_i64_i32 v[24:25], s[22:23], v26, s36, v[0:1]
	v_mad_i64_i32 v[4:5], s[22:23], v2, s36, v[0:1]
	v_add_u32_e32 v2, 56, v26
	v_add_u32_e32 v26, 60, v26
	v_mad_i64_i32 v[2:3], s[22:23], v2, s36, v[0:1]
	v_mad_i64_i32 v[0:1], s[22:23], v26, s36, v[0:1]
	global_load_dwordx4 v[24:27], v[24:25], off
	s_movk_i32 s36, 0x404
	v_mul_lo_u32 v23, v23, s36
	v_add3_u32 v23, s17, v160, v23
	v_add_u32_e32 v36, 0x1010, v23
	s_lshl_b32 s21, s21, 7
	v_readlane_b32 s22, v252, 51
	s_add_u32 s22, s22, s21
	v_readlane_b32 s21, v252, 52
	s_addc_u32 s23, s21, 0
	s_waitcnt vmcnt(0)
	ds_write2_b32 v23, v24, v25 offset1:1
	ds_write2_b32 v23, v26, v27 offset0:2 offset1:3
	global_load_dwordx4 v[24:27], v[28:29], off
	v_add_u32_e32 v28, 0x2020, v23
	s_waitcnt vmcnt(0)
	ds_write2_b32 v36, v24, v25 offset1:1
	v_add_u32_e32 v24, 0x1018, v23
	ds_write2_b32 v24, v26, v27 offset1:1
	global_load_dwordx4 v[24:27], v[30:31], off
	s_waitcnt vmcnt(0)
	ds_write2_b32 v28, v24, v25 offset1:1
	v_add_u32_e32 v24, 0x2028, v23
	ds_write2_b32 v24, v26, v27 offset1:1
	global_load_dwordx4 v[24:27], v[32:33], off
	v_add_u32_e32 v28, 0x3030, v23
	s_waitcnt vmcnt(0)
	ds_write2_b32 v28, v24, v25 offset1:1
	v_add_u32_e32 v24, 0x3038, v23
	ds_write2_b32 v24, v26, v27 offset1:1
	global_load_dwordx4 v[24:27], v[34:35], off
	v_add_u32_e32 v28, 0x4040, v23
	s_waitcnt vmcnt(0)
	ds_write2_b32 v28, v24, v25 offset1:1
	v_add_u32_e32 v24, 0x4048, v23
	ds_write2_b32 v24, v26, v27 offset1:1
	global_load_dwordx4 v[24:27], v[20:21], off
	v_add_u32_e32 v20, 0x5058, v23
	v_add_u32_e32 v28, 0x5050, v23
	s_waitcnt vmcnt(0)
	ds_write2_b32 v20, v26, v27 offset1:1
	global_load_dwordx4 v[18:21], v[18:19], off
	ds_write2_b32 v28, v24, v25 offset1:1
	v_add_u32_e32 v24, 0x6060, v23
	s_waitcnt vmcnt(0)
	ds_write2_b32 v24, v18, v19 offset1:1
	v_add_u32_e32 v18, 0x6068, v23
	ds_write2_b32 v18, v20, v21 offset1:1
	global_load_dwordx4 v[16:19], v[16:17], off
	v_add_u32_e32 v20, 0x7070, v23
	s_waitcnt vmcnt(0)
	ds_write2_b32 v20, v16, v17 offset1:1
	v_add_u32_e32 v16, 0x7078, v23
	ds_write2_b32 v16, v18, v19 offset1:1
	global_load_dwordx4 v[14:17], v[14:15], off
	v_add_u32_e32 v18, 0x8080, v23
	s_waitcnt vmcnt(0)
	ds_write2_b32 v18, v14, v15 offset1:1
	v_add_u32_e32 v14, 0x8088, v23
	ds_write2_b32 v14, v16, v17 offset1:1
	global_load_dwordx4 v[12:15], v[12:13], off
	v_add_u32_e32 v16, 0x9090, v23
	s_waitcnt vmcnt(0)
	ds_write2_b32 v16, v12, v13 offset1:1
	v_add_u32_e32 v12, 0x9098, v23
	ds_write2_b32 v12, v14, v15 offset1:1
	global_load_dwordx4 v[10:13], v[10:11], off
	v_add_u32_e32 v14, 0xa0a0, v23
	s_waitcnt vmcnt(0)
	ds_write2_b32 v14, v10, v11 offset1:1
	v_add_u32_e32 v10, 0xa0a8, v23
	ds_write2_b32 v10, v12, v13 offset1:1
	global_load_dwordx4 v[8:11], v[8:9], off
	v_add_u32_e32 v12, 0xb0b0, v23
	s_waitcnt vmcnt(0)
	ds_write2_b32 v12, v8, v9 offset1:1
	v_add_u32_e32 v8, 0xb0b8, v23
	ds_write2_b32 v8, v10, v11 offset1:1
	global_load_dwordx4 v[6:9], v[6:7], off
	v_add_u32_e32 v10, 0xc0c0, v23
	s_waitcnt vmcnt(0)
	ds_write2_b32 v10, v6, v7 offset1:1
	v_add_u32_e32 v6, 0xc0c8, v23
	ds_write2_b32 v6, v8, v9 offset1:1
	global_load_dwordx4 v[4:7], v[4:5], off
	v_add_u32_e32 v8, 0xd0d0, v23
	s_waitcnt vmcnt(0)
	ds_write2_b32 v8, v4, v5 offset1:1
	v_add_u32_e32 v4, 0xd0d8, v23
	ds_write2_b32 v4, v6, v7 offset1:1
	global_load_dwordx4 v[2:5], v[2:3], off
	v_add_u32_e32 v6, 0xe0e0, v23
	s_waitcnt vmcnt(0)
	ds_write2_b32 v6, v2, v3 offset1:1
	v_add_u32_e32 v2, 0xe0e8, v23
	ds_write2_b32 v2, v4, v5 offset1:1
	global_load_dwordx4 v[0:3], v[0:1], off
	v_add_u32_e32 v4, 0xf0f0, v23
	s_waitcnt vmcnt(0)
	ds_write2_b32 v4, v0, v1 offset1:1
	v_add_u32_e32 v0, 0xf0f8, v23
	ds_write2_b32 v0, v2, v3 offset1:1
	v_lshlrev_b32_e32 v0, 3, v22
	v_and_b32_e32 v2, 56, v0
	v_mov_b32_e32 v4, s17
	v_lshlrev_b32_e32 v160, 1, v2
	v_ashrrev_i32_e32 v3, 3, v22
	v_mad_u32_u24 v2, v2, s36, v4
	v_lshl_add_u32 v4, v3, 2, v2
	s_waitcnt lgkmcnt(0)
	s_barrier
	ds_read_b32 v5, v4
	ds_read_b32 v6, v4 offset:1028
	ds_read_b32 v7, v4 offset:2056
	ds_read_b32 v8, v4 offset:3084
	ds_read_b32 v9, v4 offset:4112
	ds_read_b32 v10, v4 offset:5140
	ds_read_b32 v11, v4 offset:6168
	ds_read_b32 v4, v4 offset:7196
	s_waitcnt lgkmcnt(4)
	v_bfe_u32 v19, v5, 16, 1
	s_waitcnt lgkmcnt(2)
	v_bfe_u32 v18, v6, 16, 1
	v_add3_u32 v19, v5, v19, s94
	v_cvt_pk_bf16_f32 v8, v7, v8
	v_add3_u32 v18, v6, v18, s94
	v_cvt_pk_bf16_f32 v9, v9, v10
	v_mov_b32_e32 v5, v8
	v_add_u32_e32 v8, s20, v3
	s_waitcnt lgkmcnt(0)
	v_mov_b32_e32 v6, v9
	v_ashrrev_i32_e32 v9, 31, v8
	v_lshl_add_u64 v[0:1], s[22:23], 0, v[160:161]
	v_cvt_pk_bf16_f32 v4, v11, v4
	v_lshlrev_b64 v[8:9], 12, v[8:9]
	v_add_u32_e32 v3, 0x100, v22
	v_mov_b32_e32 v7, v4
	v_perm_b32 v4, v18, v19, s95
	v_lshl_add_u64 v[8:9], v[0:1], 0, v[8:9]
	v_ashrrev_i32_e32 v3, 3, v3
	global_store_dwordx4 v[8:9], v[4:7], off
	s_nop 1
	v_lshl_add_u32 v4, v3, 2, v2
	ds_read_b32 v5, v4
	ds_read_b32 v6, v4 offset:1028
	ds_read_b32 v7, v4 offset:2056
	ds_read_b32 v8, v4 offset:3084
	ds_read_b32 v9, v4 offset:4112
	ds_read_b32 v10, v4 offset:5140
	ds_read_b32 v11, v4 offset:6168
	ds_read_b32 v4, v4 offset:7196
	s_waitcnt lgkmcnt(4)
	v_bfe_u32 v19, v5, 16, 1
	s_waitcnt lgkmcnt(2)
	v_bfe_u32 v18, v6, 16, 1
	v_add3_u32 v19, v5, v19, s94
	v_cvt_pk_bf16_f32 v8, v7, v8
	v_add3_u32 v18, v6, v18, s94
	v_cvt_pk_bf16_f32 v9, v9, v10
	v_mov_b32_e32 v5, v8
	v_add_u32_e32 v8, s20, v3
	s_waitcnt lgkmcnt(0)
	v_mov_b32_e32 v6, v9
	v_ashrrev_i32_e32 v9, 31, v8
	v_cvt_pk_bf16_f32 v4, v11, v4
	v_lshlrev_b64 v[8:9], 12, v[8:9]
	v_add_u32_e32 v3, 0x200, v22
	v_mov_b32_e32 v7, v4
	v_perm_b32 v4, v18, v19, s95
	v_lshl_add_u64 v[8:9], v[0:1], 0, v[8:9]
	v_ashrrev_i32_e32 v3, 3, v3
	global_store_dwordx4 v[8:9], v[4:7], off
	s_nop 1
	v_lshl_add_u32 v4, v3, 2, v2
	ds_read_b32 v5, v4
	ds_read_b32 v6, v4 offset:1028
	ds_read_b32 v7, v4 offset:2056
	ds_read_b32 v8, v4 offset:3084
	ds_read_b32 v9, v4 offset:4112
	ds_read_b32 v10, v4 offset:5140
	ds_read_b32 v11, v4 offset:6168
	ds_read_b32 v4, v4 offset:7196
	s_waitcnt lgkmcnt(4)
	v_bfe_u32 v19, v5, 16, 1
	s_waitcnt lgkmcnt(2)
	v_bfe_u32 v18, v6, 16, 1
	v_add3_u32 v19, v5, v19, s94
	v_cvt_pk_bf16_f32 v8, v7, v8
	v_add3_u32 v18, v6, v18, s94
	v_cvt_pk_bf16_f32 v9, v9, v10
	v_mov_b32_e32 v5, v8
	v_add_u32_e32 v8, s20, v3
	s_waitcnt lgkmcnt(0)
	v_mov_b32_e32 v6, v9
	v_ashrrev_i32_e32 v9, 31, v8
	v_cvt_pk_bf16_f32 v4, v11, v4
	v_lshlrev_b64 v[8:9], 12, v[8:9]
	v_add_u32_e32 v3, 0x300, v22
	v_mov_b32_e32 v7, v4
	v_perm_b32 v4, v18, v19, s95
	v_lshl_add_u64 v[8:9], v[0:1], 0, v[8:9]
	v_ashrrev_i32_e32 v3, 3, v3
	global_store_dwordx4 v[8:9], v[4:7], off
	s_nop 1
	v_lshl_add_u32 v4, v3, 2, v2
	ds_read_b32 v5, v4
	ds_read_b32 v6, v4 offset:1028
	ds_read_b32 v7, v4 offset:2056
	ds_read_b32 v8, v4 offset:3084
	ds_read_b32 v9, v4 offset:4112
	ds_read_b32 v10, v4 offset:5140
	ds_read_b32 v11, v4 offset:6168
	ds_read_b32 v4, v4 offset:7196
	s_waitcnt lgkmcnt(4)
	v_bfe_u32 v19, v5, 16, 1
	s_waitcnt lgkmcnt(2)
	v_bfe_u32 v18, v6, 16, 1
	v_add3_u32 v19, v5, v19, s94
	v_cvt_pk_bf16_f32 v8, v7, v8
	v_add3_u32 v18, v6, v18, s94
	v_cvt_pk_bf16_f32 v9, v9, v10
	v_mov_b32_e32 v5, v8
	v_add_u32_e32 v8, s20, v3
	s_waitcnt lgkmcnt(0)
	v_mov_b32_e32 v6, v9
	v_ashrrev_i32_e32 v9, 31, v8
	v_cvt_pk_bf16_f32 v4, v11, v4
	v_lshlrev_b64 v[8:9], 12, v[8:9]
	v_add_u32_e32 v3, 0x400, v22
	v_mov_b32_e32 v7, v4
	v_perm_b32 v4, v18, v19, s95
	v_lshl_add_u64 v[8:9], v[0:1], 0, v[8:9]
	v_ashrrev_i32_e32 v3, 3, v3
	global_store_dwordx4 v[8:9], v[4:7], off
	s_nop 1
	v_lshl_add_u32 v4, v3, 2, v2
	ds_read_b32 v5, v4
	ds_read_b32 v6, v4 offset:1028
	ds_read_b32 v7, v4 offset:2056
	ds_read_b32 v8, v4 offset:3084
	ds_read_b32 v9, v4 offset:4112
	ds_read_b32 v10, v4 offset:5140
	ds_read_b32 v11, v4 offset:6168
	ds_read_b32 v4, v4 offset:7196
	s_waitcnt lgkmcnt(4)
	v_bfe_u32 v19, v5, 16, 1
	s_waitcnt lgkmcnt(2)
	v_bfe_u32 v18, v6, 16, 1
	v_add3_u32 v19, v5, v19, s94
	v_cvt_pk_bf16_f32 v8, v7, v8
	v_add3_u32 v18, v6, v18, s94
	v_cvt_pk_bf16_f32 v9, v9, v10
	v_mov_b32_e32 v5, v8
	v_add_u32_e32 v8, s20, v3
	s_waitcnt lgkmcnt(0)
	v_mov_b32_e32 v6, v9
	v_ashrrev_i32_e32 v9, 31, v8
	v_cvt_pk_bf16_f32 v4, v11, v4
	v_lshlrev_b64 v[8:9], 12, v[8:9]
	v_add_u32_e32 v3, 0x500, v22
	v_mov_b32_e32 v7, v4
	v_perm_b32 v4, v18, v19, s95
	v_lshl_add_u64 v[8:9], v[0:1], 0, v[8:9]
	v_ashrrev_i32_e32 v3, 3, v3
	global_store_dwordx4 v[8:9], v[4:7], off
	s_nop 1
	v_lshl_add_u32 v4, v3, 2, v2
	ds_read_b32 v5, v4
	ds_read_b32 v6, v4 offset:1028
	ds_read_b32 v7, v4 offset:2056
	ds_read_b32 v8, v4 offset:3084
	ds_read_b32 v9, v4 offset:4112
	ds_read_b32 v10, v4 offset:5140
	ds_read_b32 v11, v4 offset:6168
	ds_read_b32 v4, v4 offset:7196
	s_waitcnt lgkmcnt(4)
	v_bfe_u32 v19, v5, 16, 1
	s_waitcnt lgkmcnt(2)
	v_bfe_u32 v18, v6, 16, 1
	v_add3_u32 v19, v5, v19, s94
	v_cvt_pk_bf16_f32 v8, v7, v8
	v_add3_u32 v18, v6, v18, s94
	v_cvt_pk_bf16_f32 v9, v9, v10
	v_mov_b32_e32 v5, v8
	v_add_u32_e32 v8, s20, v3
	s_waitcnt lgkmcnt(0)
	v_mov_b32_e32 v6, v9
	v_ashrrev_i32_e32 v9, 31, v8
	v_cvt_pk_bf16_f32 v4, v11, v4
	v_lshlrev_b64 v[8:9], 12, v[8:9]
	v_add_u32_e32 v3, 0x600, v22
	v_mov_b32_e32 v7, v4
	v_perm_b32 v4, v18, v19, s95
	v_lshl_add_u64 v[8:9], v[0:1], 0, v[8:9]
	v_ashrrev_i32_e32 v3, 3, v3
	global_store_dwordx4 v[8:9], v[4:7], off
	s_nop 1
	v_lshl_add_u32 v4, v3, 2, v2
	ds_read_b32 v5, v4
	ds_read_b32 v6, v4 offset:1028
	ds_read_b32 v7, v4 offset:2056
	ds_read_b32 v8, v4 offset:3084
	ds_read_b32 v9, v4 offset:4112
	ds_read_b32 v10, v4 offset:5140
	ds_read_b32 v11, v4 offset:6168
	ds_read_b32 v4, v4 offset:7196
	s_waitcnt lgkmcnt(4)
	v_bfe_u32 v19, v5, 16, 1
	s_waitcnt lgkmcnt(2)
	v_bfe_u32 v18, v6, 16, 1
	v_add3_u32 v19, v5, v19, s94
	v_cvt_pk_bf16_f32 v8, v7, v8
	v_add3_u32 v18, v6, v18, s94
	v_cvt_pk_bf16_f32 v9, v9, v10
	v_mov_b32_e32 v5, v8
	v_add_u32_e32 v8, s20, v3
	s_waitcnt lgkmcnt(0)
	v_mov_b32_e32 v6, v9
	v_ashrrev_i32_e32 v9, 31, v8
	v_cvt_pk_bf16_f32 v4, v11, v4
	v_lshlrev_b64 v[8:9], 12, v[8:9]
	v_mov_b32_e32 v7, v4
	v_perm_b32 v4, v18, v19, s95
	v_lshl_add_u64 v[8:9], v[0:1], 0, v[8:9]
	v_add_u32_e32 v3, 0x700, v22
	global_store_dwordx4 v[8:9], v[4:7], off
	s_nop 1
	v_ashrrev_i32_e32 v6, 3, v3
	v_lshl_add_u32 v2, v6, 2, v2
	ds_read_b32 v3, v2
	ds_read_b32 v4, v2 offset:1028
	ds_read_b32 v5, v2 offset:2056
	ds_read_b32 v7, v2 offset:3084
	ds_read_b32 v8, v2 offset:4112
	ds_read_b32 v9, v2 offset:5140
	ds_read_b32 v10, v2 offset:6168
	ds_read_b32 v2, v2 offset:7196
	s_waitcnt lgkmcnt(4)
	v_bfe_u32 v18, v3, 16, 1
	v_add3_u32 v18, v3, v18, s94
	v_cvt_pk_bf16_f32 v7, v5, v7
	v_add_u32_e32 v6, s20, v6
	s_waitcnt lgkmcnt(0)
	v_bfe_u32 v11, v2, 16, 1
	v_bfe_u32 v12, v10, 16, 1
	v_bfe_u32 v13, v9, 16, 1
	v_bfe_u32 v14, v8, 16, 1
	v_bfe_u32 v17, v4, 16, 1
	v_mov_b32_e32 v3, v7
	v_ashrrev_i32_e32 v7, 31, v6
	v_add3_u32 v17, v4, v17, s94
	v_add3_u32 v4, v8, v14, s94
	v_add3_u32 v8, v9, v13, s94
	v_add3_u32 v5, v10, v12, s94
	v_add3_u32 v2, v2, v11, s94
	v_lshlrev_b64 v[6:7], 12, v[6:7]
	v_perm_b32 v5, v2, v5, s95
	v_perm_b32 v4, v8, v4, s95
	v_perm_b32 v2, v17, v18, s95
	v_lshl_add_u64 v[0:1], v[0:1], 0, v[6:7]
	global_store_dwordx4 v[0:1], v[2:5], off
	s_barrier

.LBB0_664:
	s_or_b64 exec, exec, s[36:37]
	v_sub_u32_e32 v13, v14, v13
	v_cvt_f32_i32_e32 v13, v13
	s_add_i32 s44, s44, 1
	s_cmp_eq_u32 s44, 8
	v_div_scale_f32 v14, s[36:37], v13, v13, 1.0
	v_rcp_f32_e32 v15, v14
	s_movk_i32 s36, 0x110
	v_fma_f32 v16, -v14, v15, 1.0
	v_fmac_f32_e32 v15, v16, v15
	v_div_scale_f32 v16, vcc, 1.0, v13, 1.0
	v_mul_f32_e32 v17, v16, v15
	v_fma_f32 v18, -v14, v17, v16
	v_fmac_f32_e32 v17, v18, v15
	v_fma_f32 v14, -v14, v17, v16
	v_div_fmas_f32 v14, v14, v15, v17
	v_div_fixup_f32 v18, v14, v13, 1.0
	v_lshl_add_u32 v13, v12, 8, v0
	ds_read_b128 v[14:17], v13 offset:2048
	s_waitcnt lgkmcnt(0)
	v_and_b32_e32 v21, 0xffff0000, v14
	v_lshlrev_b32_e32 v20, 16, v14
	v_pk_fma_f32 v[6:7], v[18:19], v[6:7], v[20:21] op_sel_hi:[0,1,1] neg_lo:[0,0,1] neg_hi:[0,0,1]
	v_and_b32_e32 v21, 0xffff0000, v15
	v_lshlrev_b32_e32 v20, 16, v15
	v_and_b32_e32 v15, 0xffff0000, v16
	v_lshlrev_b32_e32 v14, 16, v16
	v_pk_fma_f32 v[4:5], v[18:19], v[4:5], v[14:15] op_sel_hi:[0,1,1] neg_lo:[0,0,1] neg_hi:[0,0,1]
	v_and_b32_e32 v15, 0xffff0000, v17
	v_lshlrev_b32_e32 v14, 16, v17
	v_pk_fma_f32 v[8:9], v[18:19], v[8:9], v[20:21] op_sel_hi:[0,1,1] neg_lo:[0,0,1] neg_hi:[0,0,1]
	v_pk_fma_f32 v[2:3], v[18:19], v[2:3], v[14:15] op_sel_hi:[0,1,1] neg_lo:[0,0,1] neg_hi:[0,0,1]
	v_bfe_u32 v15, v5, 16, 1
	v_bfe_u32 v16, v4, 16, 1
	v_cvt_pk_bf16_f32 v6, v6, v7
	v_cvt_pk_bf16_f32 v8, v8, v9
	v_add3_u32 v4, v4, v16, s94
	v_add3_u32 v15, v5, v15, s94
	v_cvt_pk_bf16_f32 v2, v2, v3
	v_mov_b32_e32 v5, v2
	v_perm_b32 v4, v15, v4, s95
	v_mov_b32_e32 v3, v8
	v_mov_b32_e32 v2, v6
	v_mad_u64_u32 v[6:7], s[36:37], v12, s36, v[0:1]
	ds_write_b128 v6, v[2:5] offset:36864
	s_cbranch_scc1 .LBB0_669

.LBB0_670:
	v_add_u32_e32 v14, s20, v20
	v_mov_b64_e32 v[16:17], s[6:7]
	v_mad_i64_i32 v[0:1], s[22:23], v14, s0, v[16:17]
	s_lshl_b32 s70, s43, 1
	v_lshl_add_u64 v[0:1], v[0:1], 0, s[70:71]
	v_lshl_add_u64 v[0:1], v[0:1], 0, v[160:161]
	v_add_co_u32_e32 v0, vcc, 0x1000, v0
	v_ashrrev_i32_e32 v15, 31, v14
	s_nop 0
	v_addc_co_u32_e32 v1, vcc, 0, v1, vcc
	global_load_dwordx4 v[0:3], v[0:1], off
	s_nop 0
	global_load_dwordx4 v[4:7], v[12:13], off offset:16
	global_load_dwordx4 v[8:11], v[12:13], off
	ds_read_b128 v[22:25], v21
	ds_read_b128 v[26:29], v21 offset:16
	s_add_i32 s20, s20, 16
	s_cmp_lg_u32 s20, 32
	s_waitcnt vmcnt(2)
	v_and_b32_e32 v30, 0xffff0000, v0
	v_lshlrev_b32_e32 v0, 16, v0
	v_mul_f32_e32 v18, 0xbfb8aa3b, v0
	v_mul_f32_e32 v19, 0xbfb8aa3b, v30
	v_exp_f32_e32 v18, v18
	v_exp_f32_e32 v19, v19
	s_waitcnt vmcnt(0) lgkmcnt(1)
	v_pk_mul_f32 v[8:9], v[8:9], v[22:23]
	v_pk_mul_f32 v[10:11], v[10:11], v[24:25]
	s_waitcnt lgkmcnt(0)
	v_pk_mul_f32 v[4:5], v[4:5], v[26:27]
	v_pk_add_f32 v[18:19], v[18:19], 1.0 op_sel_hi:[1,0]
	v_pk_mul_f32 v[6:7], v[6:7], v[28:29]
	v_div_scale_f32 v22, s[22:23], v19, v19, v30
	v_rcp_f32_e32 v23, v22
	s_nop 0
	v_fma_f32 v31, -v22, v23, 1.0
	v_fmac_f32_e32 v23, v31, v23
	v_div_scale_f32 v31, vcc, v30, v19, v30
	v_mul_f32_e32 v32, v31, v23
	v_fma_f32 v33, -v22, v32, v31
	v_fmac_f32_e32 v32, v33, v23
	v_fma_f32 v22, -v22, v32, v31
	v_div_fmas_f32 v22, v22, v23, v32
	v_div_fixup_f32 v19, v22, v19, v30
	v_div_scale_f32 v22, s[22:23], v18, v18, v0
	v_rcp_f32_e32 v23, v22
	s_nop 0
	v_fma_f32 v30, -v22, v23, 1.0
	v_fmac_f32_e32 v23, v30, v23
	v_div_scale_f32 v30, vcc, v0, v18, v0
	v_mul_f32_e32 v31, v30, v23
	v_fma_f32 v32, -v22, v31, v30
	v_fmac_f32_e32 v31, v32, v23
	v_fma_f32 v22, -v22, v31, v30
	v_div_fmas_f32 v22, v22, v23, v31
	v_div_fixup_f32 v18, v22, v18, v0
	v_pk_mul_f32 v[8:9], v[18:19], v[8:9]
	v_and_b32_e32 v18, 0xffff0000, v1
	v_lshlrev_b32_e32 v19, 16, v1
	v_mul_f32_e32 v0, 0xbfb8aa3b, v19
	v_mul_f32_e32 v1, 0xbfb8aa3b, v18
	v_exp_f32_e32 v0, v0
	v_exp_f32_e32 v1, v1
	s_nop 0
	v_pk_add_f32 v[0:1], v[0:1], 1.0 op_sel_hi:[1,0]
	s_nop 0
	v_div_scale_f32 v22, s[22:23], v1, v1, v18
	v_rcp_f32_e32 v23, v22
	s_nop 0
	v_fma_f32 v24, -v22, v23, 1.0
	v_fmac_f32_e32 v23, v24, v23
	v_div_scale_f32 v24, vcc, v18, v1, v18
	v_mul_f32_e32 v25, v24, v23
	v_fma_f32 v30, -v22, v25, v24
	v_fmac_f32_e32 v25, v30, v23
	v_fma_f32 v22, -v22, v25, v24
	v_div_fmas_f32 v22, v22, v23, v25
	v_div_fixup_f32 v1, v22, v1, v18
	v_div_scale_f32 v18, s[22:23], v0, v0, v19
	v_rcp_f32_e32 v22, v18
	s_nop 0
	v_fma_f32 v23, -v18, v22, 1.0
	v_fmac_f32_e32 v22, v23, v22
	v_div_scale_f32 v23, vcc, v19, v0, v19
	v_mul_f32_e32 v24, v23, v22
	v_fma_f32 v25, -v18, v24, v23
	v_fmac_f32_e32 v24, v25, v22
	v_fma_f32 v18, -v18, v24, v23
	v_div_fmas_f32 v18, v18, v22, v24
	v_div_fixup_f32 v0, v18, v0, v19
	v_and_b32_e32 v18, 0xffff0000, v2
	v_lshlrev_b32_e32 v2, 16, v2
	v_pk_mul_f32 v[0:1], v[0:1], v[10:11]
	v_mul_f32_e32 v10, 0xbfb8aa3b, v2
	v_mul_f32_e32 v11, 0xbfb8aa3b, v18
	v_exp_f32_e32 v10, v10
	v_exp_f32_e32 v11, v11
	s_nop 0
	v_pk_add_f32 v[10:11], v[10:11], 1.0 op_sel_hi:[1,0]
	s_nop 0
	v_div_scale_f32 v19, s[22:23], v11, v11, v18
	v_rcp_f32_e32 v22, v19
	s_nop 0
	v_fma_f32 v23, -v19, v22, 1.0
	v_fmac_f32_e32 v22, v23, v22
	v_div_scale_f32 v23, vcc, v18, v11, v18
	v_mul_f32_e32 v24, v23, v22
	v_fma_f32 v25, -v19, v24, v23
	v_fmac_f32_e32 v24, v25, v22
	v_fma_f32 v19, -v19, v24, v23
	v_div_fmas_f32 v19, v19, v22, v24
	v_div_fixup_f32 v11, v19, v11, v18
	v_div_scale_f32 v18, s[22:23], v10, v10, v2
	v_rcp_f32_e32 v19, v18
	s_nop 0
	v_fma_f32 v22, -v18, v19, 1.0
	v_fmac_f32_e32 v19, v22, v19
	v_div_scale_f32 v22, vcc, v2, v10, v2
	v_mul_f32_e32 v23, v22, v19
	v_fma_f32 v24, -v18, v23, v22
	v_fmac_f32_e32 v23, v24, v19
	v_fma_f32 v18, -v18, v23, v22
	v_div_fmas_f32 v18, v18, v19, v23
	v_div_fixup_f32 v10, v18, v10, v2
	v_pk_mul_f32 v[4:5], v[10:11], v[4:5]
	v_and_b32_e32 v10, 0xffff0000, v3
	v_lshlrev_b32_e32 v11, 16, v3
	v_mul_f32_e32 v2, 0xbfb8aa3b, v11
	v_mul_f32_e32 v3, 0xbfb8aa3b, v10
	v_exp_f32_e32 v2, v2
	v_exp_f32_e32 v3, v3
	s_nop 0
	v_pk_add_f32 v[2:3], v[2:3], 1.0 op_sel_hi:[1,0]
	s_nop 0
	v_div_scale_f32 v18, s[22:23], v3, v3, v10
	v_rcp_f32_e32 v19, v18
	s_nop 0
	v_fma_f32 v22, -v18, v19, 1.0
	v_fmac_f32_e32 v19, v22, v19
	v_div_scale_f32 v22, vcc, v10, v3, v10
	v_mul_f32_e32 v23, v22, v19
	v_fma_f32 v24, -v18, v23, v22
	v_fmac_f32_e32 v23, v24, v19
	v_fma_f32 v18, -v18, v23, v22
	v_div_fmas_f32 v18, v18, v19, v23
	v_div_fixup_f32 v3, v18, v3, v10
	v_div_scale_f32 v10, s[22:23], v2, v2, v11
	v_rcp_f32_e32 v18, v10
	s_nop 0
	v_fma_f32 v19, -v10, v18, 1.0
	v_fmac_f32_e32 v18, v19, v18
	v_div_scale_f32 v19, vcc, v11, v2, v11
	v_mul_f32_e32 v22, v19, v18
	v_fma_f32 v23, -v10, v22, v19
	v_fmac_f32_e32 v22, v23, v18
	v_fma_f32 v10, -v10, v22, v19
	v_div_fmas_f32 v10, v10, v18, v22
	v_div_fixup_f32 v2, v10, v2, v11
	v_pk_mul_f32 v[2:3], v[2:3], v[6:7]
	v_cvt_pk_bf16_f32 v4, v4, v5
	v_cvt_pk_bf16_f32 v2, v2, v3
	v_mov_b32_e32 v3, v2
	v_mov_b32_e32 v2, v4
	v_lshlrev_b64 v[4:5], 12, v[14:15]
	v_lshl_add_u64 v[4:5], s[30:31], 0, v[4:5]
	v_lshl_add_u64 v[4:5], v[4:5], 0, s[70:71]
	v_lshl_add_u64 v[4:5], v[4:5], 0, v[160:161]
	v_cvt_pk_bf16_f32 v8, v8, v9
	v_cvt_pk_bf16_f32 v0, v0, v1
	v_add_co_u32_e32 v4, vcc, s36, v4
	v_mov_b32_e32 v1, v0
	v_mov_b32_e32 v0, v8
	v_addc_co_u32_e32 v5, vcc, 0, v5, vcc
	v_add_u32_e32 v18, 4, v14
	global_store_dwordx4 v[4:5], v[0:3], off offset:1024
	v_ashrrev_i32_e32 v19, 31, v18
	s_nop 0
	v_mad_i64_i32 v[0:1], s[22:23], v18, s0, v[16:17]
	v_lshl_add_u64 v[0:1], v[0:1], 0, s[70:71]
	v_lshl_add_u64 v[0:1], v[0:1], 0, v[160:161]
	v_add_co_u32_e32 v0, vcc, s21, v0
	s_nop 1
	v_addc_co_u32_e32 v1, vcc, 0, v1, vcc
	global_load_dwordx4 v[4:7], v[0:1], off
	s_nop 0
	global_load_dwordx4 v[0:3], v[12:13], off offset:16
	global_load_dwordx4 v[8:11], v[12:13], off
	ds_read_b128 v[22:25], v21 offset:2112
	s_waitcnt vmcnt(2)
	v_and_b32_e32 v15, 0xffff0000, v4
	v_lshlrev_b32_e32 v4, 16, v4
	v_mul_f32_e32 v26, 0xbfb8aa3b, v4
	s_waitcnt vmcnt(0) lgkmcnt(0)
	v_pk_mul_f32 v[8:9], v[8:9], v[22:23]
	v_mul_f32_e32 v22, 0xbfb8aa3b, v15
	v_exp_f32_e32 v26, v26
	v_exp_f32_e32 v27, v22
	v_pk_mul_f32 v[10:11], v[10:11], v[24:25]
	v_pk_add_f32 v[22:23], v[26:27], 1.0 op_sel_hi:[1,0]
	s_nop 0
	v_div_scale_f32 v26, s[22:23], v23, v23, v15
	v_rcp_f32_e32 v27, v26
	s_nop 0
	v_fma_f32 v28, -v26, v27, 1.0
	v_fmac_f32_e32 v27, v28, v27
	v_div_scale_f32 v28, vcc, v15, v23, v15
	v_mul_f32_e32 v29, v28, v27
	v_fma_f32 v30, -v26, v29, v28
	v_fmac_f32_e32 v29, v30, v27
	v_fma_f32 v26, -v26, v29, v28
	v_div_fmas_f32 v26, v26, v27, v29
	v_div_fixup_f32 v23, v26, v23, v15
	v_div_scale_f32 v15, s[22:23], v22, v22, v4
	v_rcp_f32_e32 v26, v15
	s_nop 0
	v_fma_f32 v27, -v15, v26, 1.0
	v_fmac_f32_e32 v26, v27, v26
	v_div_scale_f32 v27, vcc, v4, v22, v4
	v_mul_f32_e32 v28, v27, v26
	v_fma_f32 v29, -v15, v28, v27
	v_fmac_f32_e32 v28, v29, v26
	v_fma_f32 v15, -v15, v28, v27
	v_div_fmas_f32 v15, v15, v26, v28
	v_div_fixup_f32 v22, v15, v22, v4
	v_pk_mul_f32 v[8:9], v[22:23], v[8:9]
	v_and_b32_e32 v15, 0xffff0000, v5
	v_lshlrev_b32_e32 v22, 16, v5
	v_mul_f32_e32 v4, 0xbfb8aa3b, v22
	v_mul_f32_e32 v5, 0xbfb8aa3b, v15
	v_exp_f32_e32 v4, v4
	v_exp_f32_e32 v5, v5
	s_nop 0
	v_pk_add_f32 v[4:5], v[4:5], 1.0 op_sel_hi:[1,0]
	s_nop 0
	v_div_scale_f32 v23, s[22:23], v5, v5, v15
	v_rcp_f32_e32 v24, v23
	s_nop 0
	v_fma_f32 v25, -v23, v24, 1.0
	v_fmac_f32_e32 v24, v25, v24
	v_div_scale_f32 v25, vcc, v15, v5, v15
	v_mul_f32_e32 v26, v25, v24
	v_fma_f32 v27, -v23, v26, v25
	v_fmac_f32_e32 v26, v27, v24
	v_fma_f32 v23, -v23, v26, v25
	v_div_fmas_f32 v23, v23, v24, v26
	v_div_fixup_f32 v5, v23, v5, v15
	v_div_scale_f32 v15, s[22:23], v4, v4, v22
	v_rcp_f32_e32 v23, v15
	s_nop 0
	v_fma_f32 v24, -v15, v23, 1.0
	v_fmac_f32_e32 v23, v24, v23
	v_div_scale_f32 v24, vcc, v22, v4, v22
	v_mul_f32_e32 v25, v24, v23
	v_fma_f32 v26, -v15, v25, v24
	v_fmac_f32_e32 v25, v26, v23
	v_fma_f32 v15, -v15, v25, v24
	v_div_fmas_f32 v15, v15, v23, v25
	v_div_fixup_f32 v4, v15, v4, v22
	v_and_b32_e32 v15, 0xffff0000, v6
	v_lshlrev_b32_e32 v6, 16, v6
	v_pk_mul_f32 v[4:5], v[4:5], v[10:11]
	v_mul_f32_e32 v10, 0xbfb8aa3b, v6
	v_mul_f32_e32 v11, 0xbfb8aa3b, v15
	ds_read_b128 v[22:25], v21 offset:2128
	v_exp_f32_e32 v10, v10
	v_exp_f32_e32 v11, v11
	s_waitcnt lgkmcnt(0)
	v_pk_mul_f32 v[0:1], v[0:1], v[22:23]
	v_pk_add_f32 v[10:11], v[10:11], 1.0 op_sel_hi:[1,0]
	v_pk_mul_f32 v[2:3], v[2:3], v[24:25]
	v_div_scale_f32 v22, s[22:23], v11, v11, v15
	v_rcp_f32_e32 v23, v22
	s_nop 0
	v_fma_f32 v26, -v22, v23, 1.0
	v_fmac_f32_e32 v23, v26, v23
	v_div_scale_f32 v26, vcc, v15, v11, v15
	v_mul_f32_e32 v27, v26, v23
	v_fma_f32 v28, -v22, v27, v26
	v_fmac_f32_e32 v27, v28, v23
	v_fma_f32 v22, -v22, v27, v26
	v_div_fmas_f32 v22, v22, v23, v27
	v_div_fixup_f32 v11, v22, v11, v15
	v_div_scale_f32 v15, s[22:23], v10, v10, v6
	v_rcp_f32_e32 v22, v15
	s_nop 0
	v_fma_f32 v23, -v15, v22, 1.0
	v_fmac_f32_e32 v22, v23, v22
	v_div_scale_f32 v23, vcc, v6, v10, v6
	v_mul_f32_e32 v26, v23, v22
	v_fma_f32 v27, -v15, v26, v23
	v_fmac_f32_e32 v26, v27, v22
	v_fma_f32 v15, -v15, v26, v23
	v_div_fmas_f32 v15, v15, v22, v26
	v_div_fixup_f32 v10, v15, v10, v6
	v_pk_mul_f32 v[0:1], v[10:11], v[0:1]
	v_and_b32_e32 v10, 0xffff0000, v7
	v_lshlrev_b32_e32 v11, 16, v7
	v_mul_f32_e32 v6, 0xbfb8aa3b, v11
	v_mul_f32_e32 v7, 0xbfb8aa3b, v10
	v_exp_f32_e32 v6, v6
	v_exp_f32_e32 v7, v7
	s_nop 0
	v_pk_add_f32 v[6:7], v[6:7], 1.0 op_sel_hi:[1,0]
	s_nop 0
	v_div_scale_f32 v15, s[22:23], v7, v7, v10
	v_rcp_f32_e32 v22, v15
	s_nop 0
	v_fma_f32 v23, -v15, v22, 1.0
	v_fmac_f32_e32 v22, v23, v22
	v_div_scale_f32 v23, vcc, v10, v7, v10
	v_mul_f32_e32 v24, v23, v22
	v_fma_f32 v25, -v15, v24, v23
	v_fmac_f32_e32 v24, v25, v22
	v_fma_f32 v15, -v15, v24, v23
	v_div_fmas_f32 v15, v15, v22, v24
	v_div_fixup_f32 v7, v15, v7, v10
	v_div_scale_f32 v10, s[22:23], v6, v6, v11
	v_rcp_f32_e32 v15, v10
	s_nop 0
	v_fma_f32 v22, -v10, v15, 1.0
	v_fmac_f32_e32 v15, v22, v15
	v_div_scale_f32 v22, vcc, v11, v6, v11
	v_mul_f32_e32 v23, v22, v15
	v_fma_f32 v24, -v10, v23, v22
	v_fmac_f32_e32 v23, v24, v15
	v_fma_f32 v10, -v10, v23, v22
	v_div_fmas_f32 v10, v10, v15, v23
	v_div_fixup_f32 v6, v10, v6, v11
	v_pk_mul_f32 v[2:3], v[6:7], v[2:3]
	v_cvt_pk_bf16_f32 v4, v4, v5
	v_cvt_pk_bf16_f32 v0, v0, v1
	v_cvt_pk_bf16_f32 v2, v2, v3
	v_mov_b32_e32 v3, v2
	v_mov_b32_e32 v2, v0
	v_mov_b32_e32 v1, v4
	v_lshlrev_b64 v[4:5], 12, v[18:19]
	v_lshl_add_u64 v[4:5], s[30:31], 0, v[4:5]
	v_lshl_add_u64 v[4:5], v[4:5], 0, s[70:71]
	v_lshl_add_u64 v[4:5], v[4:5], 0, v[160:161]
	v_cvt_pk_bf16_f32 v8, v8, v9
	v_add_co_u32_e32 v4, vcc, s36, v4
	v_mov_b32_e32 v0, v8
	s_nop 0
	v_addc_co_u32_e32 v5, vcc, 0, v5, vcc
	v_add_u32_e32 v18, 8, v14
	global_store_dwordx4 v[4:5], v[0:3], off offset:1024
	v_ashrrev_i32_e32 v19, 31, v18
	v_add_u32_e32 v14, 12, v14
	v_mad_i64_i32 v[0:1], s[22:23], v18, s0, v[16:17]
	v_lshl_add_u64 v[0:1], v[0:1], 0, s[70:71]
	v_lshl_add_u64 v[0:1], v[0:1], 0, v[160:161]
	v_add_co_u32_e32 v0, vcc, s21, v0
	s_nop 1
	v_addc_co_u32_e32 v1, vcc, 0, v1, vcc
	global_load_dwordx4 v[4:7], v[0:1], off
	s_nop 0
	global_load_dwordx4 v[0:3], v[12:13], off offset:16
	global_load_dwordx4 v[8:11], v[12:13], off
	ds_read_b128 v[22:25], v21 offset:4224
	s_waitcnt vmcnt(2)
	v_and_b32_e32 v15, 0xffff0000, v4
	v_lshlrev_b32_e32 v4, 16, v4
	v_mul_f32_e32 v26, 0xbfb8aa3b, v4
	s_waitcnt vmcnt(0) lgkmcnt(0)
	v_pk_mul_f32 v[8:9], v[8:9], v[22:23]
	v_mul_f32_e32 v22, 0xbfb8aa3b, v15
	v_exp_f32_e32 v26, v26
	v_exp_f32_e32 v27, v22
	v_pk_mul_f32 v[10:11], v[10:11], v[24:25]
	v_pk_add_f32 v[22:23], v[26:27], 1.0 op_sel_hi:[1,0]
	s_nop 0
	v_div_scale_f32 v26, s[22:23], v23, v23, v15
	v_rcp_f32_e32 v27, v26
	s_nop 0
	v_fma_f32 v28, -v26, v27, 1.0
	v_fmac_f32_e32 v27, v28, v27
	v_div_scale_f32 v28, vcc, v15, v23, v15
	v_mul_f32_e32 v29, v28, v27
	v_fma_f32 v30, -v26, v29, v28
	v_fmac_f32_e32 v29, v30, v27
	v_fma_f32 v26, -v26, v29, v28
	v_div_fmas_f32 v26, v26, v27, v29
	v_div_fixup_f32 v23, v26, v23, v15
	v_div_scale_f32 v15, s[22:23], v22, v22, v4
	v_rcp_f32_e32 v26, v15
	s_nop 0
	v_fma_f32 v27, -v15, v26, 1.0
	v_fmac_f32_e32 v26, v27, v26
	v_div_scale_f32 v27, vcc, v4, v22, v4
	v_mul_f32_e32 v28, v27, v26
	v_fma_f32 v29, -v15, v28, v27
	v_fmac_f32_e32 v28, v29, v26
	v_fma_f32 v15, -v15, v28, v27
	v_div_fmas_f32 v15, v15, v26, v28
	v_div_fixup_f32 v22, v15, v22, v4
	v_pk_mul_f32 v[8:9], v[22:23], v[8:9]
	v_and_b32_e32 v15, 0xffff0000, v5
	v_lshlrev_b32_e32 v22, 16, v5
	v_mul_f32_e32 v4, 0xbfb8aa3b, v22
	v_mul_f32_e32 v5, 0xbfb8aa3b, v15
	v_exp_f32_e32 v4, v4
	v_exp_f32_e32 v5, v5
	s_nop 0
	v_pk_add_f32 v[4:5], v[4:5], 1.0 op_sel_hi:[1,0]
	s_nop 0
	v_div_scale_f32 v23, s[22:23], v5, v5, v15
	v_rcp_f32_e32 v24, v23
	s_nop 0
	v_fma_f32 v25, -v23, v24, 1.0
	v_fmac_f32_e32 v24, v25, v24
	v_div_scale_f32 v25, vcc, v15, v5, v15
	v_mul_f32_e32 v26, v25, v24
	v_fma_f32 v27, -v23, v26, v25
	v_fmac_f32_e32 v26, v27, v24
	v_fma_f32 v23, -v23, v26, v25
	v_div_fmas_f32 v23, v23, v24, v26
	v_div_fixup_f32 v5, v23, v5, v15
	v_div_scale_f32 v15, s[22:23], v4, v4, v22
	v_rcp_f32_e32 v23, v15
	s_nop 0
	v_fma_f32 v24, -v15, v23, 1.0
	v_fmac_f32_e32 v23, v24, v23
	v_div_scale_f32 v24, vcc, v22, v4, v22
	v_mul_f32_e32 v25, v24, v23
	v_fma_f32 v26, -v15, v25, v24
	v_fmac_f32_e32 v25, v26, v23
	v_fma_f32 v15, -v15, v25, v24
	v_div_fmas_f32 v15, v15, v23, v25
	v_div_fixup_f32 v4, v15, v4, v22
	v_and_b32_e32 v15, 0xffff0000, v6
	v_lshlrev_b32_e32 v6, 16, v6
	v_pk_mul_f32 v[4:5], v[4:5], v[10:11]
	v_mul_f32_e32 v10, 0xbfb8aa3b, v6
	v_mul_f32_e32 v11, 0xbfb8aa3b, v15
	ds_read_b128 v[22:25], v21 offset:4240
	v_exp_f32_e32 v10, v10
	v_exp_f32_e32 v11, v11
	s_waitcnt lgkmcnt(0)
	v_pk_mul_f32 v[0:1], v[0:1], v[22:23]
	v_pk_add_f32 v[10:11], v[10:11], 1.0 op_sel_hi:[1,0]
	v_pk_mul_f32 v[2:3], v[2:3], v[24:25]
	v_div_scale_f32 v22, s[22:23], v11, v11, v15
	v_rcp_f32_e32 v23, v22
	s_nop 0
	v_fma_f32 v26, -v22, v23, 1.0
	v_fmac_f32_e32 v23, v26, v23
	v_div_scale_f32 v26, vcc, v15, v11, v15
	v_mul_f32_e32 v27, v26, v23
	v_fma_f32 v28, -v22, v27, v26
	v_fmac_f32_e32 v27, v28, v23
	v_fma_f32 v22, -v22, v27, v26
	v_div_fmas_f32 v22, v22, v23, v27
	v_div_fixup_f32 v11, v22, v11, v15
	v_div_scale_f32 v15, s[22:23], v10, v10, v6
	v_rcp_f32_e32 v22, v15
	s_nop 0
	v_fma_f32 v23, -v15, v22, 1.0
	v_fmac_f32_e32 v22, v23, v22
	v_div_scale_f32 v23, vcc, v6, v10, v6
	v_mul_f32_e32 v26, v23, v22
	v_fma_f32 v27, -v15, v26, v23
	v_fmac_f32_e32 v26, v27, v22
	v_fma_f32 v15, -v15, v26, v23
	v_div_fmas_f32 v15, v15, v22, v26
	v_div_fixup_f32 v10, v15, v10, v6
	v_pk_mul_f32 v[0:1], v[10:11], v[0:1]
	v_and_b32_e32 v10, 0xffff0000, v7
	v_lshlrev_b32_e32 v11, 16, v7
	v_mul_f32_e32 v6, 0xbfb8aa3b, v11
	v_mul_f32_e32 v7, 0xbfb8aa3b, v10
	v_exp_f32_e32 v6, v6
	v_exp_f32_e32 v7, v7
	s_nop 0
	v_pk_add_f32 v[6:7], v[6:7], 1.0 op_sel_hi:[1,0]
	s_nop 0
	v_div_scale_f32 v15, s[22:23], v7, v7, v10
	v_rcp_f32_e32 v22, v15
	s_nop 0
	v_fma_f32 v23, -v15, v22, 1.0
	v_fmac_f32_e32 v22, v23, v22
	v_div_scale_f32 v23, vcc, v10, v7, v10
	v_mul_f32_e32 v24, v23, v22
	v_fma_f32 v25, -v15, v24, v23
	v_fmac_f32_e32 v24, v25, v22
	v_fma_f32 v15, -v15, v24, v23
	v_div_fmas_f32 v15, v15, v22, v24
	v_div_fixup_f32 v7, v15, v7, v10
	v_div_scale_f32 v10, s[22:23], v6, v6, v11
	v_rcp_f32_e32 v15, v10
	s_nop 0
	v_fma_f32 v22, -v10, v15, 1.0
	v_fmac_f32_e32 v15, v22, v15
	v_div_scale_f32 v22, vcc, v11, v6, v11
	v_mul_f32_e32 v23, v22, v15
	v_fma_f32 v24, -v10, v23, v22
	v_fmac_f32_e32 v23, v24, v15
	v_fma_f32 v10, -v10, v23, v22
	v_div_fmas_f32 v10, v10, v15, v23
	v_div_fixup_f32 v6, v10, v6, v11
	v_pk_mul_f32 v[2:3], v[6:7], v[2:3]
	v_cvt_pk_bf16_f32 v4, v4, v5
	v_cvt_pk_bf16_f32 v0, v0, v1
	v_cvt_pk_bf16_f32 v2, v2, v3
	v_mov_b32_e32 v3, v2
	v_mov_b32_e32 v2, v0
	v_mov_b32_e32 v1, v4
	v_lshlrev_b64 v[4:5], 12, v[18:19]
	v_lshl_add_u64 v[4:5], s[30:31], 0, v[4:5]
	v_lshl_add_u64 v[4:5], v[4:5], 0, s[70:71]
	v_lshl_add_u64 v[4:5], v[4:5], 0, v[160:161]
	v_cvt_pk_bf16_f32 v8, v8, v9
	v_add_co_u32_e32 v4, vcc, s36, v4
	v_mov_b32_e32 v0, v8
	s_nop 0
	v_addc_co_u32_e32 v5, vcc, 0, v5, vcc
	global_store_dwordx4 v[4:5], v[0:3], off offset:1024
	v_ashrrev_i32_e32 v15, 31, v14
	s_nop 0
	v_mad_i64_i32 v[0:1], s[22:23], v14, s0, v[16:17]
	v_lshl_add_u64 v[0:1], v[0:1], 0, s[70:71]
	v_lshl_add_u64 v[0:1], v[0:1], 0, v[160:161]
	v_add_co_u32_e32 v0, vcc, s21, v0
	s_nop 1
	v_addc_co_u32_e32 v1, vcc, 0, v1, vcc
	global_load_dwordx4 v[4:7], v[0:1], off
	s_nop 0
	global_load_dwordx4 v[0:3], v[12:13], off offset:16
	global_load_dwordx4 v[8:11], v[12:13], off
	ds_read_b128 v[16:19], v21 offset:6336
	ds_read_b128 v[22:25], v21 offset:6352
	v_add_u32_e32 v21, 0x2100, v21
	s_waitcnt vmcnt(2)
	v_and_b32_e32 v28, 0xffff0000, v4
	v_lshlrev_b32_e32 v4, 16, v4
	v_mul_f32_e32 v26, 0xbfb8aa3b, v4
	s_waitcnt vmcnt(0) lgkmcnt(1)
	v_pk_mul_f32 v[8:9], v[8:9], v[16:17]
	v_mul_f32_e32 v16, 0xbfb8aa3b, v28
	v_exp_f32_e32 v26, v26
	v_exp_f32_e32 v27, v16
	v_pk_mul_f32 v[10:11], v[10:11], v[18:19]
	s_waitcnt lgkmcnt(0)
	v_pk_mul_f32 v[0:1], v[0:1], v[22:23]
	v_pk_mul_f32 v[2:3], v[2:3], v[24:25]
	v_pk_add_f32 v[16:17], v[26:27], 1.0 op_sel_hi:[1,0]
	s_nop 0
	v_div_scale_f32 v26, s[22:23], v17, v17, v28
	v_rcp_f32_e32 v27, v26
	s_nop 0
	v_fma_f32 v29, -v26, v27, 1.0
	v_fmac_f32_e32 v27, v29, v27
	v_div_scale_f32 v29, vcc, v28, v17, v28
	v_mul_f32_e32 v30, v29, v27
	v_fma_f32 v31, -v26, v30, v29
	v_fmac_f32_e32 v30, v31, v27
	v_fma_f32 v26, -v26, v30, v29
	v_div_fmas_f32 v26, v26, v27, v30
	v_div_fixup_f32 v17, v26, v17, v28
	v_div_scale_f32 v26, s[22:23], v16, v16, v4
	v_rcp_f32_e32 v27, v26
	s_nop 0
	v_fma_f32 v28, -v26, v27, 1.0
	v_fmac_f32_e32 v27, v28, v27
	v_div_scale_f32 v28, vcc, v4, v16, v4
	v_mul_f32_e32 v29, v28, v27
	v_fma_f32 v30, -v26, v29, v28
	v_fmac_f32_e32 v29, v30, v27
	v_fma_f32 v26, -v26, v29, v28
	v_div_fmas_f32 v26, v26, v27, v29
	v_div_fixup_f32 v16, v26, v16, v4
	v_pk_mul_f32 v[8:9], v[16:17], v[8:9]
	v_and_b32_e32 v16, 0xffff0000, v5
	v_lshlrev_b32_e32 v17, 16, v5
	v_mul_f32_e32 v4, 0xbfb8aa3b, v17
	v_mul_f32_e32 v5, 0xbfb8aa3b, v16
	v_exp_f32_e32 v4, v4
	v_exp_f32_e32 v5, v5
	s_nop 0
	v_pk_add_f32 v[4:5], v[4:5], 1.0 op_sel_hi:[1,0]
	s_nop 0
	v_div_scale_f32 v18, s[22:23], v5, v5, v16
	v_rcp_f32_e32 v19, v18
	s_nop 0
	v_fma_f32 v26, -v18, v19, 1.0
	v_fmac_f32_e32 v19, v26, v19
	v_div_scale_f32 v26, vcc, v16, v5, v16
	v_mul_f32_e32 v27, v26, v19
	v_fma_f32 v28, -v18, v27, v26
	v_fmac_f32_e32 v27, v28, v19
	v_fma_f32 v18, -v18, v27, v26
	v_div_fmas_f32 v18, v18, v19, v27
	v_div_fixup_f32 v5, v18, v5, v16
	v_div_scale_f32 v16, s[22:23], v4, v4, v17
	v_rcp_f32_e32 v18, v16
	s_nop 0
	v_fma_f32 v19, -v16, v18, 1.0
	v_fmac_f32_e32 v18, v19, v18
	v_div_scale_f32 v19, vcc, v17, v4, v17
	v_mul_f32_e32 v26, v19, v18
	v_fma_f32 v27, -v16, v26, v19
	v_fmac_f32_e32 v26, v27, v18
	v_fma_f32 v16, -v16, v26, v19
	v_div_fmas_f32 v16, v16, v18, v26
	v_div_fixup_f32 v4, v16, v4, v17
	v_and_b32_e32 v16, 0xffff0000, v6
	v_lshlrev_b32_e32 v6, 16, v6
	v_pk_mul_f32 v[4:5], v[4:5], v[10:11]
	v_mul_f32_e32 v10, 0xbfb8aa3b, v6
	v_mul_f32_e32 v11, 0xbfb8aa3b, v16
	v_exp_f32_e32 v10, v10
	v_exp_f32_e32 v11, v11
	s_nop 0
	v_pk_add_f32 v[10:11], v[10:11], 1.0 op_sel_hi:[1,0]
	s_nop 0
	v_div_scale_f32 v17, s[22:23], v11, v11, v16
	v_rcp_f32_e32 v18, v17
	s_nop 0
	v_fma_f32 v19, -v17, v18, 1.0
	v_fmac_f32_e32 v18, v19, v18
	v_div_scale_f32 v19, vcc, v16, v11, v16
	v_mul_f32_e32 v22, v19, v18
	v_fma_f32 v23, -v17, v22, v19
	v_fmac_f32_e32 v22, v23, v18
	v_fma_f32 v17, -v17, v22, v19
	v_div_fmas_f32 v17, v17, v18, v22
	v_div_fixup_f32 v11, v17, v11, v16
	v_div_scale_f32 v16, s[22:23], v10, v10, v6
	v_rcp_f32_e32 v17, v16
	s_nop 0
	v_fma_f32 v18, -v16, v17, 1.0
	v_fmac_f32_e32 v17, v18, v17
	v_div_scale_f32 v18, vcc, v6, v10, v6
	v_mul_f32_e32 v19, v18, v17
	v_fma_f32 v22, -v16, v19, v18
	v_fmac_f32_e32 v19, v22, v17
	v_fma_f32 v16, -v16, v19, v18
	v_div_fmas_f32 v16, v16, v17, v19
	v_div_fixup_f32 v10, v16, v10, v6
	v_pk_mul_f32 v[0:1], v[10:11], v[0:1]
	v_and_b32_e32 v10, 0xffff0000, v7
	v_lshlrev_b32_e32 v11, 16, v7
	v_mul_f32_e32 v6, 0xbfb8aa3b, v11
	v_mul_f32_e32 v7, 0xbfb8aa3b, v10
	v_exp_f32_e32 v6, v6
	v_exp_f32_e32 v7, v7
	s_nop 0
	v_pk_add_f32 v[6:7], v[6:7], 1.0 op_sel_hi:[1,0]
	s_nop 0
	v_div_scale_f32 v16, s[22:23], v7, v7, v10
	v_rcp_f32_e32 v17, v16
	s_nop 0
	v_fma_f32 v18, -v16, v17, 1.0
	v_fmac_f32_e32 v17, v18, v17
	v_div_scale_f32 v18, vcc, v10, v7, v10
	v_mul_f32_e32 v19, v18, v17
	v_fma_f32 v22, -v16, v19, v18
	v_fmac_f32_e32 v19, v22, v17
	v_fma_f32 v16, -v16, v19, v18
	v_div_fmas_f32 v16, v16, v17, v19
	v_div_fixup_f32 v7, v16, v7, v10
	v_div_scale_f32 v10, s[22:23], v6, v6, v11
	v_rcp_f32_e32 v16, v10
	s_nop 0
	v_fma_f32 v17, -v10, v16, 1.0
	v_fmac_f32_e32 v16, v17, v16
	v_div_scale_f32 v17, vcc, v11, v6, v11
	v_mul_f32_e32 v18, v17, v16
	v_fma_f32 v19, -v10, v18, v17
	v_fmac_f32_e32 v18, v19, v16
	v_fma_f32 v10, -v10, v18, v17
	v_div_fmas_f32 v10, v10, v16, v18
	v_div_fixup_f32 v6, v10, v6, v11
	v_pk_mul_f32 v[2:3], v[6:7], v[2:3]
	v_cvt_pk_bf16_f32 v4, v4, v5
	v_cvt_pk_bf16_f32 v0, v0, v1
	v_cvt_pk_bf16_f32 v2, v2, v3
	v_mov_b32_e32 v3, v2
	v_mov_b32_e32 v2, v0
	v_mov_b32_e32 v1, v4
	v_lshlrev_b64 v[4:5], 12, v[14:15]
	v_lshl_add_u64 v[4:5], s[30:31], 0, v[4:5]
	v_lshl_add_u64 v[4:5], v[4:5], 0, s[70:71]
	v_lshl_add_u64 v[4:5], v[4:5], 0, v[160:161]
	v_cvt_pk_bf16_f32 v8, v8, v9
	v_add_co_u32_e32 v4, vcc, 0xcc00000, v4
	v_mov_b32_e32 v0, v8
	s_nop 0
	v_addc_co_u32_e32 v5, vcc, 0, v5, vcc
	global_store_dwordx4 v[4:5], v[0:3], off offset:1024
	s_cbranch_scc1 .LBB0_670
	s_barrier

.LBB0_676:
	v_lshl_add_u64 v[4:5], v[32:33], 0, s[38:39]
	v_add_co_u32_e32 v0, vcc, 0x6400000, v4
	s_nop 1
	v_addc_co_u32_e32 v1, vcc, 0, v5, vcc
	global_load_dwordx4 v[0:3], v[0:1], off offset:1024
	v_add_co_u32_e32 v6, vcc, 0x6403000, v4
	s_nop 1
	v_addc_co_u32_e32 v7, vcc, 0, v5, vcc
	global_load_dwordx4 v[24:27], v[6:7], off offset:2048
	v_add_co_u32_e32 v8, vcc, 0x6406000, v4
	s_waitcnt vmcnt(1)
	v_lshlrev_b32_e32 v36, 16, v0
	v_and_b32_e32 v37, 0xffff0000, v0
	v_add_f32_e32 v0, 0, v36
	v_lshlrev_b32_e32 v38, 16, v1
	v_add_f32_e32 v0, v0, v37
	s_waitcnt lgkmcnt(0)
	v_addc_co_u32_e32 v9, vcc, 0, v5, vcc
	v_and_b32_e32 v39, 0xffff0000, v1
	v_add_f32_e32 v0, v0, v38
	v_add_co_u32_e32 v6, vcc, 0x640a000, v4
	v_lshlrev_b32_e32 v40, 16, v2
	v_add_f32_e32 v0, v0, v39
	v_addc_co_u32_e32 v7, vcc, 0, v5, vcc
	v_and_b32_e32 v41, 0xffff0000, v2
	v_add_f32_e32 v0, v0, v40
	v_add_co_u32_e32 v10, vcc, 0x640d000, v4
	v_lshlrev_b32_e32 v52, 16, v3
	v_add_f32_e32 v0, v0, v41
	v_addc_co_u32_e32 v11, vcc, 0, v5, vcc
	v_and_b32_e32 v53, 0xffff0000, v3
	v_add_f32_e32 v0, v0, v52
	global_load_dwordx4 v[20:23], v[8:9], off offset:3072
	global_load_dwordx4 v[16:19], v[6:7], off
	v_add_co_u32_e32 v6, vcc, 0x6410000, v4
	v_add_f32_e32 v2, v0, v53
	s_nop 0
	v_addc_co_u32_e32 v7, vcc, 0, v5, vcc
	v_add_co_u32_e32 v34, vcc, 0x6413000, v4
	global_load_dwordx4 v[12:15], v[10:11], off offset:1024
	s_nop 0
	global_load_dwordx4 v[8:11], v[6:7], off offset:2048
	v_addc_co_u32_e32 v35, vcc, 0, v5, vcc
	v_add_co_u32_e32 v0, vcc, 0x6417000, v4
	s_waitcnt lgkmcnt(0)
	v_mov_b32_e32 v3, v2
	s_nop 1
	v_permlane32_swap_b32_e32 v3, v2
	v_add_f32_e32 v51, v2, v3
	v_addc_co_u32_e32 v1, vcc, 0, v5, vcc
	global_load_dwordx4 v[4:7], v[34:35], off offset:3072
	s_nop 0
	global_load_dwordx4 v[0:3], v[0:1], off
	s_waitcnt lgkmcnt(0)
	v_mov_b32_e32 v54, v51
	s_nop 1
	v_permlane16_swap_b32_e32 v54, v51
	v_add_f32_e32 v34, v51, v54
	s_waitcnt lgkmcnt(0)
	s_nop 1
	v_add_f32_dpp v34, v34, v34 row_mirror row_mask:0xf bank_mask:0xf
	s_waitcnt lgkmcnt(0)
	s_nop 1
	v_add_f32_dpp v34, v34, v34 row_half_mirror row_mask:0xf bank_mask:0xf
	s_waitcnt lgkmcnt(0)
	s_nop 1
	v_add_f32_dpp v34, v34, v34 quad_perm:[2,3,0,1] row_mask:0xf bank_mask:0xf
	s_waitcnt lgkmcnt(0)
	s_nop 1
	v_add_f32_dpp v34, v34, v34 quad_perm:[1,0,3,2] row_mask:0xf bank_mask:0xf
	v_mul_f32_e32 v54, 0x3b000000, v34
	v_pk_add_f32 v[34:35], v[36:37], v[54:55] op_sel_hi:[1,0] neg_lo:[0,1] neg_hi:[0,1]
	v_pk_add_f32 v[36:37], v[38:39], v[54:55] op_sel_hi:[1,0] neg_lo:[0,1] neg_hi:[0,1]
	v_pk_add_f32 v[38:39], v[40:41], v[54:55] op_sel_hi:[1,0] neg_lo:[0,1] neg_hi:[0,1]
	v_pk_add_f32 v[40:41], v[52:53], v[54:55] op_sel_hi:[1,0] neg_lo:[0,1] neg_hi:[0,1]
	v_pk_mul_f32 v[52:53], v[34:35], v[34:35]
	v_pk_mul_f32 v[54:55], v[36:37], v[36:37]
	v_add_f32_e32 v51, v52, v53
	v_add_f32_e32 v51, v54, v51
	v_pk_mul_f32 v[56:57], v[38:39], v[38:39]
	v_add_f32_e32 v51, v55, v51
	v_add_f32_e32 v51, v56, v51
	v_pk_mul_f32 v[58:59], v[40:41], v[40:41]
	v_add_f32_e32 v51, v57, v51
	v_add_f32_e32 v51, v58, v51
	v_add_f32_e32 v51, v59, v51
	s_waitcnt lgkmcnt(0)
	v_mov_b32_e32 v52, v51
	s_nop 1
	v_permlane32_swap_b32_e32 v52, v51
	v_add_f32_e32 v51, v51, v52
	s_waitcnt lgkmcnt(0)
	v_mov_b32_e32 v52, v51
	s_nop 1
	v_permlane16_swap_b32_e32 v52, v51
	v_add_f32_e32 v51, v51, v52
	s_waitcnt lgkmcnt(0)
	s_nop 1
	v_add_f32_dpp v51, v51, v51 row_mirror row_mask:0xf bank_mask:0xf
	s_waitcnt lgkmcnt(0)
	s_nop 1
	v_add_f32_dpp v51, v51, v51 row_half_mirror row_mask:0xf bank_mask:0xf
	s_waitcnt lgkmcnt(0)
	s_nop 1
	v_add_f32_dpp v51, v51, v51 quad_perm:[2,3,0,1] row_mask:0xf bank_mask:0xf
	s_nop 1
	v_add_f32_dpp v51, v51, v51 quad_perm:[1,0,3,2] row_mask:0xf bank_mask:0xf
	s_and_saveexec_b64 s[40:41], s[36:37]
	s_cbranch_execz .LBB0_678
	s_waitcnt lgkmcnt(0)
	v_fmamk_f32 v51, v51, 0x3b000000, v190
	v_mul_f32_e32 v52, 0x4b800000, v51
	v_cmp_gt_f32_e32 vcc, s79, v51
	s_nop 1
	v_cndmask_b32_e32 v51, v51, v52, vcc
	v_rsq_f32_e32 v51, v51
	s_nop 0
	v_mul_f32_e32 v52, 0x45800000, v51
	v_cndmask_b32_e32 v52, v51, v52, vcc
	v_pk_mul_f32 v[34:35], v[34:35], v[52:53] op_sel_hi:[1,0]
	v_pk_mul_f32 v[36:37], v[36:37], v[52:53] op_sel_hi:[1,0]
	v_pk_mul_f32 v[38:39], v[38:39], v[52:53] op_sel_hi:[1,0]
	v_pk_mul_f32 v[40:41], v[40:41], v[52:53] op_sel_hi:[1,0]
	v_bfe_u32 v53, v39, 16, 1
	v_bfe_u32 v54, v38, 16, 1
	v_bfe_u32 v55, v37, 16, 1
	v_bfe_u32 v56, v36, 16, 1
	v_bfe_u32 v57, v35, 16, 1
	v_bfe_u32 v58, v34, 16, 1
	v_add3_u32 v34, v34, v58, s94
	v_add3_u32 v57, v35, v57, s94
	v_add3_u32 v35, v36, v56, s94
	v_add3_u32 v55, v37, v55, s94
	v_add3_u32 v36, v38, v54, s94
	v_add3_u32 v38, v39, v53, s94
	v_cvt_pk_bf16_f32 v37, v40, v41
	v_perm_b32 v36, v38, v36, s95
	v_perm_b32 v35, v55, v35, s95
	v_perm_b32 v34, v57, v34, s95
	ds_write_b128 v50, v[34:37]
.LBB0_678:
	s_or_b64 exec, exec, s[40:41]
	s_waitcnt vmcnt(6)
	v_lshlrev_b32_e32 v34, 16, v24
	v_and_b32_e32 v35, 0xffff0000, v24
	v_add_f32_e32 v24, 0, v34
	v_add_f32_e32 v24, v24, v35
	v_lshlrev_b32_e32 v36, 16, v25
	v_and_b32_e32 v37, 0xffff0000, v25
	v_add_f32_e32 v24, v24, v36
	v_add_f32_e32 v24, v24, v37
	v_lshlrev_b32_e32 v38, 16, v26
	v_and_b32_e32 v39, 0xffff0000, v26
	v_add_f32_e32 v24, v24, v38
	v_add_f32_e32 v24, v24, v39
	v_lshlrev_b32_e32 v40, 16, v27
	v_and_b32_e32 v41, 0xffff0000, v27
	v_add_f32_e32 v24, v24, v40
	v_add_f32_e32 v24, v24, v41
	s_waitcnt lgkmcnt(0)
	v_mov_b32_e32 v25, v24
	s_nop 1
	v_permlane32_swap_b32_e32 v25, v24
	v_add_f32_e32 v24, v24, v25
	s_waitcnt lgkmcnt(0)
	v_mov_b32_e32 v25, v24
	s_nop 1
	v_permlane16_swap_b32_e32 v25, v24
	v_add_f32_e32 v24, v24, v25
	s_waitcnt lgkmcnt(0)
	s_nop 1
	v_add_f32_dpp v24, v24, v24 row_mirror row_mask:0xf bank_mask:0xf
	s_waitcnt lgkmcnt(0)
	s_nop 1
	v_add_f32_dpp v24, v24, v24 row_half_mirror row_mask:0xf bank_mask:0xf
	s_waitcnt lgkmcnt(0)
	s_nop 1
	v_add_f32_dpp v24, v24, v24 quad_perm:[2,3,0,1] row_mask:0xf bank_mask:0xf
	s_waitcnt lgkmcnt(0)
	s_nop 1
	v_add_f32_dpp v24, v24, v24 quad_perm:[1,0,3,2] row_mask:0xf bank_mask:0xf
	v_mul_f32_e32 v52, 0x3b000000, v24
	v_pk_add_f32 v[24:25], v[34:35], v[52:53] op_sel_hi:[1,0] neg_lo:[0,1] neg_hi:[0,1]
	v_pk_add_f32 v[26:27], v[36:37], v[52:53] op_sel_hi:[1,0] neg_lo:[0,1] neg_hi:[0,1]
	v_pk_add_f32 v[34:35], v[38:39], v[52:53] op_sel_hi:[1,0] neg_lo:[0,1] neg_hi:[0,1]
	v_pk_mul_f32 v[38:39], v[24:25], v[24:25]
	v_pk_add_f32 v[36:37], v[40:41], v[52:53] op_sel_hi:[1,0] neg_lo:[0,1] neg_hi:[0,1]
	v_pk_mul_f32 v[40:41], v[26:27], v[26:27]
	v_add_f32_e32 v38, v38, v39
	v_add_f32_e32 v38, v40, v38
	v_pk_mul_f32 v[52:53], v[34:35], v[34:35]
	v_add_f32_e32 v38, v41, v38
	v_add_f32_e32 v38, v52, v38
	v_pk_mul_f32 v[54:55], v[36:37], v[36:37]
	v_add_f32_e32 v38, v53, v38
	v_add_f32_e32 v38, v54, v38
	v_add_f32_e32 v38, v55, v38
	s_waitcnt lgkmcnt(0)
	v_mov_b32_e32 v39, v38
	s_nop 1
	v_permlane32_swap_b32_e32 v39, v38
	v_add_f32_e32 v38, v38, v39
	s_waitcnt lgkmcnt(0)
	v_mov_b32_e32 v39, v38
	s_nop 1
	v_permlane16_swap_b32_e32 v39, v38
	v_add_f32_e32 v38, v38, v39
	s_waitcnt lgkmcnt(0)
	s_nop 1
	v_add_f32_dpp v38, v38, v38 row_mirror row_mask:0xf bank_mask:0xf
	s_waitcnt lgkmcnt(0)
	s_nop 1
	v_add_f32_dpp v38, v38, v38 row_half_mirror row_mask:0xf bank_mask:0xf
	s_waitcnt lgkmcnt(0)
	s_nop 1
	v_add_f32_dpp v38, v38, v38 quad_perm:[2,3,0,1] row_mask:0xf bank_mask:0xf
	s_nop 1
	v_add_f32_dpp v38, v38, v38 quad_perm:[1,0,3,2] row_mask:0xf bank_mask:0xf
	s_and_saveexec_b64 s[40:41], s[36:37]
	s_cbranch_execz .LBB0_680
	s_waitcnt lgkmcnt(0)
	v_fmamk_f32 v38, v38, 0x3b000000, v190
	v_mul_f32_e32 v39, 0x4b800000, v38
	v_cmp_gt_f32_e32 vcc, s79, v38
	s_nop 1
	v_cndmask_b32_e32 v38, v38, v39, vcc
	v_rsq_f32_e32 v38, v38
	s_nop 0
	v_mul_f32_e32 v39, 0x45800000, v38
	v_cndmask_b32_e32 v38, v38, v39, vcc
	v_pk_mul_f32 v[24:25], v[24:25], v[38:39] op_sel_hi:[1,0]
	v_pk_mul_f32 v[26:27], v[26:27], v[38:39] op_sel_hi:[1,0]
	v_pk_mul_f32 v[34:35], v[34:35], v[38:39] op_sel_hi:[1,0]
	v_pk_mul_f32 v[36:37], v[36:37], v[38:39] op_sel_hi:[1,0]
	v_bfe_u32 v38, v37, 16, 1
	v_bfe_u32 v39, v36, 16, 1
	v_bfe_u32 v51, v27, 16, 1
	v_bfe_u32 v52, v26, 16, 1
	v_bfe_u32 v53, v25, 16, 1
	v_bfe_u32 v54, v24, 16, 1
	v_add3_u32 v24, v24, v54, s94
	v_add3_u32 v53, v25, v53, s94
	v_add3_u32 v25, v26, v52, s94
	v_add3_u32 v51, v27, v51, s94
	v_cvt_pk_bf16_f32 v34, v34, v35
	v_add3_u32 v27, v36, v39, s94
	v_add3_u32 v35, v37, v38, s94
	v_perm_b32 v27, v35, v27, s95
	v_mov_b32_e32 v26, v34
	v_perm_b32 v25, v51, v25, s95
	v_perm_b32 v24, v53, v24, s95
	ds_write_b128 v50, v[24:27] offset:288
.LBB0_680:
	s_or_b64 exec, exec, s[40:41]
	s_waitcnt vmcnt(5)
	v_lshlrev_b32_e32 v24, 16, v20
	v_and_b32_e32 v25, 0xffff0000, v20
	v_add_f32_e32 v20, 0, v24
	v_add_f32_e32 v20, v20, v25
	v_lshlrev_b32_e32 v26, 16, v21
	v_and_b32_e32 v27, 0xffff0000, v21
	v_add_f32_e32 v20, v20, v26
	v_add_f32_e32 v20, v20, v27
	v_lshlrev_b32_e32 v34, 16, v22
	v_and_b32_e32 v35, 0xffff0000, v22
	v_add_f32_e32 v20, v20, v34
	v_add_f32_e32 v20, v20, v35
	v_lshlrev_b32_e32 v36, 16, v23
	v_and_b32_e32 v37, 0xffff0000, v23
	v_add_f32_e32 v20, v20, v36
	v_add_f32_e32 v20, v20, v37
	s_waitcnt lgkmcnt(0)
	v_mov_b32_e32 v21, v20
	s_nop 1
	v_permlane32_swap_b32_e32 v21, v20
	v_add_f32_e32 v20, v20, v21
	s_waitcnt lgkmcnt(0)
	v_mov_b32_e32 v21, v20
	s_nop 1
	v_permlane16_swap_b32_e32 v21, v20
	v_add_f32_e32 v20, v20, v21
	s_waitcnt lgkmcnt(0)
	s_nop 1
	v_add_f32_dpp v20, v20, v20 row_mirror row_mask:0xf bank_mask:0xf
	s_waitcnt lgkmcnt(0)
	s_nop 1
	v_add_f32_dpp v20, v20, v20 row_half_mirror row_mask:0xf bank_mask:0xf
	s_waitcnt lgkmcnt(0)
	s_nop 1
	v_add_f32_dpp v20, v20, v20 quad_perm:[2,3,0,1] row_mask:0xf bank_mask:0xf
	s_waitcnt lgkmcnt(0)
	s_nop 1
	v_add_f32_dpp v20, v20, v20 quad_perm:[1,0,3,2] row_mask:0xf bank_mask:0xf
	v_mul_f32_e32 v38, 0x3b000000, v20
	v_pk_add_f32 v[20:21], v[24:25], v[38:39] op_sel_hi:[1,0] neg_lo:[0,1] neg_hi:[0,1]
	v_pk_add_f32 v[22:23], v[26:27], v[38:39] op_sel_hi:[1,0] neg_lo:[0,1] neg_hi:[0,1]
	v_pk_add_f32 v[24:25], v[34:35], v[38:39] op_sel_hi:[1,0] neg_lo:[0,1] neg_hi:[0,1]
	v_pk_mul_f32 v[34:35], v[20:21], v[20:21]
	v_pk_add_f32 v[26:27], v[36:37], v[38:39] op_sel_hi:[1,0] neg_lo:[0,1] neg_hi:[0,1]
	v_pk_mul_f32 v[36:37], v[22:23], v[22:23]
	v_add_f32_e32 v34, v34, v35
	v_add_f32_e32 v34, v36, v34
	v_pk_mul_f32 v[38:39], v[24:25], v[24:25]
	v_add_f32_e32 v34, v37, v34
	v_add_f32_e32 v34, v38, v34
	v_pk_mul_f32 v[40:41], v[26:27], v[26:27]
	v_add_f32_e32 v34, v39, v34
	v_add_f32_e32 v34, v40, v34
	v_add_f32_e32 v34, v41, v34
	s_waitcnt lgkmcnt(0)
	v_mov_b32_e32 v35, v34
	s_nop 1
	v_permlane32_swap_b32_e32 v35, v34
	v_add_f32_e32 v34, v34, v35
	s_waitcnt lgkmcnt(0)
	v_mov_b32_e32 v35, v34
	s_nop 1
	v_permlane16_swap_b32_e32 v35, v34
	v_add_f32_e32 v34, v34, v35
	s_waitcnt lgkmcnt(0)
	s_nop 1
	v_add_f32_dpp v34, v34, v34 row_mirror row_mask:0xf bank_mask:0xf
	s_waitcnt lgkmcnt(0)
	s_nop 1
	v_add_f32_dpp v34, v34, v34 row_half_mirror row_mask:0xf bank_mask:0xf
	s_waitcnt lgkmcnt(0)
	s_nop 1
	v_add_f32_dpp v34, v34, v34 quad_perm:[2,3,0,1] row_mask:0xf bank_mask:0xf
	s_nop 1
	v_add_f32_dpp v34, v34, v34 quad_perm:[1,0,3,2] row_mask:0xf bank_mask:0xf
	s_and_saveexec_b64 s[40:41], s[36:37]
	s_cbranch_execz .LBB0_682
	s_waitcnt lgkmcnt(0)
	v_fmamk_f32 v34, v34, 0x3b000000, v190
	v_mul_f32_e32 v35, 0x4b800000, v34
	v_cmp_gt_f32_e32 vcc, s79, v34
	s_nop 1
	v_cndmask_b32_e32 v34, v34, v35, vcc
	v_rsq_f32_e32 v34, v34
	s_nop 0
	v_mul_f32_e32 v35, 0x45800000, v34
	v_cndmask_b32_e32 v34, v34, v35, vcc
	v_pk_mul_f32 v[20:21], v[20:21], v[34:35] op_sel_hi:[1,0]
	v_pk_mul_f32 v[22:23], v[22:23], v[34:35] op_sel_hi:[1,0]
	v_pk_mul_f32 v[24:25], v[24:25], v[34:35] op_sel_hi:[1,0]
	v_pk_mul_f32 v[26:27], v[26:27], v[34:35] op_sel_hi:[1,0]
	v_bfe_u32 v34, v27, 16, 1
	v_bfe_u32 v35, v26, 16, 1
	v_bfe_u32 v38, v23, 16, 1
	v_bfe_u32 v39, v22, 16, 1
	v_bfe_u32 v40, v21, 16, 1
	v_bfe_u32 v41, v20, 16, 1
	v_add3_u32 v20, v20, v41, s94
	v_add3_u32 v40, v21, v40, s94
	v_add3_u32 v21, v22, v39, s94
	v_add3_u32 v38, v23, v38, s94
	v_cvt_pk_bf16_f32 v24, v24, v25
	v_add3_u32 v23, v26, v35, s94
	v_add3_u32 v25, v27, v34, s94
	v_perm_b32 v23, v25, v23, s95
	v_mov_b32_e32 v22, v24
	v_perm_b32 v21, v38, v21, s95
	v_perm_b32 v20, v40, v20, s95
	ds_write_b128 v50, v[20:23] offset:576
.LBB0_682:
	s_or_b64 exec, exec, s[40:41]
	s_waitcnt vmcnt(4)
	v_lshlrev_b32_e32 v20, 16, v16
	v_and_b32_e32 v21, 0xffff0000, v16
	v_add_f32_e32 v16, 0, v20
	v_add_f32_e32 v16, v16, v21
	v_lshlrev_b32_e32 v22, 16, v17
	v_and_b32_e32 v23, 0xffff0000, v17
	v_add_f32_e32 v16, v16, v22
	v_add_f32_e32 v16, v16, v23
	v_lshlrev_b32_e32 v24, 16, v18
	v_and_b32_e32 v25, 0xffff0000, v18
	v_add_f32_e32 v16, v16, v24
	v_add_f32_e32 v16, v16, v25
	v_lshlrev_b32_e32 v26, 16, v19
	v_and_b32_e32 v27, 0xffff0000, v19
	v_add_f32_e32 v16, v16, v26
	v_add_f32_e32 v16, v16, v27
	s_waitcnt lgkmcnt(0)
	v_mov_b32_e32 v17, v16
	s_nop 1
	v_permlane32_swap_b32_e32 v17, v16
	v_add_f32_e32 v16, v16, v17
	s_waitcnt lgkmcnt(0)
	v_mov_b32_e32 v17, v16
	s_nop 1
	v_permlane16_swap_b32_e32 v17, v16
	v_add_f32_e32 v16, v16, v17
	s_waitcnt lgkmcnt(0)
	s_nop 1
	v_add_f32_dpp v16, v16, v16 row_mirror row_mask:0xf bank_mask:0xf
	s_waitcnt lgkmcnt(0)
	s_nop 1
	v_add_f32_dpp v16, v16, v16 row_half_mirror row_mask:0xf bank_mask:0xf
	s_waitcnt lgkmcnt(0)
	s_nop 1
	v_add_f32_dpp v16, v16, v16 quad_perm:[2,3,0,1] row_mask:0xf bank_mask:0xf
	s_waitcnt lgkmcnt(0)
	s_nop 1
	v_add_f32_dpp v16, v16, v16 quad_perm:[1,0,3,2] row_mask:0xf bank_mask:0xf
	v_mul_f32_e32 v34, 0x3b000000, v16
	v_pk_add_f32 v[16:17], v[20:21], v[34:35] op_sel_hi:[1,0] neg_lo:[0,1] neg_hi:[0,1]
	v_pk_add_f32 v[18:19], v[22:23], v[34:35] op_sel_hi:[1,0] neg_lo:[0,1] neg_hi:[0,1]
	v_pk_add_f32 v[20:21], v[24:25], v[34:35] op_sel_hi:[1,0] neg_lo:[0,1] neg_hi:[0,1]
	v_pk_mul_f32 v[24:25], v[16:17], v[16:17]
	v_pk_add_f32 v[22:23], v[26:27], v[34:35] op_sel_hi:[1,0] neg_lo:[0,1] neg_hi:[0,1]
	v_pk_mul_f32 v[26:27], v[18:19], v[18:19]
	v_add_f32_e32 v24, v24, v25
	v_add_f32_e32 v24, v26, v24
	v_pk_mul_f32 v[34:35], v[20:21], v[20:21]
	v_add_f32_e32 v24, v27, v24
	v_add_f32_e32 v24, v34, v24
	v_pk_mul_f32 v[36:37], v[22:23], v[22:23]
	v_add_f32_e32 v24, v35, v24
	v_add_f32_e32 v24, v36, v24
	v_add_f32_e32 v24, v37, v24
	s_waitcnt lgkmcnt(0)
	v_mov_b32_e32 v25, v24
	s_nop 1
	v_permlane32_swap_b32_e32 v25, v24
	v_add_f32_e32 v24, v24, v25
	s_waitcnt lgkmcnt(0)
	v_mov_b32_e32 v25, v24
	s_nop 1
	v_permlane16_swap_b32_e32 v25, v24
	v_add_f32_e32 v24, v24, v25
	s_waitcnt lgkmcnt(0)
	s_nop 1
	v_add_f32_dpp v24, v24, v24 row_mirror row_mask:0xf bank_mask:0xf
	s_waitcnt lgkmcnt(0)
	s_nop 1
	v_add_f32_dpp v24, v24, v24 row_half_mirror row_mask:0xf bank_mask:0xf
	s_waitcnt lgkmcnt(0)
	s_nop 1
	v_add_f32_dpp v24, v24, v24 quad_perm:[2,3,0,1] row_mask:0xf bank_mask:0xf
	s_nop 1
	v_add_f32_dpp v24, v24, v24 quad_perm:[1,0,3,2] row_mask:0xf bank_mask:0xf
	s_and_saveexec_b64 s[40:41], s[36:37]
	s_cbranch_execz .LBB0_684
	s_waitcnt lgkmcnt(0)
	v_fmamk_f32 v24, v24, 0x3b000000, v190
	v_mul_f32_e32 v25, 0x4b800000, v24
	v_cmp_gt_f32_e32 vcc, s79, v24
	s_nop 1
	v_cndmask_b32_e32 v24, v24, v25, vcc
	v_rsq_f32_e32 v24, v24
	s_nop 0
	v_mul_f32_e32 v25, 0x45800000, v24
	v_cndmask_b32_e32 v24, v24, v25, vcc
	v_pk_mul_f32 v[16:17], v[16:17], v[24:25] op_sel_hi:[1,0]
	v_pk_mul_f32 v[18:19], v[18:19], v[24:25] op_sel_hi:[1,0]
	v_pk_mul_f32 v[20:21], v[20:21], v[24:25] op_sel_hi:[1,0]
	v_pk_mul_f32 v[22:23], v[22:23], v[24:25] op_sel_hi:[1,0]
	v_bfe_u32 v24, v23, 16, 1
	v_bfe_u32 v25, v22, 16, 1
	v_bfe_u32 v34, v19, 16, 1
	v_bfe_u32 v35, v18, 16, 1
	v_bfe_u32 v36, v17, 16, 1
	v_bfe_u32 v37, v16, 16, 1
	v_add3_u32 v16, v16, v37, s94
	v_add3_u32 v36, v17, v36, s94
	v_add3_u32 v17, v18, v35, s94
	v_add3_u32 v34, v19, v34, s94
	v_cvt_pk_bf16_f32 v20, v20, v21
	v_add3_u32 v19, v22, v25, s94
	v_add3_u32 v21, v23, v24, s94
	v_perm_b32 v19, v21, v19, s95
	v_mov_b32_e32 v18, v20
	v_perm_b32 v17, v34, v17, s95
	v_perm_b32 v16, v36, v16, s95
	ds_write_b128 v50, v[16:19] offset:864
.LBB0_684:
	s_or_b64 exec, exec, s[40:41]
	s_waitcnt vmcnt(3)
	v_lshlrev_b32_e32 v16, 16, v12
	v_and_b32_e32 v17, 0xffff0000, v12
	v_add_f32_e32 v12, 0, v16
	v_add_f32_e32 v12, v12, v17
	v_lshlrev_b32_e32 v18, 16, v13
	v_and_b32_e32 v19, 0xffff0000, v13
	v_add_f32_e32 v12, v12, v18
	v_add_f32_e32 v12, v12, v19
	v_lshlrev_b32_e32 v20, 16, v14
	v_and_b32_e32 v21, 0xffff0000, v14
	v_add_f32_e32 v12, v12, v20
	v_add_f32_e32 v12, v12, v21
	v_lshlrev_b32_e32 v22, 16, v15
	v_and_b32_e32 v23, 0xffff0000, v15
	v_add_f32_e32 v12, v12, v22
	v_add_f32_e32 v12, v12, v23
	s_waitcnt lgkmcnt(0)
	v_mov_b32_e32 v13, v12
	s_nop 1
	v_permlane32_swap_b32_e32 v13, v12
	v_add_f32_e32 v12, v12, v13
	s_waitcnt lgkmcnt(0)
	v_mov_b32_e32 v13, v12
	s_nop 1
	v_permlane16_swap_b32_e32 v13, v12
	v_add_f32_e32 v12, v12, v13
	s_waitcnt lgkmcnt(0)
	s_nop 1
	v_add_f32_dpp v12, v12, v12 row_mirror row_mask:0xf bank_mask:0xf
	s_waitcnt lgkmcnt(0)
	s_nop 1
	v_add_f32_dpp v12, v12, v12 row_half_mirror row_mask:0xf bank_mask:0xf
	s_waitcnt lgkmcnt(0)
	s_nop 1
	v_add_f32_dpp v12, v12, v12 quad_perm:[2,3,0,1] row_mask:0xf bank_mask:0xf
	s_waitcnt lgkmcnt(0)
	s_nop 1
	v_add_f32_dpp v12, v12, v12 quad_perm:[1,0,3,2] row_mask:0xf bank_mask:0xf
	v_mul_f32_e32 v24, 0x3b000000, v12
	v_pk_add_f32 v[12:13], v[16:17], v[24:25] op_sel_hi:[1,0] neg_lo:[0,1] neg_hi:[0,1]
	v_pk_add_f32 v[14:15], v[18:19], v[24:25] op_sel_hi:[1,0] neg_lo:[0,1] neg_hi:[0,1]
	v_pk_add_f32 v[16:17], v[20:21], v[24:25] op_sel_hi:[1,0] neg_lo:[0,1] neg_hi:[0,1]
	v_pk_mul_f32 v[20:21], v[12:13], v[12:13]
	v_pk_add_f32 v[18:19], v[22:23], v[24:25] op_sel_hi:[1,0] neg_lo:[0,1] neg_hi:[0,1]
	v_pk_mul_f32 v[22:23], v[14:15], v[14:15]
	v_add_f32_e32 v20, v20, v21
	v_add_f32_e32 v20, v22, v20
	v_pk_mul_f32 v[24:25], v[16:17], v[16:17]
	v_add_f32_e32 v20, v23, v20
	v_add_f32_e32 v20, v24, v20
	v_pk_mul_f32 v[26:27], v[18:19], v[18:19]
	v_add_f32_e32 v20, v25, v20
	v_add_f32_e32 v20, v26, v20
	v_add_f32_e32 v20, v27, v20
	s_waitcnt lgkmcnt(0)
	v_mov_b32_e32 v21, v20
	s_nop 1
	v_permlane32_swap_b32_e32 v21, v20
	v_add_f32_e32 v20, v20, v21
	s_waitcnt lgkmcnt(0)
	v_mov_b32_e32 v21, v20
	s_nop 1
	v_permlane16_swap_b32_e32 v21, v20
	v_add_f32_e32 v20, v20, v21
	s_waitcnt lgkmcnt(0)
	s_nop 1
	v_add_f32_dpp v20, v20, v20 row_mirror row_mask:0xf bank_mask:0xf
	s_waitcnt lgkmcnt(0)
	s_nop 1
	v_add_f32_dpp v20, v20, v20 row_half_mirror row_mask:0xf bank_mask:0xf
	s_waitcnt lgkmcnt(0)
	s_nop 1
	v_add_f32_dpp v20, v20, v20 quad_perm:[2,3,0,1] row_mask:0xf bank_mask:0xf
	s_nop 1
	v_add_f32_dpp v20, v20, v20 quad_perm:[1,0,3,2] row_mask:0xf bank_mask:0xf
	s_and_saveexec_b64 s[40:41], s[36:37]
	s_cbranch_execz .LBB0_686
	s_waitcnt lgkmcnt(0)
	v_fmamk_f32 v20, v20, 0x3b000000, v190
	v_mul_f32_e32 v21, 0x4b800000, v20
	v_cmp_gt_f32_e32 vcc, s79, v20
	s_nop 1
	v_cndmask_b32_e32 v20, v20, v21, vcc
	v_rsq_f32_e32 v20, v20
	s_nop 0
	v_mul_f32_e32 v21, 0x45800000, v20
	v_cndmask_b32_e32 v20, v20, v21, vcc
	v_pk_mul_f32 v[12:13], v[12:13], v[20:21] op_sel_hi:[1,0]
	v_pk_mul_f32 v[14:15], v[14:15], v[20:21] op_sel_hi:[1,0]
	v_pk_mul_f32 v[16:17], v[16:17], v[20:21] op_sel_hi:[1,0]
	v_pk_mul_f32 v[18:19], v[18:19], v[20:21] op_sel_hi:[1,0]
	v_bfe_u32 v20, v19, 16, 1
	v_bfe_u32 v21, v18, 16, 1
	v_bfe_u32 v24, v15, 16, 1
	v_bfe_u32 v25, v14, 16, 1
	v_bfe_u32 v26, v13, 16, 1
	v_bfe_u32 v27, v12, 16, 1
	v_add3_u32 v12, v12, v27, s94
	v_add3_u32 v26, v13, v26, s94
	v_add3_u32 v13, v14, v25, s94
	v_add3_u32 v24, v15, v24, s94
	v_cvt_pk_bf16_f32 v16, v16, v17
	v_add3_u32 v15, v18, v21, s94
	v_add3_u32 v17, v19, v20, s94
	v_perm_b32 v15, v17, v15, s95
	v_mov_b32_e32 v14, v16
	v_perm_b32 v13, v24, v13, s95
	v_perm_b32 v12, v26, v12, s95
	ds_write_b128 v50, v[12:15] offset:1152
.LBB0_686:
	s_or_b64 exec, exec, s[40:41]
	s_waitcnt vmcnt(2)
	v_lshlrev_b32_e32 v12, 16, v8
	v_and_b32_e32 v13, 0xffff0000, v8
	v_add_f32_e32 v8, 0, v12
	v_add_f32_e32 v8, v8, v13
	v_lshlrev_b32_e32 v14, 16, v9
	v_and_b32_e32 v15, 0xffff0000, v9
	v_add_f32_e32 v8, v8, v14
	v_add_f32_e32 v8, v8, v15
	v_lshlrev_b32_e32 v16, 16, v10
	v_and_b32_e32 v17, 0xffff0000, v10
	v_add_f32_e32 v8, v8, v16
	v_add_f32_e32 v8, v8, v17
	v_lshlrev_b32_e32 v18, 16, v11
	v_and_b32_e32 v19, 0xffff0000, v11
	v_add_f32_e32 v8, v8, v18
	v_add_f32_e32 v8, v8, v19
	s_waitcnt lgkmcnt(0)
	v_mov_b32_e32 v9, v8
	s_nop 1
	v_permlane32_swap_b32_e32 v9, v8
	v_add_f32_e32 v8, v8, v9
	s_waitcnt lgkmcnt(0)
	v_mov_b32_e32 v9, v8
	s_nop 1
	v_permlane16_swap_b32_e32 v9, v8
	v_add_f32_e32 v8, v8, v9
	s_waitcnt lgkmcnt(0)
	s_nop 1
	v_add_f32_dpp v8, v8, v8 row_mirror row_mask:0xf bank_mask:0xf
	s_waitcnt lgkmcnt(0)
	s_nop 1
	v_add_f32_dpp v8, v8, v8 row_half_mirror row_mask:0xf bank_mask:0xf
	s_waitcnt lgkmcnt(0)
	s_nop 1
	v_add_f32_dpp v8, v8, v8 quad_perm:[2,3,0,1] row_mask:0xf bank_mask:0xf
	s_waitcnt lgkmcnt(0)
	s_nop 1
	v_add_f32_dpp v8, v8, v8 quad_perm:[1,0,3,2] row_mask:0xf bank_mask:0xf
	v_mul_f32_e32 v20, 0x3b000000, v8
	v_pk_add_f32 v[8:9], v[12:13], v[20:21] op_sel_hi:[1,0] neg_lo:[0,1] neg_hi:[0,1]
	v_pk_add_f32 v[10:11], v[14:15], v[20:21] op_sel_hi:[1,0] neg_lo:[0,1] neg_hi:[0,1]
	v_pk_add_f32 v[12:13], v[16:17], v[20:21] op_sel_hi:[1,0] neg_lo:[0,1] neg_hi:[0,1]
	v_pk_mul_f32 v[16:17], v[8:9], v[8:9]
	v_pk_add_f32 v[14:15], v[18:19], v[20:21] op_sel_hi:[1,0] neg_lo:[0,1] neg_hi:[0,1]
	v_pk_mul_f32 v[18:19], v[10:11], v[10:11]
	v_add_f32_e32 v16, v16, v17
	v_add_f32_e32 v16, v18, v16
	v_pk_mul_f32 v[20:21], v[12:13], v[12:13]
	v_add_f32_e32 v16, v19, v16
	v_add_f32_e32 v16, v20, v16
	v_pk_mul_f32 v[22:23], v[14:15], v[14:15]
	v_add_f32_e32 v16, v21, v16
	v_add_f32_e32 v16, v22, v16
	v_add_f32_e32 v16, v23, v16
	s_waitcnt lgkmcnt(0)
	v_mov_b32_e32 v17, v16
	s_nop 1
	v_permlane32_swap_b32_e32 v17, v16
	v_add_f32_e32 v16, v16, v17
	s_waitcnt lgkmcnt(0)
	v_mov_b32_e32 v17, v16
	s_nop 1
	v_permlane16_swap_b32_e32 v17, v16
	v_add_f32_e32 v16, v16, v17
	s_waitcnt lgkmcnt(0)
	s_nop 1
	v_add_f32_dpp v16, v16, v16 row_mirror row_mask:0xf bank_mask:0xf
	s_waitcnt lgkmcnt(0)
	s_nop 1
	v_add_f32_dpp v16, v16, v16 row_half_mirror row_mask:0xf bank_mask:0xf
	s_waitcnt lgkmcnt(0)
	s_nop 1
	v_add_f32_dpp v16, v16, v16 quad_perm:[2,3,0,1] row_mask:0xf bank_mask:0xf
	s_nop 1
	v_add_f32_dpp v16, v16, v16 quad_perm:[1,0,3,2] row_mask:0xf bank_mask:0xf
	s_and_saveexec_b64 s[40:41], s[36:37]
	s_cbranch_execz .LBB0_688
	s_waitcnt lgkmcnt(0)
	v_fmamk_f32 v16, v16, 0x3b000000, v190
	v_mul_f32_e32 v17, 0x4b800000, v16
	v_cmp_gt_f32_e32 vcc, s79, v16
	s_nop 1
	v_cndmask_b32_e32 v16, v16, v17, vcc
	v_rsq_f32_e32 v16, v16
	s_nop 0
	v_mul_f32_e32 v17, 0x45800000, v16
	v_cndmask_b32_e32 v16, v16, v17, vcc
	v_pk_mul_f32 v[8:9], v[8:9], v[16:17] op_sel_hi:[1,0]
	v_pk_mul_f32 v[10:11], v[10:11], v[16:17] op_sel_hi:[1,0]
	v_pk_mul_f32 v[12:13], v[12:13], v[16:17] op_sel_hi:[1,0]
	v_pk_mul_f32 v[14:15], v[14:15], v[16:17] op_sel_hi:[1,0]
	v_bfe_u32 v16, v15, 16, 1
	v_bfe_u32 v17, v14, 16, 1
	v_bfe_u32 v20, v11, 16, 1
	v_bfe_u32 v21, v10, 16, 1
	v_bfe_u32 v22, v9, 16, 1
	v_bfe_u32 v23, v8, 16, 1
	v_add3_u32 v8, v8, v23, s94
	v_add3_u32 v22, v9, v22, s94
	v_add3_u32 v9, v10, v21, s94
	v_add3_u32 v20, v11, v20, s94
	v_cvt_pk_bf16_f32 v12, v12, v13
	v_add3_u32 v11, v14, v17, s94
	v_add3_u32 v13, v15, v16, s94
	v_perm_b32 v11, v13, v11, s95
	v_mov_b32_e32 v10, v12
	v_perm_b32 v9, v20, v9, s95
	v_perm_b32 v8, v22, v8, s95
	ds_write_b128 v50, v[8:11] offset:1440
.LBB0_688:
	s_or_b64 exec, exec, s[40:41]
	s_waitcnt vmcnt(1)
	v_lshlrev_b32_e32 v8, 16, v4
	v_and_b32_e32 v9, 0xffff0000, v4
	v_add_f32_e32 v4, 0, v8
	v_add_f32_e32 v4, v4, v9
	v_lshlrev_b32_e32 v10, 16, v5
	v_and_b32_e32 v11, 0xffff0000, v5
	v_add_f32_e32 v4, v4, v10
	v_add_f32_e32 v4, v4, v11
	v_lshlrev_b32_e32 v12, 16, v6
	v_and_b32_e32 v13, 0xffff0000, v6
	v_add_f32_e32 v4, v4, v12
	v_add_f32_e32 v4, v4, v13
	v_lshlrev_b32_e32 v14, 16, v7
	v_and_b32_e32 v15, 0xffff0000, v7
	v_add_f32_e32 v4, v4, v14
	v_add_f32_e32 v4, v4, v15
	s_waitcnt lgkmcnt(0)
	v_mov_b32_e32 v5, v4
	s_nop 1
	v_permlane32_swap_b32_e32 v5, v4
	v_add_f32_e32 v4, v4, v5
	s_waitcnt lgkmcnt(0)
	v_mov_b32_e32 v5, v4
	s_nop 1
	v_permlane16_swap_b32_e32 v5, v4
	v_add_f32_e32 v4, v4, v5
	s_waitcnt lgkmcnt(0)
	s_nop 1
	v_add_f32_dpp v4, v4, v4 row_mirror row_mask:0xf bank_mask:0xf
	s_waitcnt lgkmcnt(0)
	s_nop 1
	v_add_f32_dpp v4, v4, v4 row_half_mirror row_mask:0xf bank_mask:0xf
	s_waitcnt lgkmcnt(0)
	s_nop 1
	v_add_f32_dpp v4, v4, v4 quad_perm:[2,3,0,1] row_mask:0xf bank_mask:0xf
	s_waitcnt lgkmcnt(0)
	s_nop 1
	v_add_f32_dpp v4, v4, v4 quad_perm:[1,0,3,2] row_mask:0xf bank_mask:0xf
	v_mul_f32_e32 v16, 0x3b000000, v4
	v_pk_add_f32 v[4:5], v[8:9], v[16:17] op_sel_hi:[1,0] neg_lo:[0,1] neg_hi:[0,1]
	v_pk_add_f32 v[6:7], v[10:11], v[16:17] op_sel_hi:[1,0] neg_lo:[0,1] neg_hi:[0,1]
	v_pk_add_f32 v[8:9], v[12:13], v[16:17] op_sel_hi:[1,0] neg_lo:[0,1] neg_hi:[0,1]
	v_pk_mul_f32 v[12:13], v[4:5], v[4:5]
	v_pk_add_f32 v[10:11], v[14:15], v[16:17] op_sel_hi:[1,0] neg_lo:[0,1] neg_hi:[0,1]
	v_pk_mul_f32 v[14:15], v[6:7], v[6:7]
	v_add_f32_e32 v12, v12, v13
	v_add_f32_e32 v12, v14, v12
	v_pk_mul_f32 v[16:17], v[8:9], v[8:9]
	v_add_f32_e32 v12, v15, v12
	v_add_f32_e32 v12, v16, v12
	v_pk_mul_f32 v[18:19], v[10:11], v[10:11]
	v_add_f32_e32 v12, v17, v12
	v_add_f32_e32 v12, v18, v12
	v_add_f32_e32 v12, v19, v12
	s_waitcnt lgkmcnt(0)
	v_mov_b32_e32 v13, v12
	s_nop 1
	v_permlane32_swap_b32_e32 v13, v12
	v_add_f32_e32 v12, v12, v13
	s_waitcnt lgkmcnt(0)
	v_mov_b32_e32 v13, v12
	s_nop 1
	v_permlane16_swap_b32_e32 v13, v12
	v_add_f32_e32 v12, v12, v13
	s_waitcnt lgkmcnt(0)
	s_nop 1
	v_add_f32_dpp v12, v12, v12 row_mirror row_mask:0xf bank_mask:0xf
	s_waitcnt lgkmcnt(0)
	s_nop 1
	v_add_f32_dpp v12, v12, v12 row_half_mirror row_mask:0xf bank_mask:0xf
	s_waitcnt lgkmcnt(0)
	s_nop 1
	v_add_f32_dpp v12, v12, v12 quad_perm:[2,3,0,1] row_mask:0xf bank_mask:0xf
	s_nop 1
	v_add_f32_dpp v12, v12, v12 quad_perm:[1,0,3,2] row_mask:0xf bank_mask:0xf
	s_and_saveexec_b64 s[40:41], s[36:37]
	s_cbranch_execz .LBB0_690
	s_waitcnt lgkmcnt(0)
	v_fmamk_f32 v12, v12, 0x3b000000, v190
	v_mul_f32_e32 v13, 0x4b800000, v12
	v_cmp_gt_f32_e32 vcc, s79, v12
	s_nop 1
	v_cndmask_b32_e32 v12, v12, v13, vcc
	v_rsq_f32_e32 v12, v12
	s_nop 0
	v_mul_f32_e32 v13, 0x45800000, v12
	v_cndmask_b32_e32 v12, v12, v13, vcc
	v_pk_mul_f32 v[4:5], v[4:5], v[12:13] op_sel_hi:[1,0]
	v_pk_mul_f32 v[6:7], v[6:7], v[12:13] op_sel_hi:[1,0]
	v_pk_mul_f32 v[8:9], v[8:9], v[12:13] op_sel_hi:[1,0]
	v_pk_mul_f32 v[10:11], v[10:11], v[12:13] op_sel_hi:[1,0]
	v_bfe_u32 v12, v11, 16, 1
	v_bfe_u32 v13, v10, 16, 1
	v_bfe_u32 v16, v7, 16, 1
	v_bfe_u32 v17, v6, 16, 1
	v_bfe_u32 v18, v5, 16, 1
	v_bfe_u32 v19, v4, 16, 1
	v_add3_u32 v4, v4, v19, s94
	v_add3_u32 v18, v5, v18, s94
	v_add3_u32 v5, v6, v17, s94
	v_add3_u32 v16, v7, v16, s94
	v_cvt_pk_bf16_f32 v8, v8, v9
	v_add3_u32 v7, v10, v13, s94
	v_add3_u32 v9, v11, v12, s94
	v_perm_b32 v7, v9, v7, s95
	v_mov_b32_e32 v6, v8
	v_perm_b32 v5, v16, v5, s95
	v_perm_b32 v4, v18, v4, s95
	ds_write_b128 v50, v[4:7] offset:1728
.LBB0_690:
	s_or_b64 exec, exec, s[40:41]
	s_waitcnt vmcnt(0)
	v_lshlrev_b32_e32 v4, 16, v0
	v_and_b32_e32 v5, 0xffff0000, v0
	v_add_f32_e32 v0, 0, v4
	v_add_f32_e32 v0, v0, v5
	v_lshlrev_b32_e32 v6, 16, v1
	v_and_b32_e32 v7, 0xffff0000, v1
	v_add_f32_e32 v0, v0, v6
	v_add_f32_e32 v0, v0, v7
	v_lshlrev_b32_e32 v8, 16, v2
	v_and_b32_e32 v9, 0xffff0000, v2
	v_add_f32_e32 v0, v0, v8
	v_add_f32_e32 v0, v0, v9
	v_lshlrev_b32_e32 v10, 16, v3
	v_and_b32_e32 v11, 0xffff0000, v3
	v_add_f32_e32 v0, v0, v10
	v_add_f32_e32 v0, v0, v11
	s_waitcnt lgkmcnt(0)
	v_mov_b32_e32 v1, v0
	s_nop 1
	v_permlane32_swap_b32_e32 v1, v0
	v_add_f32_e32 v0, v0, v1
	s_waitcnt lgkmcnt(0)
	v_mov_b32_e32 v1, v0
	s_nop 1
	v_permlane16_swap_b32_e32 v1, v0
	v_add_f32_e32 v0, v0, v1
	s_waitcnt lgkmcnt(0)
	s_nop 1
	v_add_f32_dpp v0, v0, v0 row_mirror row_mask:0xf bank_mask:0xf
	s_waitcnt lgkmcnt(0)
	s_nop 1
	v_add_f32_dpp v0, v0, v0 row_half_mirror row_mask:0xf bank_mask:0xf
	s_waitcnt lgkmcnt(0)
	s_nop 1
	v_add_f32_dpp v0, v0, v0 quad_perm:[2,3,0,1] row_mask:0xf bank_mask:0xf
	s_waitcnt lgkmcnt(0)
	s_nop 1
	v_add_f32_dpp v0, v0, v0 quad_perm:[1,0,3,2] row_mask:0xf bank_mask:0xf
	v_mul_f32_e32 v12, 0x3b000000, v0
	v_pk_add_f32 v[0:1], v[4:5], v[12:13] op_sel_hi:[1,0] neg_lo:[0,1] neg_hi:[0,1]
	v_pk_add_f32 v[2:3], v[6:7], v[12:13] op_sel_hi:[1,0] neg_lo:[0,1] neg_hi:[0,1]
	v_pk_add_f32 v[4:5], v[8:9], v[12:13] op_sel_hi:[1,0] neg_lo:[0,1] neg_hi:[0,1]
	v_pk_mul_f32 v[8:9], v[0:1], v[0:1]
	v_pk_add_f32 v[6:7], v[10:11], v[12:13] op_sel_hi:[1,0] neg_lo:[0,1] neg_hi:[0,1]
	v_pk_mul_f32 v[10:11], v[2:3], v[2:3]
	v_add_f32_e32 v8, v8, v9
	v_add_f32_e32 v8, v10, v8
	v_pk_mul_f32 v[12:13], v[4:5], v[4:5]
	v_add_f32_e32 v8, v11, v8
	v_add_f32_e32 v8, v12, v8
	v_pk_mul_f32 v[14:15], v[6:7], v[6:7]
	v_add_f32_e32 v8, v13, v8
	v_add_f32_e32 v8, v14, v8
	v_add_f32_e32 v8, v15, v8
	s_waitcnt lgkmcnt(0)
	v_mov_b32_e32 v9, v8
	s_nop 1
	v_permlane32_swap_b32_e32 v9, v8
	v_add_f32_e32 v8, v8, v9
	s_waitcnt lgkmcnt(0)
	v_mov_b32_e32 v9, v8
	s_nop 1
	v_permlane16_swap_b32_e32 v9, v8
	v_add_f32_e32 v8, v8, v9
	s_waitcnt lgkmcnt(0)
	s_nop 1
	v_add_f32_dpp v8, v8, v8 row_mirror row_mask:0xf bank_mask:0xf
	s_waitcnt lgkmcnt(0)
	s_nop 1
	v_add_f32_dpp v8, v8, v8 row_half_mirror row_mask:0xf bank_mask:0xf
	s_waitcnt lgkmcnt(0)
	s_nop 1
	v_add_f32_dpp v8, v8, v8 quad_perm:[2,3,0,1] row_mask:0xf bank_mask:0xf
	s_nop 1
	v_add_f32_dpp v8, v8, v8 quad_perm:[1,0,3,2] row_mask:0xf bank_mask:0xf
	s_and_saveexec_b64 s[40:41], s[36:37]
	s_cbranch_execz .LBB0_675
	s_waitcnt lgkmcnt(0)
	v_fmamk_f32 v8, v8, 0x3b000000, v190
	v_mul_f32_e32 v9, 0x4b800000, v8
	v_cmp_gt_f32_e32 vcc, s79, v8
	s_nop 1
	v_cndmask_b32_e32 v8, v8, v9, vcc
	v_rsq_f32_e32 v8, v8
	s_nop 0
	v_mul_f32_e32 v9, 0x45800000, v8
	v_cndmask_b32_e32 v8, v8, v9, vcc
	v_pk_mul_f32 v[0:1], v[0:1], v[8:9] op_sel_hi:[1,0]
	v_pk_mul_f32 v[2:3], v[2:3], v[8:9] op_sel_hi:[1,0]
	v_pk_mul_f32 v[4:5], v[4:5], v[8:9] op_sel_hi:[1,0]
	v_pk_mul_f32 v[6:7], v[6:7], v[8:9] op_sel_hi:[1,0]
	v_bfe_u32 v12, v3, 16, 1
	v_bfe_u32 v13, v2, 16, 1
	v_bfe_u32 v14, v1, 16, 1
	v_bfe_u32 v15, v0, 16, 1
	v_add3_u32 v0, v0, v15, s94
	v_add3_u32 v14, v1, v14, s94
	v_add3_u32 v1, v2, v13, s94
	v_add3_u32 v12, v3, v12, s94
	v_cvt_pk_bf16_f32 v4, v4, v5
	v_cvt_pk_bf16_f32 v3, v6, v7
	v_mov_b32_e32 v2, v4
	v_perm_b32 v1, v12, v1, s95
	v_perm_b32 v0, v14, v0, s95
	ds_write_b128 v50, v[0:3] offset:2016
	s_branch .LBB0_675

.LBB0_693:
	s_nop 0
	v_lshl_add_u64 v[0:1], v[26:27], 0, s[36:37]
	global_load_dword v28, v[0:1], off
	v_lshl_add_u64 v[0:1], v[24:25], 0, v[160:161]
	v_add_co_u32_e32 v4, vcc, 0x6400000, v0
	v_lshl_add_u64 v[24:25], v[24:25], 0, s[40:41]
	s_nop 0
	v_addc_co_u32_e32 v5, vcc, 0, v1, vcc
	global_load_dwordx4 v[0:3], v[4:5], off
	s_nop 0
	global_load_dwordx4 v[4:7], v[4:5], off offset:2048
	ds_read_b128 v[32:35], v31
	ds_read_b128 v[36:39], v31 offset:16
	s_waitcnt vmcnt(0)
	v_and_b32_e32 v29, 0xffff0000, v4
	v_lshlrev_b32_e32 v4, 16, v4
	v_mul_f32_e32 v30, 0xbfb8aa3b, v4
	v_exp_f32_e32 v40, v30
	v_mul_f32_e32 v30, 0xbfb8aa3b, v29
	v_exp_f32_e32 v41, v30
	s_nop 0
	v_pk_add_f32 v[40:41], v[40:41], 1.0 op_sel_hi:[1,0]
	s_nop 0
	v_div_scale_f32 v30, s[20:21], v41, v41, v29
	v_rcp_f32_e32 v42, v30
	s_nop 0
	v_fma_f32 v43, -v30, v42, 1.0
	v_fmac_f32_e32 v42, v43, v42
	v_div_scale_f32 v43, vcc, v29, v41, v29
	v_mul_f32_e32 v44, v43, v42
	v_fma_f32 v45, -v30, v44, v43
	v_fmac_f32_e32 v44, v45, v42
	v_fma_f32 v30, -v30, v44, v43
	v_div_fmas_f32 v30, v30, v42, v44
	v_div_fixup_f32 v41, v30, v41, v29
	v_div_scale_f32 v29, s[20:21], v40, v40, v4
	v_rcp_f32_e32 v30, v29
	s_nop 0
	v_fma_f32 v42, -v29, v30, 1.0
	v_fmac_f32_e32 v30, v42, v30
	v_div_scale_f32 v42, vcc, v4, v40, v4
	v_mul_f32_e32 v43, v42, v30
	v_fma_f32 v44, -v29, v43, v42
	v_fmac_f32_e32 v43, v44, v30
	v_fma_f32 v29, -v29, v43, v42
	v_div_fmas_f32 v29, v29, v30, v43
	v_div_fixup_f32 v40, v29, v40, v4
	v_and_b32_e32 v43, 0xffff0000, v0
	v_lshlrev_b32_e32 v42, 16, v0
	s_waitcnt lgkmcnt(1)
	v_pk_add_f32 v[32:33], v[28:29], v[32:33] op_sel_hi:[0,1]
	v_and_b32_e32 v0, 0xffff0000, v5
	v_lshlrev_b32_e32 v29, 16, v5
	v_mul_f32_e32 v4, 0xbfb8aa3b, v29
	v_mul_f32_e32 v5, 0xbfb8aa3b, v0
	v_exp_f32_e32 v4, v4
	v_exp_f32_e32 v5, v5
	v_pk_mul_f32 v[40:41], v[40:41], v[42:43]
	v_pk_add_f32 v[4:5], v[4:5], 1.0 op_sel_hi:[1,0]
	s_nop 0
	v_div_scale_f32 v30, s[20:21], v5, v5, v0
	v_pk_mul_f32 v[32:33], v[32:33], v[40:41]
	v_rcp_f32_e32 v40, v30
	s_nop 0
	v_fma_f32 v41, -v30, v40, 1.0
	v_fmac_f32_e32 v40, v41, v40
	v_div_scale_f32 v41, vcc, v0, v5, v0
	v_mul_f32_e32 v42, v41, v40
	v_fma_f32 v43, -v30, v42, v41
	v_fmac_f32_e32 v42, v43, v40
	v_fma_f32 v30, -v30, v42, v41
	v_div_fmas_f32 v30, v30, v40, v42
	v_div_fixup_f32 v5, v30, v5, v0
	v_div_scale_f32 v0, s[20:21], v4, v4, v29
	v_rcp_f32_e32 v30, v0
	s_nop 0
	v_fma_f32 v40, -v0, v30, 1.0
	v_fmac_f32_e32 v30, v40, v30
	v_div_scale_f32 v40, vcc, v29, v4, v29
	v_mul_f32_e32 v41, v40, v30
	v_fma_f32 v42, -v0, v41, v40
	v_fmac_f32_e32 v41, v42, v30
	v_fma_f32 v0, -v0, v41, v40
	v_div_fmas_f32 v0, v0, v30, v41
	v_div_fixup_f32 v4, v0, v4, v29
	v_and_b32_e32 v41, 0xffff0000, v1
	v_lshlrev_b32_e32 v40, 16, v1
	v_pk_mul_f32 v[0:1], v[4:5], v[40:41]
	v_pk_add_f32 v[4:5], v[28:29], v[34:35] op_sel_hi:[0,1]
	v_and_b32_e32 v29, 0xffff0000, v6
	v_lshlrev_b32_e32 v6, 16, v6
	v_pk_mul_f32 v[0:1], v[4:5], v[0:1]
	v_mul_f32_e32 v4, 0xbfb8aa3b, v6
	v_mul_f32_e32 v5, 0xbfb8aa3b, v29
	v_exp_f32_e32 v4, v4
	v_exp_f32_e32 v5, v5
	s_nop 0
	v_pk_add_f32 v[4:5], v[4:5], 1.0 op_sel_hi:[1,0]
	s_nop 0
	v_div_scale_f32 v30, s[20:21], v5, v5, v29
	v_rcp_f32_e32 v34, v30
	s_nop 0
	v_fma_f32 v35, -v30, v34, 1.0
	v_fmac_f32_e32 v34, v35, v34
	v_div_scale_f32 v35, vcc, v29, v5, v29
	v_mul_f32_e32 v40, v35, v34
	v_fma_f32 v41, -v30, v40, v35
	v_fmac_f32_e32 v40, v41, v34
	v_fma_f32 v30, -v30, v40, v35
	v_div_fmas_f32 v30, v30, v34, v40
	v_div_fixup_f32 v5, v30, v5, v29
	v_div_scale_f32 v29, s[20:21], v4, v4, v6
	v_rcp_f32_e32 v30, v29
	s_nop 0
	v_fma_f32 v34, -v29, v30, 1.0
	v_fmac_f32_e32 v30, v34, v30
	v_div_scale_f32 v34, vcc, v6, v4, v6
	v_mul_f32_e32 v35, v34, v30
	v_fma_f32 v40, -v29, v35, v34
	v_fmac_f32_e32 v35, v40, v30
	v_fma_f32 v29, -v29, v35, v34
	v_div_fmas_f32 v29, v29, v30, v35
	v_div_fixup_f32 v4, v29, v4, v6
	v_and_b32_e32 v35, 0xffff0000, v2
	v_lshlrev_b32_e32 v34, 16, v2
	v_pk_mul_f32 v[4:5], v[4:5], v[34:35]
	s_waitcnt lgkmcnt(0)
	v_pk_add_f32 v[34:35], v[28:29], v[36:37] op_sel_hi:[0,1]
	v_and_b32_e32 v2, 0xffff0000, v7
	v_lshlrev_b32_e32 v29, 16, v7
	v_mul_f32_e32 v6, 0xbfb8aa3b, v29
	v_mul_f32_e32 v7, 0xbfb8aa3b, v2
	v_exp_f32_e32 v6, v6
	v_exp_f32_e32 v7, v7
	v_pk_mul_f32 v[4:5], v[34:35], v[4:5]
	v_pk_add_f32 v[6:7], v[6:7], 1.0 op_sel_hi:[1,0]
	s_nop 0
	v_div_scale_f32 v30, s[20:21], v7, v7, v2
	v_rcp_f32_e32 v34, v30
	s_nop 0
	v_fma_f32 v35, -v30, v34, 1.0
	v_fmac_f32_e32 v34, v35, v34
	v_div_scale_f32 v35, vcc, v2, v7, v2
	v_mul_f32_e32 v36, v35, v34
	v_fma_f32 v37, -v30, v36, v35
	v_fmac_f32_e32 v36, v37, v34
	v_fma_f32 v30, -v30, v36, v35
	v_div_fmas_f32 v30, v30, v34, v36
	v_div_fixup_f32 v7, v30, v7, v2
	v_div_scale_f32 v2, s[20:21], v6, v6, v29
	v_rcp_f32_e32 v30, v2
	s_nop 0
	v_fma_f32 v34, -v2, v30, 1.0
	v_fmac_f32_e32 v30, v34, v30
	v_div_scale_f32 v34, vcc, v29, v6, v29
	v_mul_f32_e32 v35, v34, v30
	v_fma_f32 v36, -v2, v35, v34
	v_fmac_f32_e32 v35, v36, v30
	v_fma_f32 v2, -v2, v35, v34
	v_div_fmas_f32 v2, v2, v30, v35
	v_div_fixup_f32 v6, v2, v6, v29
	v_and_b32_e32 v35, 0xffff0000, v3
	v_lshlrev_b32_e32 v34, 16, v3
	v_pk_mul_f32 v[2:3], v[6:7], v[34:35]
	v_pk_add_f32 v[6:7], v[28:29], v[38:39] op_sel_hi:[0,1]
	v_pk_mul_f32 v[2:3], v[6:7], v[2:3]
	v_cvt_pk_bf16_f32 v32, v32, v33
	v_cvt_pk_bf16_f32 v0, v0, v1
	v_cvt_pk_bf16_f32 v4, v4, v5
	v_cvt_pk_bf16_f32 v2, v2, v3
	v_mov_b32_e32 v3, v2
	v_mov_b32_e32 v2, v4
	v_mov_b32_e32 v1, v0
	v_mov_b32_e32 v0, v32
	v_lshl_add_u64 v[4:5], v[22:23], 0, v[160:161]
	global_store_dwordx4 v[4:5], v[0:3], off
	v_lshl_add_u64 v[28:29], v[20:21], 0, s[36:37]
	global_load_dword v30, v[28:29], off offset:16
	v_lshl_add_u64 v[0:1], v[18:19], 0, v[160:161]
	v_add_co_u32_e32 v4, vcc, s22, v0
	s_add_u32 s36, s36, 64
	s_nop 0
	v_addc_co_u32_e32 v5, vcc, 0, v1, vcc
	global_load_dwordx4 v[0:3], v[4:5], off
	s_nop 0
	global_load_dwordx4 v[4:7], v[4:5], off offset:2048
	ds_read_b128 v[32:35], v31 offset:2112
	s_addc_u32 s37, s37, 0
	v_lshl_add_u64 v[18:19], v[18:19], 0, s[40:41]
	v_lshl_add_u64 v[22:23], v[22:23], 0, s[38:39]
	s_cmpk_lg_i32 s36, 0x80
	s_waitcnt vmcnt(2) lgkmcnt(0)
	v_pk_add_f32 v[32:33], v[30:31], v[32:33] op_sel_hi:[0,1]
	s_waitcnt vmcnt(0)
	v_and_b32_e32 v38, 0xffff0000, v4
	v_lshlrev_b32_e32 v4, 16, v4
	v_mul_f32_e32 v36, 0xbfb8aa3b, v4
	v_mul_f32_e32 v37, 0xbfb8aa3b, v38
	v_exp_f32_e32 v36, v36
	v_exp_f32_e32 v37, v37
	s_nop 0
	v_pk_add_f32 v[36:37], v[36:37], 1.0 op_sel_hi:[1,0]
	s_nop 0
	v_div_scale_f32 v39, s[20:21], v37, v37, v38
	v_rcp_f32_e32 v40, v39
	s_nop 0
	v_fma_f32 v41, -v39, v40, 1.0
	v_fmac_f32_e32 v40, v41, v40
	v_div_scale_f32 v41, vcc, v38, v37, v38
	v_mul_f32_e32 v42, v41, v40
	v_fma_f32 v43, -v39, v42, v41
	v_fmac_f32_e32 v42, v43, v40
	v_fma_f32 v39, -v39, v42, v41
	v_div_fmas_f32 v39, v39, v40, v42
	v_div_fixup_f32 v37, v39, v37, v38
	v_div_scale_f32 v38, s[20:21], v36, v36, v4
	v_rcp_f32_e32 v39, v38
	s_nop 0
	v_fma_f32 v40, -v38, v39, 1.0
	v_fmac_f32_e32 v39, v40, v39
	v_div_scale_f32 v40, vcc, v4, v36, v4
	v_mul_f32_e32 v41, v40, v39
	v_fma_f32 v42, -v38, v41, v40
	v_fmac_f32_e32 v41, v42, v39
	v_fma_f32 v38, -v38, v41, v40
	v_div_fmas_f32 v38, v38, v39, v41
	v_div_fixup_f32 v36, v38, v36, v4
	v_and_b32_e32 v39, 0xffff0000, v0
	v_lshlrev_b32_e32 v38, 16, v0
	v_pk_mul_f32 v[36:37], v[36:37], v[38:39]
	v_and_b32_e32 v0, 0xffff0000, v5
	v_pk_mul_f32 v[32:33], v[32:33], v[36:37]
	v_lshlrev_b32_e32 v36, 16, v5
	v_mul_f32_e32 v4, 0xbfb8aa3b, v36
	v_mul_f32_e32 v5, 0xbfb8aa3b, v0
	v_exp_f32_e32 v4, v4
	v_exp_f32_e32 v5, v5
	s_nop 0
	v_pk_add_f32 v[4:5], v[4:5], 1.0 op_sel_hi:[1,0]
	s_nop 0
	v_div_scale_f32 v37, s[20:21], v5, v5, v0
	v_rcp_f32_e32 v38, v37
	s_nop 0
	v_fma_f32 v39, -v37, v38, 1.0
	v_fmac_f32_e32 v38, v39, v38
	v_div_scale_f32 v39, vcc, v0, v5, v0
	v_mul_f32_e32 v40, v39, v38
	v_fma_f32 v41, -v37, v40, v39
	v_fmac_f32_e32 v40, v41, v38
	v_fma_f32 v37, -v37, v40, v39
	v_div_fmas_f32 v37, v37, v38, v40
	v_div_fixup_f32 v5, v37, v5, v0
	v_div_scale_f32 v0, s[20:21], v4, v4, v36
	v_rcp_f32_e32 v37, v0
	s_nop 0
	v_fma_f32 v38, -v0, v37, 1.0
	v_fmac_f32_e32 v37, v38, v37
	v_div_scale_f32 v38, vcc, v36, v4, v36
	v_mul_f32_e32 v39, v38, v37
	v_fma_f32 v40, -v0, v39, v38
	v_fmac_f32_e32 v39, v40, v37
	v_fma_f32 v0, -v0, v39, v38
	v_div_fmas_f32 v0, v0, v37, v39
	v_div_fixup_f32 v4, v0, v4, v36
	v_and_b32_e32 v37, 0xffff0000, v1
	v_lshlrev_b32_e32 v36, 16, v1
	v_pk_mul_f32 v[0:1], v[4:5], v[36:37]
	v_pk_add_f32 v[4:5], v[30:31], v[34:35] op_sel_hi:[0,1]
	v_and_b32_e32 v38, 0xffff0000, v6
	v_lshlrev_b32_e32 v6, 16, v6
	v_pk_mul_f32 v[0:1], v[4:5], v[0:1]
	v_mul_f32_e32 v4, 0xbfb8aa3b, v6
	v_mul_f32_e32 v5, 0xbfb8aa3b, v38
	v_exp_f32_e32 v4, v4
	v_exp_f32_e32 v5, v5
	ds_read_b128 v[34:37], v31 offset:2128
	v_pk_add_f32 v[4:5], v[4:5], 1.0 op_sel_hi:[1,0]
	s_nop 0
	v_div_scale_f32 v39, s[20:21], v5, v5, v38
	v_rcp_f32_e32 v40, v39
	s_waitcnt lgkmcnt(0)
	v_pk_add_f32 v[34:35], v[30:31], v[34:35] op_sel_hi:[0,1]
	v_fma_f32 v41, -v39, v40, 1.0
	v_fmac_f32_e32 v40, v41, v40
	v_div_scale_f32 v41, vcc, v38, v5, v38
	v_mul_f32_e32 v42, v41, v40
	v_fma_f32 v43, -v39, v42, v41
	v_fmac_f32_e32 v42, v43, v40
	v_fma_f32 v39, -v39, v42, v41
	v_div_fmas_f32 v39, v39, v40, v42
	v_div_fixup_f32 v5, v39, v5, v38
	v_div_scale_f32 v38, s[20:21], v4, v4, v6
	v_rcp_f32_e32 v39, v38
	s_nop 0
	v_fma_f32 v40, -v38, v39, 1.0
	v_fmac_f32_e32 v39, v40, v39
	v_div_scale_f32 v40, vcc, v6, v4, v6
	v_mul_f32_e32 v41, v40, v39
	v_fma_f32 v42, -v38, v41, v40
	v_fmac_f32_e32 v41, v42, v39
	v_fma_f32 v38, -v38, v41, v40
	v_div_fmas_f32 v38, v38, v39, v41
	v_div_fixup_f32 v4, v38, v4, v6
	v_and_b32_e32 v39, 0xffff0000, v2
	v_lshlrev_b32_e32 v38, 16, v2
	v_pk_mul_f32 v[4:5], v[4:5], v[38:39]
	v_and_b32_e32 v2, 0xffff0000, v7
	v_pk_mul_f32 v[4:5], v[34:35], v[4:5]
	v_lshlrev_b32_e32 v34, 16, v7
	v_mul_f32_e32 v6, 0xbfb8aa3b, v34
	v_mul_f32_e32 v7, 0xbfb8aa3b, v2
	v_exp_f32_e32 v6, v6
	v_exp_f32_e32 v7, v7
	s_nop 0
	v_pk_add_f32 v[6:7], v[6:7], 1.0 op_sel_hi:[1,0]
	s_nop 0
	v_div_scale_f32 v35, s[20:21], v7, v7, v2
	v_rcp_f32_e32 v38, v35
	s_nop 0
	v_fma_f32 v39, -v35, v38, 1.0
	v_fmac_f32_e32 v38, v39, v38
	v_div_scale_f32 v39, vcc, v2, v7, v2
	v_mul_f32_e32 v40, v39, v38
	v_fma_f32 v41, -v35, v40, v39
	v_fmac_f32_e32 v40, v41, v38
	v_fma_f32 v35, -v35, v40, v39
	v_div_fmas_f32 v35, v35, v38, v40
	v_div_fixup_f32 v7, v35, v7, v2
	v_div_scale_f32 v2, s[20:21], v6, v6, v34
	v_rcp_f32_e32 v35, v2
	s_nop 0
	v_fma_f32 v38, -v2, v35, 1.0
	v_fmac_f32_e32 v35, v38, v35
	v_div_scale_f32 v38, vcc, v34, v6, v34
	v_mul_f32_e32 v39, v38, v35
	v_fma_f32 v40, -v2, v39, v38
	v_fmac_f32_e32 v39, v40, v35
	v_fma_f32 v2, -v2, v39, v38
	v_div_fmas_f32 v2, v2, v35, v39
	v_div_fixup_f32 v6, v2, v6, v34
	v_and_b32_e32 v35, 0xffff0000, v3
	v_lshlrev_b32_e32 v34, 16, v3
	v_pk_mul_f32 v[2:3], v[6:7], v[34:35]
	v_pk_add_f32 v[6:7], v[30:31], v[36:37] op_sel_hi:[0,1]
	v_pk_mul_f32 v[2:3], v[6:7], v[2:3]
	v_cvt_pk_bf16_f32 v32, v32, v33
	v_cvt_pk_bf16_f32 v0, v0, v1
	v_cvt_pk_bf16_f32 v4, v4, v5
	v_cvt_pk_bf16_f32 v2, v2, v3
	v_mov_b32_e32 v3, v2
	v_mov_b32_e32 v2, v4
	v_mov_b32_e32 v1, v0
	v_mov_b32_e32 v0, v32
	v_lshl_add_u64 v[4:5], v[16:17], 0, v[160:161]
	global_store_dwordx4 v[4:5], v[0:3], off
	global_load_dword v30, v[28:29], off offset:32
	v_lshl_add_u64 v[16:17], v[16:17], 0, s[38:39]
	v_lshl_add_u64 v[0:1], v[14:15], 0, v[160:161]
	v_add_co_u32_e32 v4, vcc, s22, v0
	v_lshl_add_u64 v[14:15], v[14:15], 0, s[40:41]
	s_nop 0
	v_addc_co_u32_e32 v5, vcc, 0, v1, vcc
	global_load_dwordx4 v[0:3], v[4:5], off
	s_nop 0
	global_load_dwordx4 v[4:7], v[4:5], off offset:2048
	ds_read_b128 v[32:35], v31 offset:4224
	s_waitcnt vmcnt(2) lgkmcnt(0)
	v_pk_add_f32 v[32:33], v[30:31], v[32:33] op_sel_hi:[0,1]
	s_waitcnt vmcnt(0)
	v_and_b32_e32 v38, 0xffff0000, v4
	v_lshlrev_b32_e32 v4, 16, v4
	v_mul_f32_e32 v36, 0xbfb8aa3b, v4
	v_mul_f32_e32 v37, 0xbfb8aa3b, v38
	v_exp_f32_e32 v36, v36
	v_exp_f32_e32 v37, v37
	s_nop 0
	v_pk_add_f32 v[36:37], v[36:37], 1.0 op_sel_hi:[1,0]
	s_nop 0
	v_div_scale_f32 v39, s[20:21], v37, v37, v38
	v_rcp_f32_e32 v40, v39
	s_nop 0
	v_fma_f32 v41, -v39, v40, 1.0
	v_fmac_f32_e32 v40, v41, v40
	v_div_scale_f32 v41, vcc, v38, v37, v38
	v_mul_f32_e32 v42, v41, v40
	v_fma_f32 v43, -v39, v42, v41
	v_fmac_f32_e32 v42, v43, v40
	v_fma_f32 v39, -v39, v42, v41
	v_div_fmas_f32 v39, v39, v40, v42
	v_div_fixup_f32 v37, v39, v37, v38
	v_div_scale_f32 v38, s[20:21], v36, v36, v4
	v_rcp_f32_e32 v39, v38
	s_nop 0
	v_fma_f32 v40, -v38, v39, 1.0
	v_fmac_f32_e32 v39, v40, v39
	v_div_scale_f32 v40, vcc, v4, v36, v4
	v_mul_f32_e32 v41, v40, v39
	v_fma_f32 v42, -v38, v41, v40
	v_fmac_f32_e32 v41, v42, v39
	v_fma_f32 v38, -v38, v41, v40
	v_div_fmas_f32 v38, v38, v39, v41
	v_div_fixup_f32 v36, v38, v36, v4
	v_and_b32_e32 v39, 0xffff0000, v0
	v_lshlrev_b32_e32 v38, 16, v0
	v_pk_mul_f32 v[36:37], v[36:37], v[38:39]
	v_and_b32_e32 v0, 0xffff0000, v5
	v_pk_mul_f32 v[32:33], v[32:33], v[36:37]
	v_lshlrev_b32_e32 v36, 16, v5
	v_mul_f32_e32 v4, 0xbfb8aa3b, v36
	v_mul_f32_e32 v5, 0xbfb8aa3b, v0
	v_exp_f32_e32 v4, v4
	v_exp_f32_e32 v5, v5
	s_nop 0
	v_pk_add_f32 v[4:5], v[4:5], 1.0 op_sel_hi:[1,0]
	s_nop 0
	v_div_scale_f32 v37, s[20:21], v5, v5, v0
	v_rcp_f32_e32 v38, v37
	s_nop 0
	v_fma_f32 v39, -v37, v38, 1.0
	v_fmac_f32_e32 v38, v39, v38
	v_div_scale_f32 v39, vcc, v0, v5, v0
	v_mul_f32_e32 v40, v39, v38
	v_fma_f32 v41, -v37, v40, v39
	v_fmac_f32_e32 v40, v41, v38
	v_fma_f32 v37, -v37, v40, v39
	v_div_fmas_f32 v37, v37, v38, v40
	v_div_fixup_f32 v5, v37, v5, v0
	v_div_scale_f32 v0, s[20:21], v4, v4, v36
	v_rcp_f32_e32 v37, v0
	s_nop 0
	v_fma_f32 v38, -v0, v37, 1.0
	v_fmac_f32_e32 v37, v38, v37
	v_div_scale_f32 v38, vcc, v36, v4, v36
	v_mul_f32_e32 v39, v38, v37
	v_fma_f32 v40, -v0, v39, v38
	v_fmac_f32_e32 v39, v40, v37
	v_fma_f32 v0, -v0, v39, v38
	v_div_fmas_f32 v0, v0, v37, v39
	v_div_fixup_f32 v4, v0, v4, v36
	v_and_b32_e32 v37, 0xffff0000, v1
	v_lshlrev_b32_e32 v36, 16, v1
	v_pk_mul_f32 v[0:1], v[4:5], v[36:37]
	v_pk_add_f32 v[4:5], v[30:31], v[34:35] op_sel_hi:[0,1]
	v_and_b32_e32 v38, 0xffff0000, v6
	v_lshlrev_b32_e32 v6, 16, v6
	v_pk_mul_f32 v[0:1], v[4:5], v[0:1]
	v_mul_f32_e32 v4, 0xbfb8aa3b, v6
	v_mul_f32_e32 v5, 0xbfb8aa3b, v38
	v_exp_f32_e32 v4, v4
	v_exp_f32_e32 v5, v5
	ds_read_b128 v[34:37], v31 offset:4240
	v_pk_add_f32 v[4:5], v[4:5], 1.0 op_sel_hi:[1,0]
	s_nop 0
	v_div_scale_f32 v39, s[20:21], v5, v5, v38
	v_rcp_f32_e32 v40, v39
	s_waitcnt lgkmcnt(0)
	v_pk_add_f32 v[34:35], v[30:31], v[34:35] op_sel_hi:[0,1]
	v_fma_f32 v41, -v39, v40, 1.0
	v_fmac_f32_e32 v40, v41, v40
	v_div_scale_f32 v41, vcc, v38, v5, v38
	v_mul_f32_e32 v42, v41, v40
	v_fma_f32 v43, -v39, v42, v41
	v_fmac_f32_e32 v42, v43, v40
	v_fma_f32 v39, -v39, v42, v41
	v_div_fmas_f32 v39, v39, v40, v42
	v_div_fixup_f32 v5, v39, v5, v38
	v_div_scale_f32 v38, s[20:21], v4, v4, v6
	v_rcp_f32_e32 v39, v38
	s_nop 0
	v_fma_f32 v40, -v38, v39, 1.0
	v_fmac_f32_e32 v39, v40, v39
	v_div_scale_f32 v40, vcc, v6, v4, v6
	v_mul_f32_e32 v41, v40, v39
	v_fma_f32 v42, -v38, v41, v40
	v_fmac_f32_e32 v41, v42, v39
	v_fma_f32 v38, -v38, v41, v40
	v_div_fmas_f32 v38, v38, v39, v41
	v_div_fixup_f32 v4, v38, v4, v6
	v_and_b32_e32 v39, 0xffff0000, v2
	v_lshlrev_b32_e32 v38, 16, v2
	v_pk_mul_f32 v[4:5], v[4:5], v[38:39]
	v_and_b32_e32 v2, 0xffff0000, v7
	v_pk_mul_f32 v[4:5], v[34:35], v[4:5]
	v_lshlrev_b32_e32 v34, 16, v7
	v_mul_f32_e32 v6, 0xbfb8aa3b, v34
	v_mul_f32_e32 v7, 0xbfb8aa3b, v2
	v_exp_f32_e32 v6, v6
	v_exp_f32_e32 v7, v7
	s_nop 0
	v_pk_add_f32 v[6:7], v[6:7], 1.0 op_sel_hi:[1,0]
	s_nop 0
	v_div_scale_f32 v35, s[20:21], v7, v7, v2
	v_rcp_f32_e32 v38, v35
	s_nop 0
	v_fma_f32 v39, -v35, v38, 1.0
	v_fmac_f32_e32 v38, v39, v38
	v_div_scale_f32 v39, vcc, v2, v7, v2
	v_mul_f32_e32 v40, v39, v38
	v_fma_f32 v41, -v35, v40, v39
	v_fmac_f32_e32 v40, v41, v38
	v_fma_f32 v35, -v35, v40, v39
	v_div_fmas_f32 v35, v35, v38, v40
	v_div_fixup_f32 v7, v35, v7, v2
	v_div_scale_f32 v2, s[20:21], v6, v6, v34
	v_rcp_f32_e32 v35, v2
	s_nop 0
	v_fma_f32 v38, -v2, v35, 1.0
	v_fmac_f32_e32 v35, v38, v35
	v_div_scale_f32 v38, vcc, v34, v6, v34
	v_mul_f32_e32 v39, v38, v35
	v_fma_f32 v40, -v2, v39, v38
	v_fmac_f32_e32 v39, v40, v35
	v_fma_f32 v2, -v2, v39, v38
	v_div_fmas_f32 v2, v2, v35, v39
	v_div_fixup_f32 v6, v2, v6, v34
	v_and_b32_e32 v35, 0xffff0000, v3
	v_lshlrev_b32_e32 v34, 16, v3
	v_pk_mul_f32 v[2:3], v[6:7], v[34:35]
	v_pk_add_f32 v[6:7], v[30:31], v[36:37] op_sel_hi:[0,1]
	v_pk_mul_f32 v[2:3], v[6:7], v[2:3]
	v_cvt_pk_bf16_f32 v32, v32, v33
	v_cvt_pk_bf16_f32 v0, v0, v1
	v_cvt_pk_bf16_f32 v4, v4, v5
	v_cvt_pk_bf16_f32 v2, v2, v3
	v_mov_b32_e32 v3, v2
	v_mov_b32_e32 v2, v4
	v_mov_b32_e32 v1, v0
	v_mov_b32_e32 v0, v32
	v_lshl_add_u64 v[4:5], v[12:13], 0, v[160:161]
	global_store_dwordx4 v[4:5], v[0:3], off
	global_load_dword v28, v[28:29], off offset:48
	v_lshl_add_u64 v[12:13], v[12:13], 0, s[38:39]
	v_lshl_add_u64 v[0:1], v[10:11], 0, v[160:161]
	v_add_co_u32_e32 v4, vcc, s22, v0
	v_lshl_add_u64 v[10:11], v[10:11], 0, s[40:41]
	s_nop 0
	v_addc_co_u32_e32 v5, vcc, 0, v1, vcc
	global_load_dwordx4 v[0:3], v[4:5], off
	s_nop 0
	global_load_dwordx4 v[4:7], v[4:5], off offset:2048
	ds_read_b128 v[32:35], v31 offset:6336
	ds_read_b128 v[36:39], v31 offset:6352
	v_add_u32_e32 v31, 0x2100, v31
	s_waitcnt vmcnt(0)
	v_and_b32_e32 v29, 0xffff0000, v4
	v_lshlrev_b32_e32 v4, 16, v4
	v_mul_f32_e32 v30, 0xbfb8aa3b, v4
	v_exp_f32_e32 v40, v30
	v_mul_f32_e32 v30, 0xbfb8aa3b, v29
	v_exp_f32_e32 v41, v30
	s_nop 0
	v_pk_add_f32 v[40:41], v[40:41], 1.0 op_sel_hi:[1,0]
	s_nop 0
	v_div_scale_f32 v30, s[20:21], v41, v41, v29
	v_rcp_f32_e32 v42, v30
	s_nop 0
	v_fma_f32 v43, -v30, v42, 1.0
	v_fmac_f32_e32 v42, v43, v42
	v_div_scale_f32 v43, vcc, v29, v41, v29
	v_mul_f32_e32 v44, v43, v42
	v_fma_f32 v45, -v30, v44, v43
	v_fmac_f32_e32 v44, v45, v42
	v_fma_f32 v30, -v30, v44, v43
	v_div_fmas_f32 v30, v30, v42, v44
	v_div_fixup_f32 v41, v30, v41, v29
	v_div_scale_f32 v29, s[20:21], v40, v40, v4
	v_rcp_f32_e32 v30, v29
	s_nop 0
	v_fma_f32 v42, -v29, v30, 1.0
	v_fmac_f32_e32 v30, v42, v30
	v_div_scale_f32 v42, vcc, v4, v40, v4
	v_mul_f32_e32 v43, v42, v30
	v_fma_f32 v44, -v29, v43, v42
	v_fmac_f32_e32 v43, v44, v30
	v_fma_f32 v29, -v29, v43, v42
	v_div_fmas_f32 v29, v29, v30, v43
	v_div_fixup_f32 v40, v29, v40, v4
	v_and_b32_e32 v43, 0xffff0000, v0
	v_lshlrev_b32_e32 v42, 16, v0
	s_waitcnt lgkmcnt(1)
	v_pk_add_f32 v[32:33], v[28:29], v[32:33] op_sel_hi:[0,1]
	v_and_b32_e32 v0, 0xffff0000, v5
	v_lshlrev_b32_e32 v29, 16, v5
	v_mul_f32_e32 v4, 0xbfb8aa3b, v29
	v_mul_f32_e32 v5, 0xbfb8aa3b, v0
	v_exp_f32_e32 v4, v4
	v_exp_f32_e32 v5, v5
	v_pk_mul_f32 v[40:41], v[40:41], v[42:43]
	v_pk_add_f32 v[4:5], v[4:5], 1.0 op_sel_hi:[1,0]
	s_nop 0
	v_div_scale_f32 v30, s[20:21], v5, v5, v0
	v_pk_mul_f32 v[32:33], v[32:33], v[40:41]
	v_rcp_f32_e32 v40, v30
	s_nop 0
	v_fma_f32 v41, -v30, v40, 1.0
	v_fmac_f32_e32 v40, v41, v40
	v_div_scale_f32 v41, vcc, v0, v5, v0
	v_mul_f32_e32 v42, v41, v40
	v_fma_f32 v43, -v30, v42, v41
	v_fmac_f32_e32 v42, v43, v40
	v_fma_f32 v30, -v30, v42, v41
	v_div_fmas_f32 v30, v30, v40, v42
	v_div_fixup_f32 v5, v30, v5, v0
	v_div_scale_f32 v0, s[20:21], v4, v4, v29
	v_rcp_f32_e32 v30, v0
	s_nop 0
	v_fma_f32 v40, -v0, v30, 1.0
	v_fmac_f32_e32 v30, v40, v30
	v_div_scale_f32 v40, vcc, v29, v4, v29
	v_mul_f32_e32 v41, v40, v30
	v_fma_f32 v42, -v0, v41, v40
	v_fmac_f32_e32 v41, v42, v30
	v_fma_f32 v0, -v0, v41, v40
	v_div_fmas_f32 v0, v0, v30, v41
	v_div_fixup_f32 v4, v0, v4, v29
	v_and_b32_e32 v41, 0xffff0000, v1
	v_lshlrev_b32_e32 v40, 16, v1
	v_pk_mul_f32 v[0:1], v[4:5], v[40:41]
	v_pk_add_f32 v[4:5], v[28:29], v[34:35] op_sel_hi:[0,1]
	v_and_b32_e32 v29, 0xffff0000, v6
	v_lshlrev_b32_e32 v6, 16, v6
	v_pk_mul_f32 v[0:1], v[4:5], v[0:1]
	v_mul_f32_e32 v4, 0xbfb8aa3b, v6
	v_mul_f32_e32 v5, 0xbfb8aa3b, v29
	v_exp_f32_e32 v4, v4
	v_exp_f32_e32 v5, v5
	s_nop 0
	v_pk_add_f32 v[4:5], v[4:5], 1.0 op_sel_hi:[1,0]
	s_nop 0
	v_div_scale_f32 v30, s[20:21], v5, v5, v29
	v_rcp_f32_e32 v34, v30
	s_nop 0
	v_fma_f32 v35, -v30, v34, 1.0
	v_fmac_f32_e32 v34, v35, v34
	v_div_scale_f32 v35, vcc, v29, v5, v29
	v_mul_f32_e32 v40, v35, v34
	v_fma_f32 v41, -v30, v40, v35
	v_fmac_f32_e32 v40, v41, v34
	v_fma_f32 v30, -v30, v40, v35
	v_div_fmas_f32 v30, v30, v34, v40
	v_div_fixup_f32 v5, v30, v5, v29
	v_div_scale_f32 v29, s[20:21], v4, v4, v6
	v_rcp_f32_e32 v30, v29
	s_nop 0
	v_fma_f32 v34, -v29, v30, 1.0
	v_fmac_f32_e32 v30, v34, v30
	v_div_scale_f32 v34, vcc, v6, v4, v6
	v_mul_f32_e32 v35, v34, v30
	v_fma_f32 v40, -v29, v35, v34
	v_fmac_f32_e32 v35, v40, v30
	v_fma_f32 v29, -v29, v35, v34
	v_div_fmas_f32 v29, v29, v30, v35
	v_div_fixup_f32 v4, v29, v4, v6
	v_and_b32_e32 v35, 0xffff0000, v2
	v_lshlrev_b32_e32 v34, 16, v2
	v_pk_mul_f32 v[4:5], v[4:5], v[34:35]
	s_waitcnt lgkmcnt(0)
	v_pk_add_f32 v[34:35], v[28:29], v[36:37] op_sel_hi:[0,1]
	v_and_b32_e32 v2, 0xffff0000, v7
	v_lshlrev_b32_e32 v29, 16, v7
	v_mul_f32_e32 v6, 0xbfb8aa3b, v29
	v_mul_f32_e32 v7, 0xbfb8aa3b, v2
	v_exp_f32_e32 v6, v6
	v_exp_f32_e32 v7, v7
	v_pk_mul_f32 v[4:5], v[34:35], v[4:5]
	v_pk_add_f32 v[6:7], v[6:7], 1.0 op_sel_hi:[1,0]
	s_nop 0
	v_div_scale_f32 v30, s[20:21], v7, v7, v2
	v_rcp_f32_e32 v34, v30
	s_nop 0
	v_fma_f32 v35, -v30, v34, 1.0
	v_fmac_f32_e32 v34, v35, v34
	v_div_scale_f32 v35, vcc, v2, v7, v2
	v_mul_f32_e32 v36, v35, v34
	v_fma_f32 v37, -v30, v36, v35
	v_fmac_f32_e32 v36, v37, v34
	v_fma_f32 v30, -v30, v36, v35
	v_div_fmas_f32 v30, v30, v34, v36
	v_div_fixup_f32 v7, v30, v7, v2
	v_div_scale_f32 v2, s[20:21], v6, v6, v29
	v_rcp_f32_e32 v30, v2
	s_nop 0
	v_fma_f32 v34, -v2, v30, 1.0
	v_fmac_f32_e32 v30, v34, v30
	v_div_scale_f32 v34, vcc, v29, v6, v29
	v_mul_f32_e32 v35, v34, v30
	v_fma_f32 v36, -v2, v35, v34
	v_fmac_f32_e32 v35, v36, v30
	v_fma_f32 v2, -v2, v35, v34
	v_div_fmas_f32 v2, v2, v30, v35
	v_div_fixup_f32 v6, v2, v6, v29
	v_and_b32_e32 v35, 0xffff0000, v3
	v_lshlrev_b32_e32 v34, 16, v3
	v_pk_mul_f32 v[2:3], v[6:7], v[34:35]
	v_pk_add_f32 v[6:7], v[28:29], v[38:39] op_sel_hi:[0,1]
	v_pk_mul_f32 v[2:3], v[6:7], v[2:3]
	v_cvt_pk_bf16_f32 v32, v32, v33
	v_cvt_pk_bf16_f32 v0, v0, v1
	v_cvt_pk_bf16_f32 v4, v4, v5
	v_cvt_pk_bf16_f32 v2, v2, v3
	v_mov_b32_e32 v3, v2
	v_mov_b32_e32 v2, v4
	v_mov_b32_e32 v1, v0
	v_mov_b32_e32 v0, v32
	v_lshl_add_u64 v[4:5], v[8:9], 0, v[160:161]
	v_lshl_add_u64 v[8:9], v[8:9], 0, s[38:39]
	global_store_dwordx4 v[4:5], v[0:3], off
	s_cbranch_scc1 .LBB0_693
	s_barrier

.LBB0_696:
	s_andn2_b64 vcc, exec, s[36:37]
	s_cbranch_vccnz .LBB0_703
	v_mov_b32_e32 v50, v189
	s_lshl_b32 s20, s19, 4
	v_readlane_b32 s38, v251, 47
	v_and_b32_e32 v0, 63, v50
	s_and_b32 s23, s20, 0x7f00
	s_lshl_b32 s36, s19, 6
	v_lshlrev_b32_e32 v0, 2, v0
	v_readlane_b32 s39, v251, 48
	s_add_i32 s37, s23, 0xffffc000
	s_and_b32 s20, s36, 0xc0
	s_nop 2
	global_load_dword v18, v0, s[38:39]
	global_load_dword v19, v0, s[38:39] offset:256
	global_load_dword v20, v0, s[38:39] offset:512
	global_load_dword v21, v0, s[38:39] offset:768
	v_ashrrev_i32_e32 v0, 2, v50
	s_or_b32 s20, s37, s20
	v_and_b32_e32 v184, -16, v0
	s_lshl_b32 s21, s19, 5
	v_and_b32_e32 v183, 15, v50
	v_add_u32_e32 v0, s20, v184
	s_and_b32 s21, s21, 0x180
	v_or_b32_e32 v0, v0, v183
	v_mov_b64_e32 v[16:17], s[6:7]
	v_mad_i64_i32 v[0:1], s[38:39], v0, s0, v[16:17]
	s_lshl_b32 s70, s21, 1
	v_lshl_add_u64 v[0:1], v[0:1], 0, s[70:71]
	v_and_b32_e32 v160, 48, v50
	v_lshl_add_u64 v[4:5], v[0:1], 0, v[160:161]
	s_movk_i32 s42, 0x1000
	v_add_co_u32_e32 v0, vcc, s42, v4
	v_mbcnt_hi_u32_b32 v151, -1, v194
	s_nop 0
	v_addc_co_u32_e32 v1, vcc, 0, v5, vcc
	global_load_dwordx4 v[0:3], v[0:1], off offset:1024
	v_and_b32_e32 v8, 64, v151
	s_mov_b64 s[38:39], 0x1400
	v_xor_b32_e32 v9, 32, v151
	v_add_u32_e32 v187, 64, v8
	v_lshl_add_u64 v[12:13], v[4:5], 0, s[38:39]
	v_xor_b32_e32 v10, 16, v151
	v_cmp_lt_i32_e32 vcc, v9, v187
	global_load_dwordx4 v[4:7], v[12:13], off offset:64
	v_xor_b32_e32 v11, 8, v151
	v_cndmask_b32_e32 v8, v151, v9, vcc
	v_cmp_lt_i32_e32 vcc, v10, v187
	v_lshlrev_b32_e32 v181, 2, v8
	s_mov_b32 s44, 0x3e000000
	v_cndmask_b32_e32 v9, v151, v10, vcc
	v_cmp_lt_i32_e32 vcc, v11, v187
	v_lshlrev_b32_e32 v182, 2, v9
	v_xor_b32_e32 v14, 4, v151
	v_cndmask_b32_e32 v10, v151, v11, vcc
	v_lshlrev_b32_e32 v24, 2, v10
	global_load_dwordx4 v[8:11], v[12:13], off offset:128
	v_cmp_lt_i32_e32 vcc, v14, v187
	v_xor_b32_e32 v15, 2, v151
	v_ashrrev_i32_e32 v185, 4, v50
	v_cndmask_b32_e32 v14, v151, v14, vcc
	v_lshlrev_b32_e32 v27, 2, v14
	v_cmp_lt_i32_e32 vcc, v15, v187
	v_lshlrev_b32_e32 v48, 4, v183
	v_mov_b32_e32 v49, v161
	v_cndmask_b32_e32 v15, v151, v15, vcc
	v_lshlrev_b32_e32 v28, 2, v15
	global_load_dwordx4 v[12:15], v[12:13], off offset:192
	s_barrier
	s_movk_i32 s39, 0x120
	v_mul_lo_u32 v211, v185, s39
	s_add_i32 s38, s23, 0xffffc040
	v_lshlrev_b32_e32 v186, 3, v50
	v_and_b32_e32 v84, 24, v186
	s_mov_b32 s22, 0
	v_mov_b32_e32 v142, 0xf149f2ca
	v_mov_b32_e32 v112, 0xf149f2ca
	s_waitcnt vmcnt(0)
	v_mul_f32_e32 v22, v18, v19
	ds_bpermute_b32 v25, v181, v22
	s_waitcnt vmcnt(4)
	v_mul_f32_e32 v23, v20, v21
	ds_bpermute_b32 v26, v181, v23
	s_waitcnt lgkmcnt(1)
	v_fmac_f32_e32 v25, v18, v19
	ds_bpermute_b32 v29, v182, v25
	s_waitcnt lgkmcnt(1)
	v_fmac_f32_e32 v26, v20, v21
	ds_bpermute_b32 v30, v182, v26
	s_waitcnt vmcnt(3)
	v_and_b32_e32 v19, 0xffff0000, v0
	v_lshlrev_b32_e32 v18, 16, v0
	v_and_b32_e32 v21, 0xffff0000, v1
	v_lshlrev_b32_e32 v20, 16, v1
	v_and_b32_e32 v1, 0xffff0000, v2
	v_lshlrev_b32_e32 v0, 16, v2
	v_and_b32_e32 v23, 0xffff0000, v3
	v_lshlrev_b32_e32 v22, 16, v3
	v_pk_mul_f32 v[2:3], v[18:19], s[44:45] op_sel_hi:[1,0]
	v_pk_mul_f32 v[0:1], v[0:1], s[44:45] op_sel_hi:[1,0]
	v_cvt_pk_bf16_f32 v51, v2, v3
	s_waitcnt lgkmcnt(1)
	v_add_f32_e32 v2, v25, v29
	s_waitcnt lgkmcnt(0)
	v_add_f32_e32 v3, v26, v30
	ds_bpermute_b32 v25, v24, v2
	ds_bpermute_b32 v24, v24, v3
	v_bfe_u32 v32, v0, 16, 1
	v_add3_u32 v55, v0, v32, s94
	v_pk_mul_f32 v[18:19], v[20:21], s[44:45] op_sel_hi:[1,0]
	s_waitcnt lgkmcnt(1)
	v_add_f32_e32 v0, v2, v25
	s_waitcnt lgkmcnt(0)
	v_add_f32_e32 v2, v3, v24
	ds_bpermute_b32 v3, v27, v0
	v_bfe_u32 v34, v18, 16, 1
	v_add3_u32 v53, v18, v34, s94
	ds_bpermute_b32 v18, v27, v2
	v_bfe_u32 v31, v1, 16, 1
	v_add3_u32 v56, v1, v31, s94
	s_waitcnt lgkmcnt(1)
	v_add_f32_e32 v205, v0, v3
	s_waitcnt vmcnt(2)
	v_and_b32_e32 v1, 0xffff0000, v4
	v_lshlrev_b32_e32 v0, 16, v4
	v_bfe_u32 v33, v19, 16, 1
	v_pk_mul_f32 v[0:1], v[0:1], s[44:45] op_sel_hi:[1,0]
	v_add3_u32 v54, v19, v33, s94
	s_waitcnt lgkmcnt(0)
	v_add_f32_e32 v207, v2, v18
	v_and_b32_e32 v19, 0xffff0000, v7
	v_lshlrev_b32_e32 v18, 16, v7
	v_and_b32_e32 v3, 0xffff0000, v5
	v_lshlrev_b32_e32 v2, 16, v5
	v_and_b32_e32 v5, 0xffff0000, v6
	v_lshlrev_b32_e32 v4, 16, v6
	v_pk_mul_f32 v[6:7], v[18:19], s[44:45] op_sel_hi:[1,0]
	v_cvt_pk_bf16_f32 v60, v0, v1
	s_waitcnt vmcnt(1)
	v_and_b32_e32 v1, 0xffff0000, v8
	v_lshlrev_b32_e32 v0, 16, v8
	v_pk_mul_f32 v[42:43], v[0:1], s[44:45] op_sel_hi:[1,0]
	v_and_b32_e32 v1, 0xffff0000, v9
	v_lshlrev_b32_e32 v0, 16, v9
	v_pk_mul_f32 v[8:9], v[0:1], s[44:45] op_sel_hi:[1,0]
	v_add_u32_e32 v0, s37, v185
	v_add_u32_e32 v18, 0x100, v50
	v_pk_mul_f32 v[20:21], v[22:23], s[44:45] op_sel_hi:[1,0]
	v_mad_i64_i32 v[0:1], s[40:41], v0, s0, v[16:17]
	v_ashrrev_i32_e32 v180, 4, v18
	v_pk_mul_f32 v[4:5], v[4:5], s[44:45] op_sel_hi:[1,0]
	v_lshl_add_u64 v[0:1], v[0:1], 0, s[70:71]
	v_add_u32_e32 v18, s37, v180
	v_add_u32_e32 v26, 0x200, v50
	v_cvt_pk_bf16_f32 v58, v20, v21
	v_cvt_pk_bf16_f32 v65, v6, v7
	v_lshl_add_u64 v[0:1], v[0:1], 0, v[48:49]
	v_mad_i64_i32 v[18:19], s[40:41], v18, s0, v[16:17]
	v_ashrrev_i32_e32 v179, 4, v26
	v_pk_mul_f32 v[2:3], v[2:3], s[44:45] op_sel_hi:[1,0]
	v_cvt_pk_bf16_f32 v63, v4, v5
	v_add_co_u32_e32 v4, vcc, s42, v0
	v_lshl_add_u64 v[18:19], v[18:19], 0, s[70:71]
	v_add_u32_e32 v26, s37, v179
	v_add_u32_e32 v34, 0x300, v50
	v_addc_co_u32_e32 v5, vcc, 0, v1, vcc
	v_lshl_add_u64 v[18:19], v[18:19], 0, v[48:49]
	v_mad_i64_i32 v[26:27], s[40:41], v26, s0, v[16:17]
	v_ashrrev_i32_e32 v178, 4, v34
	v_add_co_u32_e32 v22, vcc, s42, v18
	v_lshl_add_u64 v[26:27], v[26:27], 0, s[70:71]
	v_add_u32_e32 v34, s37, v178
	v_cvt_pk_bf16_f32 v61, v2, v3
	global_load_dwordx4 v[0:3], v[4:5], off offset:2048
	s_nop 0
	global_load_dwordx4 v[4:7], v[4:5], off offset:3072
	v_addc_co_u32_e32 v23, vcc, 0, v19, vcc
	v_lshl_add_u64 v[26:27], v[26:27], 0, v[48:49]
	v_mad_i64_i32 v[34:35], s[40:41], v34, s0, v[16:17]
	v_add_co_u32_e32 v30, vcc, s42, v26
	v_lshl_add_u64 v[34:35], v[34:35], 0, s[70:71]
	global_load_dwordx4 v[18:21], v[22:23], off offset:2048
	s_nop 0
	global_load_dwordx4 v[22:25], v[22:23], off offset:3072
	v_addc_co_u32_e32 v31, vcc, 0, v27, vcc
	v_lshl_add_u64 v[34:35], v[34:35], 0, v[48:49]
	v_add_co_u32_e32 v40, vcc, s42, v34
	ds_bpermute_b32 v206, v28, v205
	ds_bpermute_b32 v208, v28, v207
	global_load_dwordx4 v[26:29], v[30:31], off offset:2048
	s_nop 0
	global_load_dwordx4 v[30:33], v[30:31], off offset:3072
	v_addc_co_u32_e32 v41, vcc, 0, v35, vcc
	v_and_b32_e32 v39, 0xffff0000, v10
	global_load_dwordx4 v[34:37], v[40:41], off offset:2048
	v_lshlrev_b32_e32 v38, 16, v10
	v_pk_mul_f32 v[44:45], v[38:39], s[44:45] op_sel_hi:[1,0]
	global_load_dwordx4 v[38:41], v[40:41], off offset:3072
	v_bfe_u32 v69, v9, 16, 1
	v_bfe_u32 v70, v8, 16, 1
	v_add3_u32 v70, v8, v70, s94
	v_add3_u32 v69, v9, v69, s94
	s_waitcnt vmcnt(8)
	v_and_b32_e32 v9, 0xffff0000, v12
	v_lshlrev_b32_e32 v8, 16, v12
	v_pk_mul_f32 v[8:9], v[8:9], s[44:45] op_sel_hi:[1,0]
	s_movk_i32 s37, 0x110
	v_bfe_u32 v75, v9, 16, 1
	v_bfe_u32 v76, v8, 16, 1
	v_add3_u32 v75, v9, v75, s94
	v_lshrrev_b32_e32 v9, 2, v50
	v_add3_u32 v76, v8, v76, s94
	v_bfe_u32 v8, v50, 2, 2
	v_and_b32_e32 v204, 12, v9
	v_or_b32_e32 v8, v204, v8
	v_mul_u32_u24_e32 v83, 0x120, v8
	v_lshlrev_b32_e32 v8, 4, v50
	v_mul_lo_u32 v209, v185, s37
	v_and_b32_e32 v210, 0xf0, v8
	v_add3_u32 v8, s17, v209, v210
	v_mul_lo_u32 v212, v180, s37
	v_mul_lo_u32 v213, v180, s39
	v_mul_lo_u32 v214, v179, s37
	v_mul_lo_u32 v215, v179, s39
	v_mul_lo_u32 v216, v178, s37
	v_mul_lo_u32 v217, v178, s39
	v_and_b32_e32 v47, 0xffff0000, v11
	v_lshlrev_b32_e32 v46, 16, v11
	v_pk_mul_f32 v[10:11], v[46:47], s[44:45] op_sel_hi:[1,0]
	v_lshlrev_b32_e32 v12, 16, v14
	v_cvt_pk_bf16_f32 v74, v10, v11
	v_and_b32_e32 v11, 0xffff0000, v13
	v_lshlrev_b32_e32 v10, 16, v13
	v_and_b32_e32 v13, 0xffff0000, v14
	v_bfe_u32 v67, v45, 16, 1
	v_pk_mul_f32 v[12:13], v[12:13], s[44:45] op_sel_hi:[1,0]
	v_bfe_u32 v68, v44, 16, 1
	v_add3_u32 v67, v45, v67, s94
	v_bfe_u32 v71, v43, 16, 1
	v_bfe_u32 v72, v42, 16, 1
	v_add3_u32 v68, v44, v68, s94
	v_add3_u32 v72, v42, v72, s94
	v_add3_u32 v71, v43, v71, s94
	v_and_b32_e32 v43, 0xffff0000, v15
	v_lshlrev_b32_e32 v42, 16, v15
	v_cvt_pk_bf16_f32 v80, v12, v13
	v_pk_mul_f32 v[10:11], v[10:11], s[44:45] op_sel_hi:[1,0]
	s_waitcnt vmcnt(7)
	ds_write_b128 v8, v[0:3]
	v_add3_u32 v0, s17, v211, v210
	s_waitcnt vmcnt(6)
	ds_write_b128 v0, v[4:7] offset:17408
	v_add3_u32 v0, s17, v212, v210
	v_add_u32_e32 v8, s38, v180
	v_mad_i64_i32 v[8:9], s[40:41], v8, s0, v[16:17]
	v_lshl_add_u64 v[8:9], v[8:9], 0, s[70:71]
	v_lshl_add_u64 v[8:9], v[8:9], 0, v[48:49]
	s_waitcnt vmcnt(5)
	ds_write_b128 v0, v[18:21]
	v_add3_u32 v0, s17, v213, v210
	s_waitcnt vmcnt(4)
	ds_write_b128 v0, v[22:25] offset:17408
	v_add3_u32 v0, s17, v214, v210
	v_add_u32_e32 v18, s38, v179
	v_mad_i64_i32 v[18:19], s[40:41], v18, s0, v[16:17]
	v_lshl_add_u64 v[18:19], v[18:19], 0, s[70:71]
	s_waitcnt vmcnt(3)
	ds_write_b128 v0, v[26:29]
	v_add3_u32 v0, s17, v215, v210
	s_waitcnt vmcnt(2)
	ds_write_b128 v0, v[30:33] offset:17408
	v_add3_u32 v0, s17, v216, v210
	v_lshl_add_u64 v[18:19], v[18:19], 0, v[48:49]
	s_waitcnt vmcnt(1)
	ds_write_b128 v0, v[34:37]
	v_add3_u32 v0, s17, v217, v210
	v_pk_mul_f32 v[14:15], v[42:43], s[44:45] op_sel_hi:[1,0]
	s_waitcnt vmcnt(0)
	ds_write_b128 v0, v[38:41] offset:17408
	v_add_u32_e32 v0, s38, v185
	v_mad_i64_i32 v[0:1], s[40:41], v0, s0, v[16:17]
	v_lshl_add_u64 v[0:1], v[0:1], 0, s[70:71]
	v_lshl_add_u64 v[0:1], v[0:1], 0, v[48:49]
	v_add_co_u32_e32 v4, vcc, s42, v0
	s_nop 0
	s_nop 0
	v_addc_co_u32_e32 v5, vcc, 0, v1, vcc
	v_add_co_u32_e32 v12, vcc, s42, v8
	s_nop 0
	s_nop 0
	v_addc_co_u32_e32 v13, vcc, 0, v9, vcc
	v_add_co_u32_e32 v18, vcc, s42, v18
	s_nop 1
	v_addc_co_u32_e32 v19, vcc, 0, v19, vcc
	v_cvt_pk_bf16_f32 v78, v10, v11
	v_cvt_pk_bf16_f32 v82, v14, v15
	global_load_dwordx4 v[0:3], v[4:5], off offset:2048
	s_nop 0
	global_load_dwordx4 v[4:7], v[4:5], off offset:3072
	s_nop 0
	global_load_dwordx4 v[8:11], v[12:13], off offset:2048
	s_nop 0
	global_load_dwordx4 v[12:15], v[12:13], off offset:3072
	s_nop 0
	global_load_dwordx4 v[20:23], v[18:19], off offset:2048
	global_load_dwordx4 v[28:31], v[18:19], off offset:3072
	v_add_u32_e32 v18, s38, v178
	v_mad_i64_i32 v[16:17], s[38:39], v18, s0, v[16:17]
	v_lshl_add_u64 v[16:17], v[16:17], 0, s[70:71]
	v_lshl_add_u64 v[16:17], v[16:17], 0, v[48:49]
	v_add_co_u32_e32 v16, vcc, s42, v16
	v_mul_u32_u24_e32 v49, 0x110, v183
	s_nop 0
	v_addc_co_u32_e32 v17, vcc, 0, v17, vcc
	global_load_dwordx4 v[40:43], v[16:17], off offset:2048
	global_load_dwordx4 v[44:47], v[16:17], off offset:3072
	v_add3_u32 v219, s17, v160, v49
	v_add_u32_e32 v49, s23, v178
	v_add_u32_e32 v49, 0xffffc080, v49
	v_mov_b32_e32 v16, v51
	v_mad_i64_i32 v[50:51], s[38:39], v49, s0, 0
	s_and_b32 s38, s36, 0x300
	v_add_u32_e32 v49, s23, v179
	v_readlane_b32 s37, v251, 56
	v_or3_b32 v50, v50, s38, v48
	v_add_u32_e32 v49, 0xffffc080, v49
	v_add3_u32 v218, v84, s37, v83
	v_lshl_add_u64 v[134:135], s[30:31], 0, v[50:51]
	v_mad_i64_i32 v[50:51], s[36:37], v49, s0, 0
	v_add_u32_e32 v49, s23, v180
	v_or3_b32 v50, v50, s38, v48
	v_add_u32_e32 v49, 0xffffc080, v49
	v_lshl_add_u64 v[136:137], s[30:31], 0, v[50:51]
	v_mad_i64_i32 v[50:51], s[36:37], v49, s0, 0
	v_add_u32_e32 v49, s23, v185
	v_or3_b32 v50, v50, s38, v48
	v_add_u32_e32 v49, 0xffffc080, v49
	v_lshl_add_u64 v[138:139], s[30:31], 0, v[50:51]
	v_mad_i64_i32 v[50:51], s[36:37], v49, s0, 0
	v_or3_b32 v50, v50, s38, v48
	v_mov_b32_e32 v48, 0
	v_mov_b32_e32 v19, v58
	v_perm_b32 v18, v56, v55, s95
	v_perm_b32 v17, v54, v53, s95
	v_mov_b32_e32 v27, v65
	v_mov_b32_e32 v26, v63
	v_mov_b32_e32 v25, v61
	v_mov_b32_e32 v24, v60
	v_mov_b32_e32 v35, v74
	v_perm_b32 v34, v67, v68, s95
	v_perm_b32 v33, v69, v70, s95
	v_perm_b32 v32, v71, v72, s95
	v_mov_b32_e32 v39, v82
	v_mov_b32_e32 v38, v80
	v_mov_b32_e32 v37, v78
	v_perm_b32 v36, v75, v76, s95
	v_lshl_add_u64 v[140:141], s[30:31], 0, v[50:51]
	s_mov_b64 s[36:37], 0
	v_mov_b32_e32 v49, v48
	v_mov_b32_e32 v50, v48
	v_mov_b32_e32 v51, v48
	v_mov_b32_e32 v52, v48
	v_mov_b32_e32 v53, v48
	v_mov_b32_e32 v54, v48
	v_mov_b32_e32 v55, v48
	v_mov_b32_e32 v68, v48
	v_mov_b32_e32 v69, v48
	v_mov_b32_e32 v70, v48
	v_mov_b32_e32 v71, v48
	v_mov_b32_e32 v76, v48
	v_mov_b32_e32 v77, v48
	v_mov_b32_e32 v78, v48
	v_mov_b32_e32 v79, v48
	v_mov_b32_e32 v80, v48
	v_mov_b32_e32 v81, v48
	v_mov_b32_e32 v82, v48
	v_mov_b32_e32 v83, v48
	v_mov_b32_e32 v84, v48
	v_mov_b32_e32 v85, v48
	v_mov_b32_e32 v86, v48
	v_mov_b32_e32 v87, v48
	v_mov_b32_e32 v88, v48
	v_mov_b32_e32 v89, v48
	v_mov_b32_e32 v90, v48
	v_mov_b32_e32 v91, v48
	v_mov_b32_e32 v96, v48
	v_mov_b32_e32 v97, v48
	v_mov_b32_e32 v98, v48
	v_mov_b32_e32 v99, v48
	v_mov_b32_e32 v92, v48
	v_mov_b32_e32 v93, v48
	v_mov_b32_e32 v94, v48
	v_mov_b32_e32 v95, v48
	v_mov_b32_e32 v100, v48
	v_mov_b32_e32 v101, v48
	v_mov_b32_e32 v102, v48
	v_mov_b32_e32 v103, v48
	v_mov_b32_e32 v104, v48
	v_mov_b32_e32 v105, v48
	v_mov_b32_e32 v106, v48
	v_mov_b32_e32 v107, v48
	v_mov_b32_e32 v108, v48
	v_mov_b32_e32 v109, v48
	v_mov_b32_e32 v110, v48
	v_mov_b32_e32 v111, v48
	v_mov_b32_e32 v72, v48
	v_mov_b32_e32 v73, v48
	v_mov_b32_e32 v74, v48
	v_mov_b32_e32 v75, v48
	v_mov_b32_e32 v64, v48
	v_mov_b32_e32 v65, v48
	v_mov_b32_e32 v66, v48
	v_mov_b32_e32 v67, v48
	v_mov_b32_e32 v60, v48
	v_mov_b32_e32 v61, v48
	v_mov_b32_e32 v62, v48
	v_mov_b32_e32 v63, v48
	v_mov_b32_e32 v56, v48
	v_mov_b32_e32 v57, v48
	v_mov_b32_e32 v58, v48
	v_mov_b32_e32 v59, v48
	v_mov_b32_e32 v132, v48
	v_mov_b32_e32 v133, v48
	s_waitcnt lgkmcnt(0)
	s_barrier
	s_branch .LBB0_699
.LBB0_698:
	s_mul_i32 s23, s23, 0x8c00
	v_add_u32_e32 v220, s23, v218
	v_add_u32_e32 v113, s23, v219
	ds_read_b128 v[114:117], v113
	ds_read_b128 v[118:121], v113 offset:64
	s_waitcnt lgkmcnt(1)
	v_mfma_f32_16x16x32_bf16 v[114:117], v[114:117], v[16:19], 0
	s_waitcnt lgkmcnt(0)
	v_mfma_f32_16x16x32_bf16 v[144:147], v[118:121], v[24:27], v[114:117]
	ds_read_b128 v[118:121], v113 offset:4416
	s_nop 4
	ds_read_b128 v[114:117], v113 offset:4352
	s_waitcnt lgkmcnt(0)
	v_mfma_f32_16x16x32_bf16 v[114:117], v[114:117], v[16:19], 0
	v_mfma_f32_16x16x32_bf16 v[154:157], v[118:121], v[24:27], v[114:117]
	s_nop 6
	ds_read_b128 v[114:117], v113 offset:8704
	ds_read_b128 v[118:121], v113 offset:8768
	s_waitcnt lgkmcnt(1)
	v_mfma_f32_16x16x32_bf16 v[114:117], v[114:117], v[16:19], 0
	s_waitcnt lgkmcnt(0)
	v_mfma_f32_16x16x32_bf16 v[222:225], v[118:121], v[24:27], v[114:117]
	ds_read_b128 v[118:121], v113 offset:13120
	s_nop 4
	ds_read_b128 v[114:117], v113 offset:13056
	s_waitcnt lgkmcnt(0)
	v_mfma_f32_16x16x32_bf16 v[114:117], v[114:117], v[16:19], 0
	v_mfma_f32_16x16x32_bf16 v[226:229], v[118:121], v[24:27], v[114:117]
	s_nop 6
	ds_read_b128 v[114:117], v113 offset:128
	ds_read_b128 v[118:121], v113 offset:192
	ds_read_b128 v[122:125], v113 offset:4480
	s_waitcnt lgkmcnt(2)
	v_mfma_f32_16x16x32_bf16 v[114:117], v[114:117], v[32:35], 0
	s_waitcnt lgkmcnt(1)
	v_mfma_f32_16x16x32_bf16 v[128:131], v[118:121], v[36:39], v[114:117]
	s_nop 5
	ds_read_b128 v[114:117], v113 offset:4544
	s_waitcnt lgkmcnt(1)
	v_mfma_f32_16x16x32_bf16 v[122:125], v[122:125], v[32:35], 0
	s_waitcnt lgkmcnt(0)
	v_mfma_f32_16x16x32_bf16 v[120:123], v[114:117], v[36:39], v[122:125]
	ds_read_b128 v[114:117], v113 offset:8832
	s_nop 4
	ds_read_b128 v[124:127], v113 offset:8896
	s_waitcnt lgkmcnt(1)
	v_mfma_f32_16x16x32_bf16 v[114:117], v[114:117], v[32:35], 0
	s_waitcnt lgkmcnt(0)
	v_mfma_f32_16x16x32_bf16 v[116:119], v[124:127], v[36:39], v[114:117]
	ds_read_b128 v[124:127], v113 offset:13248
	ds_read_b128 v[172:175], v113 offset:13184
	s_waitcnt lgkmcnt(0)
	v_mfma_f32_16x16x32_bf16 v[172:175], v[172:175], v[32:35], 0
	v_mfma_f32_16x16x32_bf16 v[124:127], v[124:127], v[36:39], v[172:175]
	v_max3_f32 v113, v144, s8, v145
	v_max3_f32 v113, v113, v146, v147
	v_max3_f32 v113, v113, v154, v155
	v_max3_f32 v113, v113, v156, v157
	v_max3_f32 v113, v113, v222, v223
	v_max3_f32 v113, v113, v224, v225
	v_max3_f32 v113, v113, v226, v227
	v_max3_f32 v113, v113, v228, v229
	ds_bpermute_b32 v114, v182, v113
	s_waitcnt lgkmcnt(0)
	v_max_f32_e32 v114, v114, v114
	v_max_f32_e32 v113, v113, v114
	ds_bpermute_b32 v114, v181, v113
	s_waitcnt lgkmcnt(0)
	v_max3_f32 v221, v112, v113, v114
	v_sub_f32_e32 v114, v145, v221
	v_mul_f32_e32 v114, 0x3fb8aa3b, v114
	v_exp_f32_e32 v148, v114
	v_sub_f32_e32 v114, v146, v221
	v_sub_f32_e32 v113, v144, v221
	v_mul_f32_e32 v114, 0x3fb8aa3b, v114
	v_mul_f32_e32 v113, 0x3fb8aa3b, v113
	v_exp_f32_e32 v146, v114
	v_sub_f32_e32 v114, v147, v221
	v_exp_f32_e32 v144, v113
	v_mul_f32_e32 v114, 0x3fb8aa3b, v114
	v_exp_f32_e32 v152, v114
	v_sub_f32_e32 v114, v154, v221
	v_mul_f32_e32 v114, 0x3fb8aa3b, v114
	v_exp_f32_e32 v154, v114
	v_sub_f32_e32 v114, v155, v221
	v_add_f32_e32 v113, 0, v144
	v_mul_f32_e32 v114, 0x3fb8aa3b, v114
	v_add_f32_e32 v113, v148, v113
	v_exp_f32_e32 v158, v114
	v_add_f32_e32 v113, v146, v113
	v_add_f32_e32 v113, v152, v113
	v_add_f32_e32 v113, v154, v113
	v_add_f32_e32 v177, v158, v113
	v_sub_f32_e32 v113, v156, v221
	v_mul_f32_e32 v113, 0x3fb8aa3b, v113
	v_exp_f32_e32 v155, v113
	v_sub_f32_e32 v113, v157, v221
	v_mul_f32_e32 v113, 0x3fb8aa3b, v113
	v_exp_f32_e32 v173, v113
	v_sub_f32_e32 v113, v222, v221
	v_mul_f32_e32 v113, 0x3fb8aa3b, v113
	v_exp_f32_e32 v143, v113
	v_sub_f32_e32 v113, v223, v221
	v_mul_f32_e32 v113, 0x3fb8aa3b, v113
	v_exp_f32_e32 v147, v113
	v_sub_f32_e32 v113, v224, v221
	v_mul_f32_e32 v113, 0x3fb8aa3b, v113
	v_exp_f32_e32 v145, v113
	v_sub_f32_e32 v113, v225, v221
	v_mul_f32_e32 v113, 0x3fb8aa3b, v113
	v_exp_f32_e32 v153, v113
	v_sub_f32_e32 v113, v226, v221
	v_mul_f32_e32 v113, 0x3fb8aa3b, v113
	v_exp_f32_e32 v149, v113
	v_sub_f32_e32 v113, v227, v221
	v_mul_f32_e32 v113, 0x3fb8aa3b, v113
	v_exp_f32_e32 v159, v113
	v_sub_f32_e32 v113, v228, v221
	v_sub_f32_e32 v112, v112, v221
	v_mul_f32_e32 v113, 0x3fb8aa3b, v113
	v_mul_f32_e32 v112, 0x3fb8aa3b, v112
	v_exp_f32_e32 v157, v113
	v_sub_f32_e32 v113, v229, v221
	v_mul_f32_e32 v113, 0x3fb8aa3b, v113
	v_exp_f32_e32 v160, v112
	v_exp_f32_e32 v175, v113
	v_bfe_u32 v176, v144, 16, 1
	v_add3_u32 v231, v144, v176, s94
	v_pk_mul_f32 v[112:113], v[108:109], v[160:161] op_sel_hi:[1,0]
	v_pk_mul_f32 v[108:109], v[104:105], v[160:161] op_sel_hi:[1,0]
	v_pk_mul_f32 v[104:105], v[100:101], v[160:161] op_sel_hi:[1,0]
	v_pk_mul_f32 v[100:101], v[92:93], v[160:161] op_sel_hi:[1,0]
	v_pk_mul_f32 v[92:93], v[96:97], v[160:161] op_sel_hi:[1,0]
	v_max3_f32 v96, v128, s8, v129
	v_max3_f32 v96, v96, v130, v131
	v_max3_f32 v96, v96, v120, v121
	v_max3_f32 v96, v96, v122, v123
	v_max3_f32 v96, v96, v116, v117
	v_max3_f32 v96, v96, v118, v119
	v_max3_f32 v96, v96, v124, v125
	v_cvt_pk_bf16_f32 v237, v155, v173
	v_max3_f32 v96, v96, v126, v127
	v_cvt_pk_bf16_f32 v229, v157, v175
	ds_bpermute_b32 v97, v182, v96
	v_pk_mul_f32 v[114:115], v[110:111], v[160:161] op_sel_hi:[1,0]
	v_pk_mul_f32 v[110:111], v[106:107], v[160:161] op_sel_hi:[1,0]
	v_pk_mul_f32 v[106:107], v[102:103], v[160:161] op_sel_hi:[1,0]
	v_pk_mul_f32 v[102:103], v[94:95], v[160:161] op_sel_hi:[1,0]
	s_waitcnt lgkmcnt(0)
	v_max_f32_e32 v97, v97, v97
	v_max_f32_e32 v96, v96, v97
	ds_bpermute_b32 v97, v181, v96
	v_pk_mul_f32 v[94:95], v[98:99], v[160:161] op_sel_hi:[1,0]
	s_waitcnt lgkmcnt(0)
	v_max3_f32 v222, v142, v96, v97
	v_sub_f32_e32 v98, v129, v222
	v_mul_f32_e32 v98, 0x3fb8aa3b, v98
	v_exp_f32_e32 v129, v98
	v_sub_f32_e32 v98, v130, v222
	v_sub_f32_e32 v97, v128, v222
	v_mul_f32_e32 v98, 0x3fb8aa3b, v98
	v_mul_f32_e32 v97, 0x3fb8aa3b, v97
	v_exp_f32_e32 v130, v98
	v_sub_f32_e32 v98, v131, v222
	v_exp_f32_e32 v128, v97
	v_mul_f32_e32 v98, 0x3fb8aa3b, v98
	v_exp_f32_e32 v131, v98
	v_sub_f32_e32 v98, v120, v222
	v_mul_f32_e32 v98, 0x3fb8aa3b, v98
	v_exp_f32_e32 v239, v98
	v_sub_f32_e32 v98, v121, v222
	v_add_f32_e32 v97, 0, v128
	v_mul_f32_e32 v98, 0x3fb8aa3b, v98
	v_add_f32_e32 v97, v129, v97
	v_exp_f32_e32 v240, v98
	v_add_f32_e32 v97, v130, v97
	v_add_f32_e32 v97, v131, v97
	v_add_f32_e32 v97, v239, v97
	v_add_f32_e32 v176, v240, v97
	v_sub_f32_e32 v97, v122, v222
	v_mul_f32_e32 v97, 0x3fb8aa3b, v97
	v_cvt_pk_bf16_f32 v235, v154, v158
	v_exp_f32_e32 v154, v97
	v_sub_f32_e32 v97, v123, v222
	v_bfe_u32 v172, v146, 16, 1
	v_mul_f32_e32 v97, 0x3fb8aa3b, v97
	v_add3_u32 v233, v146, v172, s94
	v_exp_f32_e32 v172, v97
	v_sub_f32_e32 v97, v116, v222
	v_mul_f32_e32 v97, 0x3fb8aa3b, v97
	v_sub_f32_e32 v96, v142, v222
	v_exp_f32_e32 v142, v97
	v_sub_f32_e32 v97, v117, v222
	v_mul_f32_e32 v97, 0x3fb8aa3b, v97
	v_exp_f32_e32 v146, v97
	v_sub_f32_e32 v97, v118, v222
	v_mul_f32_e32 v97, 0x3fb8aa3b, v97
	v_bfe_u32 v156, v152, 16, 1
	v_cvt_pk_bf16_f32 v226, v145, v153
	v_exp_f32_e32 v144, v97
	v_sub_f32_e32 v97, v119, v222
	v_add3_u32 v234, v152, v156, s94
	v_mul_f32_e32 v97, 0x3fb8aa3b, v97
	v_bfe_u32 v174, v148, 16, 1
	v_exp_f32_e32 v152, v97
	v_sub_f32_e32 v97, v124, v222
	v_add3_u32 v232, v148, v174, s94
	v_mul_f32_e32 v97, 0x3fb8aa3b, v97
	v_cvt_pk_bf16_f32 v224, v143, v147
	v_exp_f32_e32 v148, v97
	v_sub_f32_e32 v97, v125, v222
	v_mul_f32_e32 v97, 0x3fb8aa3b, v97
	v_exp_f32_e32 v158, v97
	v_sub_f32_e32 v97, v126, v222
	v_mul_f32_e32 v97, 0x3fb8aa3b, v97
	v_exp_f32_e32 v156, v97
	v_sub_f32_e32 v97, v127, v222
	v_mul_f32_e32 v96, 0x3fb8aa3b, v96
	v_mul_f32_e32 v97, 0x3fb8aa3b, v97
	v_exp_f32_e32 v174, v97
	v_exp_f32_e32 v120, v96
	v_pk_add_f32 v[96:97], v[154:155], v[176:177]
	v_pk_add_f32 v[96:97], v[172:173], v[96:97]
	v_mov_b32_e32 v121, v160
	v_pk_add_f32 v[96:97], v[142:143], v[96:97]
	v_cvt_pk_bf16_f32 v227, v149, v159
	v_pk_add_f32 v[96:97], v[146:147], v[96:97]
	v_pk_mul_f32 v[98:99], v[70:71], v[120:121] op_sel_hi:[1,0]
	v_pk_add_f32 v[96:97], v[144:145], v[96:97]
	v_pk_mul_f32 v[70:71], v[50:51], v[120:121] op_sel_hi:[1,0]
	v_pk_add_f32 v[96:97], v[152:153], v[96:97]
	v_pk_mul_f32 v[50:51], v[74:75], v[120:121] op_sel_hi:[1,0]
	v_pk_add_f32 v[96:97], v[148:149], v[96:97]
	v_pk_add_f32 v[96:97], v[158:159], v[96:97]
	v_pk_add_f32 v[96:97], v[156:157], v[96:97]
	v_pk_mul_f32 v[118:119], v[78:79], v[120:121] op_sel_hi:[1,0]
	v_pk_add_f32 v[96:97], v[174:175], v[96:97]
	v_pk_mul_f32 v[116:117], v[76:77], v[120:121] op_sel_hi:[1,0]
	v_pk_fma_f32 v[132:133], v[132:133], v[120:121], v[96:97]
	v_pk_mul_f32 v[96:97], v[68:69], v[120:121] op_sel_hi:[1,0]
	v_pk_mul_f32 v[78:79], v[54:55], v[120:121] op_sel_hi:[1,0]
	v_pk_mul_f32 v[76:77], v[52:53], v[120:121] op_sel_hi:[1,0]
	v_pk_mul_f32 v[68:69], v[48:49], v[120:121] op_sel_hi:[1,0]
	v_pk_mul_f32 v[48:49], v[72:73], v[120:121] op_sel_hi:[1,0]
	v_pk_mul_f32 v[54:55], v[66:67], v[120:121] op_sel_hi:[1,0]
	v_pk_mul_f32 v[52:53], v[64:65], v[120:121] op_sel_hi:[1,0]
	v_cvt_pk_bf16_f32 v145, v154, v172
	v_cvt_pk_bf16_f32 v153, v128, v129
	v_cvt_pk_bf16_f32 v154, v130, v131
	v_cvt_pk_bf16_f32 v157, v239, v240
	v_cvt_pk_bf16_f32 v240, v142, v146
	v_cvt_pk_bf16_f32 v241, v144, v152
	v_add_u32_e32 v128, 0x1200, v220
	v_add_u32_e32 v129, 32, v220
	v_add_u32_e32 v130, 0x1220, v220
	v_add_u32_e32 v131, 64, v220
	v_add_u32_e32 v142, 0x1240, v220
	v_add_u32_e32 v144, 0x60, v220
	v_pk_mul_f32 v[90:91], v[90:91], v[160:161] op_sel_hi:[1,0]
	v_pk_mul_f32 v[88:89], v[88:89], v[160:161] op_sel_hi:[1,0]
	v_pk_mul_f32 v[86:87], v[86:87], v[160:161] op_sel_hi:[1,0]
	v_pk_mul_f32 v[84:85], v[84:85], v[160:161] op_sel_hi:[1,0]
	v_pk_mul_f32 v[82:83], v[82:83], v[160:161] op_sel_hi:[1,0]
	v_pk_mul_f32 v[80:81], v[80:81], v[160:161] op_sel_hi:[1,0]
	v_pk_mul_f32 v[62:63], v[62:63], v[120:121] op_sel_hi:[1,0]
	v_pk_mul_f32 v[60:61], v[60:61], v[120:121] op_sel_hi:[1,0]
	v_pk_mul_f32 v[58:59], v[58:59], v[120:121] op_sel_hi:[1,0]
	v_pk_mul_f32 v[56:57], v[56:57], v[120:121] op_sel_hi:[1,0]
	v_cvt_pk_bf16_f32 v242, v148, v158
	v_cvt_pk_bf16_f32 v243, v156, v174
	v_add_u32_e32 v146, 0x1260, v220
	ds_read_b64_tr_b16 v[124:125], v220
	ds_read_b64_tr_b16 v[126:127], v128
	ds_read_b64_tr_b16 v[120:121], v129
	ds_read_b64_tr_b16 v[122:123], v130
	ds_read_b64_tr_b16 v[72:73], v131
	ds_read_b64_tr_b16 v[74:75], v142
	ds_read_b64_tr_b16 v[64:65], v144
	ds_read_b64_tr_b16 v[66:67], v146
	s_waitcnt lgkmcnt(0)
	v_mov_b32_e32 v131, v237
	v_mov_b32_e32 v130, v235
	v_perm_b32 v129, v234, v233, s95
	v_perm_b32 v128, v232, v231, s95
	v_mov_b32_e32 v144, v157
	v_mov_b32_e32 v143, v154
	v_mov_b32_e32 v142, v153
	v_mfma_f32_16x16x32_bf16 v[112:115], v[124:127], v[128:131], v[112:115]
	s_nop 0
	v_mfma_f32_16x16x32_bf16 v[116:119], v[124:127], v[142:145], v[116:119]
	v_mfma_f32_16x16x32_bf16 v[124:127], v[120:123], v[128:131], v[108:111]
	v_mfma_f32_16x16x32_bf16 v[96:99], v[120:123], v[142:145], v[96:99]
	v_mfma_f32_16x16x32_bf16 v[120:123], v[72:75], v[128:131], v[104:107]
	v_mfma_f32_16x16x32_bf16 v[72:75], v[72:75], v[142:145], v[76:79]
	v_mfma_f32_16x16x32_bf16 v[146:149], v[64:67], v[128:131], v[100:103]
	v_mfma_f32_16x16x32_bf16 v[64:67], v[64:67], v[142:145], v[68:71]
	v_add_u32_e32 v108, 0x80, v220
	v_add_u32_e32 v109, 0x1280, v220
	v_add_u32_e32 v110, 0xa0, v220
	v_add_u32_e32 v111, 0x12a0, v220
	v_add_u32_e32 v152, 0xc0, v220
	v_add_u32_e32 v153, 0x12c0, v220
	v_add_u32_e32 v154, 0xe0, v220
	v_add_u32_e32 v155, 0x12e0, v220
	ds_read_b64_tr_b16 v[104:105], v108
	ds_read_b64_tr_b16 v[106:107], v109
	ds_read_b64_tr_b16 v[100:101], v110
	ds_read_b64_tr_b16 v[102:103], v111
	ds_read_b64_tr_b16 v[76:77], v152
	ds_read_b64_tr_b16 v[78:79], v153
	ds_read_b64_tr_b16 v[68:69], v154
	ds_read_b64_tr_b16 v[70:71], v155
	s_waitcnt lgkmcnt(0)
	s_nop 0
	v_mfma_f32_16x16x32_bf16 v[88:91], v[100:103], v[128:131], v[88:91]
	v_mfma_f32_16x16x32_bf16 v[84:87], v[76:79], v[128:131], v[84:87]
	v_mfma_f32_16x16x32_bf16 v[60:63], v[76:79], v[142:145], v[60:63]
	v_mfma_f32_16x16x32_bf16 v[80:83], v[68:71], v[128:131], v[80:83]
	v_mfma_f32_16x16x32_bf16 v[56:59], v[68:71], v[142:145], v[56:59]
	v_mfma_f32_16x16x32_bf16 v[152:155], v[104:107], v[128:131], v[92:95]
	v_mfma_f32_16x16x32_bf16 v[156:159], v[104:107], v[142:145], v[48:51]
	v_mfma_f32_16x16x32_bf16 v[172:175], v[100:103], v[142:145], v[52:55]
	s_nop 0
	v_add_u32_e32 v92, 0x2400, v220
	v_add_u32_e32 v93, 0x3600, v220
	v_add_u32_e32 v94, 0x2420, v220
	v_add_u32_e32 v95, 0x3620, v220
	v_add_u32_e32 v100, 0x2440, v220
	v_add_u32_e32 v101, 0x3640, v220
	v_add_u32_e32 v102, 0x2460, v220
	v_add_u32_e32 v103, 0x3660, v220
	ds_read_b64_tr_b16 v[76:77], v92
	ds_read_b64_tr_b16 v[78:79], v93
	ds_read_b64_tr_b16 v[68:69], v94
	ds_read_b64_tr_b16 v[70:71], v95
	ds_read_b64_tr_b16 v[52:53], v100
	ds_read_b64_tr_b16 v[54:55], v101
	ds_read_b64_tr_b16 v[48:49], v102
	ds_read_b64_tr_b16 v[50:51], v103
	s_waitcnt lgkmcnt(0)
	v_mov_b32_e32 v131, v229
	v_mov_b32_e32 v130, v227
	v_mov_b32_e32 v129, v226
	v_mov_b32_e32 v128, v224
	v_mov_b32_e32 v145, v243
	v_mov_b32_e32 v144, v242
	v_mov_b32_e32 v143, v241
	v_mov_b32_e32 v142, v240
	v_mfma_f32_16x16x32_bf16 v[108:111], v[76:79], v[128:131], v[112:115]
	s_nop 0
	v_mfma_f32_16x16x32_bf16 v[76:79], v[76:79], v[142:145], v[116:119]
	v_mfma_f32_16x16x32_bf16 v[104:107], v[68:71], v[128:131], v[124:127]
	v_mfma_f32_16x16x32_bf16 v[68:71], v[68:71], v[142:145], v[96:99]
	v_mfma_f32_16x16x32_bf16 v[100:103], v[52:55], v[128:131], v[120:123]
	v_mfma_f32_16x16x32_bf16 v[52:55], v[52:55], v[142:145], v[72:75]
	v_mfma_f32_16x16x32_bf16 v[92:95], v[48:51], v[128:131], v[146:149]
	v_mfma_f32_16x16x32_bf16 v[48:51], v[48:51], v[142:145], v[64:67]
	v_add_u32_e32 v96, 0x2480, v220
	v_add_u32_e32 v97, 0x3680, v220
	v_add_u32_e32 v98, 0x24a0, v220
	v_add_u32_e32 v99, 0x36a0, v220
	v_add_u32_e32 v120, 0x24c0, v220
	v_add_u32_e32 v121, 0x36c0, v220
	v_add_u32_e32 v122, 0x24e0, v220
	v_add_u32_e32 v123, 0x36e0, v220
	ds_read_b64_tr_b16 v[72:73], v96
	ds_read_b64_tr_b16 v[74:75], v97
	ds_read_b64_tr_b16 v[64:65], v98
	ds_read_b64_tr_b16 v[66:67], v99
	ds_read_b64_tr_b16 v[116:117], v120
	ds_read_b64_tr_b16 v[118:119], v121
	ds_read_b64_tr_b16 v[112:113], v122
	ds_read_b64_tr_b16 v[114:115], v123
	s_waitcnt lgkmcnt(0)
	s_nop 0
	v_mfma_f32_16x16x32_bf16 v[96:99], v[72:75], v[128:131], v[152:155]
	v_mfma_f32_16x16x32_bf16 v[72:75], v[72:75], v[142:145], v[156:159]
	v_mfma_f32_16x16x32_bf16 v[88:91], v[64:67], v[128:131], v[88:91]
	v_mfma_f32_16x16x32_bf16 v[64:67], v[64:67], v[142:145], v[172:175]
	v_mfma_f32_16x16x32_bf16 v[84:87], v[116:119], v[128:131], v[84:87]
	v_mfma_f32_16x16x32_bf16 v[60:63], v[116:119], v[142:145], v[60:63]
	v_mfma_f32_16x16x32_bf16 v[80:83], v[112:115], v[128:131], v[80:83]
	v_mfma_f32_16x16x32_bf16 v[56:59], v[112:115], v[142:145], v[56:59]
	s_add_u32 s36, s36, 0xd0000
	s_addc_u32 s37, s37, 0
	s_add_i32 s22, s22, 1
	s_cmp_lg_u32 s36, 0x340000
	v_mov_b32_e32 v142, v222
	v_mov_b32_e32 v112, v221
	s_barrier
	s_cbranch_scc0 .LBB0_702

.LBB0_702:
	s_waitcnt vmcnt(7)
	v_xor_b32_e32 v0, 1, v151
	v_cmp_lt_i32_e32 vcc, v0, v187
	v_add_f32_e32 v2, v205, v206
	s_mov_b32 s22, 0x3fb8aa3b
	v_cndmask_b32_e32 v0, v151, v0, vcc
	v_lshlrev_b32_e32 v0, 2, v0
	ds_bpermute_b32 v3, v0, v2
	v_add_f32_e32 v1, v207, v208
	ds_bpermute_b32 v0, v0, v1
	s_mov_b32 s23, 0xc2ce8ed0
	s_mov_b32 s36, 0x42b17218
	s_waitcnt lgkmcnt(1)
	v_add_f32_e32 v2, v2, v3
	v_mul_f32_e32 v3, 0x3fb8aa3b, v2
	s_waitcnt vmcnt(6)
	v_fma_f32 v4, v2, s22, -v3
	v_rndne_f32_e32 v5, v3
	v_fmac_f32_e32 v4, 0x32a5705f, v2
	v_sub_f32_e32 v3, v3, v5
	v_add_f32_e32 v3, v3, v4
	v_exp_f32_e32 v3, v3
	v_cvt_i32_f32_e32 v4, v5
	v_cmp_ngt_f32_e32 vcc, s23, v2
	s_waitcnt lgkmcnt(0)
	v_add_f32_e32 v0, v1, v0
	v_mul_f32_e32 v1, 0x3fb8aa3b, v0
	v_ldexp_f32 v3, v3, v4
	v_cndmask_b32_e32 v3, 0, v3, vcc
	v_cmp_nlt_f32_e32 vcc, s36, v2
	v_rndne_f32_e32 v4, v1
	s_movk_i32 s52, 0x210
	v_cndmask_b32_e32 v2, v200, v3, vcc
	v_fma_f32 v3, v0, s22, -v1
	v_fmac_f32_e32 v3, 0x32a5705f, v0
	v_sub_f32_e32 v1, v1, v4
	v_add_f32_e32 v1, v1, v3
	v_exp_f32_e32 v1, v1
	v_cvt_i32_f32_e32 v3, v4
	v_cmp_ngt_f32_e32 vcc, s23, v0
	s_barrier
	v_ldexp_f32 v1, v1, v3
	v_cndmask_b32_e32 v1, 0, v1, vcc
	v_cmp_nlt_f32_e32 vcc, s36, v0
	s_lshl_b32 s70, s21, 1
	s_nop 0
	v_cndmask_b32_e32 v0, v200, v1, vcc
	ds_bpermute_b32 v1, v182, v133
	v_sub_f32_e32 v0, v2, v0
	v_readlane_b32 s36, v253, 12
	v_readlane_b32 s48, v253, 24
	v_readlane_b32 s49, v253, 25
	s_waitcnt lgkmcnt(0)
	v_add_f32_e32 v1, v133, v1
	ds_bpermute_b32 v2, v181, v1
	s_mov_b32 s21, 0xcc00000
	v_readlane_b32 s37, v253, 13
	v_readlane_b32 s38, v253, 14
	v_readlane_b32 s39, v253, 15
	s_waitcnt lgkmcnt(0)
	v_add_f32_e32 v2, v1, v2
	ds_bpermute_b32 v1, v182, v132
	v_div_scale_f32 v3, s[22:23], v2, v2, 1.0
	v_rcp_f32_e32 v4, v3
	v_readlane_b32 s40, v253, 16
	s_waitcnt lgkmcnt(0)
	v_add_f32_e32 v1, v132, v1
	ds_bpermute_b32 v151, v181, v1
	v_fma_f32 v5, -v3, v4, 1.0
	v_fmac_f32_e32 v4, v5, v4
	v_div_scale_f32 v5, vcc, 1.0, v2, 1.0
	v_mul_f32_e32 v6, v5, v4
	v_fma_f32 v7, -v3, v6, v5
	v_fmac_f32_e32 v6, v7, v4
	v_fma_f32 v3, -v3, v6, v5
	s_waitcnt lgkmcnt(0)
	v_pk_add_f32 v[0:1], v[150:151], v[0:1]
	v_div_fmas_f32 v3, v3, v4, v6
	v_div_fixup_f32 v2, v3, v2, 1.0
	v_div_scale_f32 v3, s[22:23], v1, v1, v0
	v_rcp_f32_e32 v4, v3
	v_readlane_b32 s22, v251, 41
	v_readlane_b32 s41, v253, 17
	v_readlane_b32 s42, v253, 18
	v_fma_f32 v5, -v3, v4, 1.0
	v_fmac_f32_e32 v4, v5, v4
	v_div_scale_f32 v5, vcc, v0, v1, v0
	v_mul_f32_e32 v6, v5, v4
	v_fma_f32 v7, -v3, v6, v5
	v_fmac_f32_e32 v6, v7, v4
	v_fma_f32 v3, -v3, v6, v5
	v_div_fmas_f32 v3, v3, v4, v6
	v_div_fixup_f32 v0, v3, v1, v0
	v_or_b32_e32 v1, v184, v183
	v_mul_lo_u32 v1, v1, s52
	v_lshlrev_b32_e32 v3, 2, v204
	v_pk_mul_f32 v[4:5], v[76:77], v[0:1] op_sel_hi:[1,0]
	s_waitcnt vmcnt(5)
	v_pk_mul_f32 v[8:9], v[78:79], v[0:1] op_sel_hi:[1,0]
	v_pk_fma_f32 v[4:5], v[108:109], v[2:3], v[4:5] op_sel_hi:[1,0,1] neg_lo:[0,0,1] neg_hi:[0,0,1]
	v_add3_u32 v112, s17, v1, v3
	v_pk_mul_f32 v[6:7], v[4:5], v[4:5]
	v_pk_fma_f32 v[8:9], v[110:111], v[2:3], v[8:9] op_sel_hi:[1,0,1] neg_lo:[0,0,1] neg_hi:[0,0,1]
	s_waitcnt vmcnt(4)
	v_pk_mul_f32 v[12:13], v[68:69], v[0:1] op_sel_hi:[1,0]
	v_pk_mul_f32 v[16:17], v[70:71], v[0:1] op_sel_hi:[1,0]
	s_waitcnt vmcnt(3)
	v_pk_mul_f32 v[20:21], v[52:53], v[0:1] op_sel_hi:[1,0]
	v_pk_mul_f32 v[24:25], v[54:55], v[0:1] op_sel_hi:[1,0]
	s_waitcnt vmcnt(2)
	v_pk_mul_f32 v[28:29], v[48:49], v[0:1] op_sel_hi:[1,0]
	v_pk_mul_f32 v[32:33], v[50:51], v[0:1] op_sel_hi:[1,0]
	v_pk_mul_f32 v[36:37], v[72:73], v[0:1] op_sel_hi:[1,0]
	s_waitcnt vmcnt(1)
	v_pk_mul_f32 v[40:41], v[74:75], v[0:1] op_sel_hi:[1,0]
	s_waitcnt vmcnt(0)
	v_pk_mul_f32 v[44:45], v[64:65], v[0:1] op_sel_hi:[1,0]
	v_pk_mul_f32 v[48:49], v[66:67], v[0:1] op_sel_hi:[1,0]
	v_pk_mul_f32 v[52:53], v[60:61], v[0:1] op_sel_hi:[1,0]
	v_pk_mul_f32 v[60:61], v[62:63], v[0:1] op_sel_hi:[1,0]
	v_pk_mul_f32 v[56:57], v[56:57], v[0:1] op_sel_hi:[1,0]
	v_pk_mul_f32 v[0:1], v[58:59], v[0:1] op_sel_hi:[1,0]
	v_pk_mul_f32 v[10:11], v[8:9], v[8:9]
	v_pk_fma_f32 v[12:13], v[104:105], v[2:3], v[12:13] op_sel_hi:[1,0,1] neg_lo:[0,0,1] neg_hi:[0,0,1]
	v_pk_fma_f32 v[16:17], v[106:107], v[2:3], v[16:17] op_sel_hi:[1,0,1] neg_lo:[0,0,1] neg_hi:[0,0,1]
	v_pk_fma_f32 v[20:21], v[100:101], v[2:3], v[20:21] op_sel_hi:[1,0,1] neg_lo:[0,0,1] neg_hi:[0,0,1]
	v_pk_fma_f32 v[24:25], v[102:103], v[2:3], v[24:25] op_sel_hi:[1,0,1] neg_lo:[0,0,1] neg_hi:[0,0,1]
	v_pk_fma_f32 v[28:29], v[92:93], v[2:3], v[28:29] op_sel_hi:[1,0,1] neg_lo:[0,0,1] neg_hi:[0,0,1]
	v_pk_fma_f32 v[32:33], v[94:95], v[2:3], v[32:33] op_sel_hi:[1,0,1] neg_lo:[0,0,1] neg_hi:[0,0,1]
	v_pk_fma_f32 v[36:37], v[96:97], v[2:3], v[36:37] op_sel_hi:[1,0,1] neg_lo:[0,0,1] neg_hi:[0,0,1]
	v_pk_fma_f32 v[40:41], v[98:99], v[2:3], v[40:41] op_sel_hi:[1,0,1] neg_lo:[0,0,1] neg_hi:[0,0,1]
	v_pk_fma_f32 v[44:45], v[88:89], v[2:3], v[44:45] op_sel_hi:[1,0,1] neg_lo:[0,0,1] neg_hi:[0,0,1]
	v_pk_fma_f32 v[48:49], v[90:91], v[2:3], v[48:49] op_sel_hi:[1,0,1] neg_lo:[0,0,1] neg_hi:[0,0,1]
	v_pk_fma_f32 v[52:53], v[84:85], v[2:3], v[52:53] op_sel_hi:[1,0,1] neg_lo:[0,0,1] neg_hi:[0,0,1]
	v_pk_fma_f32 v[60:61], v[86:87], v[2:3], v[60:61] op_sel_hi:[1,0,1] neg_lo:[0,0,1] neg_hi:[0,0,1]
	v_pk_fma_f32 v[56:57], v[80:81], v[2:3], v[56:57] op_sel_hi:[1,0,1] neg_lo:[0,0,1] neg_hi:[0,0,1]
	v_pk_fma_f32 v[58:59], v[82:83], v[2:3], v[0:1] op_sel_hi:[1,0,1] neg_lo:[0,0,1] neg_hi:[0,0,1]
	v_add_f32_e32 v2, v6, v7
	v_add_f32_e32 v2, v10, v2
	v_pk_mul_f32 v[14:15], v[12:13], v[12:13]
	v_add_f32_e32 v2, v11, v2
	v_add_f32_e32 v2, v14, v2
	v_pk_mul_f32 v[18:19], v[16:17], v[16:17]
	v_add_f32_e32 v2, v15, v2
	v_add_f32_e32 v2, v18, v2
	v_pk_mul_f32 v[22:23], v[20:21], v[20:21]
	v_add_f32_e32 v2, v19, v2
	v_add_f32_e32 v2, v22, v2
	v_pk_mul_f32 v[26:27], v[24:25], v[24:25]
	v_add_f32_e32 v2, v23, v2
	v_add_f32_e32 v2, v26, v2
	v_pk_mul_f32 v[30:31], v[28:29], v[28:29]
	v_add_f32_e32 v2, v27, v2
	v_add_f32_e32 v2, v30, v2
	v_pk_mul_f32 v[34:35], v[32:33], v[32:33]
	v_add_f32_e32 v2, v31, v2
	v_add_f32_e32 v2, v34, v2
	v_pk_mul_f32 v[38:39], v[36:37], v[36:37]
	v_add_f32_e32 v2, v35, v2
	v_add_f32_e32 v2, v38, v2
	v_pk_mul_f32 v[42:43], v[40:41], v[40:41]
	v_add_f32_e32 v2, v39, v2
	v_add_f32_e32 v2, v42, v2
	v_pk_mul_f32 v[46:47], v[44:45], v[44:45]
	v_add_f32_e32 v2, v43, v2
	v_add_f32_e32 v2, v46, v2
	v_pk_mul_f32 v[50:51], v[48:49], v[48:49]
	v_add_f32_e32 v2, v47, v2
	v_add_f32_e32 v2, v50, v2
	v_pk_mul_f32 v[54:55], v[52:53], v[52:53]
	v_add_f32_e32 v2, v51, v2
	v_add_f32_e32 v2, v54, v2
	v_pk_mul_f32 v[62:63], v[60:61], v[60:61]
	v_add_f32_e32 v2, v55, v2
	v_add_f32_e32 v2, v62, v2
	v_pk_mul_f32 v[64:65], v[56:57], v[56:57]
	v_add_f32_e32 v2, v63, v2
	v_add_f32_e32 v2, v64, v2
	v_pk_mul_f32 v[0:1], v[58:59], v[58:59]
	v_add_f32_e32 v2, v65, v2
	v_add_f32_e32 v0, v0, v2
	v_add_f32_e32 v0, v1, v0
	ds_bpermute_b32 v1, v182, v0
	v_mov_b64_e32 v[14:15], s[6:7]
	v_readlane_b32 s43, v253, 19
	v_readlane_b32 s44, v253, 20
	v_readlane_b32 s45, v253, 21
	s_waitcnt lgkmcnt(0)
	v_add_f32_e32 v0, v0, v1
	ds_bpermute_b32 v1, v181, v0
	v_readlane_b32 s46, v253, 22
	v_readlane_b32 s47, v253, 23
	v_readlane_b32 s50, v253, 26
	v_readlane_b32 s51, v253, 27
	s_waitcnt lgkmcnt(0)
	v_add_f32_e32 v0, v0, v1
	v_fmamk_f32 v0, v0, 0x3c000000, v193
	v_cmp_gt_f32_e32 vcc, s79, v0
	v_mul_f32_e32 v1, 0x4b800000, v0
	s_nop 0
	v_cndmask_b32_e32 v0, v0, v1, vcc
	v_rsq_f32_e32 v0, v0
	s_nop 0
	v_mul_f32_e32 v1, 0x45800000, v0
	v_cndmask_b32_e32 v0, v0, v1, vcc
	v_mul_f32_e32 v6, v203, v0
	v_pk_mul_f32 v[0:1], v[4:5], v[6:7] op_sel_hi:[1,0]
	v_pk_mul_f32 v[2:3], v[8:9], v[6:7] op_sel_hi:[1,0]
	ds_write_b128 v112, v[0:3]
	v_pk_mul_f32 v[0:1], v[12:13], v[6:7] op_sel_hi:[1,0]
	v_pk_mul_f32 v[2:3], v[16:17], v[6:7] op_sel_hi:[1,0]
	ds_write_b128 v112, v[0:3] offset:64
	v_pk_mul_f32 v[0:1], v[20:21], v[6:7] op_sel_hi:[1,0]
	v_pk_mul_f32 v[2:3], v[24:25], v[6:7] op_sel_hi:[1,0]
	ds_write_b128 v112, v[0:3] offset:128
	v_pk_mul_f32 v[0:1], v[28:29], v[6:7] op_sel_hi:[1,0]
	v_pk_mul_f32 v[2:3], v[32:33], v[6:7] op_sel_hi:[1,0]
	ds_write_b128 v112, v[0:3] offset:192
	v_pk_mul_f32 v[0:1], v[36:37], v[6:7] op_sel_hi:[1,0]
	v_pk_mul_f32 v[2:3], v[40:41], v[6:7] op_sel_hi:[1,0]
	ds_write_b128 v112, v[0:3] offset:256
	v_pk_mul_f32 v[0:1], v[44:45], v[6:7] op_sel_hi:[1,0]
	v_pk_mul_f32 v[2:3], v[48:49], v[6:7] op_sel_hi:[1,0]
	ds_write_b128 v112, v[0:3] offset:320
	v_pk_mul_f32 v[0:1], v[52:53], v[6:7] op_sel_hi:[1,0]
	v_pk_mul_f32 v[2:3], v[60:61], v[6:7] op_sel_hi:[1,0]
	ds_write_b128 v112, v[0:3] offset:384
	v_pk_mul_f32 v[0:1], v[56:57], v[6:7] op_sel_hi:[1,0]
	v_pk_mul_f32 v[2:3], v[58:59], v[6:7] op_sel_hi:[1,0]
	v_and_b32_e32 v5, 0x78, v186
	v_add_u32_e32 v16, s20, v185
	ds_write_b128 v112, v[0:3] offset:448
	v_or_b32_e32 v4, s22, v5
	v_mad_i64_i32 v[0:1], s[22:23], v16, s0, v[14:15]
	v_lshl_add_u64 v[0:1], v[0:1], 0, s[70:71]
	v_lshlrev_b32_e32 v160, 1, v5
	v_lshl_add_u64 v[0:1], v[0:1], 0, v[160:161]
	v_add_co_u32_e32 v0, vcc, s3, v0
	s_waitcnt lgkmcnt(0)
	s_nop 0
	v_addc_co_u32_e32 v1, vcc, 0, v1, vcc
	s_barrier
	global_load_dwordx4 v[0:3], v[0:1], off
	v_mul_lo_u32 v6, v185, s52
	v_lshlrev_b32_e32 v20, 2, v5
	v_mov_b32_e32 v5, v161
	v_add3_u32 v6, s17, v6, v20
	v_lshl_add_u64 v[12:13], v[4:5], 2, s[48:49]
	v_ashrrev_i32_e32 v17, 31, v16
	s_waitcnt vmcnt(0)
	v_and_b32_e32 v21, 0xffff0000, v0
	v_lshlrev_b32_e32 v0, 16, v0
	v_mul_f32_e32 v4, 0xbfb8aa3b, v0
	v_exp_f32_e32 v18, v4
	ds_read_b128 v[22:25], v6
	ds_read_b128 v[4:7], v6 offset:16
	global_load_dwordx4 v[8:11], v[12:13], off offset:16
	global_load_dwordx4 v[26:29], v[12:13], off
	v_mul_f32_e32 v19, 0xbfb8aa3b, v21
	v_exp_f32_e32 v19, v19
	s_waitcnt vmcnt(1) lgkmcnt(0)
	v_pk_mul_f32 v[4:5], v[4:5], v[8:9]
	v_pk_add_f32 v[18:19], v[18:19], 1.0 op_sel_hi:[1,0]
	s_waitcnt vmcnt(0)
	v_pk_mul_f32 v[22:23], v[22:23], v[26:27]
	v_div_scale_f32 v26, s[22:23], v19, v19, v21
	v_rcp_f32_e32 v27, v26
	v_pk_mul_f32 v[6:7], v[6:7], v[10:11]
	v_fma_f32 v30, -v26, v27, 1.0
	v_fmac_f32_e32 v27, v30, v27
	v_div_scale_f32 v30, vcc, v21, v19, v21
	v_mul_f32_e32 v31, v30, v27
	v_fma_f32 v32, -v26, v31, v30
	v_fmac_f32_e32 v31, v32, v27
	v_fma_f32 v26, -v26, v31, v30
	v_div_fmas_f32 v26, v26, v27, v31
	v_div_fixup_f32 v19, v26, v19, v21
	v_div_scale_f32 v21, s[22:23], v18, v18, v0
	v_rcp_f32_e32 v26, v21
	s_nop 0
	v_fma_f32 v27, -v21, v26, 1.0
	v_fmac_f32_e32 v26, v27, v26
	v_div_scale_f32 v27, vcc, v0, v18, v0
	v_mul_f32_e32 v30, v27, v26
	v_fma_f32 v31, -v21, v30, v27
	v_fmac_f32_e32 v30, v31, v26
	v_fma_f32 v21, -v21, v30, v27
	v_div_fmas_f32 v21, v21, v26, v30
	v_div_fixup_f32 v18, v21, v18, v0
	v_and_b32_e32 v21, 0xffff0000, v1
	v_lshlrev_b32_e32 v26, 16, v1
	v_mul_f32_e32 v0, 0xbfb8aa3b, v26
	v_mul_f32_e32 v1, 0xbfb8aa3b, v21
	v_exp_f32_e32 v0, v0
	v_exp_f32_e32 v1, v1
	v_pk_mul_f32 v[18:19], v[22:23], v[18:19]
	v_pk_mul_f32 v[22:23], v[24:25], v[28:29]
	v_pk_add_f32 v[0:1], v[0:1], 1.0 op_sel_hi:[1,0]
	s_nop 0
	v_div_scale_f32 v24, s[22:23], v1, v1, v21
	v_rcp_f32_e32 v25, v24
	s_nop 0
	v_fma_f32 v27, -v24, v25, 1.0
	v_fmac_f32_e32 v25, v27, v25
	v_div_scale_f32 v27, vcc, v21, v1, v21
	v_mul_f32_e32 v28, v27, v25
	v_fma_f32 v29, -v24, v28, v27
	v_fmac_f32_e32 v28, v29, v25
	v_fma_f32 v24, -v24, v28, v27
	v_div_fmas_f32 v24, v24, v25, v28
	v_div_fixup_f32 v1, v24, v1, v21
	v_div_scale_f32 v21, s[22:23], v0, v0, v26
	v_rcp_f32_e32 v24, v21
	s_nop 0
	v_fma_f32 v25, -v21, v24, 1.0
	v_fmac_f32_e32 v24, v25, v24
	v_div_scale_f32 v25, vcc, v26, v0, v26
	v_mul_f32_e32 v27, v25, v24
	v_fma_f32 v28, -v21, v27, v25
	v_fmac_f32_e32 v27, v28, v24
	v_fma_f32 v21, -v21, v27, v25
	v_div_fmas_f32 v21, v21, v24, v27
	v_div_fixup_f32 v0, v21, v0, v26
	v_and_b32_e32 v21, 0xffff0000, v2
	v_lshlrev_b32_e32 v2, 16, v2
	v_pk_mul_f32 v[0:1], v[22:23], v[0:1]
	v_mul_f32_e32 v22, 0xbfb8aa3b, v2
	v_mul_f32_e32 v8, 0xbfb8aa3b, v21
	v_exp_f32_e32 v22, v22
	v_exp_f32_e32 v23, v8
	s_nop 0
	v_pk_add_f32 v[8:9], v[22:23], 1.0 op_sel_hi:[1,0]
	s_nop 0
	v_div_scale_f32 v22, s[22:23], v9, v9, v21
	v_rcp_f32_e32 v23, v22
	s_nop 0
	v_fma_f32 v24, -v22, v23, 1.0
	v_fmac_f32_e32 v23, v24, v23
	v_div_scale_f32 v24, vcc, v21, v9, v21
	v_mul_f32_e32 v25, v24, v23
	v_fma_f32 v26, -v22, v25, v24
	v_fmac_f32_e32 v25, v26, v23
	v_fma_f32 v22, -v22, v25, v24
	v_div_fmas_f32 v22, v22, v23, v25
	v_div_fixup_f32 v9, v22, v9, v21
	v_div_scale_f32 v21, s[22:23], v8, v8, v2
	v_rcp_f32_e32 v22, v21
	s_nop 0
	v_fma_f32 v23, -v21, v22, 1.0
	v_fmac_f32_e32 v22, v23, v22
	v_div_scale_f32 v23, vcc, v2, v8, v2
	v_mul_f32_e32 v24, v23, v22
	v_fma_f32 v25, -v21, v24, v23
	v_fmac_f32_e32 v24, v25, v22
	v_fma_f32 v21, -v21, v24, v23
	v_div_fmas_f32 v21, v21, v22, v24
	v_div_fixup_f32 v8, v21, v8, v2
	v_pk_mul_f32 v[4:5], v[8:9], v[4:5]
	v_and_b32_e32 v8, 0xffff0000, v3
	v_lshlrev_b32_e32 v9, 16, v3
	v_mul_f32_e32 v2, 0xbfb8aa3b, v9
	v_mul_f32_e32 v3, 0xbfb8aa3b, v8
	v_exp_f32_e32 v2, v2
	v_exp_f32_e32 v3, v3
	s_nop 0
	v_pk_add_f32 v[2:3], v[2:3], 1.0 op_sel_hi:[1,0]
	s_nop 0
	v_div_scale_f32 v10, s[22:23], v3, v3, v8
	v_rcp_f32_e32 v11, v10
	s_nop 0
	v_fma_f32 v21, -v10, v11, 1.0
	v_fmac_f32_e32 v11, v21, v11
	v_div_scale_f32 v21, vcc, v8, v3, v8
	v_mul_f32_e32 v22, v21, v11
	v_fma_f32 v23, -v10, v22, v21
	v_fmac_f32_e32 v22, v23, v11
	v_fma_f32 v10, -v10, v22, v21
	v_div_fmas_f32 v10, v10, v11, v22
	v_div_fixup_f32 v3, v10, v3, v8
	v_div_scale_f32 v8, s[22:23], v2, v2, v9
	v_rcp_f32_e32 v10, v8
	s_nop 0
	v_fma_f32 v11, -v8, v10, 1.0
	v_fmac_f32_e32 v10, v11, v10
	v_div_scale_f32 v11, vcc, v9, v2, v9
	v_mul_f32_e32 v21, v11, v10
	v_fma_f32 v22, -v8, v21, v11
	v_fmac_f32_e32 v21, v22, v10
	v_fma_f32 v8, -v8, v21, v11
	v_div_fmas_f32 v8, v8, v10, v21
	v_div_fixup_f32 v2, v8, v2, v9
	v_pk_mul_f32 v[2:3], v[2:3], v[6:7]
	v_cvt_pk_bf16_f32 v4, v4, v5
	v_cvt_pk_bf16_f32 v2, v2, v3
	v_mov_b32_e32 v3, v2
	v_mov_b32_e32 v2, v4
	v_lshlrev_b64 v[4:5], 12, v[16:17]
	v_lshl_add_u64 v[4:5], s[30:31], 0, v[4:5]
	v_lshl_add_u64 v[4:5], v[4:5], 0, s[70:71]
	v_lshl_add_u64 v[4:5], v[4:5], 0, v[160:161]
	v_cvt_pk_bf16_f32 v18, v18, v19
	v_cvt_pk_bf16_f32 v0, v0, v1
	v_add_co_u32_e32 v4, vcc, s21, v4
	v_mov_b32_e32 v1, v0
	v_mov_b32_e32 v0, v18
	v_addc_co_u32_e32 v5, vcc, 0, v5, vcc
	v_add_u32_e32 v16, s20, v180
	global_store_dwordx4 v[4:5], v[0:3], off offset:2048
	v_mul_lo_u32 v4, v180, s52
	v_add3_u32 v4, s17, v4, v20
	v_mad_i64_i32 v[0:1], s[22:23], v16, s0, v[14:15]
	v_lshl_add_u64 v[0:1], v[0:1], 0, s[70:71]
	v_lshl_add_u64 v[0:1], v[0:1], 0, v[160:161]
	v_add_co_u32_e32 v0, vcc, s3, v0
	v_ashrrev_i32_e32 v17, 31, v16
	s_nop 0
	v_addc_co_u32_e32 v1, vcc, 0, v1, vcc
	global_load_dwordx4 v[0:3], v[0:1], off
	s_waitcnt vmcnt(0)
	v_and_b32_e32 v21, 0xffff0000, v0
	v_lshlrev_b32_e32 v0, 16, v0
	v_mul_f32_e32 v5, 0xbfb8aa3b, v0
	v_exp_f32_e32 v18, v5
	ds_read_b128 v[22:25], v4
	ds_read_b128 v[4:7], v4 offset:16
	global_load_dwordx4 v[8:11], v[12:13], off offset:16
	global_load_dwordx4 v[26:29], v[12:13], off
	v_mul_f32_e32 v19, 0xbfb8aa3b, v21
	v_exp_f32_e32 v19, v19
	s_waitcnt vmcnt(1) lgkmcnt(0)
	v_pk_mul_f32 v[4:5], v[4:5], v[8:9]
	v_pk_add_f32 v[18:19], v[18:19], 1.0 op_sel_hi:[1,0]
	s_waitcnt vmcnt(0)
	v_pk_mul_f32 v[22:23], v[22:23], v[26:27]
	v_div_scale_f32 v26, s[22:23], v19, v19, v21
	v_rcp_f32_e32 v27, v26
	v_pk_mul_f32 v[6:7], v[6:7], v[10:11]
	v_fma_f32 v30, -v26, v27, 1.0
	v_fmac_f32_e32 v27, v30, v27
	v_div_scale_f32 v30, vcc, v21, v19, v21
	v_mul_f32_e32 v31, v30, v27
	v_fma_f32 v32, -v26, v31, v30
	v_fmac_f32_e32 v31, v32, v27
	v_fma_f32 v26, -v26, v31, v30
	v_div_fmas_f32 v26, v26, v27, v31
	v_div_fixup_f32 v19, v26, v19, v21
	v_div_scale_f32 v21, s[22:23], v18, v18, v0
	v_rcp_f32_e32 v26, v21
	s_nop 0
	v_fma_f32 v27, -v21, v26, 1.0
	v_fmac_f32_e32 v26, v27, v26
	v_div_scale_f32 v27, vcc, v0, v18, v0
	v_mul_f32_e32 v30, v27, v26
	v_fma_f32 v31, -v21, v30, v27
	v_fmac_f32_e32 v30, v31, v26
	v_fma_f32 v21, -v21, v30, v27
	v_div_fmas_f32 v21, v21, v26, v30
	v_div_fixup_f32 v18, v21, v18, v0
	v_and_b32_e32 v21, 0xffff0000, v1
	v_lshlrev_b32_e32 v26, 16, v1
	v_mul_f32_e32 v0, 0xbfb8aa3b, v26
	v_mul_f32_e32 v1, 0xbfb8aa3b, v21
	v_exp_f32_e32 v0, v0
	v_exp_f32_e32 v1, v1
	v_pk_mul_f32 v[18:19], v[22:23], v[18:19]
	v_pk_mul_f32 v[22:23], v[24:25], v[28:29]
	v_pk_add_f32 v[0:1], v[0:1], 1.0 op_sel_hi:[1,0]
	s_nop 0
	v_div_scale_f32 v24, s[22:23], v1, v1, v21
	v_rcp_f32_e32 v25, v24
	s_nop 0
	v_fma_f32 v27, -v24, v25, 1.0
	v_fmac_f32_e32 v25, v27, v25
	v_div_scale_f32 v27, vcc, v21, v1, v21
	v_mul_f32_e32 v28, v27, v25
	v_fma_f32 v29, -v24, v28, v27
	v_fmac_f32_e32 v28, v29, v25
	v_fma_f32 v24, -v24, v28, v27
	v_div_fmas_f32 v24, v24, v25, v28
	v_div_fixup_f32 v1, v24, v1, v21
	v_div_scale_f32 v21, s[22:23], v0, v0, v26
	v_rcp_f32_e32 v24, v21
	s_nop 0
	v_fma_f32 v25, -v21, v24, 1.0
	v_fmac_f32_e32 v24, v25, v24
	v_div_scale_f32 v25, vcc, v26, v0, v26
	v_mul_f32_e32 v27, v25, v24
	v_fma_f32 v28, -v21, v27, v25
	v_fmac_f32_e32 v27, v28, v24
	v_fma_f32 v21, -v21, v27, v25
	v_div_fmas_f32 v21, v21, v24, v27
	v_div_fixup_f32 v0, v21, v0, v26
	v_and_b32_e32 v21, 0xffff0000, v2
	v_lshlrev_b32_e32 v2, 16, v2
	v_pk_mul_f32 v[0:1], v[22:23], v[0:1]
	v_mul_f32_e32 v22, 0xbfb8aa3b, v2
	v_mul_f32_e32 v8, 0xbfb8aa3b, v21
	v_exp_f32_e32 v22, v22
	v_exp_f32_e32 v23, v8
	s_nop 0
	v_pk_add_f32 v[8:9], v[22:23], 1.0 op_sel_hi:[1,0]
	s_nop 0
	v_div_scale_f32 v22, s[22:23], v9, v9, v21
	v_rcp_f32_e32 v23, v22
	s_nop 0
	v_fma_f32 v24, -v22, v23, 1.0
	v_fmac_f32_e32 v23, v24, v23
	v_div_scale_f32 v24, vcc, v21, v9, v21
	v_mul_f32_e32 v25, v24, v23
	v_fma_f32 v26, -v22, v25, v24
	v_fmac_f32_e32 v25, v26, v23
	v_fma_f32 v22, -v22, v25, v24
	v_div_fmas_f32 v22, v22, v23, v25
	v_div_fixup_f32 v9, v22, v9, v21
	v_div_scale_f32 v21, s[22:23], v8, v8, v2
	v_rcp_f32_e32 v22, v21
	s_nop 0
	v_fma_f32 v23, -v21, v22, 1.0
	v_fmac_f32_e32 v22, v23, v22
	v_div_scale_f32 v23, vcc, v2, v8, v2
	v_mul_f32_e32 v24, v23, v22
	v_fma_f32 v25, -v21, v24, v23
	v_fmac_f32_e32 v24, v25, v22
	v_fma_f32 v21, -v21, v24, v23
	v_div_fmas_f32 v21, v21, v22, v24
	v_div_fixup_f32 v8, v21, v8, v2
	v_pk_mul_f32 v[4:5], v[8:9], v[4:5]
	v_and_b32_e32 v8, 0xffff0000, v3
	v_lshlrev_b32_e32 v9, 16, v3
	v_mul_f32_e32 v2, 0xbfb8aa3b, v9
	v_mul_f32_e32 v3, 0xbfb8aa3b, v8
	v_exp_f32_e32 v2, v2
	v_exp_f32_e32 v3, v3
	s_nop 0
	v_pk_add_f32 v[2:3], v[2:3], 1.0 op_sel_hi:[1,0]
	s_nop 0
	v_div_scale_f32 v10, s[22:23], v3, v3, v8
	v_rcp_f32_e32 v11, v10
	s_nop 0
	v_fma_f32 v21, -v10, v11, 1.0
	v_fmac_f32_e32 v11, v21, v11
	v_div_scale_f32 v21, vcc, v8, v3, v8
	v_mul_f32_e32 v22, v21, v11
	v_fma_f32 v23, -v10, v22, v21
	v_fmac_f32_e32 v22, v23, v11
	v_fma_f32 v10, -v10, v22, v21
	v_div_fmas_f32 v10, v10, v11, v22
	v_div_fixup_f32 v3, v10, v3, v8
	v_div_scale_f32 v8, s[22:23], v2, v2, v9
	v_rcp_f32_e32 v10, v8
	s_nop 0
	v_fma_f32 v11, -v8, v10, 1.0
	v_fmac_f32_e32 v10, v11, v10
	v_div_scale_f32 v11, vcc, v9, v2, v9
	v_mul_f32_e32 v21, v11, v10
	v_fma_f32 v22, -v8, v21, v11
	v_fmac_f32_e32 v21, v22, v10
	v_fma_f32 v8, -v8, v21, v11
	v_div_fmas_f32 v8, v8, v10, v21
	v_div_fixup_f32 v2, v8, v2, v9
	v_pk_mul_f32 v[2:3], v[2:3], v[6:7]
	v_cvt_pk_bf16_f32 v4, v4, v5
	v_cvt_pk_bf16_f32 v2, v2, v3
	v_mov_b32_e32 v3, v2
	v_mov_b32_e32 v2, v4
	v_lshlrev_b64 v[4:5], 12, v[16:17]
	v_lshl_add_u64 v[4:5], s[30:31], 0, v[4:5]
	v_lshl_add_u64 v[4:5], v[4:5], 0, s[70:71]
	v_lshl_add_u64 v[4:5], v[4:5], 0, v[160:161]
	v_cvt_pk_bf16_f32 v18, v18, v19
	v_cvt_pk_bf16_f32 v0, v0, v1
	v_add_co_u32_e32 v4, vcc, s21, v4
	v_mov_b32_e32 v1, v0
	v_mov_b32_e32 v0, v18
	v_addc_co_u32_e32 v5, vcc, 0, v5, vcc
	v_add_u32_e32 v16, s20, v179
	global_store_dwordx4 v[4:5], v[0:3], off offset:2048
	v_mul_lo_u32 v4, v179, s52
	v_add3_u32 v4, s17, v4, v20
	v_mad_i64_i32 v[0:1], s[22:23], v16, s0, v[14:15]
	v_lshl_add_u64 v[0:1], v[0:1], 0, s[70:71]
	v_lshl_add_u64 v[0:1], v[0:1], 0, v[160:161]
	v_add_co_u32_e32 v0, vcc, s3, v0
	v_ashrrev_i32_e32 v17, 31, v16
	s_nop 0
	v_addc_co_u32_e32 v1, vcc, 0, v1, vcc
	global_load_dwordx4 v[0:3], v[0:1], off
	s_waitcnt vmcnt(0)
	v_and_b32_e32 v21, 0xffff0000, v0
	v_lshlrev_b32_e32 v0, 16, v0
	v_mul_f32_e32 v5, 0xbfb8aa3b, v0
	v_exp_f32_e32 v18, v5
	ds_read_b128 v[22:25], v4
	ds_read_b128 v[4:7], v4 offset:16
	global_load_dwordx4 v[8:11], v[12:13], off offset:16
	global_load_dwordx4 v[26:29], v[12:13], off
	v_mul_f32_e32 v19, 0xbfb8aa3b, v21
	v_exp_f32_e32 v19, v19
	s_waitcnt vmcnt(1) lgkmcnt(0)
	v_pk_mul_f32 v[4:5], v[4:5], v[8:9]
	v_pk_add_f32 v[18:19], v[18:19], 1.0 op_sel_hi:[1,0]
	s_waitcnt vmcnt(0)
	v_pk_mul_f32 v[22:23], v[22:23], v[26:27]
	v_div_scale_f32 v26, s[22:23], v19, v19, v21
	v_rcp_f32_e32 v27, v26
	v_pk_mul_f32 v[6:7], v[6:7], v[10:11]
	v_fma_f32 v30, -v26, v27, 1.0
	v_fmac_f32_e32 v27, v30, v27
	v_div_scale_f32 v30, vcc, v21, v19, v21
	v_mul_f32_e32 v31, v30, v27
	v_fma_f32 v32, -v26, v31, v30
	v_fmac_f32_e32 v31, v32, v27
	v_fma_f32 v26, -v26, v31, v30
	v_div_fmas_f32 v26, v26, v27, v31
	v_div_fixup_f32 v19, v26, v19, v21
	v_div_scale_f32 v21, s[22:23], v18, v18, v0
	v_rcp_f32_e32 v26, v21
	s_nop 0
	v_fma_f32 v27, -v21, v26, 1.0
	v_fmac_f32_e32 v26, v27, v26
	v_div_scale_f32 v27, vcc, v0, v18, v0
	v_mul_f32_e32 v30, v27, v26
	v_fma_f32 v31, -v21, v30, v27
	v_fmac_f32_e32 v30, v31, v26
	v_fma_f32 v21, -v21, v30, v27
	v_div_fmas_f32 v21, v21, v26, v30
	v_div_fixup_f32 v18, v21, v18, v0
	v_and_b32_e32 v21, 0xffff0000, v1
	v_lshlrev_b32_e32 v26, 16, v1
	v_mul_f32_e32 v0, 0xbfb8aa3b, v26
	v_mul_f32_e32 v1, 0xbfb8aa3b, v21
	v_exp_f32_e32 v0, v0
	v_exp_f32_e32 v1, v1
	v_pk_mul_f32 v[18:19], v[22:23], v[18:19]
	v_pk_mul_f32 v[22:23], v[24:25], v[28:29]
	v_pk_add_f32 v[0:1], v[0:1], 1.0 op_sel_hi:[1,0]
	s_nop 0
	v_div_scale_f32 v24, s[22:23], v1, v1, v21
	v_rcp_f32_e32 v25, v24
	s_nop 0
	v_fma_f32 v27, -v24, v25, 1.0
	v_fmac_f32_e32 v25, v27, v25
	v_div_scale_f32 v27, vcc, v21, v1, v21
	v_mul_f32_e32 v28, v27, v25
	v_fma_f32 v29, -v24, v28, v27
	v_fmac_f32_e32 v28, v29, v25
	v_fma_f32 v24, -v24, v28, v27
	v_div_fmas_f32 v24, v24, v25, v28
	v_div_fixup_f32 v1, v24, v1, v21
	v_div_scale_f32 v21, s[22:23], v0, v0, v26
	v_rcp_f32_e32 v24, v21
	s_nop 0
	v_fma_f32 v25, -v21, v24, 1.0
	v_fmac_f32_e32 v24, v25, v24
	v_div_scale_f32 v25, vcc, v26, v0, v26
	v_mul_f32_e32 v27, v25, v24
	v_fma_f32 v28, -v21, v27, v25
	v_fmac_f32_e32 v27, v28, v24
	v_fma_f32 v21, -v21, v27, v25
	v_div_fmas_f32 v21, v21, v24, v27
	v_div_fixup_f32 v0, v21, v0, v26
	v_and_b32_e32 v21, 0xffff0000, v2
	v_lshlrev_b32_e32 v2, 16, v2
	v_pk_mul_f32 v[0:1], v[22:23], v[0:1]
	v_mul_f32_e32 v22, 0xbfb8aa3b, v2
	v_mul_f32_e32 v8, 0xbfb8aa3b, v21
	v_exp_f32_e32 v22, v22
	v_exp_f32_e32 v23, v8
	s_nop 0
	v_pk_add_f32 v[8:9], v[22:23], 1.0 op_sel_hi:[1,0]
	s_nop 0
	v_div_scale_f32 v22, s[22:23], v9, v9, v21
	v_rcp_f32_e32 v23, v22
	s_nop 0
	v_fma_f32 v24, -v22, v23, 1.0
	v_fmac_f32_e32 v23, v24, v23
	v_div_scale_f32 v24, vcc, v21, v9, v21
	v_mul_f32_e32 v25, v24, v23
	v_fma_f32 v26, -v22, v25, v24
	v_fmac_f32_e32 v25, v26, v23
	v_fma_f32 v22, -v22, v25, v24
	v_div_fmas_f32 v22, v22, v23, v25
	v_div_fixup_f32 v9, v22, v9, v21
	v_div_scale_f32 v21, s[22:23], v8, v8, v2
	v_rcp_f32_e32 v22, v21
	s_nop 0
	v_fma_f32 v23, -v21, v22, 1.0
	v_fmac_f32_e32 v22, v23, v22
	v_div_scale_f32 v23, vcc, v2, v8, v2
	v_mul_f32_e32 v24, v23, v22
	v_fma_f32 v25, -v21, v24, v23
	v_fmac_f32_e32 v24, v25, v22
	v_fma_f32 v21, -v21, v24, v23
	v_div_fmas_f32 v21, v21, v22, v24
	v_div_fixup_f32 v8, v21, v8, v2
	v_pk_mul_f32 v[4:5], v[8:9], v[4:5]
	v_and_b32_e32 v8, 0xffff0000, v3
	v_lshlrev_b32_e32 v9, 16, v3
	v_mul_f32_e32 v2, 0xbfb8aa3b, v9
	v_mul_f32_e32 v3, 0xbfb8aa3b, v8
	v_exp_f32_e32 v2, v2
	v_exp_f32_e32 v3, v3
	s_nop 0
	v_pk_add_f32 v[2:3], v[2:3], 1.0 op_sel_hi:[1,0]
	s_nop 0
	v_div_scale_f32 v10, s[22:23], v3, v3, v8
	v_rcp_f32_e32 v11, v10
	s_nop 0
	v_fma_f32 v21, -v10, v11, 1.0
	v_fmac_f32_e32 v11, v21, v11
	v_div_scale_f32 v21, vcc, v8, v3, v8
	v_mul_f32_e32 v22, v21, v11
	v_fma_f32 v23, -v10, v22, v21
	v_fmac_f32_e32 v22, v23, v11
	v_fma_f32 v10, -v10, v22, v21
	v_div_fmas_f32 v10, v10, v11, v22
	v_div_fixup_f32 v3, v10, v3, v8
	v_div_scale_f32 v8, s[22:23], v2, v2, v9
	v_rcp_f32_e32 v10, v8
	s_nop 0
	v_fma_f32 v11, -v8, v10, 1.0
	v_fmac_f32_e32 v10, v11, v10
	v_div_scale_f32 v11, vcc, v9, v2, v9
	v_mul_f32_e32 v21, v11, v10
	v_fma_f32 v22, -v8, v21, v11
	v_fmac_f32_e32 v21, v22, v10
	v_fma_f32 v8, -v8, v21, v11
	v_div_fmas_f32 v8, v8, v10, v21
	v_div_fixup_f32 v2, v8, v2, v9
	v_pk_mul_f32 v[2:3], v[2:3], v[6:7]
	v_cvt_pk_bf16_f32 v4, v4, v5
	v_cvt_pk_bf16_f32 v2, v2, v3
	v_mov_b32_e32 v3, v2
	v_mov_b32_e32 v2, v4
	v_lshlrev_b64 v[4:5], 12, v[16:17]
	v_lshl_add_u64 v[4:5], s[30:31], 0, v[4:5]
	v_lshl_add_u64 v[4:5], v[4:5], 0, s[70:71]
	v_lshl_add_u64 v[4:5], v[4:5], 0, v[160:161]
	v_cvt_pk_bf16_f32 v18, v18, v19
	v_cvt_pk_bf16_f32 v0, v0, v1
	v_add_co_u32_e32 v4, vcc, s21, v4
	v_mov_b32_e32 v1, v0
	v_mov_b32_e32 v0, v18
	v_addc_co_u32_e32 v5, vcc, 0, v5, vcc
	v_add_u32_e32 v16, s20, v178
	global_store_dwordx4 v[4:5], v[0:3], off offset:2048
	v_mul_lo_u32 v4, v178, s52
	v_add3_u32 v4, s17, v4, v20
	v_mad_i64_i32 v[0:1], s[20:21], v16, s0, v[14:15]
	v_lshl_add_u64 v[0:1], v[0:1], 0, s[70:71]
	v_lshl_add_u64 v[0:1], v[0:1], 0, v[160:161]
	v_add_co_u32_e32 v0, vcc, s3, v0
	v_ashrrev_i32_e32 v17, 31, v16
	s_nop 0
	v_addc_co_u32_e32 v1, vcc, 0, v1, vcc
	global_load_dwordx4 v[0:3], v[0:1], off
	s_waitcnt vmcnt(0)
	v_and_b32_e32 v24, 0xffff0000, v0
	v_lshlrev_b32_e32 v0, 16, v0
	v_mul_f32_e32 v5, 0xbfb8aa3b, v0
	v_exp_f32_e32 v22, v5
	ds_read_b128 v[18:21], v4
	ds_read_b128 v[4:7], v4 offset:16
	global_load_dwordx4 v[8:11], v[12:13], off offset:16
	s_nop 0
	global_load_dwordx4 v[12:15], v[12:13], off
	s_waitcnt vmcnt(1) lgkmcnt(0)
	v_pk_mul_f32 v[4:5], v[4:5], v[8:9]
	s_waitcnt vmcnt(0)
	v_pk_mul_f32 v[12:13], v[18:19], v[12:13]
	v_mul_f32_e32 v18, 0xbfb8aa3b, v24
	v_exp_f32_e32 v23, v18
	v_pk_mul_f32 v[14:15], v[20:21], v[14:15]
	v_pk_mul_f32 v[6:7], v[6:7], v[10:11]
	v_pk_add_f32 v[18:19], v[22:23], 1.0 op_sel_hi:[1,0]
	s_nop 0
	v_div_scale_f32 v22, s[20:21], v19, v19, v24
	v_rcp_f32_e32 v23, v22
	s_nop 0
	v_fma_f32 v25, -v22, v23, 1.0
	v_fmac_f32_e32 v23, v25, v23
	v_div_scale_f32 v25, vcc, v24, v19, v24
	v_mul_f32_e32 v26, v25, v23
	v_fma_f32 v27, -v22, v26, v25
	v_fmac_f32_e32 v26, v27, v23
	v_fma_f32 v22, -v22, v26, v25
	v_div_fmas_f32 v22, v22, v23, v26
	v_div_fixup_f32 v19, v22, v19, v24
	v_div_scale_f32 v22, s[20:21], v18, v18, v0
	v_rcp_f32_e32 v23, v22
	s_nop 0
	v_fma_f32 v24, -v22, v23, 1.0
	v_fmac_f32_e32 v23, v24, v23
	v_div_scale_f32 v24, vcc, v0, v18, v0
	v_mul_f32_e32 v25, v24, v23
	v_fma_f32 v26, -v22, v25, v24
	v_fmac_f32_e32 v25, v26, v23
	v_fma_f32 v22, -v22, v25, v24
	v_div_fmas_f32 v22, v22, v23, v25
	v_div_fixup_f32 v18, v22, v18, v0
	v_pk_mul_f32 v[12:13], v[12:13], v[18:19]
	v_and_b32_e32 v18, 0xffff0000, v1
	v_lshlrev_b32_e32 v19, 16, v1
	v_mul_f32_e32 v0, 0xbfb8aa3b, v19
	v_mul_f32_e32 v1, 0xbfb8aa3b, v18
	v_exp_f32_e32 v0, v0
	v_exp_f32_e32 v1, v1
	s_nop 0
	v_pk_add_f32 v[0:1], v[0:1], 1.0 op_sel_hi:[1,0]
	s_nop 0
	v_div_scale_f32 v20, s[20:21], v1, v1, v18
	v_rcp_f32_e32 v21, v20
	s_nop 0
	v_fma_f32 v22, -v20, v21, 1.0
	v_fmac_f32_e32 v21, v22, v21
	v_div_scale_f32 v22, vcc, v18, v1, v18
	v_mul_f32_e32 v23, v22, v21
	v_fma_f32 v24, -v20, v23, v22
	v_fmac_f32_e32 v23, v24, v21
	v_fma_f32 v20, -v20, v23, v22
	v_div_fmas_f32 v20, v20, v21, v23
	v_div_fixup_f32 v1, v20, v1, v18
	v_div_scale_f32 v18, s[20:21], v0, v0, v19
	v_rcp_f32_e32 v20, v18
	s_nop 0
	v_fma_f32 v21, -v18, v20, 1.0
	v_fmac_f32_e32 v20, v21, v20
	v_div_scale_f32 v21, vcc, v19, v0, v19
	v_mul_f32_e32 v22, v21, v20
	v_fma_f32 v23, -v18, v22, v21
	v_fmac_f32_e32 v22, v23, v20
	v_fma_f32 v18, -v18, v22, v21
	v_div_fmas_f32 v18, v18, v20, v22
	v_div_fixup_f32 v0, v18, v0, v19
	v_and_b32_e32 v18, 0xffff0000, v2
	v_lshlrev_b32_e32 v2, 16, v2
	v_pk_mul_f32 v[0:1], v[14:15], v[0:1]
	v_mul_f32_e32 v14, 0xbfb8aa3b, v2
	v_mul_f32_e32 v8, 0xbfb8aa3b, v18
	v_exp_f32_e32 v14, v14
	v_exp_f32_e32 v15, v8
	s_nop 0
	v_pk_add_f32 v[8:9], v[14:15], 1.0 op_sel_hi:[1,0]
	s_nop 0
	v_div_scale_f32 v14, s[20:21], v9, v9, v18
	v_rcp_f32_e32 v15, v14
	s_nop 0
	v_fma_f32 v19, -v14, v15, 1.0
	v_fmac_f32_e32 v15, v19, v15
	v_div_scale_f32 v19, vcc, v18, v9, v18
	v_mul_f32_e32 v20, v19, v15
	v_fma_f32 v21, -v14, v20, v19
	v_fmac_f32_e32 v20, v21, v15
	v_fma_f32 v14, -v14, v20, v19
	v_div_fmas_f32 v14, v14, v15, v20
	v_div_fixup_f32 v9, v14, v9, v18
	v_div_scale_f32 v14, s[20:21], v8, v8, v2
	v_rcp_f32_e32 v15, v14
	s_nop 0
	v_fma_f32 v18, -v14, v15, 1.0
	v_fmac_f32_e32 v15, v18, v15
	v_div_scale_f32 v18, vcc, v2, v8, v2
	v_mul_f32_e32 v19, v18, v15
	v_fma_f32 v20, -v14, v19, v18
	v_fmac_f32_e32 v19, v20, v15
	v_fma_f32 v14, -v14, v19, v18
	v_div_fmas_f32 v14, v14, v15, v19
	v_div_fixup_f32 v8, v14, v8, v2
	v_pk_mul_f32 v[4:5], v[8:9], v[4:5]
	v_and_b32_e32 v8, 0xffff0000, v3
	v_lshlrev_b32_e32 v9, 16, v3
	v_mul_f32_e32 v2, 0xbfb8aa3b, v9
	v_mul_f32_e32 v3, 0xbfb8aa3b, v8
	v_exp_f32_e32 v2, v2
	v_exp_f32_e32 v3, v3
	s_nop 0
	v_pk_add_f32 v[2:3], v[2:3], 1.0 op_sel_hi:[1,0]
	s_nop 0
	v_div_scale_f32 v10, s[20:21], v3, v3, v8
	v_rcp_f32_e32 v11, v10
	s_nop 0
	v_fma_f32 v14, -v10, v11, 1.0
	v_fmac_f32_e32 v11, v14, v11
	v_div_scale_f32 v14, vcc, v8, v3, v8
	v_mul_f32_e32 v15, v14, v11
	v_fma_f32 v18, -v10, v15, v14
	v_fmac_f32_e32 v15, v18, v11
	v_fma_f32 v10, -v10, v15, v14
	v_div_fmas_f32 v10, v10, v11, v15
	v_div_fixup_f32 v3, v10, v3, v8
	v_div_scale_f32 v8, s[20:21], v2, v2, v9
	v_rcp_f32_e32 v10, v8
	s_nop 0
	v_fma_f32 v11, -v8, v10, 1.0
	v_fmac_f32_e32 v10, v11, v10
	v_div_scale_f32 v11, vcc, v9, v2, v9
	v_mul_f32_e32 v14, v11, v10
	v_fma_f32 v15, -v8, v14, v11
	v_fmac_f32_e32 v14, v15, v10
	v_fma_f32 v8, -v8, v14, v11
	v_div_fmas_f32 v8, v8, v10, v14
	v_div_fixup_f32 v2, v8, v2, v9
	v_pk_mul_f32 v[2:3], v[2:3], v[6:7]
	v_cvt_pk_bf16_f32 v4, v4, v5
	v_cvt_pk_bf16_f32 v2, v2, v3
	v_mov_b32_e32 v3, v2
	v_mov_b32_e32 v2, v4
	v_lshlrev_b64 v[4:5], 12, v[16:17]
	v_lshl_add_u64 v[4:5], s[30:31], 0, v[4:5]
	v_lshl_add_u64 v[4:5], v[4:5], 0, s[70:71]
	v_lshl_add_u64 v[4:5], v[4:5], 0, v[160:161]
	v_cvt_pk_bf16_f32 v12, v12, v13
	v_cvt_pk_bf16_f32 v0, v0, v1
	v_add_co_u32_e32 v4, vcc, 0xcc00000, v4
	v_mov_b32_e32 v1, v0
	v_mov_b32_e32 v0, v12
	v_addc_co_u32_e32 v5, vcc, 0, v5, vcc
	global_store_dwordx4 v[4:5], v[0:3], off offset:2048
	s_barrier

.LBB0_726:
	s_or_b64 exec, exec, s[50:51]
	v_ashrrev_i32_e32 v21, 31, v20
	v_lshl_add_u64 v[20:21], v[20:21], 2, s[26:27]
	global_load_dword v24, v[20:21], off
	s_movk_i32 s50, 0xfee0
	v_mov_b32_e32 v44, v41
	v_mov_b32_e32 v19, v18
	v_mov_b32_e32 v20, v18
	v_mov_b32_e32 v21, v18
	v_mov_b32_e32 v156, v44
	v_add_lshl_u32 v155, v35, s50, 1
	v_and_b32_e32 v155, -4, v155
	v_add_u32_e32 v155, v25, v155
	v_add_u32_e32 v154, 0x8260, v155
	ds_read_b128 v[236:239], v156
	ds_read2_b32 v[204:205], v154 offset1:1
	ds_read2_b32 v[206:207], v154 offset0:2 offset1:3
	ds_read_b32 v208, v154 offset:16
	ds_read_b128 v[240:243], v156 offset:64
	ds_read2_b32 v[210:211], v154 offset0:16 offset1:17
	ds_read2_b32 v[212:213], v154 offset0:18 offset1:19
	ds_read_b32 v214, v154 offset:80
	ds_read_b128 v[244:247], v156 offset:128
	ds_read2_b32 v[216:217], v154 offset0:32 offset1:33
	ds_read2_b32 v[218:219], v154 offset0:34 offset1:35
	ds_read_b32 v220, v154 offset:144
	ds_read_b128 v[144:147], v156 offset:192
	ds_read2_b32 v[222:223], v154 offset0:48 offset1:49
	ds_read2_b32 v[224:225], v154 offset0:50 offset1:51
	ds_read_b32 v226, v154 offset:208
	s_waitcnt lgkmcnt(12)
	v_alignbyte_b32 v228, v205, v204, v36
	v_alignbyte_b32 v229, v206, v205, v36
	v_alignbyte_b32 v230, v207, v206, v36
	v_alignbyte_b32 v231, v208, v207, v36
	ds_read2_b32 v[204:205], v154 offset0:64 offset1:65
	ds_read2_b32 v[206:207], v154 offset0:66 offset1:67
	ds_read_b32 v208, v154 offset:272
	v_mfma_f32_16x16x32_bf16 v[18:21], v[228:231], v[236:239], v[18:21]
	ds_read_b128 v[236:239], v156 offset:256
	s_waitcnt lgkmcnt(12)
	v_alignbyte_b32 v232, v211, v210, v36
	v_alignbyte_b32 v233, v212, v211, v36
	v_alignbyte_b32 v234, v213, v212, v36
	v_alignbyte_b32 v235, v214, v213, v36
	ds_read2_b32 v[210:211], v154 offset0:80 offset1:81
	ds_read2_b32 v[212:213], v154 offset0:82 offset1:83
	ds_read_b32 v214, v154 offset:336
	v_mfma_f32_16x16x32_bf16 v[18:21], v[232:235], v[240:243], v[18:21]
	ds_read_b128 v[240:243], v156 offset:320
	s_waitcnt lgkmcnt(12)
	v_alignbyte_b32 v228, v217, v216, v36
	v_alignbyte_b32 v229, v218, v217, v36
	v_alignbyte_b32 v230, v219, v218, v36
	v_alignbyte_b32 v231, v220, v219, v36
	ds_read2_b32 v[216:217], v154 offset0:96 offset1:97
	ds_read2_b32 v[218:219], v154 offset0:98 offset1:99
	ds_read_b32 v220, v154 offset:400
	v_mfma_f32_16x16x32_bf16 v[18:21], v[228:231], v[244:247], v[18:21]
	ds_read_b128 v[244:247], v156 offset:384
	s_waitcnt lgkmcnt(12)
	v_alignbyte_b32 v232, v223, v222, v36
	v_alignbyte_b32 v233, v224, v223, v36
	v_alignbyte_b32 v234, v225, v224, v36
	v_alignbyte_b32 v235, v226, v225, v36
	ds_read2_b32 v[222:223], v154 offset0:112 offset1:113
	ds_read2_b32 v[224:225], v154 offset0:114 offset1:115
	ds_read_b32 v226, v154 offset:464
	v_mfma_f32_16x16x32_bf16 v[18:21], v[232:235], v[144:147], v[18:21]
	ds_read_b128 v[144:147], v156 offset:448
	s_waitcnt lgkmcnt(12)
	v_alignbyte_b32 v228, v205, v204, v36
	v_alignbyte_b32 v229, v206, v205, v36
	v_alignbyte_b32 v230, v207, v206, v36
	v_alignbyte_b32 v231, v208, v207, v36
	ds_read2_b32 v[204:205], v154 offset0:128 offset1:129
	ds_read2_b32 v[206:207], v154 offset0:130 offset1:131
	ds_read_b32 v208, v154 offset:528
	v_mfma_f32_16x16x32_bf16 v[18:21], v[228:231], v[236:239], v[18:21]
	ds_read_b128 v[236:239], v156 offset:512
	s_waitcnt lgkmcnt(12)
	v_alignbyte_b32 v232, v211, v210, v36
	v_alignbyte_b32 v233, v212, v211, v36
	v_alignbyte_b32 v234, v213, v212, v36
	v_alignbyte_b32 v235, v214, v213, v36
	ds_read2_b32 v[210:211], v154 offset0:144 offset1:145
	ds_read2_b32 v[212:213], v154 offset0:146 offset1:147
	ds_read_b32 v214, v154 offset:592
	v_mfma_f32_16x16x32_bf16 v[18:21], v[232:235], v[240:243], v[18:21]
	ds_read_b128 v[240:243], v156 offset:576
	s_waitcnt lgkmcnt(12)
	v_alignbyte_b32 v228, v217, v216, v36
	v_alignbyte_b32 v229, v218, v217, v36
	v_alignbyte_b32 v230, v219, v218, v36
	v_alignbyte_b32 v231, v220, v219, v36
	ds_read2_b32 v[216:217], v154 offset0:160 offset1:161
	ds_read2_b32 v[218:219], v154 offset0:162 offset1:163
	ds_read_b32 v220, v154 offset:656
	v_mfma_f32_16x16x32_bf16 v[18:21], v[228:231], v[244:247], v[18:21]
	ds_read_b128 v[244:247], v156 offset:640
	s_waitcnt lgkmcnt(12)
	v_alignbyte_b32 v232, v223, v222, v36
	v_alignbyte_b32 v233, v224, v223, v36
	v_alignbyte_b32 v234, v225, v224, v36
	v_alignbyte_b32 v235, v226, v225, v36
	ds_read2_b32 v[222:223], v154 offset0:176 offset1:177
	ds_read2_b32 v[224:225], v154 offset0:178 offset1:179
	ds_read_b32 v226, v154 offset:720
	v_mfma_f32_16x16x32_bf16 v[18:21], v[232:235], v[144:147], v[18:21]
	ds_read_b128 v[144:147], v156 offset:704
	s_waitcnt lgkmcnt(12)
	v_alignbyte_b32 v228, v205, v204, v36
	v_alignbyte_b32 v229, v206, v205, v36
	v_alignbyte_b32 v230, v207, v206, v36
	v_alignbyte_b32 v231, v208, v207, v36
	ds_read2_b32 v[204:205], v154 offset0:192 offset1:193
	ds_read2_b32 v[206:207], v154 offset0:194 offset1:195
	ds_read_b32 v208, v154 offset:784
	v_mfma_f32_16x16x32_bf16 v[18:21], v[228:231], v[236:239], v[18:21]
	ds_read_b128 v[236:239], v156 offset:768
	s_waitcnt lgkmcnt(12)
	v_alignbyte_b32 v232, v211, v210, v36
	v_alignbyte_b32 v233, v212, v211, v36
	v_alignbyte_b32 v234, v213, v212, v36
	v_alignbyte_b32 v235, v214, v213, v36
	ds_read2_b32 v[210:211], v154 offset0:208 offset1:209
	ds_read2_b32 v[212:213], v154 offset0:210 offset1:211
	ds_read_b32 v214, v154 offset:848
	v_mfma_f32_16x16x32_bf16 v[18:21], v[232:235], v[240:243], v[18:21]
	ds_read_b128 v[240:243], v156 offset:832
	s_waitcnt lgkmcnt(12)
	v_alignbyte_b32 v228, v217, v216, v36
	v_alignbyte_b32 v229, v218, v217, v36
	v_alignbyte_b32 v230, v219, v218, v36
	v_alignbyte_b32 v231, v220, v219, v36
	ds_read2_b32 v[216:217], v154 offset0:224 offset1:225
	ds_read2_b32 v[218:219], v154 offset0:226 offset1:227
	ds_read_b32 v220, v154 offset:912
	v_mfma_f32_16x16x32_bf16 v[18:21], v[228:231], v[244:247], v[18:21]
	ds_read_b128 v[244:247], v156 offset:896
	s_waitcnt lgkmcnt(12)
	v_alignbyte_b32 v232, v223, v222, v36
	v_alignbyte_b32 v233, v224, v223, v36
	v_alignbyte_b32 v234, v225, v224, v36
	v_alignbyte_b32 v235, v226, v225, v36
	ds_read2_b32 v[222:223], v154 offset0:240 offset1:241
	ds_read2_b32 v[224:225], v154 offset0:242 offset1:243
	ds_read_b32 v226, v154 offset:976
	v_mfma_f32_16x16x32_bf16 v[18:21], v[232:235], v[144:147], v[18:21]
	ds_read_b128 v[144:147], v156 offset:960
	s_waitcnt lgkmcnt(12)
	v_alignbyte_b32 v228, v205, v204, v36
	v_alignbyte_b32 v229, v206, v205, v36
	v_alignbyte_b32 v230, v207, v206, v36
	v_alignbyte_b32 v231, v208, v207, v36
	s_nop 1
	v_mfma_f32_16x16x32_bf16 v[18:21], v[228:231], v[236:239], v[18:21]
	s_waitcnt lgkmcnt(8)
	v_alignbyte_b32 v232, v211, v210, v36
	v_alignbyte_b32 v233, v212, v211, v36
	v_alignbyte_b32 v234, v213, v212, v36
	v_alignbyte_b32 v235, v214, v213, v36
	s_nop 1
	v_mfma_f32_16x16x32_bf16 v[18:21], v[232:235], v[240:243], v[18:21]
	s_waitcnt lgkmcnt(4)
	v_alignbyte_b32 v228, v217, v216, v36
	v_alignbyte_b32 v229, v218, v217, v36
	v_alignbyte_b32 v230, v219, v218, v36
	v_alignbyte_b32 v231, v220, v219, v36
	s_nop 1
	v_mfma_f32_16x16x32_bf16 v[18:21], v[228:231], v[244:247], v[18:21]
	s_waitcnt lgkmcnt(0)
	v_alignbyte_b32 v232, v223, v222, v36
	v_alignbyte_b32 v233, v224, v223, v36
	v_alignbyte_b32 v234, v225, v224, v36
	v_alignbyte_b32 v235, v226, v225, v36
	s_nop 1
	v_mfma_f32_16x16x32_bf16 v[18:21], v[232:235], v[144:147], v[18:21]
	v_add_u32_e32 v45, s53, v1
	s_movk_i32 s50, 0x600
	v_add_f32_e32 v42, v42, v43
	v_mul_lo_u32 v46, v45, s50
	v_div_scale_f32 v43, s[50:51], v42, v42, 1.0
	v_rcp_f32_e32 v44, v43
	s_nop 0
	v_fma_f32 v47, -v43, v44, 1.0
	v_fmac_f32_e32 v44, v47, v44
	v_div_scale_f32 v47, vcc, 1.0, v42, 1.0
	v_mul_f32_e32 v48, v47, v44
	v_fma_f32 v49, -v43, v48, v47
	v_fmac_f32_e32 v48, v49, v44
	v_fma_f32 v43, -v43, v48, v47
	v_div_fmas_f32 v43, v43, v44, v48
	v_div_fixup_f32 v44, v43, v42, 1.0
	v_lshlrev_b32_e32 v42, 1, v37
	v_add3_u32 v42, s17, v46, v42
	ds_read_b64 v[46:47], v42 offset:512
	v_lshl_add_u32 v43, v45, 9, v38
	ds_read_b64 v[48:49], v43 offset:24576
	s_waitcnt lgkmcnt(1)
	v_and_b32_e32 v53, 0xffff0000, v46
	v_lshlrev_b32_e32 v52, 16, v46
	v_pk_mul_f32 v[52:53], v[110:111], v[52:53] op_sel_hi:[0,1]
	s_waitcnt lgkmcnt(0)
	v_and_b32_e32 v51, 0xffff0000, v48
	v_lshlrev_b32_e32 v50, 16, v48
	v_pk_fma_f32 v[18:19], v[44:45], v[18:19], v[52:53] op_sel_hi:[0,1,1]
	v_pk_mul_f32 v[18:19], v[18:19], v[50:51]
	v_and_b32_e32 v51, 0xffff0000, v49
	v_lshlrev_b32_e32 v50, 16, v49
	v_and_b32_e32 v49, 0xffff0000, v47
	v_lshlrev_b32_e32 v48, 16, v47
	v_pk_mul_f32 v[46:47], v[110:111], v[48:49] op_sel_hi:[0,1]
	v_pk_fma_f32 v[20:21], v[44:45], v[20:21], v[46:47] op_sel_hi:[0,1,1]
	v_pk_mul_f32 v[20:21], v[20:21], v[50:51]
	v_bfe_u32 v45, v19, 16, 1
	v_bfe_u32 v46, v18, 16, 1
	v_add3_u32 v18, v18, v46, s94
	v_add3_u32 v45, v19, v45, s94
	v_cvt_pk_bf16_f32 v20, v20, v21
	v_mov_b32_e32 v19, v20
	v_perm_b32 v18, v45, v18, s95
	ds_write_b64 v42, v[18:19] offset:512
	s_waitcnt vmcnt(1)
	ds_write_b128 v28, v[14:17] offset:32800
	s_and_saveexec_b64 s[50:51], s[44:45]
	ds_write_b128 v28, v[10:13] offset:33824
	s_or_b64 exec, exec, s[50:51]
	ds_bpermute_b32 v14, v29, v27
	s_or_b32 s50, s52, 1
	s_cmp_gt_u32 s50, 6
	s_waitcnt lgkmcnt(0)
	v_add_f32_e32 v14, v27, v14
	ds_bpermute_b32 v15, v30, v14
	s_waitcnt lgkmcnt(0)
	v_add_f32_e32 v14, v14, v15
	ds_bpermute_b32 v15, v31, v14
	s_waitcnt lgkmcnt(0)
	v_add_f32_e32 v14, v14, v15
	ds_bpermute_b32 v15, v32, v14
	s_waitcnt lgkmcnt(0)
	v_add_f32_e32 v14, v14, v15
	ds_bpermute_b32 v15, v33, v14
	s_waitcnt lgkmcnt(0)
	v_add_f32_e32 v18, v14, v15
	ds_bpermute_b32 v19, v34, v18
	s_cbranch_scc1 .LBB0_736
	v_add_u32_e32 v16, 4, v26
	v_add_u32_e32 v2, s74, v16
	v_mad_i64_i32 v[14:15], s[50:51], v2, s9, v[22:23]
	global_load_dwordx4 v[2:5], v[14:15], off
	s_and_saveexec_b64 s[50:51], s[44:45]
	s_cbranch_execz .LBB0_733
	global_load_dwordx4 v[6:9], v[14:15], off offset:1024

.LBB0_736:
	v_mov_b32_e32 v14, 0
	s_mov_b32 s50, 0
	s_movk_i32 s51, 0xfee0
	v_mov_b32_e32 v15, v14
	v_mov_b32_e32 v16, v14
	v_mov_b32_e32 v17, v14
	v_mov_b32_e32 v156, v41
	v_add_lshl_u32 v155, v35, s51, 1
	v_and_b32_e32 v155, -4, v155
	v_add_u32_e32 v155, v25, v155
	v_add_u32_e32 v154, 0x8260, v155
	ds_read_b128 v[236:239], v156
	ds_read2_b32 v[204:205], v154 offset1:1
	ds_read2_b32 v[206:207], v154 offset0:2 offset1:3
	ds_read_b32 v208, v154 offset:16
	ds_read_b128 v[240:243], v156 offset:64
	ds_read2_b32 v[210:211], v154 offset0:16 offset1:17
	ds_read2_b32 v[212:213], v154 offset0:18 offset1:19
	ds_read_b32 v214, v154 offset:80
	ds_read_b128 v[244:247], v156 offset:128
	ds_read2_b32 v[216:217], v154 offset0:32 offset1:33
	ds_read2_b32 v[218:219], v154 offset0:34 offset1:35
	ds_read_b32 v220, v154 offset:144
	ds_read_b128 v[144:147], v156 offset:192
	ds_read2_b32 v[222:223], v154 offset0:48 offset1:49
	ds_read2_b32 v[224:225], v154 offset0:50 offset1:51
	ds_read_b32 v226, v154 offset:208
	s_waitcnt lgkmcnt(12)
	v_alignbyte_b32 v228, v205, v204, v36
	v_alignbyte_b32 v229, v206, v205, v36
	v_alignbyte_b32 v230, v207, v206, v36
	v_alignbyte_b32 v231, v208, v207, v36
	ds_read2_b32 v[204:205], v154 offset0:64 offset1:65
	ds_read2_b32 v[206:207], v154 offset0:66 offset1:67
	ds_read_b32 v208, v154 offset:272
	v_mfma_f32_16x16x32_bf16 v[14:17], v[228:231], v[236:239], v[14:17]
	ds_read_b128 v[236:239], v156 offset:256
	s_waitcnt lgkmcnt(12)
	v_alignbyte_b32 v232, v211, v210, v36
	v_alignbyte_b32 v233, v212, v211, v36
	v_alignbyte_b32 v234, v213, v212, v36
	v_alignbyte_b32 v235, v214, v213, v36
	ds_read2_b32 v[210:211], v154 offset0:80 offset1:81
	ds_read2_b32 v[212:213], v154 offset0:82 offset1:83
	ds_read_b32 v214, v154 offset:336
	v_mfma_f32_16x16x32_bf16 v[14:17], v[232:235], v[240:243], v[14:17]
	ds_read_b128 v[240:243], v156 offset:320
	s_waitcnt lgkmcnt(12)
	v_alignbyte_b32 v228, v217, v216, v36
	v_alignbyte_b32 v229, v218, v217, v36
	v_alignbyte_b32 v230, v219, v218, v36
	v_alignbyte_b32 v231, v220, v219, v36
	ds_read2_b32 v[216:217], v154 offset0:96 offset1:97
	ds_read2_b32 v[218:219], v154 offset0:98 offset1:99
	ds_read_b32 v220, v154 offset:400
	v_mfma_f32_16x16x32_bf16 v[14:17], v[228:231], v[244:247], v[14:17]
	ds_read_b128 v[244:247], v156 offset:384
	s_waitcnt lgkmcnt(12)
	v_alignbyte_b32 v232, v223, v222, v36
	v_alignbyte_b32 v233, v224, v223, v36
	v_alignbyte_b32 v234, v225, v224, v36
	v_alignbyte_b32 v235, v226, v225, v36
	ds_read2_b32 v[222:223], v154 offset0:112 offset1:113
	ds_read2_b32 v[224:225], v154 offset0:114 offset1:115
	ds_read_b32 v226, v154 offset:464
	v_mfma_f32_16x16x32_bf16 v[14:17], v[232:235], v[144:147], v[14:17]
	ds_read_b128 v[144:147], v156 offset:448
	s_waitcnt lgkmcnt(12)
	v_alignbyte_b32 v228, v205, v204, v36
	v_alignbyte_b32 v229, v206, v205, v36
	v_alignbyte_b32 v230, v207, v206, v36
	v_alignbyte_b32 v231, v208, v207, v36
	ds_read2_b32 v[204:205], v154 offset0:128 offset1:129
	ds_read2_b32 v[206:207], v154 offset0:130 offset1:131
	ds_read_b32 v208, v154 offset:528
	v_mfma_f32_16x16x32_bf16 v[14:17], v[228:231], v[236:239], v[14:17]
	ds_read_b128 v[236:239], v156 offset:512
	s_waitcnt lgkmcnt(12)
	v_alignbyte_b32 v232, v211, v210, v36
	v_alignbyte_b32 v233, v212, v211, v36
	v_alignbyte_b32 v234, v213, v212, v36
	v_alignbyte_b32 v235, v214, v213, v36
	ds_read2_b32 v[210:211], v154 offset0:144 offset1:145
	ds_read2_b32 v[212:213], v154 offset0:146 offset1:147
	ds_read_b32 v214, v154 offset:592
	v_mfma_f32_16x16x32_bf16 v[14:17], v[232:235], v[240:243], v[14:17]
	ds_read_b128 v[240:243], v156 offset:576
	s_waitcnt lgkmcnt(12)
	v_alignbyte_b32 v228, v217, v216, v36
	v_alignbyte_b32 v229, v218, v217, v36
	v_alignbyte_b32 v230, v219, v218, v36
	v_alignbyte_b32 v231, v220, v219, v36
	ds_read2_b32 v[216:217], v154 offset0:160 offset1:161
	ds_read2_b32 v[218:219], v154 offset0:162 offset1:163
	ds_read_b32 v220, v154 offset:656
	v_mfma_f32_16x16x32_bf16 v[14:17], v[228:231], v[244:247], v[14:17]
	ds_read_b128 v[244:247], v156 offset:640
	s_waitcnt lgkmcnt(12)
	v_alignbyte_b32 v232, v223, v222, v36
	v_alignbyte_b32 v233, v224, v223, v36
	v_alignbyte_b32 v234, v225, v224, v36
	v_alignbyte_b32 v235, v226, v225, v36
	ds_read2_b32 v[222:223], v154 offset0:176 offset1:177
	ds_read2_b32 v[224:225], v154 offset0:178 offset1:179
	ds_read_b32 v226, v154 offset:720
	v_mfma_f32_16x16x32_bf16 v[14:17], v[232:235], v[144:147], v[14:17]
	ds_read_b128 v[144:147], v156 offset:704
	s_waitcnt lgkmcnt(12)
	v_alignbyte_b32 v228, v205, v204, v36
	v_alignbyte_b32 v229, v206, v205, v36
	v_alignbyte_b32 v230, v207, v206, v36
	v_alignbyte_b32 v231, v208, v207, v36
	ds_read2_b32 v[204:205], v154 offset0:192 offset1:193
	ds_read2_b32 v[206:207], v154 offset0:194 offset1:195
	ds_read_b32 v208, v154 offset:784
	v_mfma_f32_16x16x32_bf16 v[14:17], v[228:231], v[236:239], v[14:17]
	ds_read_b128 v[236:239], v156 offset:768
	s_waitcnt lgkmcnt(12)
	v_alignbyte_b32 v232, v211, v210, v36
	v_alignbyte_b32 v233, v212, v211, v36
	v_alignbyte_b32 v234, v213, v212, v36
	v_alignbyte_b32 v235, v214, v213, v36
	ds_read2_b32 v[210:211], v154 offset0:208 offset1:209
	ds_read2_b32 v[212:213], v154 offset0:210 offset1:211
	ds_read_b32 v214, v154 offset:848
	v_mfma_f32_16x16x32_bf16 v[14:17], v[232:235], v[240:243], v[14:17]
	ds_read_b128 v[240:243], v156 offset:832
	s_waitcnt lgkmcnt(12)
	v_alignbyte_b32 v228, v217, v216, v36
	v_alignbyte_b32 v229, v218, v217, v36
	v_alignbyte_b32 v230, v219, v218, v36
	v_alignbyte_b32 v231, v220, v219, v36
	ds_read2_b32 v[216:217], v154 offset0:224 offset1:225
	ds_read2_b32 v[218:219], v154 offset0:226 offset1:227
	ds_read_b32 v220, v154 offset:912
	v_mfma_f32_16x16x32_bf16 v[14:17], v[228:231], v[244:247], v[14:17]
	ds_read_b128 v[244:247], v156 offset:896
	s_waitcnt lgkmcnt(12)
	v_alignbyte_b32 v232, v223, v222, v36
	v_alignbyte_b32 v233, v224, v223, v36
	v_alignbyte_b32 v234, v225, v224, v36
	v_alignbyte_b32 v235, v226, v225, v36
	ds_read2_b32 v[222:223], v154 offset0:240 offset1:241
	ds_read2_b32 v[224:225], v154 offset0:242 offset1:243
	ds_read_b32 v226, v154 offset:976
	v_mfma_f32_16x16x32_bf16 v[14:17], v[232:235], v[144:147], v[14:17]
	ds_read_b128 v[144:147], v156 offset:960
	s_waitcnt lgkmcnt(12)
	v_alignbyte_b32 v228, v205, v204, v36
	v_alignbyte_b32 v229, v206, v205, v36
	v_alignbyte_b32 v230, v207, v206, v36
	v_alignbyte_b32 v231, v208, v207, v36
	s_nop 1
	v_mfma_f32_16x16x32_bf16 v[14:17], v[228:231], v[236:239], v[14:17]
	s_waitcnt lgkmcnt(8)
	v_alignbyte_b32 v232, v211, v210, v36
	v_alignbyte_b32 v233, v212, v211, v36
	v_alignbyte_b32 v234, v213, v212, v36
	v_alignbyte_b32 v235, v214, v213, v36
	s_nop 1
	v_mfma_f32_16x16x32_bf16 v[14:17], v[232:235], v[240:243], v[14:17]
	s_waitcnt lgkmcnt(4)
	v_alignbyte_b32 v228, v217, v216, v36
	v_alignbyte_b32 v229, v218, v217, v36
	v_alignbyte_b32 v230, v219, v218, v36
	v_alignbyte_b32 v231, v220, v219, v36
	s_nop 1
	v_mfma_f32_16x16x32_bf16 v[14:17], v[228:231], v[244:247], v[14:17]
	s_waitcnt lgkmcnt(0)
	v_alignbyte_b32 v232, v223, v222, v36
	v_alignbyte_b32 v233, v224, v223, v36
	v_alignbyte_b32 v234, v225, v224, v36
	v_alignbyte_b32 v235, v226, v225, v36
	s_nop 1
	v_mfma_f32_16x16x32_bf16 v[14:17], v[232:235], v[144:147], v[14:17]
	v_add_f32_e32 v18, v18, v19
	v_div_scale_f32 v19, s[50:51], v18, v18, 1.0
	v_rcp_f32_e32 v20, v19
	s_add_i32 s50, s52, 2
	v_add_u32_e32 v41, 0x1800, v41
	s_cmp_gt_u32 s52, 5
	v_fma_f32 v21, -v19, v20, 1.0
	v_fmac_f32_e32 v20, v21, v20
	v_div_scale_f32 v21, vcc, 1.0, v18, 1.0
	v_mul_f32_e32 v26, v21, v20
	v_fma_f32 v27, -v19, v26, v21
	v_fmac_f32_e32 v26, v27, v20
	v_fma_f32 v19, -v19, v26, v21
	v_div_fmas_f32 v19, v19, v20, v26
	ds_read_b64 v[20:21], v42 offset:512
	v_div_fixup_f32 v18, v19, v18, 1.0
	s_mov_b32 s52, s50
	s_waitcnt lgkmcnt(0)
	v_and_b32_e32 v27, 0xffff0000, v20
	v_lshlrev_b32_e32 v26, 16, v20
	s_waitcnt vmcnt(0)
	v_pk_mul_f32 v[26:27], v[24:25], v[26:27] op_sel_hi:[0,1]
	v_pk_fma_f32 v[14:15], v[18:19], v[14:15], v[26:27] op_sel_hi:[0,1,1]
	v_and_b32_e32 v27, 0xffff0000, v21
	v_lshlrev_b32_e32 v26, 16, v21
	v_pk_mul_f32 v[20:21], v[24:25], v[26:27] op_sel_hi:[0,1]
	v_pk_fma_f32 v[16:17], v[18:19], v[16:17], v[20:21] op_sel_hi:[0,1,1]
	v_bfe_u32 v20, v15, 16, 1
	v_bfe_u32 v21, v14, 16, 1
	v_add3_u32 v14, v14, v21, s94
	v_add3_u32 v20, v15, v20, s94
	v_cvt_pk_bf16_f32 v16, v16, v17
	v_mov_b32_e32 v15, v16
	v_perm_b32 v14, v20, v14, s95
	ds_write_b64 v42, v[14:15] offset:512
	s_cbranch_scc0 .LBB0_720
	v_cmp_eq_u32_e32 vcc, 0, v0
	s_and_saveexec_b64 s[42:43], vcc
	s_cbranch_execz .LBB0_749
	s_lshr_b32 s22, s22, 2
	s_and_b32 s22, s22, 4
	v_readlane_b32 s44, v251, 49
	s_add_u32 s22, s44, s22
	v_readlane_b32 s44, v251, 50
	s_addc_u32 s45, s44, 0
	s_lshl_b32 s23, s23, 3
	s_add_u32 s44, s22, s23
	s_addc_u32 s45, s45, 0
	s_mov_b32 s22, 0x400001
	s_branch .LBB0_742

.LBB0_749:
	s_or_b64 exec, exec, s[42:43]
	v_add_u32_e32 v0, s21, v0
	v_mov_b64_e32 v[2:3], s[6:7]
	v_ashrrev_i32_e32 v1, 31, v0
	v_mad_i64_i32 v[2:3], s[22:23], v0, s0, v[2:3]
	s_mov_b64 s[22:23], 0x3000
	v_lshlrev_b64 v[0:1], 12, v[0:1]
	v_lshl_add_u64 v[22:23], v[2:3], 0, s[22:23]
	v_lshl_add_u64 v[0:1], s[30:31], 0, v[0:1]
	s_mov_b64 s[22:23], 0xcc00c00
	v_lshl_add_u64 v[20:21], v[0:1], 0, s[22:23]
	s_mov_b64 s[22:23], 0x2800
	v_lshl_add_u64 v[28:29], v[104:105], 0, s[22:23]
	v_lshl_add_u64 v[0:1], v[28:29], 0, s[70:71]
	s_waitcnt lgkmcnt(0)
	s_barrier
	global_load_dwordx4 v[0:3], v[0:1], off
	v_lshl_add_u64 v[26:27], v[106:107], 0, s[22:23]
	v_lshl_add_u64 v[24:25], v[108:109], 0, s[22:23]
	s_add_u32 s44, s46, 0x2000
	s_addc_u32 s45, s47, 0
	s_add_u32 s42, s46, 0x3800
	s_addc_u32 s43, s47, 0
	v_lshl_add_u64 v[30:31], v[20:21], 0, s[70:71]
	s_waitcnt vmcnt(0)
	v_cndmask_b32_e64 v6, 0, v1, s[36:37]
	v_cndmask_b32_e64 v7, 0, v0, s[36:37]
	v_lshl_add_u64 v[0:1], v[26:27], 0, s[70:71]
	v_cndmask_b32_e64 v4, 0, v3, s[36:37]
	v_cndmask_b32_e64 v5, 0, v2, s[36:37]
	global_load_dwordx4 v[0:3], v[0:1], off
	v_and_b32_e32 v13, 0xffff0000, v7
	v_lshlrev_b32_e32 v12, 16, v7
	v_and_b32_e32 v43, 0xffff0000, v6
	v_lshlrev_b32_e32 v42, 16, v6
	v_and_b32_e32 v39, 0xffff0000, v5
	v_lshlrev_b32_e32 v38, 16, v5
	v_and_b32_e32 v35, 0xffff0000, v4
	v_lshlrev_b32_e32 v34, 16, v4
	s_waitcnt vmcnt(0)
	v_cndmask_b32_e64 v10, 0, v1, s[38:39]
	v_cndmask_b32_e64 v11, 0, v0, s[38:39]
	v_lshl_add_u64 v[0:1], v[24:25], 0, s[70:71]
	v_cndmask_b32_e64 v8, 0, v3, s[38:39]
	v_cndmask_b32_e64 v9, 0, v2, s[38:39]
	global_load_dwordx4 v[0:3], v[0:1], off
	v_and_b32_e32 v17, 0xffff0000, v11
	v_lshlrev_b32_e32 v16, 16, v11
	v_and_b32_e32 v45, 0xffff0000, v10
	v_lshlrev_b32_e32 v44, 16, v10
	v_and_b32_e32 v41, 0xffff0000, v9
	v_lshlrev_b32_e32 v40, 16, v9
	v_and_b32_e32 v37, 0xffff0000, v8
	v_lshlrev_b32_e32 v36, 16, v8
	s_waitcnt vmcnt(0)
	v_cndmask_b32_e64 v64, 0, v1, s[40:41]
	v_cndmask_b32_e64 v60, 0, v0, s[40:41]
	v_lshl_add_u64 v[0:1], v[22:23], 0, s[70:71]
	v_cndmask_b32_e64 v46, 0, v3, s[40:41]
	v_cndmask_b32_e64 v47, 0, v2, s[40:41]
	global_load_dwordx4 v[0:3], v[0:1], off
	s_nop 0
	global_load_dwordx4 v[4:7], v161, s[48:49] offset:2064
	global_load_dwordx4 v[48:51], v161, s[48:49] offset:2048
	global_load_dwordx4 v[8:11], v161, s[46:47] offset:2064
	global_load_dwordx4 v[52:55], v161, s[46:47] offset:2048
	s_lshl_b32 s70, s20, 1
	s_waitcnt vmcnt(1)
	v_pk_fma_f32 v[4:5], v[8:9], v[38:39], v[4:5]
	s_waitcnt vmcnt(0)
	v_pk_fma_f32 v[18:19], v[52:53], v[12:13], v[48:49]
	global_load_dwordx4 v[12:15], v161, s[44:45] offset:16
	global_load_dwordx4 v[56:59], v196, s[46:47]
	v_and_b32_e32 v49, 0xffff0000, v60
	v_lshlrev_b32_e32 v48, 16, v60
	v_pk_fma_f32 v[42:43], v[54:55], v[42:43], v[50:51]
	v_and_b32_e32 v9, 0xffff0000, v47
	v_lshlrev_b32_e32 v8, 16, v47
	v_pk_fma_f32 v[6:7], v[10:11], v[34:35], v[6:7]
	s_waitcnt vmcnt(1)
	v_pk_fma_f32 v[4:5], v[12:13], v[40:41], v[4:5]
	s_waitcnt vmcnt(0)
	v_pk_fma_f32 v[32:33], v[56:57], v[16:17], v[18:19]
	global_load_dwordx4 v[16:19], v161, s[42:43] offset:16
	global_load_dwordx4 v[60:63], v197, s[46:47] offset:2048
	v_and_b32_e32 v56, 0xffff0000, v0
	v_lshlrev_b32_e32 v0, 16, v0
	v_pk_fma_f32 v[42:43], v[58:59], v[44:45], v[42:43]
	v_and_b32_e32 v45, 0xffff0000, v64
	v_lshlrev_b32_e32 v44, 16, v64
	v_pk_fma_f32 v[6:7], v[14:15], v[36:37], v[6:7]
	s_waitcnt vmcnt(1)
	v_pk_fma_f32 v[4:5], v[16:17], v[8:9], v[4:5]
	s_waitcnt vmcnt(0)
	v_pk_fma_f32 v[32:33], v[60:61], v[48:49], v[32:33]
	ds_read_u16 v49, v82 offset:512
	ds_read_u16 v52, v82 offset:2048
	v_mul_f32_e32 v48, 0xbfb8aa3b, v0
	v_exp_f32_e32 v48, v48
	v_pk_fma_f32 v[42:43], v[62:63], v[44:45], v[42:43]
	v_and_b32_e32 v16, 0xffff0000, v2
	s_waitcnt lgkmcnt(0)
	v_lshlrev_b32_e32 v53, 16, v52
	v_lshlrev_b32_e32 v52, 16, v49
	v_mul_f32_e32 v49, 0xbfb8aa3b, v56
	v_exp_f32_e32 v49, v49
	v_pk_mul_f32 v[32:33], v[32:33], v[52:53]
	v_lshlrev_b32_e32 v2, 16, v2
	v_mul_f32_e32 v8, 0xbfb8aa3b, v2
	v_pk_add_f32 v[48:49], v[48:49], 1.0 op_sel_hi:[1,0]
	v_exp_f32_e32 v8, v8
	v_div_scale_f32 v52, s[22:23], v49, v49, v56
	v_rcp_f32_e32 v53, v52
	s_nop 0
	v_fma_f32 v57, -v52, v53, 1.0
	v_fmac_f32_e32 v53, v57, v53
	v_div_scale_f32 v57, vcc, v56, v49, v56
	v_mul_f32_e32 v60, v57, v53
	v_fma_f32 v61, -v52, v60, v57
	v_fmac_f32_e32 v60, v61, v53
	v_fma_f32 v52, -v52, v60, v57
	v_div_fmas_f32 v52, v52, v53, v60
	v_div_fixup_f32 v49, v52, v49, v56
	v_div_scale_f32 v52, s[22:23], v48, v48, v0
	v_rcp_f32_e32 v53, v52
	s_nop 0
	v_fma_f32 v56, -v52, v53, 1.0
	v_fmac_f32_e32 v53, v56, v53
	v_div_scale_f32 v56, vcc, v0, v48, v0
	v_mul_f32_e32 v57, v56, v53
	v_fma_f32 v60, -v52, v57, v56
	v_fmac_f32_e32 v57, v60, v53
	v_fma_f32 v52, -v52, v57, v56
	v_div_fmas_f32 v52, v52, v53, v57
	v_div_fixup_f32 v48, v52, v48, v0
	v_pk_mul_f32 v[32:33], v[48:49], v[32:33]
	v_and_b32_e32 v48, 0xffff0000, v1
	v_lshlrev_b32_e32 v49, 16, v1
	ds_read_u16 v1, v82 offset:3584
	ds_read_u16 v44, v82 offset:5120
	v_mul_f32_e32 v0, 0xbfb8aa3b, v49
	v_exp_f32_e32 v0, v0
	ds_read_u16 v9, v82 offset:6656
	ds_read_u16 v12, v82 offset:8192
	s_waitcnt lgkmcnt(2)
	v_lshlrev_b32_e32 v45, 16, v44
	v_lshlrev_b32_e32 v44, 16, v1
	v_mul_f32_e32 v1, 0xbfb8aa3b, v48
	v_exp_f32_e32 v1, v1
	v_pk_mul_f32 v[42:43], v[42:43], v[44:45]
	s_waitcnt lgkmcnt(0)
	v_lshlrev_b32_e32 v13, 16, v12
	v_lshlrev_b32_e32 v12, 16, v9
	v_pk_add_f32 v[0:1], v[0:1], 1.0 op_sel_hi:[1,0]
	v_mul_f32_e32 v9, 0xbfb8aa3b, v16
	v_div_scale_f32 v44, s[22:23], v1, v1, v48
	v_rcp_f32_e32 v45, v44
	v_exp_f32_e32 v9, v9
	v_pk_mul_f32 v[4:5], v[4:5], v[12:13]
	v_fma_f32 v50, -v44, v45, 1.0
	v_fmac_f32_e32 v45, v50, v45
	v_div_scale_f32 v50, vcc, v48, v1, v48
	v_mul_f32_e32 v51, v50, v45
	v_fma_f32 v52, -v44, v51, v50
	v_fmac_f32_e32 v51, v52, v45
	v_fma_f32 v44, -v44, v51, v50
	v_div_fmas_f32 v44, v44, v45, v51
	v_div_fixup_f32 v1, v44, v1, v48
	v_div_scale_f32 v44, s[22:23], v0, v0, v49
	v_rcp_f32_e32 v45, v44
	v_pk_add_f32 v[8:9], v[8:9], 1.0 op_sel_hi:[1,0]
	v_fma_f32 v48, -v44, v45, 1.0
	v_div_scale_f32 v12, s[22:23], v9, v9, v16
	v_fmac_f32_e32 v45, v48, v45
	v_div_scale_f32 v48, vcc, v49, v0, v49
	v_rcp_f32_e32 v13, v12
	v_mul_f32_e32 v50, v48, v45
	v_fma_f32 v51, -v44, v50, v48
	v_fmac_f32_e32 v50, v51, v45
	v_fma_f32 v44, -v44, v50, v48
	v_fma_f32 v17, -v12, v13, 1.0
	v_div_fmas_f32 v44, v44, v45, v50
	v_fmac_f32_e32 v13, v17, v13
	v_div_scale_f32 v17, vcc, v16, v9, v16
	v_mul_f32_e32 v38, v17, v13
	v_fma_f32 v39, -v12, v38, v17
	v_fmac_f32_e32 v38, v39, v13
	v_fma_f32 v12, -v12, v38, v17
	v_div_fmas_f32 v12, v12, v13, v38
	v_div_fixup_f32 v9, v12, v9, v16
	v_div_scale_f32 v12, s[22:23], v8, v8, v2
	v_rcp_f32_e32 v13, v12
	v_div_fixup_f32 v0, v44, v0, v49
	v_pk_mul_f32 v[0:1], v[0:1], v[42:43]
	v_fma_f32 v16, -v12, v13, 1.0
	v_fmac_f32_e32 v13, v16, v13
	v_div_scale_f32 v16, vcc, v2, v8, v2
	v_mul_f32_e32 v17, v16, v13
	v_fma_f32 v38, -v12, v17, v16
	v_fmac_f32_e32 v17, v38, v13
	v_fma_f32 v12, -v12, v17, v16
	v_div_fmas_f32 v12, v12, v13, v17
	v_div_fixup_f32 v8, v12, v8, v2
	v_pk_mul_f32 v[4:5], v[8:9], v[4:5]
	v_and_b32_e32 v9, 0xffff0000, v46
	v_lshlrev_b32_e32 v8, 16, v46
	v_pk_fma_f32 v[6:7], v[18:19], v[8:9], v[6:7]
	v_and_b32_e32 v9, 0xffff0000, v3
	v_lshlrev_b32_e32 v8, 16, v3
	ds_read_u16 v3, v82 offset:9728
	ds_read_u16 v10, v82 offset:11264
	v_mul_f32_e32 v2, 0xbfb8aa3b, v8
	v_exp_f32_e32 v2, v2
	s_waitcnt lgkmcnt(0)
	v_lshlrev_b32_e32 v11, 16, v10
	v_lshlrev_b32_e32 v10, 16, v3
	v_mul_f32_e32 v3, 0xbfb8aa3b, v9
	v_exp_f32_e32 v3, v3
	v_pk_mul_f32 v[6:7], v[6:7], v[10:11]
	v_pk_add_f32 v[2:3], v[2:3], 1.0 op_sel_hi:[1,0]
	s_nop 0
	v_div_scale_f32 v10, s[22:23], v3, v3, v9
	v_rcp_f32_e32 v11, v10
	s_nop 0
	v_fma_f32 v12, -v10, v11, 1.0
	v_fmac_f32_e32 v11, v12, v11
	v_div_scale_f32 v12, vcc, v9, v3, v9
	v_mul_f32_e32 v13, v12, v11
	v_fma_f32 v14, -v10, v13, v12
	v_fmac_f32_e32 v13, v14, v11
	v_fma_f32 v10, -v10, v13, v12
	v_div_fmas_f32 v10, v10, v11, v13
	v_div_fixup_f32 v3, v10, v3, v9
	v_div_scale_f32 v9, s[22:23], v2, v2, v8
	v_rcp_f32_e32 v10, v9
	s_nop 0
	v_fma_f32 v11, -v9, v10, 1.0
	v_fmac_f32_e32 v10, v11, v10
	v_div_scale_f32 v11, vcc, v8, v2, v8
	v_mul_f32_e32 v12, v11, v10
	v_fma_f32 v13, -v9, v12, v11
	v_fmac_f32_e32 v12, v13, v10
	v_fma_f32 v9, -v9, v12, v11
	v_div_fmas_f32 v9, v9, v10, v12
	v_div_fixup_f32 v2, v9, v2, v8
	v_pk_mul_f32 v[2:3], v[2:3], v[6:7]
	v_bfe_u32 v12, v33, 16, 1
	v_bfe_u32 v13, v32, 16, 1
	v_add3_u32 v13, v32, v13, s94
	v_add3_u32 v12, v33, v12, s94
	v_cvt_pk_bf16_f32 v0, v0, v1
	v_cvt_pk_bf16_f32 v4, v4, v5
	v_cvt_pk_bf16_f32 v2, v2, v3
	v_mov_b32_e32 v3, v2
	v_mov_b32_e32 v2, v4
	v_mov_b32_e32 v1, v0
	v_perm_b32 v0, v12, v13, s95
	global_store_dwordx4 v[30:31], v[0:3], off
	v_lshl_add_u64 v[30:31], v[20:21], 0, s[70:71]
	s_nop 0
	v_lshl_add_u64 v[0:1], v[28:29], 0, s[70:71]
	global_load_dwordx4 v[0:3], v[0:1], off
	s_waitcnt vmcnt(0)
	v_cndmask_b32_e64 v6, 0, v1, s[36:37]
	v_cndmask_b32_e64 v7, 0, v0, s[36:37]
	v_lshl_add_u64 v[0:1], v[26:27], 0, s[70:71]
	v_cndmask_b32_e64 v4, 0, v3, s[36:37]
	v_cndmask_b32_e64 v5, 0, v2, s[36:37]
	global_load_dwordx4 v[0:3], v[0:1], off
	v_and_b32_e32 v13, 0xffff0000, v7
	v_lshlrev_b32_e32 v12, 16, v7
	v_and_b32_e32 v41, 0xffff0000, v6
	v_lshlrev_b32_e32 v40, 16, v6
	v_and_b32_e32 v37, 0xffff0000, v5
	v_lshlrev_b32_e32 v36, 16, v5
	v_and_b32_e32 v33, 0xffff0000, v4
	v_lshlrev_b32_e32 v32, 16, v4
	s_waitcnt vmcnt(0)
	v_cndmask_b32_e64 v10, 0, v1, s[38:39]
	v_cndmask_b32_e64 v11, 0, v0, s[38:39]
	v_lshl_add_u64 v[0:1], v[24:25], 0, s[70:71]
	v_cndmask_b32_e64 v8, 0, v3, s[38:39]
	v_cndmask_b32_e64 v9, 0, v2, s[38:39]
	global_load_dwordx4 v[0:3], v[0:1], off
	v_and_b32_e32 v17, 0xffff0000, v11
	v_lshlrev_b32_e32 v16, 16, v11
	v_and_b32_e32 v43, 0xffff0000, v10
	v_lshlrev_b32_e32 v42, 16, v10
	v_and_b32_e32 v39, 0xffff0000, v9
	v_lshlrev_b32_e32 v38, 16, v9
	v_and_b32_e32 v35, 0xffff0000, v8
	v_lshlrev_b32_e32 v34, 16, v8
	s_add_u32 s38, s46, 0x2020
	s_addc_u32 s39, s47, 0
	s_add_u32 s36, s46, 0x3820
	s_addc_u32 s37, s47, 0
	s_waitcnt vmcnt(0)
	v_cndmask_b32_e64 v46, 0, v1, s[40:41]
	v_cndmask_b32_e64 v47, 0, v0, s[40:41]
	v_lshl_add_u64 v[0:1], v[22:23], 0, s[70:71]
	v_cndmask_b32_e64 v44, 0, v3, s[40:41]
	v_cndmask_b32_e64 v45, 0, v2, s[40:41]
	global_load_dwordx4 v[0:3], v[0:1], off
	s_nop 0
	global_load_dwordx4 v[4:7], v161, s[48:49] offset:2096
	global_load_dwordx4 v[18:21], v161, s[48:49] offset:2080
	global_load_dwordx4 v[8:11], v161, s[46:47] offset:2096
	global_load_dwordx4 v[22:25], v161, s[46:47] offset:2080
	s_waitcnt vmcnt(1)
	v_pk_fma_f32 v[4:5], v[8:9], v[36:37], v[4:5]
	s_waitcnt vmcnt(0)
	v_pk_fma_f32 v[18:19], v[22:23], v[12:13], v[18:19]
	global_load_dwordx4 v[12:15], v161, s[38:39] offset:16
	global_load_dwordx4 v[26:29], v196, s[46:47] offset:32
	v_pk_fma_f32 v[20:21], v[24:25], v[40:41], v[20:21]
	v_and_b32_e32 v25, 0xffff0000, v46
	v_lshlrev_b32_e32 v24, 16, v46
	v_and_b32_e32 v9, 0xffff0000, v45
	v_lshlrev_b32_e32 v8, 16, v45
	v_pk_fma_f32 v[6:7], v[10:11], v[32:33], v[6:7]
	s_waitcnt vmcnt(1)
	v_pk_fma_f32 v[4:5], v[12:13], v[38:39], v[4:5]
	s_waitcnt vmcnt(0)
	v_pk_fma_f32 v[22:23], v[26:27], v[16:17], v[18:19]
	global_load_dwordx4 v[16:19], v161, s[36:37] offset:16
	global_load_dwordx4 v[48:51], v197, s[46:47] offset:2080
	v_and_b32_e32 v27, 0xffff0000, v47
	v_lshlrev_b32_e32 v26, 16, v47
	v_and_b32_e32 v47, 0xffff0000, v0
	v_lshlrev_b32_e32 v0, 16, v0
	v_pk_fma_f32 v[20:21], v[28:29], v[42:43], v[20:21]
	v_pk_fma_f32 v[6:7], v[14:15], v[34:35], v[6:7]
	s_waitcnt vmcnt(1)
	v_pk_fma_f32 v[4:5], v[16:17], v[8:9], v[4:5]
	s_waitcnt vmcnt(0)
	v_pk_fma_f32 v[22:23], v[48:49], v[26:27], v[22:23]
	ds_read_u16 v27, v82 offset:12800
	ds_read_u16 v48, v82 offset:14336
	v_mul_f32_e32 v26, 0xbfb8aa3b, v0
	v_exp_f32_e32 v26, v26
	v_pk_fma_f32 v[20:21], v[50:51], v[24:25], v[20:21]
	v_and_b32_e32 v16, 0xffff0000, v2
	s_waitcnt lgkmcnt(0)
	v_lshlrev_b32_e32 v49, 16, v48
	v_lshlrev_b32_e32 v48, 16, v27
	v_mul_f32_e32 v27, 0xbfb8aa3b, v47
	v_exp_f32_e32 v27, v27
	v_pk_mul_f32 v[22:23], v[22:23], v[48:49]
	v_lshlrev_b32_e32 v2, 16, v2
	v_mul_f32_e32 v8, 0xbfb8aa3b, v2
	v_pk_add_f32 v[26:27], v[26:27], 1.0 op_sel_hi:[1,0]
	v_exp_f32_e32 v8, v8
	v_div_scale_f32 v48, s[20:21], v27, v27, v47
	v_rcp_f32_e32 v49, v48
	s_nop 0
	v_fma_f32 v52, -v48, v49, 1.0
	v_fmac_f32_e32 v49, v52, v49
	v_div_scale_f32 v52, vcc, v47, v27, v47
	v_mul_f32_e32 v53, v52, v49
	v_fma_f32 v54, -v48, v53, v52
	v_fmac_f32_e32 v53, v54, v49
	v_fma_f32 v48, -v48, v53, v52
	v_div_fmas_f32 v48, v48, v49, v53
	v_div_fixup_f32 v27, v48, v27, v47
	v_div_scale_f32 v47, s[20:21], v26, v26, v0
	v_rcp_f32_e32 v48, v47
	s_nop 0
	v_fma_f32 v49, -v47, v48, 1.0
	v_fmac_f32_e32 v48, v49, v48
	v_div_scale_f32 v49, vcc, v0, v26, v0
	v_mul_f32_e32 v52, v49, v48
	v_fma_f32 v53, -v47, v52, v49
	v_fmac_f32_e32 v52, v53, v48
	v_fma_f32 v47, -v47, v52, v49
	v_div_fmas_f32 v47, v47, v48, v52
	v_div_fixup_f32 v26, v47, v26, v0
	v_pk_mul_f32 v[22:23], v[26:27], v[22:23]
	v_and_b32_e32 v26, 0xffff0000, v1
	v_lshlrev_b32_e32 v27, 16, v1
	ds_read_u16 v1, v82 offset:15872
	ds_read_u16 v24, v82 offset:17408
	v_mul_f32_e32 v0, 0xbfb8aa3b, v27
	v_exp_f32_e32 v0, v0
	ds_read_u16 v9, v82 offset:18944
	ds_read_u16 v12, v82 offset:20480
	s_waitcnt lgkmcnt(2)
	v_lshlrev_b32_e32 v25, 16, v24
	v_lshlrev_b32_e32 v24, 16, v1
	v_mul_f32_e32 v1, 0xbfb8aa3b, v26
	v_exp_f32_e32 v1, v1
	v_pk_mul_f32 v[20:21], v[20:21], v[24:25]
	s_waitcnt lgkmcnt(0)
	v_lshlrev_b32_e32 v13, 16, v12
	v_lshlrev_b32_e32 v12, 16, v9
	v_pk_add_f32 v[0:1], v[0:1], 1.0 op_sel_hi:[1,0]
	v_mul_f32_e32 v9, 0xbfb8aa3b, v16
	v_div_scale_f32 v24, s[20:21], v1, v1, v26
	v_rcp_f32_e32 v25, v24
	v_exp_f32_e32 v9, v9
	v_pk_mul_f32 v[4:5], v[4:5], v[12:13]
	v_fma_f32 v28, -v24, v25, 1.0
	v_fmac_f32_e32 v25, v28, v25
	v_div_scale_f32 v28, vcc, v26, v1, v26
	v_mul_f32_e32 v29, v28, v25
	v_fma_f32 v40, -v24, v29, v28
	v_fmac_f32_e32 v29, v40, v25
	v_fma_f32 v24, -v24, v29, v28
	v_div_fmas_f32 v24, v24, v25, v29
	v_div_fixup_f32 v1, v24, v1, v26
	v_div_scale_f32 v24, s[20:21], v0, v0, v27
	v_rcp_f32_e32 v25, v24
	v_pk_add_f32 v[8:9], v[8:9], 1.0 op_sel_hi:[1,0]
	v_fma_f32 v26, -v24, v25, 1.0
	v_fmac_f32_e32 v25, v26, v25
	v_div_scale_f32 v26, vcc, v27, v0, v27
	v_div_scale_f32 v12, s[20:21], v9, v9, v16
	v_mul_f32_e32 v28, v26, v25
	v_rcp_f32_e32 v13, v12
	v_fma_f32 v29, -v24, v28, v26
	v_fmac_f32_e32 v28, v29, v25
	v_fma_f32 v24, -v24, v28, v26
	v_div_fmas_f32 v24, v24, v25, v28
	v_fma_f32 v17, -v12, v13, 1.0
	v_div_fixup_f32 v0, v24, v0, v27
	v_fmac_f32_e32 v13, v17, v13
	v_div_scale_f32 v17, vcc, v16, v9, v16
	v_pk_mul_f32 v[0:1], v[0:1], v[20:21]
	v_mul_f32_e32 v20, v17, v13
	v_fma_f32 v21, -v12, v20, v17
	v_fmac_f32_e32 v20, v21, v13
	v_fma_f32 v12, -v12, v20, v17
	v_div_fmas_f32 v12, v12, v13, v20
	v_div_fixup_f32 v9, v12, v9, v16
	v_div_scale_f32 v12, s[20:21], v8, v8, v2
	v_rcp_f32_e32 v13, v12
	s_nop 0
	v_fma_f32 v16, -v12, v13, 1.0
	v_fmac_f32_e32 v13, v16, v13
	v_div_scale_f32 v16, vcc, v2, v8, v2
	v_mul_f32_e32 v17, v16, v13
	v_fma_f32 v20, -v12, v17, v16
	v_fmac_f32_e32 v17, v20, v13
	v_fma_f32 v12, -v12, v17, v16
	v_div_fmas_f32 v12, v12, v13, v17
	v_div_fixup_f32 v8, v12, v8, v2
	v_pk_mul_f32 v[4:5], v[8:9], v[4:5]
	v_and_b32_e32 v9, 0xffff0000, v44
	v_lshlrev_b32_e32 v8, 16, v44
	v_pk_fma_f32 v[6:7], v[18:19], v[8:9], v[6:7]
	v_and_b32_e32 v9, 0xffff0000, v3
	v_lshlrev_b32_e32 v8, 16, v3
	ds_read_u16 v3, v82 offset:22016
	ds_read_u16 v10, v82 offset:23552
	v_mul_f32_e32 v2, 0xbfb8aa3b, v8
	v_exp_f32_e32 v2, v2
	s_waitcnt lgkmcnt(0)
	v_lshlrev_b32_e32 v11, 16, v10
	v_lshlrev_b32_e32 v10, 16, v3
	v_mul_f32_e32 v3, 0xbfb8aa3b, v9
	v_exp_f32_e32 v3, v3
	v_pk_mul_f32 v[6:7], v[6:7], v[10:11]
	v_pk_add_f32 v[2:3], v[2:3], 1.0 op_sel_hi:[1,0]
	s_nop 0
	v_div_scale_f32 v10, s[20:21], v3, v3, v9
	v_rcp_f32_e32 v11, v10
	s_nop 0
	v_fma_f32 v12, -v10, v11, 1.0
	v_fmac_f32_e32 v11, v12, v11
	v_div_scale_f32 v12, vcc, v9, v3, v9
	v_mul_f32_e32 v13, v12, v11
	v_fma_f32 v14, -v10, v13, v12
	v_fmac_f32_e32 v13, v14, v11
	v_fma_f32 v10, -v10, v13, v12
	v_div_fmas_f32 v10, v10, v11, v13
	v_div_fixup_f32 v3, v10, v3, v9
	v_div_scale_f32 v9, s[20:21], v2, v2, v8
	v_rcp_f32_e32 v10, v9
	s_nop 0
	v_fma_f32 v11, -v9, v10, 1.0
	v_fmac_f32_e32 v10, v11, v10
	v_div_scale_f32 v11, vcc, v8, v2, v8
	v_mul_f32_e32 v12, v11, v10
	v_fma_f32 v13, -v9, v12, v11
	v_fmac_f32_e32 v12, v13, v10
	v_fma_f32 v9, -v9, v12, v11
	v_div_fmas_f32 v9, v9, v10, v12
	v_div_fixup_f32 v2, v9, v2, v8
	v_pk_mul_f32 v[2:3], v[2:3], v[6:7]
	v_bfe_u32 v12, v23, 16, 1
	v_bfe_u32 v13, v22, 16, 1
	v_add3_u32 v13, v22, v13, s94
	v_add3_u32 v12, v23, v12, s94
	v_cvt_pk_bf16_f32 v0, v0, v1
	v_cvt_pk_bf16_f32 v4, v4, v5
	v_cvt_pk_bf16_f32 v2, v2, v3
	v_mov_b32_e32 v3, v2
	v_mov_b32_e32 v2, v4
	v_mov_b32_e32 v1, v0
	v_perm_b32 v0, v12, v13, s95
	global_store_dwordx4 v[30:31], v[0:3], off
	s_barrier

.LBB0_751:
	s_andn2_b64 vcc, exec, s[36:37]
	s_cbranch_vccnz .LBB0_774
	v_mov_b32_e32 v56, v189
	v_readlane_b32 s36, v251, 47
	v_and_b32_e32 v0, 63, v56
	v_lshlrev_b32_e32 v0, 2, v0
	v_readlane_b32 s37, v251, 48
	s_nop 4
	global_load_dword v16, v0, s[36:37]
	global_load_dword v17, v0, s[36:37] offset:256
	global_load_dword v18, v0, s[36:37] offset:512
	global_load_dword v19, v0, s[36:37] offset:768
	s_add_i32 s20, s19, 0xffffff00
	s_lshr_b32 s38, s20, 6
	s_lshl_b32 s20, s19, 6
	s_lshl_b32 s23, s38, 10
	s_and_b32 s20, s20, 0x3c0
	s_or_b32 s20, s23, s20
	v_ashrrev_i32_e32 v0, 2, v56
	s_addk_i32 s20, 0x1000
	v_and_b32_e32 v206, -16, v0
	v_and_b32_e32 v204, 15, v56
	v_add_u32_e32 v0, s20, v206
	s_lshl_b32 s21, s19, 3
	v_or_b32_e32 v2, v0, v204
	v_mov_b64_e32 v[0:1], s[6:7]
	s_and_b32 s21, s21, 0x180
	v_mad_i64_i32 v[0:1], s[36:37], v2, s0, v[0:1]
	s_lshl_b32 s36, s21, 1
	s_mov_b32 s37, s71
	v_lshl_add_u64 v[0:1], v[0:1], 0, s[36:37]
	v_and_b32_e32 v160, 48, v56
	v_lshl_add_u64 v[4:5], v[0:1], 0, v[160:161]
	s_movk_i32 s22, 0x1000
	v_add_co_u32_e32 v0, vcc, s22, v4
	v_mbcnt_hi_u32_b32 v151, -1, v194
	s_nop 0
	v_addc_co_u32_e32 v1, vcc, 0, v5, vcc
	global_load_dwordx4 v[0:3], v[0:1], off offset:1024
	v_and_b32_e32 v8, 64, v151
	s_mov_b64 s[36:37], 0x1400
	v_xor_b32_e32 v9, 32, v151
	v_add_u32_e32 v208, 64, v8
	v_lshl_add_u64 v[12:13], v[4:5], 0, s[36:37]
	v_xor_b32_e32 v10, 16, v151
	v_cmp_lt_i32_e32 vcc, v9, v208
	global_load_dwordx4 v[4:7], v[12:13], off offset:64
	v_xor_b32_e32 v11, 8, v151
	v_cndmask_b32_e32 v8, v151, v9, vcc
	v_cmp_lt_i32_e32 vcc, v10, v208
	v_lshlrev_b32_e32 v141, 2, v8
	v_xor_b32_e32 v14, 4, v151
	v_cndmask_b32_e32 v9, v151, v10, vcc
	v_cmp_lt_i32_e32 vcc, v11, v208
	v_lshlrev_b32_e32 v205, 2, v9
	s_mov_b32 s40, 0x3e000000
	v_cndmask_b32_e32 v10, v151, v11, vcc
	v_lshlrev_b32_e32 v22, 2, v10
	global_load_dwordx4 v[8:11], v[12:13], off offset:128
	v_cmp_lt_i32_e32 vcc, v14, v208
	v_xor_b32_e32 v15, 2, v151
	s_lshl_b32 s36, s38, 19
	v_cndmask_b32_e32 v14, v151, v14, vcc
	v_lshlrev_b32_e32 v25, 2, v14
	v_cmp_lt_i32_e32 vcc, v15, v208
	v_readlane_b32 s37, v251, 42
	v_ashrrev_i32_e32 v138, 4, v56
	v_cndmask_b32_e32 v15, v151, v15, vcc
	v_lshlrev_b32_e32 v26, 2, v15
	global_load_dwordx4 v[12:15], v[12:13], off offset:192
	s_or_b32 s36, s36, s37
	v_ashrrev_i32_e32 v139, 31, v138
	s_or_b32 s70, s36, s21
	v_lshlrev_b64 v[42:43], 9, v[138:139]
	v_lshlrev_b32_e32 v140, 3, v204
	v_readlane_b32 s36, v252, 55
	v_readlane_b32 s38, v252, 57
	v_readlane_b32 s37, v252, 56
	v_readlane_b32 s39, v252, 58
	v_or_b32_e32 v44, s70, v140
	v_mov_b32_e32 v45, v161
	s_barrier
	v_lshlrev_b32_e32 v207, 3, v56
	s_mov_b32 s22, 0
	v_mov_b32_e32 v154, 0xf149f2ca
	s_waitcnt vmcnt(0)
	v_mul_f32_e32 v20, v16, v17
	ds_bpermute_b32 v23, v141, v20
	s_waitcnt vmcnt(4)
	v_mul_f32_e32 v21, v18, v19
	ds_bpermute_b32 v24, v141, v21
	v_mov_b32_e32 v112, 0xf149f2ca
	s_mov_b64 s[42:43], 0x1800
	s_waitcnt lgkmcnt(1)
	v_fmac_f32_e32 v23, v16, v17
	ds_bpermute_b32 v27, v205, v23
	s_waitcnt lgkmcnt(1)
	v_fmac_f32_e32 v24, v18, v19
	ds_bpermute_b32 v28, v205, v24
	s_mov_b64 s[44:45], 0x1c00
	s_mov_b64 s[46:47], 0xf7c0000
	s_waitcnt lgkmcnt(1)
	v_add_f32_e32 v23, v23, v27
	ds_bpermute_b32 v27, v22, v23
	s_waitcnt lgkmcnt(1)
	v_add_f32_e32 v24, v24, v28
	ds_bpermute_b32 v22, v22, v24
	s_mov_b64 s[48:49], 0xfbc0000
	s_waitcnt lgkmcnt(0)
	v_add_f32_e32 v22, v24, v22
	ds_bpermute_b32 v24, v25, v22
	s_waitcnt lgkmcnt(0)
	v_add_f32_e32 v212, v22, v24
	ds_bpermute_b32 v213, v26, v212
	s_waitcnt vmcnt(3)
	v_and_b32_e32 v17, 0xffff0000, v0
	v_lshlrev_b32_e32 v16, 16, v0
	v_and_b32_e32 v19, 0xffff0000, v1
	v_lshlrev_b32_e32 v18, 16, v1
	v_and_b32_e32 v1, 0xffff0000, v2
	v_lshlrev_b32_e32 v0, 16, v2
	v_and_b32_e32 v21, 0xffff0000, v3
	v_lshlrev_b32_e32 v20, 16, v3
	v_pk_mul_f32 v[2:3], v[16:17], s[40:41] op_sel_hi:[1,0]
	v_pk_mul_f32 v[0:1], v[0:1], s[40:41] op_sel_hi:[1,0]
	v_bfe_u32 v33, v2, 16, 1
	v_add3_u32 v57, v2, v33, s94
	v_add_f32_e32 v2, v23, v27
	ds_bpermute_b32 v23, v25, v2
	v_cvt_pk_bf16_f32 v62, v0, v1
	s_waitcnt vmcnt(2)
	v_and_b32_e32 v1, 0xffff0000, v4
	v_lshlrev_b32_e32 v0, 16, v4
	v_pk_mul_f32 v[0:1], v[0:1], s[40:41] op_sel_hi:[1,0]
	v_pk_mul_f32 v[16:17], v[18:19], s[40:41] op_sel_hi:[1,0]
	s_waitcnt lgkmcnt(0)
	v_add_f32_e32 v210, v2, v23
	v_cvt_pk_bf16_f32 v74, v0, v1
	s_waitcnt vmcnt(1)
	v_and_b32_e32 v1, 0xffff0000, v8
	v_lshlrev_b32_e32 v0, 16, v8
	v_bfe_u32 v28, v3, 16, 1
	v_cvt_pk_bf16_f32 v60, v16, v17
	v_and_b32_e32 v17, 0xffff0000, v7
	v_lshlrev_b32_e32 v16, 16, v7
	v_pk_mul_f32 v[40:41], v[0:1], s[40:41] op_sel_hi:[1,0]
	v_and_b32_e32 v1, 0xffff0000, v9
	v_lshlrev_b32_e32 v0, 16, v9
	v_and_b32_e32 v37, 0xffff0000, v10
	v_lshlrev_b32_e32 v36, 16, v10
	v_add_u32_e32 v10, 0x100, v56
	v_pk_mul_f32 v[18:19], v[20:21], s[40:41] op_sel_hi:[1,0]
	v_add3_u32 v58, v3, v28, s94
	v_and_b32_e32 v3, 0xffff0000, v5
	v_lshlrev_b32_e32 v2, 16, v5
	v_and_b32_e32 v5, 0xffff0000, v6
	v_lshlrev_b32_e32 v4, 16, v6
	v_pk_mul_f32 v[6:7], v[16:17], s[40:41] op_sel_hi:[1,0]
	v_pk_mul_f32 v[8:9], v[0:1], s[40:41] op_sel_hi:[1,0]
	v_lshl_add_u64 v[0:1], v[42:43], 0, s[70:71]
	v_ashrrev_i32_e32 v136, 4, v10
	v_pk_mul_f32 v[2:3], v[2:3], s[40:41] op_sel_hi:[1,0]
	v_pk_mul_f32 v[4:5], v[4:5], s[40:41] op_sel_hi:[1,0]
	v_or_b32_e32 v0, v0, v140
	v_ashrrev_i32_e32 v137, 31, v136
	v_add_u32_e32 v10, 0x200, v56
	v_cvt_pk_bf16_f32 v72, v18, v19
	v_cvt_pk_bf16_f32 v80, v6, v7
	v_lshlrev_b64 v[0:1], 1, v[0:1]
	v_lshlrev_b64 v[16:17], 9, v[136:137]
	v_ashrrev_i32_e32 v134, 4, v10
	v_add_u32_e32 v10, 0x300, v56
	v_cvt_pk_bf16_f32 v76, v2, v3
	v_cvt_pk_bf16_f32 v78, v4, v5
	v_lshl_add_u64 v[2:3], s[36:37], 0, v[0:1]
	v_lshl_add_u64 v[4:5], s[38:39], 0, v[0:1]
	v_lshl_add_u64 v[16:17], v[16:17], 0, v[44:45]
	v_ashrrev_i32_e32 v135, 31, v134
	v_ashrrev_i32_e32 v132, 4, v10
	global_load_dwordx4 v[0:3], v[2:3], off
	s_nop 0
	global_load_dwordx4 v[4:7], v[4:5], off
	v_lshlrev_b64 v[46:47], 1, v[16:17]
	v_lshlrev_b64 v[24:25], 9, v[134:135]
	v_ashrrev_i32_e32 v133, 31, v132
	v_lshl_add_u64 v[16:17], s[36:37], 0, v[46:47]
	v_lshl_add_u64 v[20:21], s[38:39], 0, v[46:47]
	v_lshl_add_u64 v[24:25], v[24:25], 0, v[44:45]
	v_lshlrev_b64 v[32:33], 9, v[132:133]
	global_load_dwordx4 v[16:19], v[16:17], off
	s_nop 0
	global_load_dwordx4 v[20:23], v[20:21], off
	v_lshlrev_b64 v[48:49], 1, v[24:25]
	v_lshl_add_u64 v[32:33], v[32:33], 0, v[44:45]
	v_lshl_add_u64 v[24:25], s[36:37], 0, v[48:49]
	v_lshl_add_u64 v[28:29], s[38:39], 0, v[48:49]
	v_lshlrev_b64 v[50:51], 1, v[32:33]
	ds_bpermute_b32 v211, v26, v210
	global_load_dwordx4 v[24:27], v[24:25], off
	s_nop 0
	global_load_dwordx4 v[28:31], v[28:29], off
	v_lshl_add_u64 v[32:33], s[36:37], 0, v[50:51]
	global_load_dwordx4 v[32:35], v[32:33], off
	v_pk_mul_f32 v[52:53], v[36:37], s[40:41] op_sel_hi:[1,0]
	v_lshl_add_u64 v[36:37], s[38:39], 0, v[50:51]
	global_load_dwordx4 v[36:39], v[36:37], off
	v_and_b32_e32 v55, 0xffff0000, v11
	v_lshlrev_b32_e32 v54, 16, v11
	v_pk_mul_f32 v[10:11], v[54:55], s[40:41] op_sel_hi:[1,0]
	v_bfe_u32 v54, v11, 16, 1
	v_bfe_u32 v55, v10, 16, 1
	v_add3_u32 v55, v10, v55, s94
	v_add3_u32 v54, v11, v54, s94
	s_waitcnt vmcnt(8)
	v_and_b32_e32 v11, 0xffff0000, v13
	v_lshlrev_b32_e32 v10, 16, v13
	v_pk_mul_f32 v[10:11], v[10:11], s[40:41] op_sel_hi:[1,0]
	v_cvt_pk_bf16_f32 v82, v40, v41
	v_cvt_pk_bf16_f32 v84, v8, v9
	v_and_b32_e32 v9, 0xffff0000, v12
	v_lshlrev_b32_e32 v8, 16, v12
	v_and_b32_e32 v13, 0xffff0000, v14
	v_lshlrev_b32_e32 v12, 16, v14
	v_and_b32_e32 v41, 0xffff0000, v15
	v_lshlrev_b32_e32 v40, 16, v15
	v_bfe_u32 v67, v10, 16, 1
	v_pk_mul_f32 v[8:9], v[8:9], s[40:41] op_sel_hi:[1,0]
	v_pk_mul_f32 v[12:13], v[12:13], s[40:41] op_sel_hi:[1,0]
	v_pk_mul_f32 v[14:15], v[40:41], s[40:41] op_sel_hi:[1,0]
	v_add3_u32 v87, v10, v67, s94
	s_movk_i32 s40, 0x110
	v_lshlrev_b32_e32 v10, 4, v56
	v_mul_lo_u32 v214, v138, s40
	v_and_b32_e32 v215, 0xf0, v10
	s_movk_i32 s41, 0x120
	v_add3_u32 v10, s17, v214, v215
	v_mul_lo_u32 v216, v138, s41
	v_mul_lo_u32 v217, v136, s40
	v_mul_lo_u32 v218, v136, s41
	v_mul_lo_u32 v219, v134, s40
	v_mul_lo_u32 v220, v134, s41
	v_mul_lo_u32 v221, v132, s40
	v_mul_lo_u32 v222, v132, s41
	s_mov_b64 s[40:41], 0x10000
	v_cvt_pk_bf16_f32 v14, v14, v15
	v_cvt_pk_bf16_f32 v52, v52, v53
	v_bfe_u32 v66, v11, 16, 1
	v_cvt_pk_bf16_f32 v86, v8, v9
	s_waitcnt vmcnt(7)
	ds_write_b128 v10, v[0:3]
	v_add3_u32 v0, s17, v216, v215
	s_waitcnt vmcnt(6)
	ds_write_b128 v0, v[4:7] offset:17408
	v_add3_u32 v0, s17, v217, v215
	v_add3_u32 v88, v11, v66, s94
	v_cvt_pk_bf16_f32 v12, v12, v13
	v_lshrrev_b32_e32 v9, 2, v56
	s_waitcnt vmcnt(5)
	ds_write_b128 v0, v[16:19]
	v_add3_u32 v0, s17, v218, v215
	s_waitcnt vmcnt(4)
	ds_write_b128 v0, v[20:23] offset:17408
	v_add3_u32 v0, s17, v219, v215
	v_bfe_u32 v8, v56, 2, 2
	v_and_b32_e32 v209, 12, v9
	v_or_b32_e32 v8, v209, v8
	s_waitcnt vmcnt(3)
	ds_write_b128 v0, v[24:27]
	v_add3_u32 v0, s17, v220, v215
	s_waitcnt vmcnt(2)
	ds_write_b128 v0, v[28:31] offset:17408
	v_add3_u32 v0, s17, v221, v215
	s_waitcnt vmcnt(1)
	ds_write_b128 v0, v[32:35]
	v_add3_u32 v0, s17, v222, v215
	s_waitcnt vmcnt(0)
	ds_write_b128 v0, v[36:39] offset:17408
	v_lshl_add_u64 v[0:1], v[42:43], 0, v[44:45]
	v_lshl_add_u64 v[0:1], v[0:1], 1, v[166:167]
	v_lshl_add_u64 v[2:3], s[36:37], 0, v[0:1]
	v_lshl_add_u64 v[0:1], s[38:39], 0, v[0:1]
	global_load_dwordx4 v[16:19], v[2:3], off
	global_load_dwordx4 v[20:23], v[0:1], off
	v_lshl_add_u64 v[0:1], v[46:47], 0, s[40:41]
	v_lshl_add_u64 v[2:3], s[36:37], 0, v[0:1]
	v_lshl_add_u64 v[0:1], s[38:39], 0, v[0:1]
	global_load_dwordx4 v[24:27], v[2:3], off
	global_load_dwordx4 v[28:31], v[0:1], off
	v_lshl_add_u64 v[0:1], v[48:49], 0, s[40:41]
	v_lshl_add_u64 v[2:3], s[36:37], 0, v[0:1]
	v_lshl_add_u64 v[0:1], s[38:39], 0, v[0:1]
	global_load_dwordx4 v[36:39], v[2:3], off
	global_load_dwordx4 v[40:43], v[0:1], off
	v_lshl_add_u64 v[0:1], v[50:51], 0, s[40:41]
	v_lshl_add_u64 v[2:3], s[36:37], 0, v[0:1]
	v_lshl_add_u64 v[0:1], s[38:39], 0, v[0:1]
	global_load_dwordx4 v[64:67], v[2:3], off
	global_load_dwordx4 v[68:71], v[0:1], off
	v_mul_u32_u24_e32 v32, 0x110, v204
	v_add3_u32 v224, s17, v160, v32
	v_lshlrev_b64 v[32:33], 10, v[132:133]
	v_lshlrev_b32_e32 v160, 1, v44
	v_lshl_add_u64 v[32:33], v[32:33], 0, v[160:161]
	v_lshl_add_u64 v[144:145], s[30:31], 0, v[32:33]
	v_add_u32_e32 v32, s23, v132
	v_add_u32_e32 v133, 0xe80, v32
	v_lshlrev_b64 v[32:33], 10, v[134:135]
	v_lshl_add_u64 v[32:33], v[32:33], 0, v[160:161]
	v_lshl_add_u64 v[146:147], s[30:31], 0, v[32:33]
	v_add_u32_e32 v32, s23, v134
	v_add_u32_e32 v135, 0xe80, v32
	v_lshlrev_b64 v[32:33], 10, v[136:137]
	v_lshl_add_u64 v[32:33], v[32:33], 0, v[160:161]
	v_lshl_add_u64 v[148:149], s[30:31], 0, v[32:33]
	v_add_u32_e32 v32, s23, v136
	v_add_u32_e32 v137, 0xe80, v32
	v_lshlrev_b64 v[32:33], 10, v[138:139]
	v_lshl_add_u64 v[32:33], v[32:33], 0, v[160:161]
	v_lshl_add_u64 v[152:153], s[30:31], 0, v[32:33]
	v_add_u32_e32 v32, s23, v138
	v_mul_u32_u24_e32 v8, 0x120, v8
	v_and_b32_e32 v9, 24, v207
	v_readlane_b32 s36, v251, 56
	v_add_u32_e32 v139, 0xe80, v32
	v_mov_b32_e32 v32, 0
	v_add3_u32 v223, v9, s36, v8
	v_mov_b32_e32 v3, v72
	v_mov_b32_e32 v2, v62
	v_mov_b32_e32 v1, v60
	v_perm_b32 v0, v58, v57, s95
	v_mov_b32_e32 v7, v80
	v_mov_b32_e32 v6, v78
	v_mov_b32_e32 v5, v76
	v_mov_b32_e32 v4, v74
	v_perm_b32 v11, v54, v55, s95
	v_mov_b32_e32 v10, v52
	v_mov_b32_e32 v9, v84
	v_mov_b32_e32 v8, v82
	v_mov_b32_e32 v15, v14
	v_mov_b32_e32 v14, v12
	v_perm_b32 v13, v88, v87, s95
	v_mov_b32_e32 v12, v86
	s_mov_b64 s[38:39], 0
	v_mov_b32_e32 v33, v32
	v_mov_b32_e32 v34, v32
	v_mov_b32_e32 v35, v32
	v_mov_b32_e32 v44, v32
	v_mov_b32_e32 v45, v32
	v_mov_b32_e32 v46, v32
	v_mov_b32_e32 v47, v32
	v_mov_b32_e32 v60, v32
	v_mov_b32_e32 v61, v32
	v_mov_b32_e32 v62, v32
	v_mov_b32_e32 v63, v32
	v_mov_b32_e32 v76, v32
	v_mov_b32_e32 v77, v32
	v_mov_b32_e32 v78, v32
	v_mov_b32_e32 v79, v32
	v_mov_b32_e32 v80, v32
	v_mov_b32_e32 v81, v32
	v_mov_b32_e32 v82, v32
	v_mov_b32_e32 v83, v32
	v_mov_b32_e32 v84, v32
	v_mov_b32_e32 v85, v32
	v_mov_b32_e32 v86, v32
	v_mov_b32_e32 v87, v32
	v_mov_b32_e32 v88, v32
	v_mov_b32_e32 v89, v32
	v_mov_b32_e32 v90, v32
	v_mov_b32_e32 v91, v32
	v_mov_b32_e32 v96, v32
	v_mov_b32_e32 v97, v32
	v_mov_b32_e32 v98, v32
	v_mov_b32_e32 v99, v32
	v_mov_b32_e32 v92, v32
	v_mov_b32_e32 v93, v32
	v_mov_b32_e32 v94, v32
	v_mov_b32_e32 v95, v32
	v_mov_b32_e32 v100, v32
	v_mov_b32_e32 v101, v32
	v_mov_b32_e32 v102, v32
	v_mov_b32_e32 v103, v32
	v_mov_b32_e32 v104, v32
	v_mov_b32_e32 v105, v32
	v_mov_b32_e32 v106, v32
	v_mov_b32_e32 v107, v32
	v_mov_b32_e32 v108, v32
	v_mov_b32_e32 v109, v32
	v_mov_b32_e32 v110, v32
	v_mov_b32_e32 v111, v32
	v_mov_b32_e32 v72, v32
	v_mov_b32_e32 v73, v32
	v_mov_b32_e32 v74, v32
	v_mov_b32_e32 v75, v32
	v_mov_b32_e32 v56, v32
	v_mov_b32_e32 v57, v32
	v_mov_b32_e32 v58, v32
	v_mov_b32_e32 v59, v32
	v_mov_b32_e32 v52, v32
	v_mov_b32_e32 v53, v32
	v_mov_b32_e32 v54, v32
	v_mov_b32_e32 v55, v32
	v_mov_b32_e32 v48, v32
	v_mov_b32_e32 v49, v32
	v_mov_b32_e32 v50, v32
	v_mov_b32_e32 v51, v32
	v_mov_b32_e32 v142, v32
	v_mov_b32_e32 v143, v32
	s_waitcnt lgkmcnt(0)
	s_barrier
	s_branch .LBB0_755

.LBB0_754:
	s_mul_i32 s23, s23, 0x8c00
	v_add_u32_e32 v225, s23, v223
	v_add_u32_e32 v113, s23, v224
	ds_read_b128 v[114:117], v113
	ds_read_b128 v[118:121], v113 offset:64
	s_waitcnt lgkmcnt(1)
	v_mfma_f32_16x16x32_bf16 v[114:117], v[114:117], v[0:3], 0
	s_waitcnt lgkmcnt(0)
	v_mfma_f32_16x16x32_bf16 v[156:159], v[118:121], v[4:7], v[114:117]
	ds_read_b128 v[118:121], v113 offset:4416
	s_nop 4
	ds_read_b128 v[114:117], v113 offset:4352
	s_waitcnt lgkmcnt(0)
	v_mfma_f32_16x16x32_bf16 v[114:117], v[114:117], v[0:3], 0
	v_mfma_f32_16x16x32_bf16 v[172:175], v[118:121], v[4:7], v[114:117]
	s_nop 6
	ds_read_b128 v[114:117], v113 offset:8704
	ds_read_b128 v[118:121], v113 offset:8768
	s_waitcnt lgkmcnt(1)
	v_mfma_f32_16x16x32_bf16 v[114:117], v[114:117], v[0:3], 0
	s_waitcnt lgkmcnt(0)
	v_mfma_f32_16x16x32_bf16 v[178:181], v[118:121], v[4:7], v[114:117]
	ds_read_b128 v[118:121], v113 offset:13120
	s_nop 4
	ds_read_b128 v[114:117], v113 offset:13056
	s_waitcnt lgkmcnt(0)
	v_mfma_f32_16x16x32_bf16 v[114:117], v[114:117], v[0:3], 0
	v_mfma_f32_16x16x32_bf16 v[228:231], v[118:121], v[4:7], v[114:117]
	s_nop 6
	ds_read_b128 v[114:117], v113 offset:128
	ds_read_b128 v[118:121], v113 offset:192
	ds_read_b128 v[122:125], v113 offset:4480
	s_waitcnt lgkmcnt(2)
	v_mfma_f32_16x16x32_bf16 v[114:117], v[114:117], v[8:11], 0
	s_waitcnt lgkmcnt(1)
	v_mfma_f32_16x16x32_bf16 v[128:131], v[118:121], v[12:15], v[114:117]
	s_nop 5
	ds_read_b128 v[114:117], v113 offset:4544
	s_waitcnt lgkmcnt(1)
	v_mfma_f32_16x16x32_bf16 v[122:125], v[122:125], v[8:11], 0
	s_waitcnt lgkmcnt(0)
	v_mfma_f32_16x16x32_bf16 v[120:123], v[114:117], v[12:15], v[122:125]
	ds_read_b128 v[114:117], v113 offset:8832
	s_nop 4
	ds_read_b128 v[124:127], v113 offset:8896
	s_waitcnt lgkmcnt(1)
	v_mfma_f32_16x16x32_bf16 v[114:117], v[114:117], v[8:11], 0
	s_waitcnt lgkmcnt(0)
	v_mfma_f32_16x16x32_bf16 v[116:119], v[124:127], v[12:15], v[114:117]
	ds_read_b128 v[124:127], v113 offset:13248
	ds_read_b128 v[182:185], v113 offset:13184
	s_waitcnt lgkmcnt(0)
	v_mfma_f32_16x16x32_bf16 v[182:185], v[182:185], v[8:11], 0
	v_mfma_f32_16x16x32_bf16 v[124:127], v[124:127], v[12:15], v[182:185]
	v_max3_f32 v113, v156, s8, v157
	v_max3_f32 v113, v113, v158, v159
	v_max3_f32 v113, v113, v172, v173
	v_max3_f32 v113, v113, v174, v175
	v_max3_f32 v113, v113, v178, v179
	v_max3_f32 v113, v113, v180, v181
	v_max3_f32 v113, v113, v228, v229
	v_max3_f32 v113, v113, v230, v231
	ds_bpermute_b32 v114, v205, v113
	s_waitcnt lgkmcnt(0)
	v_max_f32_e32 v114, v114, v114
	v_max_f32_e32 v113, v113, v114
	ds_bpermute_b32 v114, v141, v113
	s_waitcnt lgkmcnt(0)
	v_max3_f32 v226, v112, v113, v114
	v_sub_f32_e32 v114, v157, v226
	v_mul_f32_e32 v114, 0x3fb8aa3b, v114
	v_exp_f32_e32 v176, v114
	v_sub_f32_e32 v114, v158, v226
	v_sub_f32_e32 v113, v156, v226
	v_mul_f32_e32 v114, 0x3fb8aa3b, v114
	v_mul_f32_e32 v113, 0x3fb8aa3b, v113
	v_exp_f32_e32 v158, v114
	v_sub_f32_e32 v114, v159, v226
	v_exp_f32_e32 v156, v113
	v_mul_f32_e32 v114, 0x3fb8aa3b, v114
	v_exp_f32_e32 v182, v114
	v_sub_f32_e32 v114, v172, v226
	v_mul_f32_e32 v114, 0x3fb8aa3b, v114
	v_exp_f32_e32 v172, v114
	v_sub_f32_e32 v114, v173, v226
	v_add_f32_e32 v113, 0, v156
	v_mul_f32_e32 v114, 0x3fb8aa3b, v114
	v_add_f32_e32 v113, v176, v113
	v_exp_f32_e32 v184, v114
	v_add_f32_e32 v113, v158, v113
	v_add_f32_e32 v113, v182, v113
	v_add_f32_e32 v113, v172, v113
	v_add_f32_e32 v187, v184, v113
	v_sub_f32_e32 v113, v174, v226
	v_mul_f32_e32 v113, 0x3fb8aa3b, v113
	v_exp_f32_e32 v177, v113
	v_sub_f32_e32 v113, v175, v226
	v_mul_f32_e32 v113, 0x3fb8aa3b, v113
	v_exp_f32_e32 v183, v113
	v_sub_f32_e32 v113, v178, v226
	v_mul_f32_e32 v113, 0x3fb8aa3b, v113
	v_exp_f32_e32 v155, v113
	v_sub_f32_e32 v113, v179, v226
	v_mul_f32_e32 v113, 0x3fb8aa3b, v113
	v_exp_f32_e32 v159, v113
	v_sub_f32_e32 v113, v180, v226
	v_mul_f32_e32 v113, 0x3fb8aa3b, v113
	v_exp_f32_e32 v157, v113
	v_sub_f32_e32 v113, v181, v226
	v_mul_f32_e32 v113, 0x3fb8aa3b, v113
	v_exp_f32_e32 v175, v113
	v_sub_f32_e32 v113, v228, v226
	v_mul_f32_e32 v113, 0x3fb8aa3b, v113
	v_exp_f32_e32 v173, v113
	v_sub_f32_e32 v113, v229, v226
	v_mul_f32_e32 v113, 0x3fb8aa3b, v113
	v_exp_f32_e32 v181, v113
	v_sub_f32_e32 v113, v230, v226
	v_sub_f32_e32 v112, v112, v226
	v_mul_f32_e32 v113, 0x3fb8aa3b, v113
	v_mul_f32_e32 v112, 0x3fb8aa3b, v112
	v_exp_f32_e32 v179, v113
	v_sub_f32_e32 v113, v231, v226
	v_mul_f32_e32 v113, 0x3fb8aa3b, v113
	v_exp_f32_e32 v160, v112
	v_exp_f32_e32 v185, v113
	v_pk_mul_f32 v[112:113], v[108:109], v[160:161] op_sel_hi:[1,0]
	v_pk_mul_f32 v[108:109], v[104:105], v[160:161] op_sel_hi:[1,0]
	v_pk_mul_f32 v[104:105], v[100:101], v[160:161] op_sel_hi:[1,0]
	v_pk_mul_f32 v[100:101], v[92:93], v[160:161] op_sel_hi:[1,0]
	v_pk_mul_f32 v[92:93], v[96:97], v[160:161] op_sel_hi:[1,0]
	v_max3_f32 v96, v128, s8, v129
	v_max3_f32 v96, v96, v130, v131
	v_max3_f32 v96, v96, v120, v121
	v_max3_f32 v96, v96, v122, v123
	v_max3_f32 v96, v96, v116, v117
	v_max3_f32 v96, v96, v118, v119
	v_max3_f32 v96, v96, v124, v125
	v_cvt_pk_bf16_f32 v242, v177, v183
	v_max3_f32 v96, v96, v126, v127
	v_cvt_pk_bf16_f32 v234, v179, v185
	ds_bpermute_b32 v97, v205, v96
	v_pk_mul_f32 v[114:115], v[110:111], v[160:161] op_sel_hi:[1,0]
	v_pk_mul_f32 v[110:111], v[106:107], v[160:161] op_sel_hi:[1,0]
	v_pk_mul_f32 v[106:107], v[102:103], v[160:161] op_sel_hi:[1,0]
	v_pk_mul_f32 v[102:103], v[94:95], v[160:161] op_sel_hi:[1,0]
	s_waitcnt lgkmcnt(0)
	v_max_f32_e32 v97, v97, v97
	v_max_f32_e32 v96, v96, v97
	ds_bpermute_b32 v97, v141, v96
	v_pk_mul_f32 v[94:95], v[98:99], v[160:161] op_sel_hi:[1,0]
	s_waitcnt lgkmcnt(0)
	v_max3_f32 v227, v154, v96, v97
	v_sub_f32_e32 v98, v129, v227
	v_mul_f32_e32 v98, 0x3fb8aa3b, v98
	v_exp_f32_e32 v129, v98
	v_sub_f32_e32 v98, v130, v227
	v_sub_f32_e32 v97, v128, v227
	v_mul_f32_e32 v98, 0x3fb8aa3b, v98
	v_mul_f32_e32 v97, 0x3fb8aa3b, v97
	v_exp_f32_e32 v130, v98
	v_sub_f32_e32 v98, v131, v227
	v_exp_f32_e32 v128, v97
	v_mul_f32_e32 v98, 0x3fb8aa3b, v98
	v_exp_f32_e32 v131, v98
	v_sub_f32_e32 v98, v120, v227
	v_mul_f32_e32 v98, 0x3fb8aa3b, v98
	v_exp_f32_e32 v244, v98
	v_sub_f32_e32 v98, v121, v227
	v_add_f32_e32 v97, 0, v128
	v_mul_f32_e32 v98, 0x3fb8aa3b, v98
	v_add_f32_e32 v97, v129, v97
	v_exp_f32_e32 v245, v98
	v_add_f32_e32 v97, v130, v97
	v_add_f32_e32 v97, v131, v97
	v_add_f32_e32 v97, v244, v97
	v_add_f32_e32 v186, v245, v97
	v_sub_f32_e32 v97, v122, v227
	v_mul_f32_e32 v97, 0x3fb8aa3b, v97
	v_cvt_pk_bf16_f32 v237, v156, v176
	v_exp_f32_e32 v176, v97
	v_sub_f32_e32 v97, v123, v227
	v_bfe_u32 v174, v182, 16, 1
	v_mul_f32_e32 v97, 0x3fb8aa3b, v97
	v_add3_u32 v239, v182, v174, s94
	v_exp_f32_e32 v182, v97
	v_sub_f32_e32 v97, v116, v227
	v_mul_f32_e32 v97, 0x3fb8aa3b, v97
	v_bfe_u32 v178, v158, 16, 1
	v_sub_f32_e32 v96, v154, v227
	v_exp_f32_e32 v154, v97
	v_sub_f32_e32 v97, v117, v227
	v_add3_u32 v238, v158, v178, s94
	v_mul_f32_e32 v97, 0x3fb8aa3b, v97
	v_exp_f32_e32 v158, v97
	v_sub_f32_e32 v97, v118, v227
	v_mul_f32_e32 v97, 0x3fb8aa3b, v97
	v_cvt_pk_bf16_f32 v231, v157, v175
	v_exp_f32_e32 v156, v97
	v_sub_f32_e32 v97, v119, v227
	v_mul_f32_e32 v97, 0x3fb8aa3b, v97
	v_exp_f32_e32 v174, v97
	v_sub_f32_e32 v97, v124, v227
	v_cvt_pk_bf16_f32 v240, v172, v184
	v_mul_f32_e32 v97, 0x3fb8aa3b, v97
	v_cvt_pk_bf16_f32 v229, v155, v159
	v_exp_f32_e32 v172, v97
	v_sub_f32_e32 v97, v125, v227
	v_mul_f32_e32 v97, 0x3fb8aa3b, v97
	v_exp_f32_e32 v180, v97
	v_sub_f32_e32 v97, v126, v227
	v_mul_f32_e32 v97, 0x3fb8aa3b, v97
	v_exp_f32_e32 v178, v97
	v_sub_f32_e32 v97, v127, v227
	v_mul_f32_e32 v96, 0x3fb8aa3b, v96
	v_mul_f32_e32 v97, 0x3fb8aa3b, v97
	v_exp_f32_e32 v184, v97
	v_exp_f32_e32 v120, v96
	v_pk_add_f32 v[96:97], v[176:177], v[186:187]
	v_pk_add_f32 v[96:97], v[182:183], v[96:97]
	v_mov_b32_e32 v121, v160
	v_pk_add_f32 v[96:97], v[154:155], v[96:97]
	v_cvt_pk_bf16_f32 v232, v173, v181
	v_pk_add_f32 v[96:97], v[158:159], v[96:97]
	v_pk_mul_f32 v[98:99], v[62:63], v[120:121] op_sel_hi:[1,0]
	v_pk_add_f32 v[96:97], v[156:157], v[96:97]
	v_pk_mul_f32 v[62:63], v[34:35], v[120:121] op_sel_hi:[1,0]
	v_pk_add_f32 v[96:97], v[174:175], v[96:97]
	v_pk_mul_f32 v[34:35], v[74:75], v[120:121] op_sel_hi:[1,0]
	v_pk_add_f32 v[96:97], v[172:173], v[96:97]
	v_pk_add_f32 v[96:97], v[180:181], v[96:97]
	v_pk_add_f32 v[96:97], v[178:179], v[96:97]
	v_pk_mul_f32 v[90:91], v[90:91], v[160:161] op_sel_hi:[1,0]
	v_pk_add_f32 v[96:97], v[184:185], v[96:97]
	v_pk_mul_f32 v[88:89], v[88:89], v[160:161] op_sel_hi:[1,0]
	v_pk_mul_f32 v[86:87], v[86:87], v[160:161] op_sel_hi:[1,0]
	v_pk_mul_f32 v[84:85], v[84:85], v[160:161] op_sel_hi:[1,0]
	v_pk_mul_f32 v[82:83], v[82:83], v[160:161] op_sel_hi:[1,0]
	v_pk_mul_f32 v[80:81], v[80:81], v[160:161] op_sel_hi:[1,0]
	v_pk_fma_f32 v[142:143], v[142:143], v[120:121], v[96:97]
	v_pk_mul_f32 v[118:119], v[78:79], v[120:121] op_sel_hi:[1,0]
	v_pk_mul_f32 v[116:117], v[76:77], v[120:121] op_sel_hi:[1,0]
	v_pk_mul_f32 v[96:97], v[60:61], v[120:121] op_sel_hi:[1,0]
	v_pk_mul_f32 v[78:79], v[46:47], v[120:121] op_sel_hi:[1,0]
	v_pk_mul_f32 v[76:77], v[44:45], v[120:121] op_sel_hi:[1,0]
	v_pk_mul_f32 v[60:61], v[32:33], v[120:121] op_sel_hi:[1,0]
	v_pk_mul_f32 v[32:33], v[72:73], v[120:121] op_sel_hi:[1,0]
	v_pk_mul_f32 v[46:47], v[58:59], v[120:121] op_sel_hi:[1,0]
	v_pk_mul_f32 v[44:45], v[56:57], v[120:121] op_sel_hi:[1,0]
	v_cvt_pk_bf16_f32 v173, v128, v129
	v_cvt_pk_bf16_f32 v175, v130, v131
	v_cvt_pk_bf16_f32 v177, v244, v245
	v_cvt_pk_bf16_f32 v247, v154, v158
	v_cvt_pk_bf16_f32 v248, v156, v174
	v_add_u32_e32 v128, 0x1200, v225
	v_add_u32_e32 v129, 32, v225
	v_add_u32_e32 v130, 0x1220, v225
	v_add_u32_e32 v131, 64, v225
	v_add_u32_e32 v154, 0x1240, v225
	v_add_u32_e32 v156, 0x60, v225
	v_pk_mul_f32 v[54:55], v[54:55], v[120:121] op_sel_hi:[1,0]
	v_pk_mul_f32 v[52:53], v[52:53], v[120:121] op_sel_hi:[1,0]
	v_pk_mul_f32 v[50:51], v[50:51], v[120:121] op_sel_hi:[1,0]
	v_pk_mul_f32 v[48:49], v[48:49], v[120:121] op_sel_hi:[1,0]
	v_cvt_pk_bf16_f32 v249, v172, v180
	v_cvt_pk_bf16_f32 v250, v178, v184
	v_add_u32_e32 v172, 0x1260, v225
	ds_read_b64_tr_b16 v[124:125], v225
	ds_read_b64_tr_b16 v[126:127], v128
	ds_read_b64_tr_b16 v[120:121], v129
	ds_read_b64_tr_b16 v[122:123], v130
	ds_read_b64_tr_b16 v[72:73], v131
	ds_read_b64_tr_b16 v[74:75], v154
	ds_read_b64_tr_b16 v[56:57], v156
	ds_read_b64_tr_b16 v[58:59], v172
	s_waitcnt lgkmcnt(0)
	v_mov_b32_e32 v131, v242
	v_mov_b32_e32 v130, v240
	v_perm_b32 v129, v239, v238, s95
	v_mov_b32_e32 v128, v237
	v_mov_b32_e32 v156, v177
	v_mov_b32_e32 v155, v175
	v_mov_b32_e32 v154, v173
	v_cvt_pk_bf16_f32 v157, v176, v182
	v_mfma_f32_16x16x32_bf16 v[112:115], v[124:127], v[128:131], v[112:115]
	s_nop 0
	v_mfma_f32_16x16x32_bf16 v[116:119], v[124:127], v[154:157], v[116:119]
	v_mfma_f32_16x16x32_bf16 v[124:127], v[120:123], v[128:131], v[108:111]
	v_mfma_f32_16x16x32_bf16 v[96:99], v[120:123], v[154:157], v[96:99]
	v_mfma_f32_16x16x32_bf16 v[120:123], v[72:75], v[128:131], v[104:107]
	v_mfma_f32_16x16x32_bf16 v[72:75], v[72:75], v[154:157], v[76:79]
	v_mfma_f32_16x16x32_bf16 v[172:175], v[56:59], v[128:131], v[100:103]
	v_mfma_f32_16x16x32_bf16 v[56:59], v[56:59], v[154:157], v[60:63]
	v_add_u32_e32 v108, 0x80, v225
	v_add_u32_e32 v109, 0x1280, v225
	v_add_u32_e32 v110, 0xa0, v225
	v_add_u32_e32 v111, 0x12a0, v225
	v_add_u32_e32 v159, 0xc0, v225
	v_add_u32_e32 v160, 0x12c0, v225
	v_add_u32_e32 v176, 0xe0, v225
	v_add_u32_e32 v177, 0x12e0, v225
	ds_read_b64_tr_b16 v[104:105], v108
	ds_read_b64_tr_b16 v[106:107], v109
	ds_read_b64_tr_b16 v[100:101], v110
	ds_read_b64_tr_b16 v[102:103], v111
	ds_read_b64_tr_b16 v[76:77], v159
	ds_read_b64_tr_b16 v[78:79], v160
	ds_read_b64_tr_b16 v[60:61], v176
	ds_read_b64_tr_b16 v[62:63], v177
	s_waitcnt lgkmcnt(0)
	s_nop 0
	v_mfma_f32_16x16x32_bf16 v[88:91], v[100:103], v[128:131], v[88:91]
	v_mfma_f32_16x16x32_bf16 v[84:87], v[76:79], v[128:131], v[84:87]
	v_mfma_f32_16x16x32_bf16 v[52:55], v[76:79], v[154:157], v[52:55]
	v_mfma_f32_16x16x32_bf16 v[80:83], v[60:63], v[128:131], v[80:83]
	v_mfma_f32_16x16x32_bf16 v[48:51], v[60:63], v[154:157], v[48:51]
	v_mfma_f32_16x16x32_bf16 v[176:179], v[104:107], v[128:131], v[92:95]
	v_mfma_f32_16x16x32_bf16 v[180:183], v[104:107], v[154:157], v[32:35]
	v_mfma_f32_16x16x32_bf16 v[184:187], v[100:103], v[154:157], v[44:47]
	s_nop 0
	v_add_u32_e32 v92, 0x2400, v225
	v_add_u32_e32 v93, 0x3600, v225
	v_add_u32_e32 v94, 0x2420, v225
	v_add_u32_e32 v95, 0x3620, v225
	v_add_u32_e32 v100, 0x2440, v225
	v_add_u32_e32 v101, 0x3640, v225
	v_add_u32_e32 v102, 0x2460, v225
	v_add_u32_e32 v103, 0x3660, v225
	ds_read_b64_tr_b16 v[76:77], v92
	ds_read_b64_tr_b16 v[78:79], v93
	ds_read_b64_tr_b16 v[60:61], v94
	ds_read_b64_tr_b16 v[62:63], v95
	ds_read_b64_tr_b16 v[44:45], v100
	ds_read_b64_tr_b16 v[46:47], v101
	ds_read_b64_tr_b16 v[32:33], v102
	ds_read_b64_tr_b16 v[34:35], v103
	s_waitcnt lgkmcnt(0)
	v_mov_b32_e32 v131, v234
	v_mov_b32_e32 v130, v232
	v_mov_b32_e32 v129, v231
	v_mov_b32_e32 v128, v229
	v_mov_b32_e32 v157, v250
	v_mov_b32_e32 v156, v249
	v_mov_b32_e32 v155, v248
	v_mov_b32_e32 v154, v247
	v_mfma_f32_16x16x32_bf16 v[108:111], v[76:79], v[128:131], v[112:115]
	s_nop 0
	v_mfma_f32_16x16x32_bf16 v[76:79], v[76:79], v[154:157], v[116:119]
	v_mfma_f32_16x16x32_bf16 v[104:107], v[60:63], v[128:131], v[124:127]
	v_mfma_f32_16x16x32_bf16 v[60:63], v[60:63], v[154:157], v[96:99]
	v_mfma_f32_16x16x32_bf16 v[100:103], v[44:47], v[128:131], v[120:123]
	v_mfma_f32_16x16x32_bf16 v[44:47], v[44:47], v[154:157], v[72:75]
	v_mfma_f32_16x16x32_bf16 v[92:95], v[32:35], v[128:131], v[172:175]
	v_mfma_f32_16x16x32_bf16 v[32:35], v[32:35], v[154:157], v[56:59]
	v_add_u32_e32 v96, 0x2480, v225
	v_add_u32_e32 v97, 0x3680, v225
	v_add_u32_e32 v98, 0x24a0, v225
	v_add_u32_e32 v99, 0x36a0, v225
	v_add_u32_e32 v120, 0x24c0, v225
	v_add_u32_e32 v121, 0x36c0, v225
	v_add_u32_e32 v122, 0x24e0, v225
	v_add_u32_e32 v123, 0x36e0, v225
	ds_read_b64_tr_b16 v[72:73], v96
	ds_read_b64_tr_b16 v[74:75], v97
	ds_read_b64_tr_b16 v[56:57], v98
	ds_read_b64_tr_b16 v[58:59], v99
	ds_read_b64_tr_b16 v[116:117], v120
	ds_read_b64_tr_b16 v[118:119], v121
	ds_read_b64_tr_b16 v[112:113], v122
	ds_read_b64_tr_b16 v[114:115], v123
	s_waitcnt lgkmcnt(0)
	s_nop 0
	v_mfma_f32_16x16x32_bf16 v[96:99], v[72:75], v[128:131], v[176:179]
	v_mfma_f32_16x16x32_bf16 v[72:75], v[72:75], v[154:157], v[180:183]
	v_mfma_f32_16x16x32_bf16 v[88:91], v[56:59], v[128:131], v[88:91]
	v_mfma_f32_16x16x32_bf16 v[56:59], v[56:59], v[154:157], v[184:187]
	v_mfma_f32_16x16x32_bf16 v[84:87], v[116:119], v[128:131], v[84:87]
	v_mfma_f32_16x16x32_bf16 v[52:55], v[116:119], v[154:157], v[52:55]
	v_mfma_f32_16x16x32_bf16 v[80:83], v[112:115], v[128:131], v[80:83]
	v_mfma_f32_16x16x32_bf16 v[48:51], v[112:115], v[154:157], v[48:51]
	s_add_u32 s38, s38, 0x10000
	s_addc_u32 s39, s39, 0
	s_add_i32 s22, s22, 1
	v_add_u32_e32 v133, 64, v133
	v_add_u32_e32 v135, 64, v135
	v_add_u32_e32 v137, 64, v137
	v_add_u32_e32 v139, 64, v139
	s_cmp_lg_u32 s38, 0x180000
	v_mov_b32_e32 v154, v227
	v_mov_b32_e32 v112, v226
	s_barrier
	s_cbranch_scc0 .LBB0_773

.LBB0_773:
	v_xor_b32_e32 v0, 1, v151
	v_cmp_lt_i32_e32 vcc, v0, v208
	v_add_f32_e32 v2, v210, v211
	s_mov_b32 s22, 0x3fb8aa3b
	v_cndmask_b32_e32 v0, v151, v0, vcc
	v_lshlrev_b32_e32 v0, 2, v0
	ds_bpermute_b32 v3, v0, v2
	v_add_f32_e32 v1, v212, v213
	ds_bpermute_b32 v0, v0, v1
	s_mov_b32 s23, 0xc2ce8ed0
	s_mov_b32 s36, 0x42b17218
	s_waitcnt lgkmcnt(1)
	v_add_f32_e32 v2, v2, v3
	v_mul_f32_e32 v3, 0x3fb8aa3b, v2
	v_fma_f32 v4, v2, s22, -v3
	v_rndne_f32_e32 v5, v3
	v_fmac_f32_e32 v4, 0x32a5705f, v2
	v_sub_f32_e32 v3, v3, v5
	v_add_f32_e32 v3, v3, v4
	v_exp_f32_e32 v3, v3
	v_cvt_i32_f32_e32 v4, v5
	v_cmp_ngt_f32_e32 vcc, s23, v2
	s_waitcnt lgkmcnt(0)
	v_add_f32_e32 v0, v1, v0
	v_mul_f32_e32 v1, 0x3fb8aa3b, v0
	v_ldexp_f32 v3, v3, v4
	v_cndmask_b32_e32 v3, 0, v3, vcc
	v_cmp_nlt_f32_e32 vcc, s36, v2
	v_rndne_f32_e32 v4, v1
	s_movk_i32 s52, 0x210
	v_cndmask_b32_e32 v2, v200, v3, vcc
	v_fma_f32 v3, v0, s22, -v1
	v_fmac_f32_e32 v3, 0x32a5705f, v0
	v_sub_f32_e32 v1, v1, v4
	v_add_f32_e32 v1, v1, v3
	v_exp_f32_e32 v1, v1
	v_cvt_i32_f32_e32 v3, v4
	v_cmp_ngt_f32_e32 vcc, s23, v0
	s_barrier
	v_ldexp_f32 v1, v1, v3
	v_cndmask_b32_e32 v1, 0, v1, vcc
	v_cmp_nlt_f32_e32 vcc, s36, v0
	s_lshl_b32 s70, s21, 1
	s_nop 0
	v_cndmask_b32_e32 v0, v200, v1, vcc
	ds_bpermute_b32 v1, v205, v143
	v_sub_f32_e32 v0, v2, v0
	v_readlane_b32 s36, v253, 12
	v_readlane_b32 s48, v253, 24
	v_readlane_b32 s49, v253, 25
	s_waitcnt lgkmcnt(0)
	v_add_f32_e32 v1, v143, v1
	ds_bpermute_b32 v2, v141, v1
	s_mov_b32 s21, 0xcc00000
	v_readlane_b32 s37, v253, 13
	v_readlane_b32 s38, v253, 14
	v_readlane_b32 s39, v253, 15
	s_waitcnt lgkmcnt(0)
	v_add_f32_e32 v2, v1, v2
	ds_bpermute_b32 v1, v205, v142
	v_div_scale_f32 v3, s[22:23], v2, v2, 1.0
	v_rcp_f32_e32 v4, v3
	v_readlane_b32 s40, v253, 16
	s_waitcnt lgkmcnt(0)
	v_add_f32_e32 v1, v142, v1
	ds_bpermute_b32 v151, v141, v1
	v_fma_f32 v5, -v3, v4, 1.0
	v_fmac_f32_e32 v4, v5, v4
	v_div_scale_f32 v5, vcc, 1.0, v2, 1.0
	v_mul_f32_e32 v6, v5, v4
	v_fma_f32 v7, -v3, v6, v5
	v_fmac_f32_e32 v6, v7, v4
	v_fma_f32 v3, -v3, v6, v5
	s_waitcnt lgkmcnt(0)
	v_pk_add_f32 v[0:1], v[150:151], v[0:1]
	v_div_fmas_f32 v3, v3, v4, v6
	v_div_fixup_f32 v2, v3, v2, 1.0
	v_div_scale_f32 v3, s[22:23], v1, v1, v0
	v_rcp_f32_e32 v4, v3
	v_readlane_b32 s22, v251, 41
	v_readlane_b32 s41, v253, 17
	v_readlane_b32 s42, v253, 18
	v_fma_f32 v5, -v3, v4, 1.0
	v_fmac_f32_e32 v4, v5, v4
	v_div_scale_f32 v5, vcc, v0, v1, v0
	v_mul_f32_e32 v6, v5, v4
	v_fma_f32 v7, -v3, v6, v5
	v_fmac_f32_e32 v6, v7, v4
	v_fma_f32 v3, -v3, v6, v5
	v_div_fmas_f32 v3, v3, v4, v6
	v_div_fixup_f32 v0, v3, v1, v0
	v_or_b32_e32 v1, v206, v204
	v_mul_lo_u32 v1, v1, s52
	v_lshlrev_b32_e32 v3, 2, v209
	v_pk_mul_f32 v[4:5], v[76:77], v[0:1] op_sel_hi:[1,0]
	v_pk_mul_f32 v[8:9], v[78:79], v[0:1] op_sel_hi:[1,0]
	v_pk_fma_f32 v[4:5], v[108:109], v[2:3], v[4:5] op_sel_hi:[1,0,1] neg_lo:[0,0,1] neg_hi:[0,0,1]
	s_waitcnt vmcnt(1)
	v_add3_u32 v66, s17, v1, v3
	v_pk_mul_f32 v[6:7], v[4:5], v[4:5]
	v_pk_fma_f32 v[8:9], v[110:111], v[2:3], v[8:9] op_sel_hi:[1,0,1] neg_lo:[0,0,1] neg_hi:[0,0,1]
	v_pk_mul_f32 v[12:13], v[60:61], v[0:1] op_sel_hi:[1,0]
	v_pk_mul_f32 v[16:17], v[62:63], v[0:1] op_sel_hi:[1,0]
	v_pk_mul_f32 v[20:21], v[44:45], v[0:1] op_sel_hi:[1,0]
	v_pk_mul_f32 v[24:25], v[46:47], v[0:1] op_sel_hi:[1,0]
	v_pk_mul_f32 v[28:29], v[32:33], v[0:1] op_sel_hi:[1,0]
	v_pk_mul_f32 v[32:33], v[34:35], v[0:1] op_sel_hi:[1,0]
	v_pk_mul_f32 v[36:37], v[72:73], v[0:1] op_sel_hi:[1,0]
	v_pk_mul_f32 v[40:41], v[74:75], v[0:1] op_sel_hi:[1,0]
	v_pk_mul_f32 v[44:45], v[56:57], v[0:1] op_sel_hi:[1,0]
	v_pk_mul_f32 v[56:57], v[58:59], v[0:1] op_sel_hi:[1,0]
	v_pk_mul_f32 v[52:53], v[52:53], v[0:1] op_sel_hi:[1,0]
	v_pk_mul_f32 v[54:55], v[54:55], v[0:1] op_sel_hi:[1,0]
	v_pk_mul_f32 v[48:49], v[48:49], v[0:1] op_sel_hi:[1,0]
	v_pk_mul_f32 v[0:1], v[50:51], v[0:1] op_sel_hi:[1,0]
	v_pk_mul_f32 v[10:11], v[8:9], v[8:9]
	v_pk_fma_f32 v[12:13], v[104:105], v[2:3], v[12:13] op_sel_hi:[1,0,1] neg_lo:[0,0,1] neg_hi:[0,0,1]
	v_pk_fma_f32 v[16:17], v[106:107], v[2:3], v[16:17] op_sel_hi:[1,0,1] neg_lo:[0,0,1] neg_hi:[0,0,1]
	v_pk_fma_f32 v[20:21], v[100:101], v[2:3], v[20:21] op_sel_hi:[1,0,1] neg_lo:[0,0,1] neg_hi:[0,0,1]
	v_pk_fma_f32 v[24:25], v[102:103], v[2:3], v[24:25] op_sel_hi:[1,0,1] neg_lo:[0,0,1] neg_hi:[0,0,1]
	v_pk_fma_f32 v[28:29], v[92:93], v[2:3], v[28:29] op_sel_hi:[1,0,1] neg_lo:[0,0,1] neg_hi:[0,0,1]
	v_pk_fma_f32 v[32:33], v[94:95], v[2:3], v[32:33] op_sel_hi:[1,0,1] neg_lo:[0,0,1] neg_hi:[0,0,1]
	v_pk_fma_f32 v[36:37], v[96:97], v[2:3], v[36:37] op_sel_hi:[1,0,1] neg_lo:[0,0,1] neg_hi:[0,0,1]
	v_pk_fma_f32 v[40:41], v[98:99], v[2:3], v[40:41] op_sel_hi:[1,0,1] neg_lo:[0,0,1] neg_hi:[0,0,1]
	v_pk_fma_f32 v[44:45], v[88:89], v[2:3], v[44:45] op_sel_hi:[1,0,1] neg_lo:[0,0,1] neg_hi:[0,0,1]
	v_pk_fma_f32 v[56:57], v[90:91], v[2:3], v[56:57] op_sel_hi:[1,0,1] neg_lo:[0,0,1] neg_hi:[0,0,1]
	v_pk_fma_f32 v[52:53], v[84:85], v[2:3], v[52:53] op_sel_hi:[1,0,1] neg_lo:[0,0,1] neg_hi:[0,0,1]
	v_pk_fma_f32 v[54:55], v[86:87], v[2:3], v[54:55] op_sel_hi:[1,0,1] neg_lo:[0,0,1] neg_hi:[0,0,1]
	v_pk_fma_f32 v[48:49], v[80:81], v[2:3], v[48:49] op_sel_hi:[1,0,1] neg_lo:[0,0,1] neg_hi:[0,0,1]
	v_pk_fma_f32 v[50:51], v[82:83], v[2:3], v[0:1] op_sel_hi:[1,0,1] neg_lo:[0,0,1] neg_hi:[0,0,1]
	v_add_f32_e32 v2, v6, v7
	v_add_f32_e32 v2, v10, v2
	v_pk_mul_f32 v[14:15], v[12:13], v[12:13]
	v_add_f32_e32 v2, v11, v2
	v_add_f32_e32 v2, v14, v2
	v_pk_mul_f32 v[18:19], v[16:17], v[16:17]
	v_add_f32_e32 v2, v15, v2
	v_add_f32_e32 v2, v18, v2
	v_pk_mul_f32 v[22:23], v[20:21], v[20:21]
	v_add_f32_e32 v2, v19, v2
	v_add_f32_e32 v2, v22, v2
	v_pk_mul_f32 v[26:27], v[24:25], v[24:25]
	v_add_f32_e32 v2, v23, v2
	v_add_f32_e32 v2, v26, v2
	v_pk_mul_f32 v[30:31], v[28:29], v[28:29]
	v_add_f32_e32 v2, v27, v2
	v_add_f32_e32 v2, v30, v2
	v_pk_mul_f32 v[34:35], v[32:33], v[32:33]
	v_add_f32_e32 v2, v31, v2
	v_add_f32_e32 v2, v34, v2
	v_pk_mul_f32 v[38:39], v[36:37], v[36:37]
	v_add_f32_e32 v2, v35, v2
	v_add_f32_e32 v2, v38, v2
	v_pk_mul_f32 v[42:43], v[40:41], v[40:41]
	v_add_f32_e32 v2, v39, v2
	v_add_f32_e32 v2, v42, v2
	v_pk_mul_f32 v[46:47], v[44:45], v[44:45]
	v_add_f32_e32 v2, v43, v2
	v_add_f32_e32 v2, v46, v2
	v_pk_mul_f32 v[58:59], v[56:57], v[56:57]
	v_add_f32_e32 v2, v47, v2
	v_add_f32_e32 v2, v58, v2
	v_pk_mul_f32 v[60:61], v[52:53], v[52:53]
	v_add_f32_e32 v2, v59, v2
	v_add_f32_e32 v2, v60, v2
	v_pk_mul_f32 v[62:63], v[54:55], v[54:55]
	v_add_f32_e32 v2, v61, v2
	v_add_f32_e32 v2, v62, v2
	v_pk_mul_f32 v[64:65], v[48:49], v[48:49]
	v_add_f32_e32 v2, v63, v2
	v_add_f32_e32 v2, v64, v2
	v_pk_mul_f32 v[0:1], v[50:51], v[50:51]
	v_add_f32_e32 v2, v65, v2
	v_add_f32_e32 v0, v0, v2
	v_add_f32_e32 v0, v1, v0
	ds_bpermute_b32 v1, v205, v0
	v_mov_b64_e32 v[14:15], s[6:7]
	v_readlane_b32 s43, v253, 19
	v_readlane_b32 s44, v253, 20
	v_readlane_b32 s45, v253, 21
	s_waitcnt lgkmcnt(0)
	v_add_f32_e32 v0, v0, v1
	ds_bpermute_b32 v1, v141, v0
	v_readlane_b32 s46, v253, 22
	v_readlane_b32 s47, v253, 23
	v_readlane_b32 s50, v253, 26
	v_readlane_b32 s51, v253, 27
	s_waitcnt lgkmcnt(0)
	v_add_f32_e32 v0, v0, v1
	v_fmamk_f32 v0, v0, 0x3c000000, v193
	v_cmp_gt_f32_e32 vcc, s79, v0
	v_mul_f32_e32 v1, 0x4b800000, v0
	s_nop 0
	v_cndmask_b32_e32 v0, v0, v1, vcc
	v_rsq_f32_e32 v0, v0
	s_nop 0
	v_mul_f32_e32 v1, 0x45800000, v0
	v_cndmask_b32_e32 v0, v0, v1, vcc
	v_mul_f32_e32 v6, v203, v0
	v_pk_mul_f32 v[0:1], v[4:5], v[6:7] op_sel_hi:[1,0]
	v_pk_mul_f32 v[2:3], v[8:9], v[6:7] op_sel_hi:[1,0]
	ds_write_b128 v66, v[0:3]
	v_pk_mul_f32 v[0:1], v[12:13], v[6:7] op_sel_hi:[1,0]
	v_pk_mul_f32 v[2:3], v[16:17], v[6:7] op_sel_hi:[1,0]
	ds_write_b128 v66, v[0:3] offset:64
	v_pk_mul_f32 v[0:1], v[20:21], v[6:7] op_sel_hi:[1,0]
	v_pk_mul_f32 v[2:3], v[24:25], v[6:7] op_sel_hi:[1,0]
	ds_write_b128 v66, v[0:3] offset:128
	v_pk_mul_f32 v[0:1], v[28:29], v[6:7] op_sel_hi:[1,0]
	v_pk_mul_f32 v[2:3], v[32:33], v[6:7] op_sel_hi:[1,0]
	ds_write_b128 v66, v[0:3] offset:192
	v_pk_mul_f32 v[0:1], v[36:37], v[6:7] op_sel_hi:[1,0]
	v_pk_mul_f32 v[2:3], v[40:41], v[6:7] op_sel_hi:[1,0]
	ds_write_b128 v66, v[0:3] offset:256
	v_pk_mul_f32 v[0:1], v[44:45], v[6:7] op_sel_hi:[1,0]
	v_pk_mul_f32 v[2:3], v[56:57], v[6:7] op_sel_hi:[1,0]
	ds_write_b128 v66, v[0:3] offset:320
	v_pk_mul_f32 v[0:1], v[52:53], v[6:7] op_sel_hi:[1,0]
	v_pk_mul_f32 v[2:3], v[54:55], v[6:7] op_sel_hi:[1,0]
	ds_write_b128 v66, v[0:3] offset:384
	v_pk_mul_f32 v[0:1], v[48:49], v[6:7] op_sel_hi:[1,0]
	v_pk_mul_f32 v[2:3], v[50:51], v[6:7] op_sel_hi:[1,0]
	v_and_b32_e32 v5, 0x78, v207
	v_add_u32_e32 v16, s20, v138
	ds_write_b128 v66, v[0:3] offset:448
	v_or_b32_e32 v4, s22, v5
	v_mad_i64_i32 v[0:1], s[22:23], v16, s0, v[14:15]
	v_lshl_add_u64 v[0:1], v[0:1], 0, s[70:71]
	v_lshlrev_b32_e32 v160, 1, v5
	v_lshl_add_u64 v[0:1], v[0:1], 0, v[160:161]
	v_add_co_u32_e32 v0, vcc, s3, v0
	s_waitcnt lgkmcnt(0)
	s_nop 0
	v_addc_co_u32_e32 v1, vcc, 0, v1, vcc
	s_barrier
	global_load_dwordx4 v[0:3], v[0:1], off
	v_mul_lo_u32 v6, v138, s52
	v_lshlrev_b32_e32 v20, 2, v5
	v_mov_b32_e32 v5, v161
	v_add3_u32 v6, s17, v6, v20
	v_lshl_add_u64 v[12:13], v[4:5], 2, s[48:49]
	v_ashrrev_i32_e32 v17, 31, v16
	s_waitcnt vmcnt(0)
	v_and_b32_e32 v21, 0xffff0000, v0
	v_lshlrev_b32_e32 v0, 16, v0
	v_mul_f32_e32 v4, 0xbfb8aa3b, v0
	v_exp_f32_e32 v18, v4
	ds_read_b128 v[22:25], v6
	ds_read_b128 v[4:7], v6 offset:16
	global_load_dwordx4 v[8:11], v[12:13], off offset:16
	global_load_dwordx4 v[26:29], v[12:13], off
	v_mul_f32_e32 v19, 0xbfb8aa3b, v21
	v_exp_f32_e32 v19, v19
	s_waitcnt vmcnt(1) lgkmcnt(0)
	v_pk_mul_f32 v[4:5], v[4:5], v[8:9]
	v_pk_add_f32 v[18:19], v[18:19], 1.0 op_sel_hi:[1,0]
	s_waitcnt vmcnt(0)
	v_pk_mul_f32 v[22:23], v[22:23], v[26:27]
	v_div_scale_f32 v26, s[22:23], v19, v19, v21
	v_rcp_f32_e32 v27, v26
	v_pk_mul_f32 v[6:7], v[6:7], v[10:11]
	v_fma_f32 v30, -v26, v27, 1.0
	v_fmac_f32_e32 v27, v30, v27
	v_div_scale_f32 v30, vcc, v21, v19, v21
	v_mul_f32_e32 v31, v30, v27
	v_fma_f32 v32, -v26, v31, v30
	v_fmac_f32_e32 v31, v32, v27
	v_fma_f32 v26, -v26, v31, v30
	v_div_fmas_f32 v26, v26, v27, v31
	v_div_fixup_f32 v19, v26, v19, v21
	v_div_scale_f32 v21, s[22:23], v18, v18, v0
	v_rcp_f32_e32 v26, v21
	s_nop 0
	v_fma_f32 v27, -v21, v26, 1.0
	v_fmac_f32_e32 v26, v27, v26
	v_div_scale_f32 v27, vcc, v0, v18, v0
	v_mul_f32_e32 v30, v27, v26
	v_fma_f32 v31, -v21, v30, v27
	v_fmac_f32_e32 v30, v31, v26
	v_fma_f32 v21, -v21, v30, v27
	v_div_fmas_f32 v21, v21, v26, v30
	v_div_fixup_f32 v18, v21, v18, v0
	v_and_b32_e32 v21, 0xffff0000, v1
	v_lshlrev_b32_e32 v26, 16, v1
	v_mul_f32_e32 v0, 0xbfb8aa3b, v26
	v_mul_f32_e32 v1, 0xbfb8aa3b, v21
	v_exp_f32_e32 v0, v0
	v_exp_f32_e32 v1, v1
	v_pk_mul_f32 v[18:19], v[22:23], v[18:19]
	v_pk_mul_f32 v[22:23], v[24:25], v[28:29]
	v_pk_add_f32 v[0:1], v[0:1], 1.0 op_sel_hi:[1,0]
	s_nop 0
	v_div_scale_f32 v24, s[22:23], v1, v1, v21
	v_rcp_f32_e32 v25, v24
	s_nop 0
	v_fma_f32 v27, -v24, v25, 1.0
	v_fmac_f32_e32 v25, v27, v25
	v_div_scale_f32 v27, vcc, v21, v1, v21
	v_mul_f32_e32 v28, v27, v25
	v_fma_f32 v29, -v24, v28, v27
	v_fmac_f32_e32 v28, v29, v25
	v_fma_f32 v24, -v24, v28, v27
	v_div_fmas_f32 v24, v24, v25, v28
	v_div_fixup_f32 v1, v24, v1, v21
	v_div_scale_f32 v21, s[22:23], v0, v0, v26
	v_rcp_f32_e32 v24, v21
	s_nop 0
	v_fma_f32 v25, -v21, v24, 1.0
	v_fmac_f32_e32 v24, v25, v24
	v_div_scale_f32 v25, vcc, v26, v0, v26
	v_mul_f32_e32 v27, v25, v24
	v_fma_f32 v28, -v21, v27, v25
	v_fmac_f32_e32 v27, v28, v24
	v_fma_f32 v21, -v21, v27, v25
	v_div_fmas_f32 v21, v21, v24, v27
	v_div_fixup_f32 v0, v21, v0, v26
	v_and_b32_e32 v21, 0xffff0000, v2
	v_lshlrev_b32_e32 v2, 16, v2
	v_pk_mul_f32 v[0:1], v[22:23], v[0:1]
	v_mul_f32_e32 v22, 0xbfb8aa3b, v2
	v_mul_f32_e32 v8, 0xbfb8aa3b, v21
	v_exp_f32_e32 v22, v22
	v_exp_f32_e32 v23, v8
	s_nop 0
	v_pk_add_f32 v[8:9], v[22:23], 1.0 op_sel_hi:[1,0]
	s_nop 0
	v_div_scale_f32 v22, s[22:23], v9, v9, v21
	v_rcp_f32_e32 v23, v22
	s_nop 0
	v_fma_f32 v24, -v22, v23, 1.0
	v_fmac_f32_e32 v23, v24, v23
	v_div_scale_f32 v24, vcc, v21, v9, v21
	v_mul_f32_e32 v25, v24, v23
	v_fma_f32 v26, -v22, v25, v24
	v_fmac_f32_e32 v25, v26, v23
	v_fma_f32 v22, -v22, v25, v24
	v_div_fmas_f32 v22, v22, v23, v25
	v_div_fixup_f32 v9, v22, v9, v21
	v_div_scale_f32 v21, s[22:23], v8, v8, v2
	v_rcp_f32_e32 v22, v21
	s_nop 0
	v_fma_f32 v23, -v21, v22, 1.0
	v_fmac_f32_e32 v22, v23, v22
	v_div_scale_f32 v23, vcc, v2, v8, v2
	v_mul_f32_e32 v24, v23, v22
	v_fma_f32 v25, -v21, v24, v23
	v_fmac_f32_e32 v24, v25, v22
	v_fma_f32 v21, -v21, v24, v23
	v_div_fmas_f32 v21, v21, v22, v24
	v_div_fixup_f32 v8, v21, v8, v2
	v_pk_mul_f32 v[4:5], v[8:9], v[4:5]
	v_and_b32_e32 v8, 0xffff0000, v3
	v_lshlrev_b32_e32 v9, 16, v3
	v_mul_f32_e32 v2, 0xbfb8aa3b, v9
	v_mul_f32_e32 v3, 0xbfb8aa3b, v8
	v_exp_f32_e32 v2, v2
	v_exp_f32_e32 v3, v3
	s_nop 0
	v_pk_add_f32 v[2:3], v[2:3], 1.0 op_sel_hi:[1,0]
	s_nop 0
	v_div_scale_f32 v10, s[22:23], v3, v3, v8
	v_rcp_f32_e32 v11, v10
	s_nop 0
	v_fma_f32 v21, -v10, v11, 1.0
	v_fmac_f32_e32 v11, v21, v11
	v_div_scale_f32 v21, vcc, v8, v3, v8
	v_mul_f32_e32 v22, v21, v11
	v_fma_f32 v23, -v10, v22, v21
	v_fmac_f32_e32 v22, v23, v11
	v_fma_f32 v10, -v10, v22, v21
	v_div_fmas_f32 v10, v10, v11, v22
	v_div_fixup_f32 v3, v10, v3, v8
	v_div_scale_f32 v8, s[22:23], v2, v2, v9
	v_rcp_f32_e32 v10, v8
	s_nop 0
	v_fma_f32 v11, -v8, v10, 1.0
	v_fmac_f32_e32 v10, v11, v10
	v_div_scale_f32 v11, vcc, v9, v2, v9
	v_mul_f32_e32 v21, v11, v10
	v_fma_f32 v22, -v8, v21, v11
	v_fmac_f32_e32 v21, v22, v10
	v_fma_f32 v8, -v8, v21, v11
	v_div_fmas_f32 v8, v8, v10, v21
	v_div_fixup_f32 v2, v8, v2, v9
	v_pk_mul_f32 v[2:3], v[2:3], v[6:7]
	v_cvt_pk_bf16_f32 v4, v4, v5
	v_cvt_pk_bf16_f32 v2, v2, v3
	v_mov_b32_e32 v3, v2
	v_mov_b32_e32 v2, v4
	v_lshlrev_b64 v[4:5], 12, v[16:17]
	v_lshl_add_u64 v[4:5], s[30:31], 0, v[4:5]
	v_lshl_add_u64 v[4:5], v[4:5], 0, s[70:71]
	v_lshl_add_u64 v[4:5], v[4:5], 0, v[160:161]
	v_cvt_pk_bf16_f32 v18, v18, v19
	v_cvt_pk_bf16_f32 v0, v0, v1
	v_add_co_u32_e32 v4, vcc, s21, v4
	v_mov_b32_e32 v1, v0
	v_mov_b32_e32 v0, v18
	v_addc_co_u32_e32 v5, vcc, 0, v5, vcc
	v_add_u32_e32 v16, s20, v136
	global_store_dwordx4 v[4:5], v[0:3], off offset:2048
	v_mul_lo_u32 v4, v136, s52
	v_add3_u32 v4, s17, v4, v20
	v_mad_i64_i32 v[0:1], s[22:23], v16, s0, v[14:15]
	v_lshl_add_u64 v[0:1], v[0:1], 0, s[70:71]
	v_lshl_add_u64 v[0:1], v[0:1], 0, v[160:161]
	v_add_co_u32_e32 v0, vcc, s3, v0
	v_ashrrev_i32_e32 v17, 31, v16
	s_nop 0
	v_addc_co_u32_e32 v1, vcc, 0, v1, vcc
	global_load_dwordx4 v[0:3], v[0:1], off
	s_waitcnt vmcnt(0)
	v_and_b32_e32 v21, 0xffff0000, v0
	v_lshlrev_b32_e32 v0, 16, v0
	v_mul_f32_e32 v5, 0xbfb8aa3b, v0
	v_exp_f32_e32 v18, v5
	ds_read_b128 v[22:25], v4
	ds_read_b128 v[4:7], v4 offset:16
	global_load_dwordx4 v[8:11], v[12:13], off offset:16
	global_load_dwordx4 v[26:29], v[12:13], off
	v_mul_f32_e32 v19, 0xbfb8aa3b, v21
	v_exp_f32_e32 v19, v19
	s_waitcnt vmcnt(1) lgkmcnt(0)
	v_pk_mul_f32 v[4:5], v[4:5], v[8:9]
	v_pk_add_f32 v[18:19], v[18:19], 1.0 op_sel_hi:[1,0]
	s_waitcnt vmcnt(0)
	v_pk_mul_f32 v[22:23], v[22:23], v[26:27]
	v_div_scale_f32 v26, s[22:23], v19, v19, v21
	v_rcp_f32_e32 v27, v26
	v_pk_mul_f32 v[6:7], v[6:7], v[10:11]
	v_fma_f32 v30, -v26, v27, 1.0
	v_fmac_f32_e32 v27, v30, v27
	v_div_scale_f32 v30, vcc, v21, v19, v21
	v_mul_f32_e32 v31, v30, v27
	v_fma_f32 v32, -v26, v31, v30
	v_fmac_f32_e32 v31, v32, v27
	v_fma_f32 v26, -v26, v31, v30
	v_div_fmas_f32 v26, v26, v27, v31
	v_div_fixup_f32 v19, v26, v19, v21
	v_div_scale_f32 v21, s[22:23], v18, v18, v0
	v_rcp_f32_e32 v26, v21
	s_nop 0
	v_fma_f32 v27, -v21, v26, 1.0
	v_fmac_f32_e32 v26, v27, v26
	v_div_scale_f32 v27, vcc, v0, v18, v0
	v_mul_f32_e32 v30, v27, v26
	v_fma_f32 v31, -v21, v30, v27
	v_fmac_f32_e32 v30, v31, v26
	v_fma_f32 v21, -v21, v30, v27
	v_div_fmas_f32 v21, v21, v26, v30
	v_div_fixup_f32 v18, v21, v18, v0
	v_and_b32_e32 v21, 0xffff0000, v1
	v_lshlrev_b32_e32 v26, 16, v1
	v_mul_f32_e32 v0, 0xbfb8aa3b, v26
	v_mul_f32_e32 v1, 0xbfb8aa3b, v21
	v_exp_f32_e32 v0, v0
	v_exp_f32_e32 v1, v1
	v_pk_mul_f32 v[18:19], v[22:23], v[18:19]
	v_pk_mul_f32 v[22:23], v[24:25], v[28:29]
	v_pk_add_f32 v[0:1], v[0:1], 1.0 op_sel_hi:[1,0]
	s_nop 0
	v_div_scale_f32 v24, s[22:23], v1, v1, v21
	v_rcp_f32_e32 v25, v24
	s_nop 0
	v_fma_f32 v27, -v24, v25, 1.0
	v_fmac_f32_e32 v25, v27, v25
	v_div_scale_f32 v27, vcc, v21, v1, v21
	v_mul_f32_e32 v28, v27, v25
	v_fma_f32 v29, -v24, v28, v27
	v_fmac_f32_e32 v28, v29, v25
	v_fma_f32 v24, -v24, v28, v27
	v_div_fmas_f32 v24, v24, v25, v28
	v_div_fixup_f32 v1, v24, v1, v21
	v_div_scale_f32 v21, s[22:23], v0, v0, v26
	v_rcp_f32_e32 v24, v21
	s_nop 0
	v_fma_f32 v25, -v21, v24, 1.0
	v_fmac_f32_e32 v24, v25, v24
	v_div_scale_f32 v25, vcc, v26, v0, v26
	v_mul_f32_e32 v27, v25, v24
	v_fma_f32 v28, -v21, v27, v25
	v_fmac_f32_e32 v27, v28, v24
	v_fma_f32 v21, -v21, v27, v25
	v_div_fmas_f32 v21, v21, v24, v27
	v_div_fixup_f32 v0, v21, v0, v26
	v_and_b32_e32 v21, 0xffff0000, v2
	v_lshlrev_b32_e32 v2, 16, v2
	v_pk_mul_f32 v[0:1], v[22:23], v[0:1]
	v_mul_f32_e32 v22, 0xbfb8aa3b, v2
	v_mul_f32_e32 v8, 0xbfb8aa3b, v21
	v_exp_f32_e32 v22, v22
	v_exp_f32_e32 v23, v8
	s_nop 0
	v_pk_add_f32 v[8:9], v[22:23], 1.0 op_sel_hi:[1,0]
	s_nop 0
	v_div_scale_f32 v22, s[22:23], v9, v9, v21
	v_rcp_f32_e32 v23, v22
	s_nop 0
	v_fma_f32 v24, -v22, v23, 1.0
	v_fmac_f32_e32 v23, v24, v23
	v_div_scale_f32 v24, vcc, v21, v9, v21
	v_mul_f32_e32 v25, v24, v23
	v_fma_f32 v26, -v22, v25, v24
	v_fmac_f32_e32 v25, v26, v23
	v_fma_f32 v22, -v22, v25, v24
	v_div_fmas_f32 v22, v22, v23, v25
	v_div_fixup_f32 v9, v22, v9, v21
	v_div_scale_f32 v21, s[22:23], v8, v8, v2
	v_rcp_f32_e32 v22, v21
	s_nop 0
	v_fma_f32 v23, -v21, v22, 1.0
	v_fmac_f32_e32 v22, v23, v22
	v_div_scale_f32 v23, vcc, v2, v8, v2
	v_mul_f32_e32 v24, v23, v22
	v_fma_f32 v25, -v21, v24, v23
	v_fmac_f32_e32 v24, v25, v22
	v_fma_f32 v21, -v21, v24, v23
	v_div_fmas_f32 v21, v21, v22, v24
	v_div_fixup_f32 v8, v21, v8, v2
	v_pk_mul_f32 v[4:5], v[8:9], v[4:5]
	v_and_b32_e32 v8, 0xffff0000, v3
	v_lshlrev_b32_e32 v9, 16, v3
	v_mul_f32_e32 v2, 0xbfb8aa3b, v9
	v_mul_f32_e32 v3, 0xbfb8aa3b, v8
	v_exp_f32_e32 v2, v2
	v_exp_f32_e32 v3, v3
	s_nop 0
	v_pk_add_f32 v[2:3], v[2:3], 1.0 op_sel_hi:[1,0]
	s_nop 0
	v_div_scale_f32 v10, s[22:23], v3, v3, v8
	v_rcp_f32_e32 v11, v10
	s_nop 0
	v_fma_f32 v21, -v10, v11, 1.0
	v_fmac_f32_e32 v11, v21, v11
	v_div_scale_f32 v21, vcc, v8, v3, v8
	v_mul_f32_e32 v22, v21, v11
	v_fma_f32 v23, -v10, v22, v21
	v_fmac_f32_e32 v22, v23, v11
	v_fma_f32 v10, -v10, v22, v21
	v_div_fmas_f32 v10, v10, v11, v22
	v_div_fixup_f32 v3, v10, v3, v8
	v_div_scale_f32 v8, s[22:23], v2, v2, v9
	v_rcp_f32_e32 v10, v8
	s_nop 0
	v_fma_f32 v11, -v8, v10, 1.0
	v_fmac_f32_e32 v10, v11, v10
	v_div_scale_f32 v11, vcc, v9, v2, v9
	v_mul_f32_e32 v21, v11, v10
	v_fma_f32 v22, -v8, v21, v11
	v_fmac_f32_e32 v21, v22, v10
	v_fma_f32 v8, -v8, v21, v11
	v_div_fmas_f32 v8, v8, v10, v21
	v_div_fixup_f32 v2, v8, v2, v9
	v_pk_mul_f32 v[2:3], v[2:3], v[6:7]
	v_cvt_pk_bf16_f32 v4, v4, v5
	v_cvt_pk_bf16_f32 v2, v2, v3
	v_mov_b32_e32 v3, v2
	v_mov_b32_e32 v2, v4
	v_lshlrev_b64 v[4:5], 12, v[16:17]
	v_lshl_add_u64 v[4:5], s[30:31], 0, v[4:5]
	v_lshl_add_u64 v[4:5], v[4:5], 0, s[70:71]
	v_lshl_add_u64 v[4:5], v[4:5], 0, v[160:161]
	v_cvt_pk_bf16_f32 v18, v18, v19
	v_cvt_pk_bf16_f32 v0, v0, v1
	v_add_co_u32_e32 v4, vcc, s21, v4
	v_mov_b32_e32 v1, v0
	v_mov_b32_e32 v0, v18
	v_addc_co_u32_e32 v5, vcc, 0, v5, vcc
	v_add_u32_e32 v16, s20, v134
	global_store_dwordx4 v[4:5], v[0:3], off offset:2048
	v_mul_lo_u32 v4, v134, s52
	v_add3_u32 v4, s17, v4, v20
	v_mad_i64_i32 v[0:1], s[22:23], v16, s0, v[14:15]
	v_lshl_add_u64 v[0:1], v[0:1], 0, s[70:71]
	v_lshl_add_u64 v[0:1], v[0:1], 0, v[160:161]
	v_add_co_u32_e32 v0, vcc, s3, v0
	v_ashrrev_i32_e32 v17, 31, v16
	s_nop 0
	v_addc_co_u32_e32 v1, vcc, 0, v1, vcc
	global_load_dwordx4 v[0:3], v[0:1], off
	s_waitcnt vmcnt(0)
	v_and_b32_e32 v21, 0xffff0000, v0
	v_lshlrev_b32_e32 v0, 16, v0
	v_mul_f32_e32 v5, 0xbfb8aa3b, v0
	v_exp_f32_e32 v18, v5
	ds_read_b128 v[22:25], v4
	ds_read_b128 v[4:7], v4 offset:16
	global_load_dwordx4 v[8:11], v[12:13], off offset:16
	global_load_dwordx4 v[26:29], v[12:13], off
	v_mul_f32_e32 v19, 0xbfb8aa3b, v21
	v_exp_f32_e32 v19, v19
	s_waitcnt vmcnt(1) lgkmcnt(0)
	v_pk_mul_f32 v[4:5], v[4:5], v[8:9]
	v_pk_add_f32 v[18:19], v[18:19], 1.0 op_sel_hi:[1,0]
	s_waitcnt vmcnt(0)
	v_pk_mul_f32 v[22:23], v[22:23], v[26:27]
	v_div_scale_f32 v26, s[22:23], v19, v19, v21
	v_rcp_f32_e32 v27, v26
	v_pk_mul_f32 v[6:7], v[6:7], v[10:11]
	v_fma_f32 v30, -v26, v27, 1.0
	v_fmac_f32_e32 v27, v30, v27
	v_div_scale_f32 v30, vcc, v21, v19, v21
	v_mul_f32_e32 v31, v30, v27
	v_fma_f32 v32, -v26, v31, v30
	v_fmac_f32_e32 v31, v32, v27
	v_fma_f32 v26, -v26, v31, v30
	v_div_fmas_f32 v26, v26, v27, v31
	v_div_fixup_f32 v19, v26, v19, v21
	v_div_scale_f32 v21, s[22:23], v18, v18, v0
	v_rcp_f32_e32 v26, v21
	s_nop 0
	v_fma_f32 v27, -v21, v26, 1.0
	v_fmac_f32_e32 v26, v27, v26
	v_div_scale_f32 v27, vcc, v0, v18, v0
	v_mul_f32_e32 v30, v27, v26
	v_fma_f32 v31, -v21, v30, v27
	v_fmac_f32_e32 v30, v31, v26
	v_fma_f32 v21, -v21, v30, v27
	v_div_fmas_f32 v21, v21, v26, v30
	v_div_fixup_f32 v18, v21, v18, v0
	v_and_b32_e32 v21, 0xffff0000, v1
	v_lshlrev_b32_e32 v26, 16, v1
	v_mul_f32_e32 v0, 0xbfb8aa3b, v26
	v_mul_f32_e32 v1, 0xbfb8aa3b, v21
	v_exp_f32_e32 v0, v0
	v_exp_f32_e32 v1, v1
	v_pk_mul_f32 v[18:19], v[22:23], v[18:19]
	v_pk_mul_f32 v[22:23], v[24:25], v[28:29]
	v_pk_add_f32 v[0:1], v[0:1], 1.0 op_sel_hi:[1,0]
	s_nop 0
	v_div_scale_f32 v24, s[22:23], v1, v1, v21
	v_rcp_f32_e32 v25, v24
	s_nop 0
	v_fma_f32 v27, -v24, v25, 1.0
	v_fmac_f32_e32 v25, v27, v25
	v_div_scale_f32 v27, vcc, v21, v1, v21
	v_mul_f32_e32 v28, v27, v25
	v_fma_f32 v29, -v24, v28, v27
	v_fmac_f32_e32 v28, v29, v25
	v_fma_f32 v24, -v24, v28, v27
	v_div_fmas_f32 v24, v24, v25, v28
	v_div_fixup_f32 v1, v24, v1, v21
	v_div_scale_f32 v21, s[22:23], v0, v0, v26
	v_rcp_f32_e32 v24, v21
	s_nop 0
	v_fma_f32 v25, -v21, v24, 1.0
	v_fmac_f32_e32 v24, v25, v24
	v_div_scale_f32 v25, vcc, v26, v0, v26
	v_mul_f32_e32 v27, v25, v24
	v_fma_f32 v28, -v21, v27, v25
	v_fmac_f32_e32 v27, v28, v24
	v_fma_f32 v21, -v21, v27, v25
	v_div_fmas_f32 v21, v21, v24, v27
	v_div_fixup_f32 v0, v21, v0, v26
	v_and_b32_e32 v21, 0xffff0000, v2
	v_lshlrev_b32_e32 v2, 16, v2
	v_pk_mul_f32 v[0:1], v[22:23], v[0:1]
	v_mul_f32_e32 v22, 0xbfb8aa3b, v2
	v_mul_f32_e32 v8, 0xbfb8aa3b, v21
	v_exp_f32_e32 v22, v22
	v_exp_f32_e32 v23, v8
	s_nop 0
	v_pk_add_f32 v[8:9], v[22:23], 1.0 op_sel_hi:[1,0]
	s_nop 0
	v_div_scale_f32 v22, s[22:23], v9, v9, v21
	v_rcp_f32_e32 v23, v22
	s_nop 0
	v_fma_f32 v24, -v22, v23, 1.0
	v_fmac_f32_e32 v23, v24, v23
	v_div_scale_f32 v24, vcc, v21, v9, v21
	v_mul_f32_e32 v25, v24, v23
	v_fma_f32 v26, -v22, v25, v24
	v_fmac_f32_e32 v25, v26, v23
	v_fma_f32 v22, -v22, v25, v24
	v_div_fmas_f32 v22, v22, v23, v25
	v_div_fixup_f32 v9, v22, v9, v21
	v_div_scale_f32 v21, s[22:23], v8, v8, v2
	v_rcp_f32_e32 v22, v21
	s_nop 0
	v_fma_f32 v23, -v21, v22, 1.0
	v_fmac_f32_e32 v22, v23, v22
	v_div_scale_f32 v23, vcc, v2, v8, v2
	v_mul_f32_e32 v24, v23, v22
	v_fma_f32 v25, -v21, v24, v23
	v_fmac_f32_e32 v24, v25, v22
	v_fma_f32 v21, -v21, v24, v23
	v_div_fmas_f32 v21, v21, v22, v24
	v_div_fixup_f32 v8, v21, v8, v2
	v_pk_mul_f32 v[4:5], v[8:9], v[4:5]
	v_and_b32_e32 v8, 0xffff0000, v3
	v_lshlrev_b32_e32 v9, 16, v3
	v_mul_f32_e32 v2, 0xbfb8aa3b, v9
	v_mul_f32_e32 v3, 0xbfb8aa3b, v8
	v_exp_f32_e32 v2, v2
	v_exp_f32_e32 v3, v3
	s_nop 0
	v_pk_add_f32 v[2:3], v[2:3], 1.0 op_sel_hi:[1,0]
	s_nop 0
	v_div_scale_f32 v10, s[22:23], v3, v3, v8
	v_rcp_f32_e32 v11, v10
	s_nop 0
	v_fma_f32 v21, -v10, v11, 1.0
	v_fmac_f32_e32 v11, v21, v11
	v_div_scale_f32 v21, vcc, v8, v3, v8
	v_mul_f32_e32 v22, v21, v11
	v_fma_f32 v23, -v10, v22, v21
	v_fmac_f32_e32 v22, v23, v11
	v_fma_f32 v10, -v10, v22, v21
	v_div_fmas_f32 v10, v10, v11, v22
	v_div_fixup_f32 v3, v10, v3, v8
	v_div_scale_f32 v8, s[22:23], v2, v2, v9
	v_rcp_f32_e32 v10, v8
	s_nop 0
	v_fma_f32 v11, -v8, v10, 1.0
	v_fmac_f32_e32 v10, v11, v10
	v_div_scale_f32 v11, vcc, v9, v2, v9
	v_mul_f32_e32 v21, v11, v10
	v_fma_f32 v22, -v8, v21, v11
	v_fmac_f32_e32 v21, v22, v10
	v_fma_f32 v8, -v8, v21, v11
	v_div_fmas_f32 v8, v8, v10, v21
	v_div_fixup_f32 v2, v8, v2, v9
	v_pk_mul_f32 v[2:3], v[2:3], v[6:7]
	v_cvt_pk_bf16_f32 v4, v4, v5
	v_cvt_pk_bf16_f32 v2, v2, v3
	v_mov_b32_e32 v3, v2
	v_mov_b32_e32 v2, v4
	v_lshlrev_b64 v[4:5], 12, v[16:17]
	v_lshl_add_u64 v[4:5], s[30:31], 0, v[4:5]
	v_lshl_add_u64 v[4:5], v[4:5], 0, s[70:71]
	v_lshl_add_u64 v[4:5], v[4:5], 0, v[160:161]
	v_cvt_pk_bf16_f32 v18, v18, v19
	v_cvt_pk_bf16_f32 v0, v0, v1
	v_add_co_u32_e32 v4, vcc, s21, v4
	v_mov_b32_e32 v1, v0
	v_mov_b32_e32 v0, v18
	v_addc_co_u32_e32 v5, vcc, 0, v5, vcc
	v_add_u32_e32 v16, s20, v132
	global_store_dwordx4 v[4:5], v[0:3], off offset:2048
	v_mul_lo_u32 v4, v132, s52
	v_add3_u32 v4, s17, v4, v20
	v_mad_i64_i32 v[0:1], s[20:21], v16, s0, v[14:15]
	v_lshl_add_u64 v[0:1], v[0:1], 0, s[70:71]
	v_lshl_add_u64 v[0:1], v[0:1], 0, v[160:161]
	v_add_co_u32_e32 v0, vcc, s3, v0
	v_ashrrev_i32_e32 v17, 31, v16
	s_nop 0
	v_addc_co_u32_e32 v1, vcc, 0, v1, vcc
	global_load_dwordx4 v[0:3], v[0:1], off
	s_waitcnt vmcnt(0)
	v_and_b32_e32 v24, 0xffff0000, v0
	v_lshlrev_b32_e32 v0, 16, v0
	v_mul_f32_e32 v5, 0xbfb8aa3b, v0
	v_exp_f32_e32 v22, v5
	ds_read_b128 v[18:21], v4
	ds_read_b128 v[4:7], v4 offset:16
	global_load_dwordx4 v[8:11], v[12:13], off offset:16
	s_nop 0
	global_load_dwordx4 v[12:15], v[12:13], off
	s_waitcnt vmcnt(1) lgkmcnt(0)
	v_pk_mul_f32 v[4:5], v[4:5], v[8:9]
	s_waitcnt vmcnt(0)
	v_pk_mul_f32 v[12:13], v[18:19], v[12:13]
	v_mul_f32_e32 v18, 0xbfb8aa3b, v24
	v_exp_f32_e32 v23, v18
	v_pk_mul_f32 v[14:15], v[20:21], v[14:15]
	v_pk_mul_f32 v[6:7], v[6:7], v[10:11]
	v_pk_add_f32 v[18:19], v[22:23], 1.0 op_sel_hi:[1,0]
	s_nop 0
	v_div_scale_f32 v22, s[20:21], v19, v19, v24
	v_rcp_f32_e32 v23, v22
	s_nop 0
	v_fma_f32 v25, -v22, v23, 1.0
	v_fmac_f32_e32 v23, v25, v23
	v_div_scale_f32 v25, vcc, v24, v19, v24
	v_mul_f32_e32 v26, v25, v23
	v_fma_f32 v27, -v22, v26, v25
	v_fmac_f32_e32 v26, v27, v23
	v_fma_f32 v22, -v22, v26, v25
	v_div_fmas_f32 v22, v22, v23, v26
	v_div_fixup_f32 v19, v22, v19, v24
	v_div_scale_f32 v22, s[20:21], v18, v18, v0
	v_rcp_f32_e32 v23, v22
	s_nop 0
	v_fma_f32 v24, -v22, v23, 1.0
	v_fmac_f32_e32 v23, v24, v23
	v_div_scale_f32 v24, vcc, v0, v18, v0
	v_mul_f32_e32 v25, v24, v23
	v_fma_f32 v26, -v22, v25, v24
	v_fmac_f32_e32 v25, v26, v23
	v_fma_f32 v22, -v22, v25, v24
	v_div_fmas_f32 v22, v22, v23, v25
	v_div_fixup_f32 v18, v22, v18, v0
	v_pk_mul_f32 v[12:13], v[12:13], v[18:19]
	v_and_b32_e32 v18, 0xffff0000, v1
	v_lshlrev_b32_e32 v19, 16, v1
	v_mul_f32_e32 v0, 0xbfb8aa3b, v19
	v_mul_f32_e32 v1, 0xbfb8aa3b, v18
	v_exp_f32_e32 v0, v0
	v_exp_f32_e32 v1, v1
	s_nop 0
	v_pk_add_f32 v[0:1], v[0:1], 1.0 op_sel_hi:[1,0]
	s_nop 0
	v_div_scale_f32 v20, s[20:21], v1, v1, v18
	v_rcp_f32_e32 v21, v20
	s_nop 0
	v_fma_f32 v22, -v20, v21, 1.0
	v_fmac_f32_e32 v21, v22, v21
	v_div_scale_f32 v22, vcc, v18, v1, v18
	v_mul_f32_e32 v23, v22, v21
	v_fma_f32 v24, -v20, v23, v22
	v_fmac_f32_e32 v23, v24, v21
	v_fma_f32 v20, -v20, v23, v22
	v_div_fmas_f32 v20, v20, v21, v23
	v_div_fixup_f32 v1, v20, v1, v18
	v_div_scale_f32 v18, s[20:21], v0, v0, v19
	v_rcp_f32_e32 v20, v18
	s_nop 0
	v_fma_f32 v21, -v18, v20, 1.0
	v_fmac_f32_e32 v20, v21, v20
	v_div_scale_f32 v21, vcc, v19, v0, v19
	v_mul_f32_e32 v22, v21, v20
	v_fma_f32 v23, -v18, v22, v21
	v_fmac_f32_e32 v22, v23, v20
	v_fma_f32 v18, -v18, v22, v21
	v_div_fmas_f32 v18, v18, v20, v22
	v_div_fixup_f32 v0, v18, v0, v19
	v_and_b32_e32 v18, 0xffff0000, v2
	v_lshlrev_b32_e32 v2, 16, v2
	v_pk_mul_f32 v[0:1], v[14:15], v[0:1]
	v_mul_f32_e32 v14, 0xbfb8aa3b, v2
	v_mul_f32_e32 v8, 0xbfb8aa3b, v18
	v_exp_f32_e32 v14, v14
	v_exp_f32_e32 v15, v8
	s_nop 0
	v_pk_add_f32 v[8:9], v[14:15], 1.0 op_sel_hi:[1,0]
	s_nop 0
	v_div_scale_f32 v14, s[20:21], v9, v9, v18
	v_rcp_f32_e32 v15, v14
	s_nop 0
	v_fma_f32 v19, -v14, v15, 1.0
	v_fmac_f32_e32 v15, v19, v15
	v_div_scale_f32 v19, vcc, v18, v9, v18
	v_mul_f32_e32 v20, v19, v15
	v_fma_f32 v21, -v14, v20, v19
	v_fmac_f32_e32 v20, v21, v15
	v_fma_f32 v14, -v14, v20, v19
	v_div_fmas_f32 v14, v14, v15, v20
	v_div_fixup_f32 v9, v14, v9, v18
	v_div_scale_f32 v14, s[20:21], v8, v8, v2
	v_rcp_f32_e32 v15, v14
	s_nop 0
	v_fma_f32 v18, -v14, v15, 1.0
	v_fmac_f32_e32 v15, v18, v15
	v_div_scale_f32 v18, vcc, v2, v8, v2
	v_mul_f32_e32 v19, v18, v15
	v_fma_f32 v20, -v14, v19, v18
	v_fmac_f32_e32 v19, v20, v15
	v_fma_f32 v14, -v14, v19, v18
	v_div_fmas_f32 v14, v14, v15, v19
	v_div_fixup_f32 v8, v14, v8, v2
	v_pk_mul_f32 v[4:5], v[8:9], v[4:5]
	v_and_b32_e32 v8, 0xffff0000, v3
	v_lshlrev_b32_e32 v9, 16, v3
	v_mul_f32_e32 v2, 0xbfb8aa3b, v9
	v_mul_f32_e32 v3, 0xbfb8aa3b, v8
	v_exp_f32_e32 v2, v2
	v_exp_f32_e32 v3, v3
	s_nop 0
	v_pk_add_f32 v[2:3], v[2:3], 1.0 op_sel_hi:[1,0]
	s_nop 0
	v_div_scale_f32 v10, s[20:21], v3, v3, v8
	v_rcp_f32_e32 v11, v10
	s_nop 0
	v_fma_f32 v14, -v10, v11, 1.0
	v_fmac_f32_e32 v11, v14, v11
	v_div_scale_f32 v14, vcc, v8, v3, v8
	v_mul_f32_e32 v15, v14, v11
	v_fma_f32 v18, -v10, v15, v14
	v_fmac_f32_e32 v15, v18, v11
	v_fma_f32 v10, -v10, v15, v14
	v_div_fmas_f32 v10, v10, v11, v15
	v_div_fixup_f32 v3, v10, v3, v8
	v_div_scale_f32 v8, s[20:21], v2, v2, v9
	v_rcp_f32_e32 v10, v8
	s_nop 0
	v_fma_f32 v11, -v8, v10, 1.0
	v_fmac_f32_e32 v10, v11, v10
	v_div_scale_f32 v11, vcc, v9, v2, v9
	v_mul_f32_e32 v14, v11, v10
	v_fma_f32 v15, -v8, v14, v11
	v_fmac_f32_e32 v14, v15, v10
	v_fma_f32 v8, -v8, v14, v11
	v_div_fmas_f32 v8, v8, v10, v14
	v_div_fixup_f32 v2, v8, v2, v9
	v_pk_mul_f32 v[2:3], v[2:3], v[6:7]
	v_cvt_pk_bf16_f32 v4, v4, v5
	v_cvt_pk_bf16_f32 v2, v2, v3
	v_mov_b32_e32 v3, v2
	v_mov_b32_e32 v2, v4
	v_lshlrev_b64 v[4:5], 12, v[16:17]
	v_lshl_add_u64 v[4:5], s[30:31], 0, v[4:5]
	v_lshl_add_u64 v[4:5], v[4:5], 0, s[70:71]
	v_lshl_add_u64 v[4:5], v[4:5], 0, v[160:161]
	v_cvt_pk_bf16_f32 v12, v12, v13
	v_cvt_pk_bf16_f32 v0, v0, v1
	v_add_co_u32_e32 v4, vcc, 0xcc00000, v4
	v_mov_b32_e32 v1, v0
	v_mov_b32_e32 v0, v12
	v_addc_co_u32_e32 v5, vcc, 0, v5, vcc
	global_store_dwordx4 v[4:5], v[0:3], off offset:2048
	s_barrier

.Lhl_conv_a:
	s_waitcnt lgkmcnt(9)
	v_alignbyte_b32 v228, v205, v204, v80
	v_alignbyte_b32 v229, v206, v205, v80
	v_alignbyte_b32 v230, v207, v206, v80
	v_alignbyte_b32 v231, v208, v207, v80
	ds_read2_b32 v[204:205], v157 offset0:16 offset1:17
	ds_read2_b32 v[206:207], v157 offset0:18 offset1:19
	ds_read_b32 v208, v157 offset:80
	ds_read_b128 v[240:243], v91 offset:64
	v_mfma_f32_16x16x32_bf16 v[50:53], v[228:231], v[236:239], v[50:53]
	s_waitcnt lgkmcnt(10)
	v_alignbyte_b32 v232, v211, v210, v80
	v_alignbyte_b32 v233, v212, v211, v80
	v_alignbyte_b32 v234, v213, v212, v80
	v_alignbyte_b32 v235, v214, v213, v80
	ds_read2_b32 v[210:211], v156 offset0:16 offset1:17
	ds_read2_b32 v[212:213], v156 offset0:18 offset1:19
	ds_read_b32 v214, v156 offset:80
	v_mfma_f32_16x16x32_bf16 v[54:57], v[232:235], v[236:239], v[54:57]
	s_waitcnt lgkmcnt(10)
	v_alignbyte_b32 v228, v217, v216, v80
	v_alignbyte_b32 v229, v218, v217, v80
	v_alignbyte_b32 v230, v219, v218, v80
	v_alignbyte_b32 v231, v220, v219, v80
	ds_read2_b32 v[216:217], v155 offset0:16 offset1:17
	ds_read2_b32 v[218:219], v155 offset0:18 offset1:19
	ds_read_b32 v220, v155 offset:80
	v_mfma_f32_16x16x32_bf16 v[42:45], v[228:231], v[236:239], v[42:45]
	s_waitcnt lgkmcnt(10)
	v_alignbyte_b32 v232, v223, v222, v80
	v_alignbyte_b32 v233, v224, v223, v80
	v_alignbyte_b32 v234, v225, v224, v80
	v_alignbyte_b32 v235, v226, v225, v80
	ds_read2_b32 v[222:223], v154 offset0:16 offset1:17
	ds_read2_b32 v[224:225], v154 offset0:18 offset1:19
	ds_read_b32 v226, v154 offset:80
	v_mfma_f32_16x16x32_bf16 v[46:49], v[232:235], v[236:239], v[46:49]
	s_waitcnt lgkmcnt(9)
	v_alignbyte_b32 v228, v205, v204, v80
	v_alignbyte_b32 v229, v206, v205, v80
	v_alignbyte_b32 v230, v207, v206, v80
	v_alignbyte_b32 v231, v208, v207, v80
	ds_read2_b32 v[204:205], v157 offset0:32 offset1:33
	ds_read2_b32 v[206:207], v157 offset0:34 offset1:35
	ds_read_b32 v208, v157 offset:144
	ds_read_b128 v[236:239], v91 offset:128
	v_mfma_f32_16x16x32_bf16 v[50:53], v[228:231], v[240:243], v[50:53]
	s_waitcnt lgkmcnt(10)
	v_alignbyte_b32 v232, v211, v210, v80
	v_alignbyte_b32 v233, v212, v211, v80
	v_alignbyte_b32 v234, v213, v212, v80
	v_alignbyte_b32 v235, v214, v213, v80
	ds_read2_b32 v[210:211], v156 offset0:32 offset1:33
	ds_read2_b32 v[212:213], v156 offset0:34 offset1:35
	ds_read_b32 v214, v156 offset:144
	v_mfma_f32_16x16x32_bf16 v[54:57], v[232:235], v[240:243], v[54:57]
	s_waitcnt lgkmcnt(10)
	v_alignbyte_b32 v228, v217, v216, v80
	v_alignbyte_b32 v229, v218, v217, v80
	v_alignbyte_b32 v230, v219, v218, v80
	v_alignbyte_b32 v231, v220, v219, v80
	ds_read2_b32 v[216:217], v155 offset0:32 offset1:33
	ds_read2_b32 v[218:219], v155 offset0:34 offset1:35
	ds_read_b32 v220, v155 offset:144
	v_mfma_f32_16x16x32_bf16 v[42:45], v[228:231], v[240:243], v[42:45]
	s_waitcnt lgkmcnt(10)
	v_alignbyte_b32 v232, v223, v222, v80
	v_alignbyte_b32 v233, v224, v223, v80
	v_alignbyte_b32 v234, v225, v224, v80
	v_alignbyte_b32 v235, v226, v225, v80
	ds_read2_b32 v[222:223], v154 offset0:32 offset1:33
	ds_read2_b32 v[224:225], v154 offset0:34 offset1:35
	ds_read_b32 v226, v154 offset:144
	v_add_u32_e32 v91, 0x80, v91
	v_add_u32_e32 v154, 0x80, v154
	v_add_u32_e32 v155, 0x80, v155
	v_add_u32_e32 v156, 0x80, v156
	v_add_u32_e32 v157, 0x80, v157
	s_add_i32 s22, s22, 64
	s_cmpk_gt_i32 s22, 0x3c0
	v_mfma_f32_16x16x32_bf16 v[46:49], v[232:235], v[240:243], v[46:49]
	s_cbranch_scc0 .Lhl_conv_a
	s_waitcnt lgkmcnt(0)
	v_add_f32_e32 v58, v87, v88
	v_div_scale_f32 v59, s[22:23], v58, v58, 1.0
	v_rcp_f32_e32 v60, v59
	s_nop 0
	v_fma_f32 v61, -v59, v60, 1.0
	v_fmac_f32_e32 v60, v61, v60
	v_div_scale_f32 v61, vcc, 1.0, v58, 1.0
	v_mul_f32_e32 v87, v61, v60
	v_fma_f32 v88, -v59, v87, v61
	v_fmac_f32_e32 v87, v88, v60
	v_fma_f32 v59, -v59, v87, v61
	v_div_fmas_f32 v59, v59, v60, v87
	v_div_fixup_f32 v58, v59, v58, 1.0
	v_lshl_add_u32 v59, v81, 1, v90
	ds_read2st64_b64 v[90:93], v59 offset0:1 offset1:2
	v_lshl_add_u32 v87, v89, 11, v82
	ds_read_b64 v[60:61], v87 offset:24576
	s_waitcnt lgkmcnt(1)
	v_and_b32_e32 v127, 0xffff0000, v90
	v_lshlrev_b32_e32 v126, 16, v90
	v_pk_mul_f32 v[126:127], v[100:101], v[126:127] op_sel_hi:[0,1]
	s_waitcnt lgkmcnt(0)
	v_and_b32_e32 v89, 0xffff0000, v60
	v_lshlrev_b32_e32 v88, 16, v60
	v_pk_fma_f32 v[50:51], v[58:59], v[50:51], v[126:127] op_sel_hi:[0,1,1]
	v_pk_mul_f32 v[50:51], v[50:51], v[88:89]
	v_and_b32_e32 v89, 0xffff0000, v61
	v_lshlrev_b32_e32 v88, 16, v61
	v_and_b32_e32 v61, 0xffff0000, v91
	v_lshlrev_b32_e32 v60, 16, v91
	v_pk_mul_f32 v[60:61], v[100:101], v[60:61] op_sel_hi:[0,1]
	v_pk_fma_f32 v[52:53], v[58:59], v[52:53], v[60:61] op_sel_hi:[0,1,1]
	v_pk_mul_f32 v[52:53], v[52:53], v[88:89]
	v_bfe_u32 v88, v51, 16, 1
	v_bfe_u32 v89, v50, 16, 1
	v_add3_u32 v50, v50, v89, s94
	v_add3_u32 v88, v51, v88, s94
	v_cvt_pk_bf16_f32 v52, v52, v53
	v_mov_b32_e32 v51, v52
	v_perm_b32 v50, v88, v50, s95
	ds_write_b64 v59, v[50:51] offset:512
	ds_read_b64 v[50:51], v87 offset:25088
	v_and_b32_e32 v61, 0xffff0000, v92
	v_lshlrev_b32_e32 v60, 16, v92
	v_pk_mul_f32 v[60:61], v[100:101], v[60:61] op_sel_hi:[0,1]
	v_pk_fma_f32 v[54:55], v[58:59], v[54:55], v[60:61] op_sel_hi:[0,1,1]
	s_waitcnt lgkmcnt(0)
	v_and_b32_e32 v53, 0xffff0000, v50
	v_lshlrev_b32_e32 v52, 16, v50
	v_pk_mul_f32 v[52:53], v[54:55], v[52:53]
	v_and_b32_e32 v55, 0xffff0000, v51
	v_lshlrev_b32_e32 v54, 16, v51
	v_and_b32_e32 v51, 0xffff0000, v93
	v_lshlrev_b32_e32 v50, 16, v93
	v_pk_mul_f32 v[50:51], v[100:101], v[50:51] op_sel_hi:[0,1]
	v_pk_fma_f32 v[50:51], v[58:59], v[56:57], v[50:51] op_sel_hi:[0,1,1]
	v_pk_mul_f32 v[50:51], v[50:51], v[54:55]
	v_cvt_pk_bf16_f32 v52, v52, v53
	v_cvt_pk_bf16_f32 v50, v50, v51
	v_mov_b32_e32 v51, v50
	v_mov_b32_e32 v50, v52
	ds_write_b64 v59, v[50:51] offset:1024
	ds_read2st64_b64 v[50:53], v59 offset0:3 offset1:4
	ds_read_b64 v[54:55], v87 offset:25600
	s_waitcnt lgkmcnt(1)
	v_and_b32_e32 v61, 0xffff0000, v50
	v_lshlrev_b32_e32 v60, 16, v50
	v_pk_mul_f32 v[60:61], v[100:101], v[60:61] op_sel_hi:[0,1]
	s_waitcnt lgkmcnt(0)
	v_and_b32_e32 v57, 0xffff0000, v54
	v_lshlrev_b32_e32 v56, 16, v54
	v_pk_fma_f32 v[42:43], v[58:59], v[42:43], v[60:61] op_sel_hi:[0,1,1]
	v_pk_mul_f32 v[42:43], v[42:43], v[56:57]
	v_and_b32_e32 v57, 0xffff0000, v55
	v_lshlrev_b32_e32 v56, 16, v55
	v_and_b32_e32 v55, 0xffff0000, v51
	v_lshlrev_b32_e32 v54, 16, v51
	v_pk_mul_f32 v[50:51], v[100:101], v[54:55] op_sel_hi:[0,1]
	v_pk_fma_f32 v[44:45], v[58:59], v[44:45], v[50:51] op_sel_hi:[0,1,1]
	v_pk_mul_f32 v[44:45], v[44:45], v[56:57]
	v_bfe_u32 v54, v43, 16, 1
	v_bfe_u32 v55, v42, 16, 1
	v_add3_u32 v42, v42, v55, s94
	v_add3_u32 v54, v43, v54, s94
	v_cvt_pk_bf16_f32 v44, v44, v45
	v_mov_b32_e32 v43, v44
	v_perm_b32 v42, v54, v42, s95
	ds_write_b64 v59, v[42:43] offset:1536
	ds_read_b64 v[42:43], v87 offset:26112
	v_and_b32_e32 v51, 0xffff0000, v52
	v_lshlrev_b32_e32 v50, 16, v52
	v_pk_mul_f32 v[50:51], v[100:101], v[50:51] op_sel_hi:[0,1]
	v_pk_fma_f32 v[46:47], v[58:59], v[46:47], v[50:51] op_sel_hi:[0,1,1]
	s_waitcnt lgkmcnt(0)
	v_and_b32_e32 v45, 0xffff0000, v42
	v_lshlrev_b32_e32 v44, 16, v42
	v_pk_mul_f32 v[44:45], v[46:47], v[44:45]
	v_and_b32_e32 v47, 0xffff0000, v43
	v_lshlrev_b32_e32 v46, 16, v43
	v_and_b32_e32 v43, 0xffff0000, v53
	v_lshlrev_b32_e32 v42, 16, v53
	v_pk_mul_f32 v[42:43], v[100:101], v[42:43] op_sel_hi:[0,1]
	v_pk_fma_f32 v[42:43], v[58:59], v[48:49], v[42:43] op_sel_hi:[0,1,1]
	v_pk_mul_f32 v[42:43], v[42:43], v[46:47]
	v_cvt_pk_bf16_f32 v44, v44, v45
	v_cvt_pk_bf16_f32 v42, v42, v43
	v_mov_b32_e32 v43, v42
	v_mov_b32_e32 v42, v44
	ds_write_b64 v59, v[42:43] offset:2048
	s_waitcnt vmcnt(5)
	ds_write_b128 v70, v[26:29] offset:40992
	s_waitcnt vmcnt(4)
	ds_write_b128 v70, v[30:33] offset:42016
	s_waitcnt vmcnt(3)
	ds_write_b128 v70, v[34:37] offset:43040
	s_waitcnt vmcnt(2)
	ds_write_b128 v70, v[38:41] offset:44064
	s_and_saveexec_b64 s[92:93], s[42:43]
	ds_write_b128 v70, v[22:25] offset:45088
	s_or_b64 exec, exec, s[92:93]
	s_waitcnt vmcnt(1)
	ds_bpermute_b32 v26, v71, v86
	s_andn2_b64 vcc, exec, s[90:91]
	s_waitcnt lgkmcnt(0)
	v_add_f32_e32 v26, v86, v26
	ds_bpermute_b32 v27, v72, v26
	s_waitcnt lgkmcnt(0)
	v_add_f32_e32 v26, v26, v27
	ds_bpermute_b32 v27, v73, v26
	s_waitcnt lgkmcnt(0)
	v_add_f32_e32 v26, v26, v27
	ds_bpermute_b32 v27, v74, v26
	s_waitcnt lgkmcnt(0)
	v_add_f32_e32 v26, v26, v27
	ds_bpermute_b32 v27, v75, v26
	s_waitcnt lgkmcnt(0)
	v_add_f32_e32 v46, v26, v27
	ds_bpermute_b32 v47, v76, v46
	s_cbranch_vccnz .LBB0_801
	v_add_u32_e32 v28, 4, v66
	v_add_u32_e32 v2, s74, v28
	v_mad_i64_i32 v[26:27], s[22:23], v2, s10, v[62:63]
	global_load_dwordx4 v[2:5], v[26:27], off
	global_load_dwordx4 v[6:9], v[26:27], off offset:1024
	global_load_dwordx4 v[10:13], v[26:27], off offset:2048
	global_load_dwordx4 v[14:17], v[26:27], off offset:3072
	s_and_saveexec_b64 s[90:91], s[42:43]
	s_cbranch_execz .LBB0_800
	v_add_co_u32_e32 v18, vcc, 0x1000, v26
	s_nop 1
	v_addc_co_u32_e32 v19, vcc, 0, v27, vcc
	global_load_dwordx4 v[18:21], v[18:19], off

.Lhl_conv_b:
	s_waitcnt lgkmcnt(9)
	v_alignbyte_b32 v228, v205, v204, v80
	v_alignbyte_b32 v229, v206, v205, v80
	v_alignbyte_b32 v230, v207, v206, v80
	v_alignbyte_b32 v231, v208, v207, v80
	ds_read2_b32 v[204:205], v157 offset0:16 offset1:17
	ds_read2_b32 v[206:207], v157 offset0:18 offset1:19
	ds_read_b32 v208, v157 offset:80
	ds_read_b128 v[240:243], v48 offset:64
	v_mfma_f32_16x16x32_bf16 v[34:37], v[228:231], v[236:239], v[34:37]
	s_waitcnt lgkmcnt(10)
	v_alignbyte_b32 v232, v211, v210, v80
	v_alignbyte_b32 v233, v212, v211, v80
	v_alignbyte_b32 v234, v213, v212, v80
	v_alignbyte_b32 v235, v214, v213, v80
	ds_read2_b32 v[210:211], v156 offset0:16 offset1:17
	ds_read2_b32 v[212:213], v156 offset0:18 offset1:19
	ds_read_b32 v214, v156 offset:80
	v_mfma_f32_16x16x32_bf16 v[38:41], v[232:235], v[236:239], v[38:41]
	s_waitcnt lgkmcnt(10)
	v_alignbyte_b32 v228, v217, v216, v80
	v_alignbyte_b32 v229, v218, v217, v80
	v_alignbyte_b32 v230, v219, v218, v80
	v_alignbyte_b32 v231, v220, v219, v80
	ds_read2_b32 v[216:217], v155 offset0:16 offset1:17
	ds_read2_b32 v[218:219], v155 offset0:18 offset1:19
	ds_read_b32 v220, v155 offset:80
	v_mfma_f32_16x16x32_bf16 v[26:29], v[228:231], v[236:239], v[26:29]
	s_waitcnt lgkmcnt(10)
	v_alignbyte_b32 v232, v223, v222, v80
	v_alignbyte_b32 v233, v224, v223, v80
	v_alignbyte_b32 v234, v225, v224, v80
	v_alignbyte_b32 v235, v226, v225, v80
	ds_read2_b32 v[222:223], v154 offset0:16 offset1:17
	ds_read2_b32 v[224:225], v154 offset0:18 offset1:19
	ds_read_b32 v226, v154 offset:80
	v_mfma_f32_16x16x32_bf16 v[30:33], v[232:235], v[236:239], v[30:33]
	s_waitcnt lgkmcnt(9)
	v_alignbyte_b32 v228, v205, v204, v80
	v_alignbyte_b32 v229, v206, v205, v80
	v_alignbyte_b32 v230, v207, v206, v80
	v_alignbyte_b32 v231, v208, v207, v80
	ds_read2_b32 v[204:205], v157 offset0:32 offset1:33
	ds_read2_b32 v[206:207], v157 offset0:34 offset1:35
	ds_read_b32 v208, v157 offset:144
	ds_read_b128 v[236:239], v48 offset:128
	v_mfma_f32_16x16x32_bf16 v[34:37], v[228:231], v[240:243], v[34:37]
	s_waitcnt lgkmcnt(10)
	v_alignbyte_b32 v232, v211, v210, v80
	v_alignbyte_b32 v233, v212, v211, v80
	v_alignbyte_b32 v234, v213, v212, v80
	v_alignbyte_b32 v235, v214, v213, v80
	ds_read2_b32 v[210:211], v156 offset0:32 offset1:33
	ds_read2_b32 v[212:213], v156 offset0:34 offset1:35
	ds_read_b32 v214, v156 offset:144
	v_mfma_f32_16x16x32_bf16 v[38:41], v[232:235], v[240:243], v[38:41]
	s_waitcnt lgkmcnt(10)
	v_alignbyte_b32 v228, v217, v216, v80
	v_alignbyte_b32 v229, v218, v217, v80
	v_alignbyte_b32 v230, v219, v218, v80
	v_alignbyte_b32 v231, v220, v219, v80
	ds_read2_b32 v[216:217], v155 offset0:32 offset1:33
	ds_read2_b32 v[218:219], v155 offset0:34 offset1:35
	ds_read_b32 v220, v155 offset:144
	v_mfma_f32_16x16x32_bf16 v[26:29], v[228:231], v[240:243], v[26:29]
	s_waitcnt lgkmcnt(10)
	v_alignbyte_b32 v232, v223, v222, v80
	v_alignbyte_b32 v233, v224, v223, v80
	v_alignbyte_b32 v234, v225, v224, v80
	v_alignbyte_b32 v235, v226, v225, v80
	ds_read2_b32 v[222:223], v154 offset0:32 offset1:33
	ds_read2_b32 v[224:225], v154 offset0:34 offset1:35
	ds_read_b32 v226, v154 offset:144
	v_add_u32_e32 v48, 0x80, v48
	v_add_u32_e32 v154, 0x80, v154
	v_add_u32_e32 v155, 0x80, v155
	v_add_u32_e32 v156, 0x80, v156
	v_add_u32_e32 v157, 0x80, v157
	s_add_i32 s22, s22, 64
	s_cmpk_lt_i32 s22, 0x3c1
	v_mfma_f32_16x16x32_bf16 v[30:33], v[232:235], v[240:243], v[30:33]
	s_cbranch_scc1 .Lhl_conv_b
	s_waitcnt lgkmcnt(0)
	v_add_f32_e32 v42, v46, v47
	v_div_scale_f32 v43, s[22:23], v42, v42, 1.0
	v_rcp_f32_e32 v44, v43
	s_mov_b32 s22, 4
	s_mov_b64 s[90:91], 0
	s_mov_b64 s[92:93], -1
	v_fma_f32 v45, -v43, v44, 1.0
	v_fmac_f32_e32 v44, v45, v44
	v_div_scale_f32 v45, vcc, 1.0, v42, 1.0
	v_mul_f32_e32 v46, v45, v44
	v_fma_f32 v47, -v43, v46, v45
	v_fmac_f32_e32 v46, v47, v44
	v_fma_f32 v43, -v43, v46, v45
	v_div_fmas_f32 v43, v43, v44, v46
	ds_read2st64_b64 v[44:47], v59 offset0:1 offset1:2
	v_div_fixup_f32 v42, v43, v42, 1.0
	s_and_b64 vcc, exec, s[88:89]
	s_waitcnt lgkmcnt(0)
	v_and_b32_e32 v49, 0xffff0000, v44
	v_lshlrev_b32_e32 v48, 16, v44
	s_waitcnt vmcnt(0)
	v_pk_mul_f32 v[48:49], v[64:65], v[48:49] op_sel_hi:[0,1]
	v_pk_fma_f32 v[34:35], v[42:43], v[34:35], v[48:49] op_sel_hi:[0,1,1]
	v_and_b32_e32 v49, 0xffff0000, v45
	v_lshlrev_b32_e32 v48, 16, v45
	v_pk_mul_f32 v[44:45], v[64:65], v[48:49] op_sel_hi:[0,1]
	v_pk_fma_f32 v[36:37], v[42:43], v[36:37], v[44:45] op_sel_hi:[0,1,1]
	v_bfe_u32 v43, v37, 16, 1
	v_bfe_u32 v44, v36, 16, 1
	v_bfe_u32 v45, v35, 16, 1
	v_add3_u32 v45, v35, v45, s94
	v_add3_u32 v35, v36, v44, s94
	v_add3_u32 v36, v37, v43, s94
	v_perm_b32 v35, v36, v35, s95
	v_and_b32_e32 v37, 0xffff0000, v46
	v_lshlrev_b32_e32 v36, 16, v46
	v_pk_mul_f32 v[36:37], v[64:65], v[36:37] op_sel_hi:[0,1]
	v_pk_fma_f32 v[36:37], v[42:43], v[38:39], v[36:37] op_sel_hi:[0,1,1]
	v_and_b32_e32 v39, 0xffff0000, v47
	v_lshlrev_b32_e32 v38, 16, v47
	v_pk_mul_f32 v[38:39], v[64:65], v[38:39] op_sel_hi:[0,1]
	v_pk_fma_f32 v[38:39], v[42:43], v[40:41], v[38:39] op_sel_hi:[0,1,1]
	v_bfe_u32 v48, v34, 16, 1
	v_bfe_u32 v43, v37, 16, 1
	v_bfe_u32 v44, v36, 16, 1
	v_add3_u32 v34, v34, v48, s94
	v_add3_u32 v36, v36, v44, s94
	v_add3_u32 v43, v37, v43, s94
	v_cvt_pk_bf16_f32 v38, v38, v39
	v_perm_b32 v34, v45, v34, s95
	v_mov_b32_e32 v37, v38
	v_perm_b32 v36, v43, v36, s95
	ds_write2st64_b64 v59, v[34:35], v[36:37] offset0:1 offset1:2
	ds_read2st64_b64 v[34:37], v59 offset0:3 offset1:4
	s_waitcnt lgkmcnt(0)
	v_and_b32_e32 v39, 0xffff0000, v34
	v_lshlrev_b32_e32 v38, 16, v34
	v_pk_mul_f32 v[38:39], v[64:65], v[38:39] op_sel_hi:[0,1]
	v_pk_fma_f32 v[26:27], v[42:43], v[26:27], v[38:39] op_sel_hi:[0,1,1]
	v_and_b32_e32 v39, 0xffff0000, v35
	v_lshlrev_b32_e32 v38, 16, v35
	v_pk_mul_f32 v[34:35], v[64:65], v[38:39] op_sel_hi:[0,1]
	v_pk_fma_f32 v[28:29], v[42:43], v[28:29], v[34:35] op_sel_hi:[0,1,1]
	v_bfe_u32 v38, v27, 16, 1
	v_add3_u32 v38, v27, v38, s94
	v_cvt_pk_bf16_f32 v28, v28, v29
	v_mov_b32_e32 v27, v28
	v_and_b32_e32 v29, 0xffff0000, v36
	v_lshlrev_b32_e32 v28, 16, v36
	v_pk_mul_f32 v[28:29], v[64:65], v[28:29] op_sel_hi:[0,1]
	v_pk_fma_f32 v[28:29], v[42:43], v[30:31], v[28:29] op_sel_hi:[0,1,1]
	v_and_b32_e32 v31, 0xffff0000, v37
	v_lshlrev_b32_e32 v30, 16, v37
	v_pk_mul_f32 v[30:31], v[64:65], v[30:31] op_sel_hi:[0,1]
	v_pk_fma_f32 v[30:31], v[42:43], v[32:33], v[30:31] op_sel_hi:[0,1,1]
	v_bfe_u32 v39, v26, 16, 1
	v_bfe_u32 v34, v29, 16, 1
	v_bfe_u32 v35, v28, 16, 1
	v_add3_u32 v26, v26, v39, s94
	v_add3_u32 v28, v28, v35, s94
	v_add3_u32 v34, v29, v34, s94
	v_cvt_pk_bf16_f32 v30, v30, v31
	v_perm_b32 v26, v38, v26, s95
	v_mov_b32_e32 v29, v30
	v_perm_b32 v28, v34, v28, s95
	ds_write2st64_b64 v59, v[26:27], v[28:29] offset0:3 offset1:4
	s_cbranch_vccz .LBB0_789
	v_cmp_eq_u32_e32 vcc, 0, v0
	s_and_saveexec_b64 s[42:43], vcc
	s_cbranch_execz .LBB0_838
	s_lshr_b32 s20, s20, 3
	s_and_b32 s20, s20, 4
	v_readlane_b32 s22, v251, 49
	s_add_u32 s20, s22, s20
	v_readlane_b32 s22, v251, 50
	s_addc_u32 s22, s22, 0
	s_lshl_b32 s21, s21, 5
	s_add_u32 s88, s20, s21
	s_addc_u32 s89, s22, 0
	s_mov_b32 s20, 0x400001
	s_branch .LBB0_807

.LBB0_838:
	s_or_b64 exec, exec, s[42:43]
	v_lshl_add_u64 v[2:3], v[94:95], 0, s[70:71]
	v_add_co_u32_e32 v2, vcc, 0x2000, v2
	s_waitcnt lgkmcnt(0)
	s_nop 0
	v_addc_co_u32_e32 v3, vcc, 0, v3, vcc
	s_barrier
	global_load_dwordx4 v[2:5], v[2:3], off offset:2048
	v_add_u32_e32 v34, s19, v0
	v_mov_b64_e32 v[36:37], s[6:7]
	v_mad_i64_i32 v[0:1], s[20:21], v34, s0, v[36:37]
	v_lshl_add_u64 v[0:1], v[0:1], 0, s[70:71]
	s_movk_i32 s23, 0x3000
	v_ashrrev_i32_e32 v35, 31, v34
	s_mov_b32 s22, 0xcc00000
	v_readlane_b32 s88, v253, 36
	v_readlane_b32 s89, v253, 37
	s_waitcnt vmcnt(0)
	v_cndmask_b32_e64 v8, 0, v3, s[36:37]
	v_cndmask_b32_e64 v9, 0, v2, s[36:37]
	v_lshl_add_u64 v[2:3], v[96:97], 0, s[70:71]
	v_add_co_u32_e32 v2, vcc, s3, v2
	v_cndmask_b32_e64 v6, 0, v5, s[36:37]
	s_nop 0
	v_addc_co_u32_e32 v3, vcc, 0, v3, vcc
	v_cndmask_b32_e64 v7, 0, v4, s[36:37]
	global_load_dwordx4 v[2:5], v[2:3], off offset:2048
	v_and_b32_e32 v13, 0xffff0000, v9
	v_lshlrev_b32_e32 v12, 16, v9
	v_and_b32_e32 v47, 0xffff0000, v8
	v_lshlrev_b32_e32 v46, 16, v8
	v_and_b32_e32 v43, 0xffff0000, v7
	v_lshlrev_b32_e32 v42, 16, v7
	v_and_b32_e32 v39, 0xffff0000, v6
	v_lshlrev_b32_e32 v38, 16, v6
	s_add_u32 s36, s86, 0x2000
	s_addc_u32 s37, s87, 0
	s_waitcnt vmcnt(0)
	v_cndmask_b32_e64 v14, 0, v3, s[38:39]
	v_cndmask_b32_e64 v15, 0, v2, s[38:39]
	v_lshl_add_u64 v[2:3], v[98:99], 0, s[70:71]
	v_add_co_u32_e32 v2, vcc, s3, v2
	v_cndmask_b32_e64 v10, 0, v5, s[38:39]
	s_nop 0
	v_addc_co_u32_e32 v3, vcc, 0, v3, vcc
	v_cndmask_b32_e64 v11, 0, v4, s[38:39]
	global_load_dwordx4 v[2:5], v[2:3], off offset:2048
	v_add_co_u32_e32 v0, vcc, s23, v0
	v_and_b32_e32 v45, 0xffff0000, v11
	s_nop 0
	v_addc_co_u32_e32 v1, vcc, 0, v1, vcc
	v_lshlrev_b32_e32 v44, 16, v11
	v_and_b32_e32 v41, 0xffff0000, v10
	v_lshlrev_b32_e32 v40, 16, v10
	v_and_b32_e32 v17, 0xffff0000, v15
	v_lshlrev_b32_e32 v16, 16, v15
	v_and_b32_e32 v49, 0xffff0000, v14
	v_lshlrev_b32_e32 v48, 16, v14
	s_add_u32 s38, s86, 0x3800
	s_addc_u32 s39, s87, 0
	s_waitcnt vmcnt(0)
	v_cndmask_b32_e64 v50, 0, v5, s[40:41]
	v_cndmask_b32_e64 v51, 0, v4, s[40:41]
	v_cndmask_b32_e64 v52, 0, v3, s[40:41]
	v_cndmask_b32_e64 v30, 0, v2, s[40:41]
	global_load_dwordx4 v[0:3], v[0:1], off
	s_nop 0
	global_load_dwordx4 v[4:7], v161, s[84:85] offset:2064
	global_load_dwordx4 v[18:21], v161, s[84:85] offset:2048
	global_load_dwordx4 v[8:11], v161, s[86:87] offset:2064
	global_load_dwordx4 v[22:25], v161, s[86:87] offset:2048
	s_waitcnt vmcnt(1)
	v_pk_fma_f32 v[4:5], v[8:9], v[42:43], v[4:5]
	s_waitcnt vmcnt(0)
	v_pk_fma_f32 v[18:19], v[22:23], v[12:13], v[18:19]
	global_load_dwordx4 v[12:15], v161, s[36:37] offset:16
	global_load_dwordx4 v[26:29], v196, s[86:87]
	v_and_b32_e32 v53, 0xffff0000, v0
	v_lshlrev_b32_e32 v0, 16, v0
	v_pk_fma_f32 v[20:21], v[24:25], v[46:47], v[20:21]
	v_and_b32_e32 v25, 0xffff0000, v52
	v_lshlrev_b32_e32 v24, 16, v52
	v_and_b32_e32 v9, 0xffff0000, v51
	v_lshlrev_b32_e32 v8, 16, v51
	v_pk_fma_f32 v[6:7], v[10:11], v[38:39], v[6:7]
	v_and_b32_e32 v10, 0xffff0000, v3
	v_lshlrev_b32_e32 v11, 16, v3
	s_waitcnt vmcnt(1)
	v_pk_fma_f32 v[4:5], v[12:13], v[44:45], v[4:5]
	s_waitcnt vmcnt(0)
	v_pk_fma_f32 v[22:23], v[26:27], v[16:17], v[18:19]
	v_and_b32_e32 v27, 0xffff0000, v30
	v_lshlrev_b32_e32 v26, 16, v30
	global_load_dwordx4 v[16:19], v161, s[38:39] offset:16
	global_load_dwordx4 v[30:33], v197, s[86:87] offset:2048
	v_pk_fma_f32 v[20:21], v[28:29], v[48:49], v[20:21]
	v_pk_fma_f32 v[6:7], v[14:15], v[40:41], v[6:7]
	s_waitcnt vmcnt(1)
	v_pk_fma_f32 v[4:5], v[16:17], v[8:9], v[4:5]
	s_waitcnt vmcnt(0)
	v_pk_fma_f32 v[22:23], v[30:31], v[26:27], v[22:23]
	ds_read_u16 v27, v101 offset:512
	ds_read_u16 v30, v101 offset:3584
	v_mul_f32_e32 v26, 0xbfb8aa3b, v0
	v_exp_f32_e32 v26, v26
	v_pk_fma_f32 v[20:21], v[32:33], v[24:25], v[20:21]
	v_and_b32_e32 v16, 0xffff0000, v2
	s_waitcnt lgkmcnt(0)
	v_lshlrev_b32_e32 v31, 16, v30
	v_lshlrev_b32_e32 v30, 16, v27
	v_mul_f32_e32 v27, 0xbfb8aa3b, v53
	v_exp_f32_e32 v27, v27
	v_pk_mul_f32 v[22:23], v[22:23], v[30:31]
	v_lshlrev_b32_e32 v2, 16, v2
	v_mul_f32_e32 v8, 0xbfb8aa3b, v2
	v_pk_add_f32 v[26:27], v[26:27], 1.0 op_sel_hi:[1,0]
	v_exp_f32_e32 v8, v8
	v_div_scale_f32 v30, s[20:21], v27, v27, v53
	v_rcp_f32_e32 v31, v30
	s_nop 0
	v_fma_f32 v54, -v30, v31, 1.0
	v_fmac_f32_e32 v31, v54, v31
	v_div_scale_f32 v54, vcc, v53, v27, v53
	v_mul_f32_e32 v55, v54, v31
	v_fma_f32 v56, -v30, v55, v54
	v_fmac_f32_e32 v55, v56, v31
	v_fma_f32 v30, -v30, v55, v54
	v_div_fmas_f32 v30, v30, v31, v55
	v_div_fixup_f32 v27, v30, v27, v53
	v_div_scale_f32 v30, s[20:21], v26, v26, v0
	v_rcp_f32_e32 v31, v30
	s_nop 0
	v_fma_f32 v53, -v30, v31, 1.0
	v_fmac_f32_e32 v31, v53, v31
	v_div_scale_f32 v53, vcc, v0, v26, v0
	v_mul_f32_e32 v54, v53, v31
	v_fma_f32 v55, -v30, v54, v53
	v_fmac_f32_e32 v54, v55, v31
	v_fma_f32 v30, -v30, v54, v53
	v_div_fmas_f32 v30, v30, v31, v54
	v_div_fixup_f32 v26, v30, v26, v0
	v_pk_mul_f32 v[22:23], v[26:27], v[22:23]
	v_and_b32_e32 v26, 0xffff0000, v1
	v_lshlrev_b32_e32 v27, 16, v1
	ds_read_u16 v1, v101 offset:6656
	ds_read_u16 v24, v101 offset:9728
	v_mul_f32_e32 v0, 0xbfb8aa3b, v27
	v_exp_f32_e32 v0, v0
	ds_read_u16 v9, v101 offset:12800
	ds_read_u16 v12, v101 offset:15872
	s_waitcnt lgkmcnt(2)
	v_lshlrev_b32_e32 v25, 16, v24
	v_lshlrev_b32_e32 v24, 16, v1
	v_mul_f32_e32 v1, 0xbfb8aa3b, v26
	v_exp_f32_e32 v1, v1
	v_pk_mul_f32 v[20:21], v[20:21], v[24:25]
	s_waitcnt lgkmcnt(0)
	v_lshlrev_b32_e32 v13, 16, v12
	v_lshlrev_b32_e32 v12, 16, v9
	v_pk_add_f32 v[0:1], v[0:1], 1.0 op_sel_hi:[1,0]
	v_mul_f32_e32 v9, 0xbfb8aa3b, v16
	v_div_scale_f32 v24, s[20:21], v1, v1, v26
	v_rcp_f32_e32 v25, v24
	v_exp_f32_e32 v9, v9
	v_pk_mul_f32 v[4:5], v[4:5], v[12:13]
	v_fma_f32 v28, -v24, v25, 1.0
	v_fmac_f32_e32 v25, v28, v25
	v_div_scale_f32 v28, vcc, v26, v1, v26
	v_mul_f32_e32 v29, v28, v25
	v_fma_f32 v30, -v24, v29, v28
	v_fmac_f32_e32 v29, v30, v25
	v_fma_f32 v24, -v24, v29, v28
	v_div_fmas_f32 v24, v24, v25, v29
	v_div_fixup_f32 v1, v24, v1, v26
	v_div_scale_f32 v24, s[20:21], v0, v0, v27
	v_rcp_f32_e32 v25, v24
	v_pk_add_f32 v[8:9], v[8:9], 1.0 op_sel_hi:[1,0]
	v_fma_f32 v26, -v24, v25, 1.0
	v_fmac_f32_e32 v25, v26, v25
	v_div_scale_f32 v26, vcc, v27, v0, v27
	v_div_scale_f32 v12, s[20:21], v9, v9, v16
	v_mul_f32_e32 v28, v26, v25
	v_rcp_f32_e32 v13, v12
	v_fma_f32 v29, -v24, v28, v26
	v_fmac_f32_e32 v28, v29, v25
	v_fma_f32 v24, -v24, v28, v26
	v_div_fmas_f32 v24, v24, v25, v28
	v_fma_f32 v17, -v12, v13, 1.0
	v_div_fixup_f32 v0, v24, v0, v27
	v_fmac_f32_e32 v13, v17, v13
	v_div_scale_f32 v17, vcc, v16, v9, v16
	v_pk_mul_f32 v[0:1], v[0:1], v[20:21]
	v_mul_f32_e32 v20, v17, v13
	v_fma_f32 v21, -v12, v20, v17
	v_fmac_f32_e32 v20, v21, v13
	v_fma_f32 v12, -v12, v20, v17
	v_div_fmas_f32 v12, v12, v13, v20
	v_div_fixup_f32 v9, v12, v9, v16
	v_div_scale_f32 v12, s[20:21], v8, v8, v2
	v_rcp_f32_e32 v13, v12
	s_nop 0
	v_fma_f32 v16, -v12, v13, 1.0
	v_fmac_f32_e32 v13, v16, v13
	v_div_scale_f32 v16, vcc, v2, v8, v2
	v_mul_f32_e32 v17, v16, v13
	v_fma_f32 v20, -v12, v17, v16
	v_fmac_f32_e32 v17, v20, v13
	v_fma_f32 v12, -v12, v17, v16
	v_div_fmas_f32 v12, v12, v13, v17
	v_div_fixup_f32 v8, v12, v8, v2
	v_pk_mul_f32 v[4:5], v[8:9], v[4:5]
	v_and_b32_e32 v9, 0xffff0000, v50
	v_lshlrev_b32_e32 v8, 16, v50
	v_pk_fma_f32 v[6:7], v[18:19], v[8:9], v[6:7]
	ds_read_u16 v3, v101 offset:18944
	ds_read_u16 v8, v101 offset:22016
	v_mul_f32_e32 v2, 0xbfb8aa3b, v11
	v_exp_f32_e32 v2, v2
	s_waitcnt lgkmcnt(0)
	v_lshlrev_b32_e32 v9, 16, v8
	v_lshlrev_b32_e32 v8, 16, v3
	v_mul_f32_e32 v3, 0xbfb8aa3b, v10
	v_exp_f32_e32 v3, v3
	v_pk_mul_f32 v[6:7], v[6:7], v[8:9]
	v_pk_add_f32 v[2:3], v[2:3], 1.0 op_sel_hi:[1,0]
	s_nop 0
	v_div_scale_f32 v8, s[20:21], v3, v3, v10
	v_rcp_f32_e32 v9, v8
	s_nop 0
	v_fma_f32 v12, -v8, v9, 1.0
	v_fmac_f32_e32 v9, v12, v9
	v_div_scale_f32 v12, vcc, v10, v3, v10
	v_mul_f32_e32 v13, v12, v9
	v_fma_f32 v14, -v8, v13, v12
	v_fmac_f32_e32 v13, v14, v9
	v_fma_f32 v8, -v8, v13, v12
	v_div_fmas_f32 v8, v8, v9, v13
	v_div_fixup_f32 v3, v8, v3, v10
	v_div_scale_f32 v8, s[20:21], v2, v2, v11
	v_rcp_f32_e32 v9, v8
	s_nop 0
	v_fma_f32 v10, -v8, v9, 1.0
	v_fmac_f32_e32 v9, v10, v9
	v_div_scale_f32 v10, vcc, v11, v2, v11
	v_mul_f32_e32 v12, v10, v9
	v_fma_f32 v13, -v8, v12, v10
	v_fmac_f32_e32 v12, v13, v9
	v_fma_f32 v8, -v8, v12, v10
	v_div_fmas_f32 v8, v8, v9, v12
	v_div_fixup_f32 v2, v8, v2, v11
	v_pk_mul_f32 v[2:3], v[2:3], v[6:7]
	v_cvt_pk_bf16_f32 v4, v4, v5
	v_cvt_pk_bf16_f32 v2, v2, v3
	v_mov_b32_e32 v3, v2
	v_mov_b32_e32 v2, v4
	v_lshlrev_b64 v[4:5], 12, v[34:35]
	v_lshl_add_u64 v[4:5], s[30:31], 0, v[4:5]
	v_bfe_u32 v12, v23, 16, 1
	v_bfe_u32 v13, v22, 16, 1
	v_lshl_add_u64 v[4:5], v[4:5], 0, s[70:71]
	v_add3_u32 v13, v22, v13, s94
	v_add3_u32 v12, v23, v12, s94
	v_cvt_pk_bf16_f32 v0, v0, v1
	v_add_co_u32_e32 v4, vcc, s22, v4
	v_mov_b32_e32 v1, v0
	v_perm_b32 v0, v12, v13, s95
	v_addc_co_u32_e32 v5, vcc, 0, v5, vcc
	global_store_dwordx4 v[4:5], v[0:3], off offset:3072
	v_add_u32_e32 v34, s19, v124
	v_ashrrev_i32_e32 v35, 31, v34
	v_lshl_add_u64 v[0:1], v[110:111], 0, s[70:71]
	v_add_co_u32_e32 v0, vcc, s3, v0
	s_nop 1
	v_addc_co_u32_e32 v1, vcc, 0, v1, vcc
	global_load_dwordx4 v[0:3], v[0:1], off offset:2048
	s_waitcnt vmcnt(0)
	v_cndmask_b32_e64 v6, 0, v1, s[50:51]
	v_cndmask_b32_e64 v7, 0, v0, s[50:51]
	v_lshl_add_u64 v[0:1], v[114:115], 0, s[70:71]
	v_add_co_u32_e32 v0, vcc, s3, v0
	v_cndmask_b32_e64 v4, 0, v3, s[50:51]
	s_nop 0
	v_addc_co_u32_e32 v1, vcc, 0, v1, vcc
	v_cndmask_b32_e64 v5, 0, v2, s[50:51]
	global_load_dwordx4 v[0:3], v[0:1], off offset:2048
	v_and_b32_e32 v13, 0xffff0000, v7
	v_lshlrev_b32_e32 v12, 16, v7
	v_and_b32_e32 v47, 0xffff0000, v6
	v_lshlrev_b32_e32 v46, 16, v6
	v_and_b32_e32 v43, 0xffff0000, v5
	v_lshlrev_b32_e32 v42, 16, v5
	v_and_b32_e32 v39, 0xffff0000, v4
	v_lshlrev_b32_e32 v38, 16, v4
	s_waitcnt vmcnt(0)
	v_cndmask_b32_e64 v10, 0, v1, s[56:57]
	v_cndmask_b32_e64 v11, 0, v0, s[56:57]
	v_lshl_add_u64 v[0:1], v[118:119], 0, s[70:71]
	v_add_co_u32_e32 v0, vcc, s3, v0
	v_cndmask_b32_e64 v8, 0, v3, s[56:57]
	s_nop 0
	v_addc_co_u32_e32 v1, vcc, 0, v1, vcc
	v_cndmask_b32_e64 v9, 0, v2, s[56:57]
	global_load_dwordx4 v[0:3], v[0:1], off offset:2048
	v_and_b32_e32 v17, 0xffff0000, v11
	v_lshlrev_b32_e32 v16, 16, v11
	v_and_b32_e32 v49, 0xffff0000, v10
	v_lshlrev_b32_e32 v48, 16, v10
	v_and_b32_e32 v45, 0xffff0000, v9
	v_lshlrev_b32_e32 v44, 16, v9
	v_and_b32_e32 v41, 0xffff0000, v8
	v_lshlrev_b32_e32 v40, 16, v8
	s_waitcnt vmcnt(0)
	v_cndmask_b32_e64 v52, 0, v1, s[60:61]
	v_cndmask_b32_e64 v30, 0, v0, s[60:61]
	v_mad_i64_i32 v[0:1], s[20:21], v34, s0, v[36:37]
	v_lshl_add_u64 v[0:1], v[0:1], 0, s[70:71]
	v_add_co_u32_e32 v0, vcc, s23, v0
	v_cndmask_b32_e64 v50, 0, v3, s[60:61]
	s_nop 0
	v_addc_co_u32_e32 v1, vcc, 0, v1, vcc
	v_cndmask_b32_e64 v51, 0, v2, s[60:61]
	global_load_dwordx4 v[0:3], v[0:1], off
	s_nop 0
	global_load_dwordx4 v[4:7], v161, s[84:85] offset:2064
	global_load_dwordx4 v[18:21], v161, s[84:85] offset:2048
	global_load_dwordx4 v[8:11], v161, s[86:87] offset:2064
	global_load_dwordx4 v[22:25], v161, s[86:87] offset:2048
	s_waitcnt vmcnt(1)
	v_pk_fma_f32 v[4:5], v[8:9], v[42:43], v[4:5]
	s_waitcnt vmcnt(0)
	v_pk_fma_f32 v[18:19], v[22:23], v[12:13], v[18:19]
	global_load_dwordx4 v[12:15], v161, s[36:37] offset:16
	global_load_dwordx4 v[26:29], v196, s[86:87]
	v_pk_fma_f32 v[20:21], v[24:25], v[46:47], v[20:21]
	v_and_b32_e32 v25, 0xffff0000, v52
	v_lshlrev_b32_e32 v24, 16, v52
	v_and_b32_e32 v9, 0xffff0000, v51
	v_lshlrev_b32_e32 v8, 16, v51
	v_pk_fma_f32 v[6:7], v[10:11], v[38:39], v[6:7]
	v_and_b32_e32 v10, 0xffff0000, v3
	v_lshlrev_b32_e32 v11, 16, v3
	s_waitcnt vmcnt(1)
	v_pk_fma_f32 v[4:5], v[12:13], v[44:45], v[4:5]
	s_waitcnt vmcnt(0)
	v_pk_fma_f32 v[22:23], v[26:27], v[16:17], v[18:19]
	v_and_b32_e32 v27, 0xffff0000, v30
	v_lshlrev_b32_e32 v26, 16, v30
	global_load_dwordx4 v[16:19], v161, s[38:39] offset:16
	global_load_dwordx4 v[30:33], v197, s[86:87] offset:2048
	v_pk_fma_f32 v[20:21], v[28:29], v[48:49], v[20:21]
	v_pk_fma_f32 v[6:7], v[14:15], v[40:41], v[6:7]
	s_waitcnt vmcnt(1)
	v_pk_fma_f32 v[4:5], v[16:17], v[8:9], v[4:5]
	s_waitcnt vmcnt(0)
	v_pk_fma_f32 v[22:23], v[30:31], v[26:27], v[22:23]
	ds_read_u16 v27, v101 offset:1024
	ds_read_u16 v31, v101 offset:4096
	v_and_b32_e32 v30, 0xffff0000, v0
	v_lshlrev_b32_e32 v0, 16, v0
	v_mul_f32_e32 v26, 0xbfb8aa3b, v0
	s_waitcnt lgkmcnt(1)
	v_lshlrev_b32_e32 v54, 16, v27
	v_mul_f32_e32 v27, 0xbfb8aa3b, v30
	v_exp_f32_e32 v26, v26
	v_exp_f32_e32 v27, v27
	s_waitcnt lgkmcnt(0)
	v_lshlrev_b32_e32 v55, 16, v31
	v_pk_mul_f32 v[22:23], v[22:23], v[54:55]
	v_pk_fma_f32 v[20:21], v[32:33], v[24:25], v[20:21]
	v_pk_add_f32 v[26:27], v[26:27], 1.0 op_sel_hi:[1,0]
	v_and_b32_e32 v16, 0xffff0000, v2
	v_div_scale_f32 v31, s[20:21], v27, v27, v30
	v_rcp_f32_e32 v53, v31
	v_lshlrev_b32_e32 v2, 16, v2
	v_mul_f32_e32 v8, 0xbfb8aa3b, v2
	v_exp_f32_e32 v8, v8
	v_fma_f32 v54, -v31, v53, 1.0
	v_fmac_f32_e32 v53, v54, v53
	v_div_scale_f32 v54, vcc, v30, v27, v30
	v_mul_f32_e32 v55, v54, v53
	v_fma_f32 v56, -v31, v55, v54
	v_fmac_f32_e32 v55, v56, v53
	v_fma_f32 v31, -v31, v55, v54
	v_div_fmas_f32 v31, v31, v53, v55
	v_div_fixup_f32 v27, v31, v27, v30
	v_div_scale_f32 v30, s[20:21], v26, v26, v0
	v_rcp_f32_e32 v31, v30
	s_nop 0
	v_fma_f32 v53, -v30, v31, 1.0
	v_fmac_f32_e32 v31, v53, v31
	v_div_scale_f32 v53, vcc, v0, v26, v0
	v_mul_f32_e32 v54, v53, v31
	v_fma_f32 v55, -v30, v54, v53
	v_fmac_f32_e32 v54, v55, v31
	v_fma_f32 v30, -v30, v54, v53
	v_div_fmas_f32 v30, v30, v31, v54
	v_div_fixup_f32 v26, v30, v26, v0
	v_pk_mul_f32 v[22:23], v[26:27], v[22:23]
	v_and_b32_e32 v26, 0xffff0000, v1
	v_lshlrev_b32_e32 v27, 16, v1
	ds_read_u16 v1, v101 offset:7168
	ds_read_u16 v24, v101 offset:10240
	v_mul_f32_e32 v0, 0xbfb8aa3b, v27
	v_exp_f32_e32 v0, v0
	ds_read_u16 v9, v101 offset:13312
	ds_read_u16 v12, v101 offset:16384
	s_waitcnt lgkmcnt(2)
	v_lshlrev_b32_e32 v25, 16, v24
	v_lshlrev_b32_e32 v24, 16, v1
	v_mul_f32_e32 v1, 0xbfb8aa3b, v26
	v_exp_f32_e32 v1, v1
	v_pk_mul_f32 v[20:21], v[20:21], v[24:25]
	s_waitcnt lgkmcnt(0)
	v_lshlrev_b32_e32 v13, 16, v12
	v_lshlrev_b32_e32 v12, 16, v9
	v_pk_add_f32 v[0:1], v[0:1], 1.0 op_sel_hi:[1,0]
	v_mul_f32_e32 v9, 0xbfb8aa3b, v16
	v_div_scale_f32 v24, s[20:21], v1, v1, v26
	v_rcp_f32_e32 v25, v24
	v_exp_f32_e32 v9, v9
	v_pk_mul_f32 v[4:5], v[4:5], v[12:13]
	v_fma_f32 v28, -v24, v25, 1.0
	v_fmac_f32_e32 v25, v28, v25
	v_div_scale_f32 v28, vcc, v26, v1, v26
	v_mul_f32_e32 v29, v28, v25
	v_fma_f32 v30, -v24, v29, v28
	v_fmac_f32_e32 v29, v30, v25
	v_fma_f32 v24, -v24, v29, v28
	v_div_fmas_f32 v24, v24, v25, v29
	v_div_fixup_f32 v1, v24, v1, v26
	v_div_scale_f32 v24, s[20:21], v0, v0, v27
	v_rcp_f32_e32 v25, v24
	v_pk_add_f32 v[8:9], v[8:9], 1.0 op_sel_hi:[1,0]
	v_fma_f32 v26, -v24, v25, 1.0
	v_fmac_f32_e32 v25, v26, v25
	v_div_scale_f32 v26, vcc, v27, v0, v27
	v_div_scale_f32 v12, s[20:21], v9, v9, v16
	v_mul_f32_e32 v28, v26, v25
	v_rcp_f32_e32 v13, v12
	v_fma_f32 v29, -v24, v28, v26
	v_fmac_f32_e32 v28, v29, v25
	v_fma_f32 v24, -v24, v28, v26
	v_div_fmas_f32 v24, v24, v25, v28
	v_fma_f32 v17, -v12, v13, 1.0
	v_div_fixup_f32 v0, v24, v0, v27
	v_fmac_f32_e32 v13, v17, v13
	v_div_scale_f32 v17, vcc, v16, v9, v16
	v_pk_mul_f32 v[0:1], v[0:1], v[20:21]
	v_mul_f32_e32 v20, v17, v13
	v_fma_f32 v21, -v12, v20, v17
	v_fmac_f32_e32 v20, v21, v13
	v_fma_f32 v12, -v12, v20, v17
	v_div_fmas_f32 v12, v12, v13, v20
	v_div_fixup_f32 v9, v12, v9, v16
	v_div_scale_f32 v12, s[20:21], v8, v8, v2
	v_rcp_f32_e32 v13, v12
	s_nop 0
	v_fma_f32 v16, -v12, v13, 1.0
	v_fmac_f32_e32 v13, v16, v13
	v_div_scale_f32 v16, vcc, v2, v8, v2
	v_mul_f32_e32 v17, v16, v13
	v_fma_f32 v20, -v12, v17, v16
	v_fmac_f32_e32 v17, v20, v13
	v_fma_f32 v12, -v12, v17, v16
	v_div_fmas_f32 v12, v12, v13, v17
	v_div_fixup_f32 v8, v12, v8, v2
	v_pk_mul_f32 v[4:5], v[8:9], v[4:5]
	v_and_b32_e32 v9, 0xffff0000, v50
	v_lshlrev_b32_e32 v8, 16, v50
	v_pk_fma_f32 v[6:7], v[18:19], v[8:9], v[6:7]
	ds_read_u16 v3, v101 offset:19456
	ds_read_u16 v8, v101 offset:22528
	v_mul_f32_e32 v2, 0xbfb8aa3b, v11
	v_exp_f32_e32 v2, v2
	s_waitcnt lgkmcnt(0)
	v_lshlrev_b32_e32 v9, 16, v8
	v_lshlrev_b32_e32 v8, 16, v3
	v_mul_f32_e32 v3, 0xbfb8aa3b, v10
	v_exp_f32_e32 v3, v3
	v_pk_mul_f32 v[6:7], v[6:7], v[8:9]
	v_pk_add_f32 v[2:3], v[2:3], 1.0 op_sel_hi:[1,0]
	s_nop 0
	v_div_scale_f32 v8, s[20:21], v3, v3, v10
	v_rcp_f32_e32 v9, v8
	s_nop 0
	v_fma_f32 v12, -v8, v9, 1.0
	v_fmac_f32_e32 v9, v12, v9
	v_div_scale_f32 v12, vcc, v10, v3, v10
	v_mul_f32_e32 v13, v12, v9
	v_fma_f32 v14, -v8, v13, v12
	v_fmac_f32_e32 v13, v14, v9
	v_fma_f32 v8, -v8, v13, v12
	v_div_fmas_f32 v8, v8, v9, v13
	v_div_fixup_f32 v3, v8, v3, v10
	v_div_scale_f32 v8, s[20:21], v2, v2, v11
	v_rcp_f32_e32 v9, v8
	s_nop 0
	v_fma_f32 v10, -v8, v9, 1.0
	v_fmac_f32_e32 v9, v10, v9
	v_div_scale_f32 v10, vcc, v11, v2, v11
	v_mul_f32_e32 v12, v10, v9
	v_fma_f32 v13, -v8, v12, v10
	v_fmac_f32_e32 v12, v13, v9
	v_fma_f32 v8, -v8, v12, v10
	v_div_fmas_f32 v8, v8, v9, v12
	v_div_fixup_f32 v2, v8, v2, v11
	v_pk_mul_f32 v[2:3], v[2:3], v[6:7]
	v_cvt_pk_bf16_f32 v4, v4, v5
	v_cvt_pk_bf16_f32 v2, v2, v3
	v_mov_b32_e32 v3, v2
	v_mov_b32_e32 v2, v4
	v_lshlrev_b64 v[4:5], 12, v[34:35]
	v_lshl_add_u64 v[4:5], s[30:31], 0, v[4:5]
	v_bfe_u32 v12, v23, 16, 1
	v_bfe_u32 v13, v22, 16, 1
	v_lshl_add_u64 v[4:5], v[4:5], 0, s[70:71]
	v_add3_u32 v13, v22, v13, s94
	v_add3_u32 v12, v23, v12, s94
	v_cvt_pk_bf16_f32 v0, v0, v1
	v_add_co_u32_e32 v4, vcc, s22, v4
	v_mov_b32_e32 v1, v0
	v_perm_b32 v0, v12, v13, s95
	v_addc_co_u32_e32 v5, vcc, 0, v5, vcc
	global_store_dwordx4 v[4:5], v[0:3], off offset:3072
	v_add_u32_e32 v34, s19, v123
	v_ashrrev_i32_e32 v35, 31, v34
	v_lshl_add_u64 v[0:1], v[108:109], 0, s[70:71]
	v_add_co_u32_e32 v0, vcc, s3, v0
	s_nop 1
	v_addc_co_u32_e32 v1, vcc, 0, v1, vcc
	global_load_dwordx4 v[0:3], v[0:1], off offset:2048
	s_waitcnt vmcnt(0)
	v_cndmask_b32_e64 v6, 0, v1, s[48:49]
	v_cndmask_b32_e64 v7, 0, v0, s[48:49]
	v_lshl_add_u64 v[0:1], v[112:113], 0, s[70:71]
	v_add_co_u32_e32 v0, vcc, s3, v0
	v_cndmask_b32_e64 v4, 0, v3, s[48:49]
	s_nop 0
	v_addc_co_u32_e32 v1, vcc, 0, v1, vcc
	v_cndmask_b32_e64 v5, 0, v2, s[48:49]
	global_load_dwordx4 v[0:3], v[0:1], off offset:2048
	v_and_b32_e32 v13, 0xffff0000, v7
	v_lshlrev_b32_e32 v12, 16, v7
	v_and_b32_e32 v47, 0xffff0000, v6
	v_lshlrev_b32_e32 v46, 16, v6
	v_and_b32_e32 v43, 0xffff0000, v5
	v_lshlrev_b32_e32 v42, 16, v5
	v_and_b32_e32 v39, 0xffff0000, v4
	v_lshlrev_b32_e32 v38, 16, v4
	s_waitcnt vmcnt(0)
	v_cndmask_b32_e64 v10, 0, v1, s[54:55]
	v_cndmask_b32_e64 v11, 0, v0, s[54:55]
	v_lshl_add_u64 v[0:1], v[116:117], 0, s[70:71]
	v_add_co_u32_e32 v0, vcc, s3, v0
	v_cndmask_b32_e64 v8, 0, v3, s[54:55]
	s_nop 0
	v_addc_co_u32_e32 v1, vcc, 0, v1, vcc
	v_cndmask_b32_e64 v9, 0, v2, s[54:55]
	global_load_dwordx4 v[0:3], v[0:1], off offset:2048
	v_and_b32_e32 v17, 0xffff0000, v11
	v_lshlrev_b32_e32 v16, 16, v11
	v_and_b32_e32 v49, 0xffff0000, v10
	v_lshlrev_b32_e32 v48, 16, v10
	v_and_b32_e32 v45, 0xffff0000, v9
	v_lshlrev_b32_e32 v44, 16, v9
	v_and_b32_e32 v41, 0xffff0000, v8
	v_lshlrev_b32_e32 v40, 16, v8
	s_waitcnt vmcnt(0)
	v_cndmask_b32_e64 v52, 0, v1, s[58:59]
	v_cndmask_b32_e64 v30, 0, v0, s[58:59]
	v_mad_i64_i32 v[0:1], s[20:21], v34, s0, v[36:37]
	v_lshl_add_u64 v[0:1], v[0:1], 0, s[70:71]
	v_add_co_u32_e32 v0, vcc, s23, v0
	v_cndmask_b32_e64 v50, 0, v3, s[58:59]
	s_nop 0
	v_addc_co_u32_e32 v1, vcc, 0, v1, vcc
	v_cndmask_b32_e64 v51, 0, v2, s[58:59]
	global_load_dwordx4 v[0:3], v[0:1], off
	s_nop 0
	global_load_dwordx4 v[4:7], v161, s[84:85] offset:2064
	global_load_dwordx4 v[18:21], v161, s[84:85] offset:2048
	global_load_dwordx4 v[8:11], v161, s[86:87] offset:2064
	global_load_dwordx4 v[22:25], v161, s[86:87] offset:2048
	s_waitcnt vmcnt(1)
	v_pk_fma_f32 v[4:5], v[8:9], v[42:43], v[4:5]
	s_waitcnt vmcnt(0)
	v_pk_fma_f32 v[18:19], v[22:23], v[12:13], v[18:19]
	global_load_dwordx4 v[12:15], v161, s[36:37] offset:16
	global_load_dwordx4 v[26:29], v196, s[86:87]
	v_pk_fma_f32 v[20:21], v[24:25], v[46:47], v[20:21]
	v_and_b32_e32 v25, 0xffff0000, v52
	v_lshlrev_b32_e32 v24, 16, v52
	v_and_b32_e32 v9, 0xffff0000, v51
	v_lshlrev_b32_e32 v8, 16, v51
	v_pk_fma_f32 v[6:7], v[10:11], v[38:39], v[6:7]
	v_and_b32_e32 v10, 0xffff0000, v3
	v_lshlrev_b32_e32 v11, 16, v3
	s_waitcnt vmcnt(1)
	v_pk_fma_f32 v[4:5], v[12:13], v[44:45], v[4:5]
	s_waitcnt vmcnt(0)
	v_pk_fma_f32 v[22:23], v[26:27], v[16:17], v[18:19]
	v_and_b32_e32 v27, 0xffff0000, v30
	v_lshlrev_b32_e32 v26, 16, v30
	global_load_dwordx4 v[16:19], v161, s[38:39] offset:16
	global_load_dwordx4 v[30:33], v197, s[86:87] offset:2048
	v_pk_fma_f32 v[20:21], v[28:29], v[48:49], v[20:21]
	v_pk_fma_f32 v[6:7], v[14:15], v[40:41], v[6:7]
	s_waitcnt vmcnt(1)
	v_pk_fma_f32 v[4:5], v[16:17], v[8:9], v[4:5]
	s_waitcnt vmcnt(0)
	v_pk_fma_f32 v[22:23], v[30:31], v[26:27], v[22:23]
	ds_read_u16 v27, v101 offset:1536
	ds_read_u16 v31, v101 offset:4608
	v_and_b32_e32 v30, 0xffff0000, v0
	v_lshlrev_b32_e32 v0, 16, v0
	v_mul_f32_e32 v26, 0xbfb8aa3b, v0
	s_waitcnt lgkmcnt(1)
	v_lshlrev_b32_e32 v54, 16, v27
	v_mul_f32_e32 v27, 0xbfb8aa3b, v30
	v_exp_f32_e32 v26, v26
	v_exp_f32_e32 v27, v27
	s_waitcnt lgkmcnt(0)
	v_lshlrev_b32_e32 v55, 16, v31
	v_pk_mul_f32 v[22:23], v[22:23], v[54:55]
	v_pk_fma_f32 v[20:21], v[32:33], v[24:25], v[20:21]
	v_pk_add_f32 v[26:27], v[26:27], 1.0 op_sel_hi:[1,0]
	v_and_b32_e32 v16, 0xffff0000, v2
	v_div_scale_f32 v31, s[20:21], v27, v27, v30
	v_rcp_f32_e32 v53, v31
	v_lshlrev_b32_e32 v2, 16, v2
	v_mul_f32_e32 v8, 0xbfb8aa3b, v2
	v_exp_f32_e32 v8, v8
	v_fma_f32 v54, -v31, v53, 1.0
	v_fmac_f32_e32 v53, v54, v53
	v_div_scale_f32 v54, vcc, v30, v27, v30
	v_mul_f32_e32 v55, v54, v53
	v_fma_f32 v56, -v31, v55, v54
	v_fmac_f32_e32 v55, v56, v53
	v_fma_f32 v31, -v31, v55, v54
	v_div_fmas_f32 v31, v31, v53, v55
	v_div_fixup_f32 v27, v31, v27, v30
	v_div_scale_f32 v30, s[20:21], v26, v26, v0
	v_rcp_f32_e32 v31, v30
	s_nop 0
	v_fma_f32 v53, -v30, v31, 1.0
	v_fmac_f32_e32 v31, v53, v31
	v_div_scale_f32 v53, vcc, v0, v26, v0
	v_mul_f32_e32 v54, v53, v31
	v_fma_f32 v55, -v30, v54, v53
	v_fmac_f32_e32 v54, v55, v31
	v_fma_f32 v30, -v30, v54, v53
	v_div_fmas_f32 v30, v30, v31, v54
	v_div_fixup_f32 v26, v30, v26, v0
	v_pk_mul_f32 v[22:23], v[26:27], v[22:23]
	v_and_b32_e32 v26, 0xffff0000, v1
	v_lshlrev_b32_e32 v27, 16, v1
	ds_read_u16 v1, v101 offset:7680
	ds_read_u16 v24, v101 offset:10752
	v_mul_f32_e32 v0, 0xbfb8aa3b, v27
	v_exp_f32_e32 v0, v0
	ds_read_u16 v9, v101 offset:13824
	ds_read_u16 v12, v101 offset:16896
	s_waitcnt lgkmcnt(2)
	v_lshlrev_b32_e32 v25, 16, v24
	v_lshlrev_b32_e32 v24, 16, v1
	v_mul_f32_e32 v1, 0xbfb8aa3b, v26
	v_exp_f32_e32 v1, v1
	v_pk_mul_f32 v[20:21], v[20:21], v[24:25]
	s_waitcnt lgkmcnt(0)
	v_lshlrev_b32_e32 v13, 16, v12
	v_lshlrev_b32_e32 v12, 16, v9
	v_pk_add_f32 v[0:1], v[0:1], 1.0 op_sel_hi:[1,0]
	v_mul_f32_e32 v9, 0xbfb8aa3b, v16
	v_div_scale_f32 v24, s[20:21], v1, v1, v26
	v_rcp_f32_e32 v25, v24
	v_exp_f32_e32 v9, v9
	v_pk_mul_f32 v[4:5], v[4:5], v[12:13]
	v_fma_f32 v28, -v24, v25, 1.0
	v_fmac_f32_e32 v25, v28, v25
	v_div_scale_f32 v28, vcc, v26, v1, v26
	v_mul_f32_e32 v29, v28, v25
	v_fma_f32 v30, -v24, v29, v28
	v_fmac_f32_e32 v29, v30, v25
	v_fma_f32 v24, -v24, v29, v28
	v_div_fmas_f32 v24, v24, v25, v29
	v_div_fixup_f32 v1, v24, v1, v26
	v_div_scale_f32 v24, s[20:21], v0, v0, v27
	v_rcp_f32_e32 v25, v24
	v_pk_add_f32 v[8:9], v[8:9], 1.0 op_sel_hi:[1,0]
	v_fma_f32 v26, -v24, v25, 1.0
	v_fmac_f32_e32 v25, v26, v25
	v_div_scale_f32 v26, vcc, v27, v0, v27
	v_div_scale_f32 v12, s[20:21], v9, v9, v16
	v_mul_f32_e32 v28, v26, v25
	v_rcp_f32_e32 v13, v12
	v_fma_f32 v29, -v24, v28, v26
	v_fmac_f32_e32 v28, v29, v25
	v_fma_f32 v24, -v24, v28, v26
	v_div_fmas_f32 v24, v24, v25, v28
	v_fma_f32 v17, -v12, v13, 1.0
	v_div_fixup_f32 v0, v24, v0, v27
	v_fmac_f32_e32 v13, v17, v13
	v_div_scale_f32 v17, vcc, v16, v9, v16
	v_pk_mul_f32 v[0:1], v[0:1], v[20:21]
	v_mul_f32_e32 v20, v17, v13
	v_fma_f32 v21, -v12, v20, v17
	v_fmac_f32_e32 v20, v21, v13
	v_fma_f32 v12, -v12, v20, v17
	v_div_fmas_f32 v12, v12, v13, v20
	v_div_fixup_f32 v9, v12, v9, v16
	v_div_scale_f32 v12, s[20:21], v8, v8, v2
	v_rcp_f32_e32 v13, v12
	s_nop 0
	v_fma_f32 v16, -v12, v13, 1.0
	v_fmac_f32_e32 v13, v16, v13
	v_div_scale_f32 v16, vcc, v2, v8, v2
	v_mul_f32_e32 v17, v16, v13
	v_fma_f32 v20, -v12, v17, v16
	v_fmac_f32_e32 v17, v20, v13
	v_fma_f32 v12, -v12, v17, v16
	v_div_fmas_f32 v12, v12, v13, v17
	v_div_fixup_f32 v8, v12, v8, v2
	v_pk_mul_f32 v[4:5], v[8:9], v[4:5]
	v_and_b32_e32 v9, 0xffff0000, v50
	v_lshlrev_b32_e32 v8, 16, v50
	v_pk_fma_f32 v[6:7], v[18:19], v[8:9], v[6:7]
	ds_read_u16 v3, v101 offset:19968
	ds_read_u16 v8, v101 offset:23040
	v_mul_f32_e32 v2, 0xbfb8aa3b, v11
	v_exp_f32_e32 v2, v2
	s_waitcnt lgkmcnt(0)
	v_lshlrev_b32_e32 v9, 16, v8
	v_lshlrev_b32_e32 v8, 16, v3
	v_mul_f32_e32 v3, 0xbfb8aa3b, v10
	v_exp_f32_e32 v3, v3
	v_pk_mul_f32 v[6:7], v[6:7], v[8:9]
	v_pk_add_f32 v[2:3], v[2:3], 1.0 op_sel_hi:[1,0]
	s_nop 0
	v_div_scale_f32 v8, s[20:21], v3, v3, v10
	v_rcp_f32_e32 v9, v8
	s_nop 0
	v_fma_f32 v12, -v8, v9, 1.0
	v_fmac_f32_e32 v9, v12, v9
	v_div_scale_f32 v12, vcc, v10, v3, v10
	v_mul_f32_e32 v13, v12, v9
	v_fma_f32 v14, -v8, v13, v12
	v_fmac_f32_e32 v13, v14, v9
	v_fma_f32 v8, -v8, v13, v12
	v_div_fmas_f32 v8, v8, v9, v13
	v_div_fixup_f32 v3, v8, v3, v10
	v_div_scale_f32 v8, s[20:21], v2, v2, v11
	v_rcp_f32_e32 v9, v8
	s_nop 0
	v_fma_f32 v10, -v8, v9, 1.0
	v_fmac_f32_e32 v9, v10, v9
	v_div_scale_f32 v10, vcc, v11, v2, v11
	v_mul_f32_e32 v12, v10, v9
	v_fma_f32 v13, -v8, v12, v10
	v_fmac_f32_e32 v12, v13, v9
	v_fma_f32 v8, -v8, v12, v10
	v_div_fmas_f32 v8, v8, v9, v12
	v_div_fixup_f32 v2, v8, v2, v11
	v_pk_mul_f32 v[2:3], v[2:3], v[6:7]
	v_cvt_pk_bf16_f32 v4, v4, v5
	v_cvt_pk_bf16_f32 v2, v2, v3
	v_mov_b32_e32 v3, v2
	v_mov_b32_e32 v2, v4
	v_lshlrev_b64 v[4:5], 12, v[34:35]
	v_lshl_add_u64 v[4:5], s[30:31], 0, v[4:5]
	v_bfe_u32 v12, v23, 16, 1
	v_bfe_u32 v13, v22, 16, 1
	v_lshl_add_u64 v[4:5], v[4:5], 0, s[70:71]
	v_add3_u32 v13, v22, v13, s94
	v_add3_u32 v12, v23, v12, s94
	v_cvt_pk_bf16_f32 v0, v0, v1
	v_add_co_u32_e32 v4, vcc, s22, v4
	v_mov_b32_e32 v1, v0
	v_perm_b32 v0, v12, v13, s95
	v_addc_co_u32_e32 v5, vcc, 0, v5, vcc
	global_store_dwordx4 v[4:5], v[0:3], off offset:3072
	v_add_u32_e32 v34, s19, v120
	v_ashrrev_i32_e32 v35, 31, v34
	v_lshl_add_u64 v[0:1], v[102:103], 0, s[70:71]
	v_add_co_u32_e32 v0, vcc, s3, v0
	s_nop 1
	v_addc_co_u32_e32 v1, vcc, 0, v1, vcc
	global_load_dwordx4 v[0:3], v[0:1], off offset:2048
	s_waitcnt vmcnt(0)
	v_cndmask_b32_e64 v6, 0, v1, s[44:45]
	v_cndmask_b32_e64 v7, 0, v0, s[44:45]
	v_lshl_add_u64 v[0:1], v[104:105], 0, s[70:71]
	v_add_co_u32_e32 v0, vcc, s3, v0
	v_cndmask_b32_e64 v4, 0, v3, s[44:45]
	s_nop 0
	v_addc_co_u32_e32 v1, vcc, 0, v1, vcc
	v_cndmask_b32_e64 v5, 0, v2, s[44:45]
	global_load_dwordx4 v[0:3], v[0:1], off offset:2048
	v_and_b32_e32 v13, 0xffff0000, v7
	v_lshlrev_b32_e32 v12, 16, v7
	v_and_b32_e32 v45, 0xffff0000, v6
	v_lshlrev_b32_e32 v44, 16, v6
	v_and_b32_e32 v41, 0xffff0000, v5
	v_lshlrev_b32_e32 v40, 16, v5
	s_waitcnt vmcnt(0)
	v_cndmask_b32_e64 v10, 0, v1, s[46:47]
	v_cndmask_b32_e64 v11, 0, v0, s[46:47]
	v_lshl_add_u64 v[0:1], v[106:107], 0, s[70:71]
	v_add_co_u32_e32 v0, vcc, s3, v0
	v_cndmask_b32_e64 v8, 0, v3, s[46:47]
	s_nop 0
	v_addc_co_u32_e32 v1, vcc, 0, v1, vcc
	v_cndmask_b32_e64 v9, 0, v2, s[46:47]
	global_load_dwordx4 v[0:3], v[0:1], off offset:2048
	v_and_b32_e32 v17, 0xffff0000, v11
	v_lshlrev_b32_e32 v16, 16, v11
	v_and_b32_e32 v47, 0xffff0000, v10
	v_lshlrev_b32_e32 v46, 16, v10
	v_and_b32_e32 v43, 0xffff0000, v9
	v_lshlrev_b32_e32 v42, 16, v9
	v_and_b32_e32 v39, 0xffff0000, v8
	v_lshlrev_b32_e32 v38, 16, v8
	s_waitcnt vmcnt(0)
	v_cndmask_b32_e64 v50, 0, v1, s[52:53]
	v_cndmask_b32_e64 v30, 0, v0, s[52:53]
	v_mad_i64_i32 v[0:1], s[20:21], v34, s0, v[36:37]
	v_lshl_add_u64 v[0:1], v[0:1], 0, s[70:71]
	v_add_co_u32_e32 v0, vcc, s23, v0
	v_cndmask_b32_e64 v48, 0, v3, s[52:53]
	s_nop 0
	v_addc_co_u32_e32 v1, vcc, 0, v1, vcc
	v_cndmask_b32_e64 v49, 0, v2, s[52:53]
	global_load_dwordx4 v[0:3], v[0:1], off
	v_and_b32_e32 v37, 0xffff0000, v4
	v_lshlrev_b32_e32 v36, 16, v4
	global_load_dwordx4 v[4:7], v161, s[84:85] offset:2064
	global_load_dwordx4 v[18:21], v161, s[84:85] offset:2048
	global_load_dwordx4 v[8:11], v161, s[86:87] offset:2064
	global_load_dwordx4 v[22:25], v161, s[86:87] offset:2048
	s_waitcnt vmcnt(1)
	v_pk_fma_f32 v[4:5], v[8:9], v[40:41], v[4:5]
	s_waitcnt vmcnt(0)
	v_pk_fma_f32 v[18:19], v[22:23], v[12:13], v[18:19]
	global_load_dwordx4 v[12:15], v161, s[36:37] offset:16
	global_load_dwordx4 v[26:29], v196, s[86:87]
	v_pk_fma_f32 v[20:21], v[24:25], v[44:45], v[20:21]
	v_and_b32_e32 v25, 0xffff0000, v50
	v_lshlrev_b32_e32 v24, 16, v50
	v_and_b32_e32 v9, 0xffff0000, v49
	v_lshlrev_b32_e32 v8, 16, v49
	v_pk_fma_f32 v[6:7], v[10:11], v[36:37], v[6:7]
	s_waitcnt vmcnt(1)
	v_pk_fma_f32 v[4:5], v[12:13], v[42:43], v[4:5]
	s_waitcnt vmcnt(0)
	v_pk_fma_f32 v[22:23], v[26:27], v[16:17], v[18:19]
	v_and_b32_e32 v27, 0xffff0000, v30
	v_lshlrev_b32_e32 v26, 16, v30
	global_load_dwordx4 v[16:19], v161, s[38:39] offset:16
	global_load_dwordx4 v[30:33], v197, s[86:87] offset:2048
	v_pk_fma_f32 v[20:21], v[28:29], v[46:47], v[20:21]
	v_pk_fma_f32 v[6:7], v[14:15], v[38:39], v[6:7]
	s_waitcnt vmcnt(1)
	v_pk_fma_f32 v[4:5], v[16:17], v[8:9], v[4:5]
	s_waitcnt vmcnt(0)
	v_pk_fma_f32 v[22:23], v[30:31], v[26:27], v[22:23]
	ds_read_u16 v27, v101 offset:2048
	ds_read_u16 v31, v101 offset:5120
	v_and_b32_e32 v30, 0xffff0000, v0
	v_lshlrev_b32_e32 v0, 16, v0
	v_mul_f32_e32 v26, 0xbfb8aa3b, v0
	s_waitcnt lgkmcnt(1)
	v_lshlrev_b32_e32 v52, 16, v27
	v_mul_f32_e32 v27, 0xbfb8aa3b, v30
	v_exp_f32_e32 v26, v26
	v_exp_f32_e32 v27, v27
	s_waitcnt lgkmcnt(0)
	v_lshlrev_b32_e32 v53, 16, v31
	v_pk_mul_f32 v[22:23], v[22:23], v[52:53]
	v_pk_fma_f32 v[20:21], v[32:33], v[24:25], v[20:21]
	v_pk_add_f32 v[26:27], v[26:27], 1.0 op_sel_hi:[1,0]
	v_and_b32_e32 v25, 0xffff0000, v1
	v_div_scale_f32 v31, s[20:21], v27, v27, v30
	v_rcp_f32_e32 v51, v31
	v_lshlrev_b32_e32 v24, 16, v1
	v_and_b32_e32 v16, 0xffff0000, v2
	v_lshlrev_b32_e32 v2, 16, v2
	v_fma_f32 v52, -v31, v51, 1.0
	v_fmac_f32_e32 v51, v52, v51
	v_div_scale_f32 v52, vcc, v30, v27, v30
	v_mul_f32_e32 v53, v52, v51
	v_fma_f32 v54, -v31, v53, v52
	v_fmac_f32_e32 v53, v54, v51
	v_fma_f32 v31, -v31, v53, v52
	v_div_fmas_f32 v31, v31, v51, v53
	v_div_fixup_f32 v27, v31, v27, v30
	v_div_scale_f32 v30, s[20:21], v26, v26, v0
	v_rcp_f32_e32 v31, v30
	v_mul_f32_e32 v8, 0xbfb8aa3b, v2
	v_exp_f32_e32 v8, v8
	v_fma_f32 v51, -v30, v31, 1.0
	v_fmac_f32_e32 v31, v51, v31
	v_div_scale_f32 v51, vcc, v0, v26, v0
	v_mul_f32_e32 v52, v51, v31
	v_fma_f32 v53, -v30, v52, v51
	v_fmac_f32_e32 v52, v53, v31
	v_fma_f32 v30, -v30, v52, v51
	v_div_fmas_f32 v30, v30, v31, v52
	v_div_fixup_f32 v26, v30, v26, v0
	v_pk_mul_f32 v[22:23], v[26:27], v[22:23]
	ds_read_u16 v1, v101 offset:8192
	ds_read_u16 v26, v101 offset:11264
	v_mul_f32_e32 v0, 0xbfb8aa3b, v24
	v_exp_f32_e32 v0, v0
	ds_read_u16 v9, v101 offset:14336
	ds_read_u16 v12, v101 offset:17408
	s_waitcnt lgkmcnt(2)
	v_lshlrev_b32_e32 v27, 16, v26
	v_lshlrev_b32_e32 v26, 16, v1
	v_mul_f32_e32 v1, 0xbfb8aa3b, v25
	v_exp_f32_e32 v1, v1
	v_pk_mul_f32 v[20:21], v[20:21], v[26:27]
	s_waitcnt lgkmcnt(0)
	v_lshlrev_b32_e32 v13, 16, v12
	v_lshlrev_b32_e32 v12, 16, v9
	v_pk_add_f32 v[0:1], v[0:1], 1.0 op_sel_hi:[1,0]
	v_mul_f32_e32 v9, 0xbfb8aa3b, v16
	v_div_scale_f32 v26, s[20:21], v1, v1, v25
	v_rcp_f32_e32 v27, v26
	v_exp_f32_e32 v9, v9
	v_pk_mul_f32 v[4:5], v[4:5], v[12:13]
	v_fma_f32 v28, -v26, v27, 1.0
	v_fmac_f32_e32 v27, v28, v27
	v_div_scale_f32 v28, vcc, v25, v1, v25
	v_mul_f32_e32 v29, v28, v27
	v_fma_f32 v30, -v26, v29, v28
	v_fmac_f32_e32 v29, v30, v27
	v_fma_f32 v26, -v26, v29, v28
	v_div_fmas_f32 v26, v26, v27, v29
	v_div_fixup_f32 v1, v26, v1, v25
	v_div_scale_f32 v25, s[20:21], v0, v0, v24
	v_rcp_f32_e32 v26, v25
	v_pk_add_f32 v[8:9], v[8:9], 1.0 op_sel_hi:[1,0]
	v_fma_f32 v27, -v25, v26, 1.0
	v_fmac_f32_e32 v26, v27, v26
	v_div_scale_f32 v27, vcc, v24, v0, v24
	v_div_scale_f32 v12, s[20:21], v9, v9, v16
	v_mul_f32_e32 v28, v27, v26
	v_rcp_f32_e32 v13, v12
	v_fma_f32 v29, -v25, v28, v27
	v_fmac_f32_e32 v28, v29, v26
	v_fma_f32 v25, -v25, v28, v27
	v_div_fmas_f32 v25, v25, v26, v28
	v_fma_f32 v17, -v12, v13, 1.0
	v_div_fixup_f32 v0, v25, v0, v24
	v_fmac_f32_e32 v13, v17, v13
	v_div_scale_f32 v17, vcc, v16, v9, v16
	v_pk_mul_f32 v[0:1], v[0:1], v[20:21]
	v_mul_f32_e32 v20, v17, v13
	v_fma_f32 v21, -v12, v20, v17
	v_fmac_f32_e32 v20, v21, v13
	v_fma_f32 v12, -v12, v20, v17
	v_div_fmas_f32 v12, v12, v13, v20
	v_div_fixup_f32 v9, v12, v9, v16
	v_div_scale_f32 v12, s[20:21], v8, v8, v2
	v_rcp_f32_e32 v13, v12
	s_nop 0
	v_fma_f32 v16, -v12, v13, 1.0
	v_fmac_f32_e32 v13, v16, v13
	v_div_scale_f32 v16, vcc, v2, v8, v2
	v_mul_f32_e32 v17, v16, v13
	v_fma_f32 v20, -v12, v17, v16
	v_fmac_f32_e32 v17, v20, v13
	v_fma_f32 v12, -v12, v17, v16
	v_div_fmas_f32 v12, v12, v13, v17
	v_div_fixup_f32 v8, v12, v8, v2
	v_pk_mul_f32 v[4:5], v[8:9], v[4:5]
	v_and_b32_e32 v9, 0xffff0000, v48
	v_lshlrev_b32_e32 v8, 16, v48
	v_pk_fma_f32 v[6:7], v[18:19], v[8:9], v[6:7]
	v_and_b32_e32 v9, 0xffff0000, v3
	v_lshlrev_b32_e32 v8, 16, v3
	ds_read_u16 v3, v101 offset:20480
	ds_read_u16 v10, v101 offset:23552
	v_mul_f32_e32 v2, 0xbfb8aa3b, v8
	v_exp_f32_e32 v2, v2
	s_waitcnt lgkmcnt(0)
	v_lshlrev_b32_e32 v11, 16, v10
	v_lshlrev_b32_e32 v10, 16, v3
	v_mul_f32_e32 v3, 0xbfb8aa3b, v9
	v_exp_f32_e32 v3, v3
	v_pk_mul_f32 v[6:7], v[6:7], v[10:11]
	v_pk_add_f32 v[2:3], v[2:3], 1.0 op_sel_hi:[1,0]
	s_nop 0
	v_div_scale_f32 v10, s[20:21], v3, v3, v9
	v_rcp_f32_e32 v11, v10
	s_nop 0
	v_fma_f32 v12, -v10, v11, 1.0
	v_fmac_f32_e32 v11, v12, v11
	v_div_scale_f32 v12, vcc, v9, v3, v9
	v_mul_f32_e32 v13, v12, v11
	v_fma_f32 v14, -v10, v13, v12
	v_fmac_f32_e32 v13, v14, v11
	v_fma_f32 v10, -v10, v13, v12
	v_div_fmas_f32 v10, v10, v11, v13
	v_div_fixup_f32 v3, v10, v3, v9
	v_div_scale_f32 v9, s[20:21], v2, v2, v8
	v_rcp_f32_e32 v10, v9
	s_nop 0
	v_fma_f32 v11, -v9, v10, 1.0
	v_fmac_f32_e32 v10, v11, v10
	v_div_scale_f32 v11, vcc, v8, v2, v8
	v_mul_f32_e32 v12, v11, v10
	v_fma_f32 v13, -v9, v12, v11
	v_fmac_f32_e32 v12, v13, v10
	v_fma_f32 v9, -v9, v12, v11
	v_div_fmas_f32 v9, v9, v10, v12
	v_div_fixup_f32 v2, v9, v2, v8
	v_pk_mul_f32 v[2:3], v[2:3], v[6:7]
	v_cvt_pk_bf16_f32 v4, v4, v5
	v_cvt_pk_bf16_f32 v2, v2, v3
	v_mov_b32_e32 v3, v2
	v_mov_b32_e32 v2, v4
	v_lshlrev_b64 v[4:5], 12, v[34:35]
	v_lshl_add_u64 v[4:5], s[30:31], 0, v[4:5]
	v_bfe_u32 v12, v23, 16, 1
	v_bfe_u32 v13, v22, 16, 1
	v_lshl_add_u64 v[4:5], v[4:5], 0, s[70:71]
	v_add3_u32 v13, v22, v13, s94
	v_add3_u32 v12, v23, v12, s94
	v_cvt_pk_bf16_f32 v0, v0, v1
	v_add_co_u32_e32 v4, vcc, 0xcc00000, v4
	v_mov_b32_e32 v1, v0
	v_perm_b32 v0, v12, v13, s95
	v_addc_co_u32_e32 v5, vcc, 0, v5, vcc
	global_store_dwordx4 v[4:5], v[0:3], off offset:3072
	s_barrier
